# static s_setprio 1 for waves 4-7 before the 4-phase K-loop, per-segment flips removed from the loop (strategy: one static priority raise for the younger half)
# speedup vs baseline: 1.0324x; 1.0026x over previous
; DI int get_tid(int wv) { int l; asm volatile("v_mbcnt_lo_u32_b32 %0, -1, 0\n\tv_mbcnt_hi_u32_b32 %0, -1, %0" : "=v"(l)); return wv * 64 + l; }
; DI int wave_of(int tid) { return __builtin_amdgcn_readfirstlane(tid >> 6); }
; #define STAGE_A(P, br, kt) do { const char* _g = (const char*)(A + (long)(br) * lda + (long)(kt) * BK); \
;     __builtin_amdgcn_global_load_lds((const unsigned*)(_g + (size_t)offA0), (unsigned*)((char*)(P) + sb0), 16, 0, 0); \
;     __builtin_amdgcn_global_load_lds((const unsigned*)(_g + (size_t)lda * 128 + (size_t)offA0), (unsigned*)((char*)(P) + sb1), 16, 0, 0); } while (0)
; #define STAGE_B(P, br, kt) do { const char* _g = (const char*)(B + (long)(br) * ldb + (long)(kt) * BK); \
;     __builtin_amdgcn_global_load_lds((const unsigned*)(_g + (size_t)offB0), (unsigned*)((char*)(P) + sb0), 16, 0, 0); \
;     __builtin_amdgcn_global_load_lds((const unsigned*)(_g + (size_t)ldb * 128 + (size_t)offB0), (unsigned*)((char*)(P) + sb1), 16, 0, 0); } while (0)
; #define BAR __builtin_amdgcn_s_barrier()
; DI void gemm_core(WVP char* smem, const u16* __restrict__ A, int lda, int ar0, int ar1,
;                   const u16* __restrict__ B, int ldb, int bc0, int K, AccT& acc) {
;     ...
;   const int tid = get_tid(WV);
;   const int wid = wave_of(tid), lane = tid & 63, wr = wid >> 2, wc = wid & 3, fr = lane & 15, fq = lane >> 4;
;   const int sb0 = tid * 16, sb1 = sb0 + 8192;
;   int R0, C0; stage_rc(sb0, R0, C0);
;   const unsigned offA0 = (unsigned)(R0 * lda + C0) * 2u, offB0 = (unsigned)(R0 * ldb + C0) * 2u;
;   const int ac0 = ar0, ac1 = ar1, bb0 = bc0, bb1 = bc0 + HALF;
;   bf16x8 At[4][2], B0[2][2], B1[2][2];
;   const int nt = K / BK;
;   __syncthreads();
;   STAGE_B(SB(0, 0), bb0, 0); STAGE_A(SA(0, 0), ac0, 0);
;   STAGE_B(SB(0, 1), bb1, 0); STAGE_A(SA(0, 1), ac1, 0);
;   if (wr == 1) BAR;
.LBB0_91:
	s_add_i32 s0, s1, s8
	s_ashr_i32 s1, s0, 31
	s_lshr_b32 s1, s1, 23
	s_add_i32 s1, s0, s1
	s_ashr_i32 s8, s1, 9
	s_and_b32 s1, s1, 0xfe00
	s_sub_i32 s0, s0, s1
	s_sext_i32_i16 s1, s0
	s_bfe_u32 s1, s1, 0x2001d
	v_mbcnt_lo_u32_b32 v6, -1, 0
	v_mbcnt_hi_u32_b32 v6, -1, v6
	s_add_i32 s1, s0, s1
	v_add_u32_e32 v0, s3, v6
	v_ashrrev_i32_e32 v2, 31, v0
	s_lshl_b32 s29, s8, 2
	s_sext_i32_i16 s8, s1
	s_and_b32 s1, s1, 0xfffc
	v_lshrrev_b32_e32 v2, 26, v2
	s_sub_i32 s0, s0, s1
	v_readfirstlane_b32 s1, v0
	v_lshlrev_b32_e32 v11, 4, v0
	v_add_u32_e32 v2, v0, v2
	v_bfe_i32 v0, v0, 27, 1
	v_lshrrev_b32_e32 v0, 22, v0
	v_add_u32_e32 v0, v11, v0
	v_and_b32_e32 v0, 0xfffffc00, v0
	v_sub_u32_e32 v0, v11, v0
	v_ashrrev_i32_e32 v7, 6, v2
	v_lshrrev_b32_e32 v2, 4, v0
	v_bitop3_b32 v0, v2, v0, 32 bitop3:0x6c
	v_ashrrev_i32_e32 v3, 31, v0
	v_lshrrev_b32_e32 v3, 26, v3
	v_add_u32_e32 v3, v0, v3
	v_lshlrev_b32_e32 v2, 3, v7
	v_ashrrev_i32_e32 v9, 6, v3
	v_and_b32_e32 v3, 0xc0, v3
	v_and_b32_e32 v2, 0xfffff0, v2
	v_sub_u32_e32 v0, v0, v3
	s_sext_i32_i16 s0, s0
	s_ashr_i32 s30, s8, 2
	v_add_u32_e32 v2, v9, v2
	v_ashrrev_i16_sdwa v0, v254, sext(v0) dst_sel:DWORD dst_unused:UNUSED_PAD src0_sel:DWORD src1_sel:BYTE_0
	s_movk_i32 s8, 0xb00
	s_add_i32 s29, s29, s0
	v_bfe_i32 v10, v0, 0, 16
	v_mul_lo_u32 v0, v2, s8
	s_mul_i32 s8, s30, 0xb0000
	s_lshl_b32 s14, s29, 8
	s_ashr_i32 s9, s8, 31
	s_or_b32 s18, s14, 0x80
	s_ashr_i32 s0, s1, 8
	s_lshl_b64 s[8:9], s[8:9], 1
	s_add_u32 s8, s54, s8
	v_lshlrev_b32_e32 v4, 5, v7
	s_addc_u32 s9, s55, s9
	s_add_i32 s19, 0, 0x10000
	v_add_u32_e32 v14, 0x2000, v11
	v_and_b32_e32 v8, 32, v4
	v_add_u32_e32 v134, s19, v11
	v_or_b32_e32 v0, v0, v8
	v_readfirstlane_b32 s15, v134
	v_add_u32_e32 v12, s19, v14
	v_add_lshl_u32 v0, v0, v10, 1
	s_mov_b32 m0, s15
	v_readfirstlane_b32 s15, v12
	s_barrier
	v_lshl_add_u64 v[2:3], s[8:9], 0, v[0:1]
	global_load_lds_dwordx4 v0, s[8:9]
	s_mov_b64 s[36:37], 0x58000
	s_mov_b32 m0, s15
	s_ashr_i32 s15, s14, 31
	s_mul_i32 s16, s29, 0x160000
	v_readlane_b32 s23, v255, 40
	v_add_u32_e32 v135, 0, v11
	v_lshl_add_u64 v[4:5], v[2:3], 0, s[36:37]
	s_mul_hi_i32 s17, s14, 0x1600
	s_add_u32 s20, s23, s16
	v_readlane_b32 s28, v255, 41
	v_readfirstlane_b32 s22, v135
	global_load_lds_dwordx4 v[4:5], off
	s_addc_u32 s21, s28, s17
	s_mov_b32 m0, s22
	v_add_u32_e32 v136, 0x2000, v135
	v_lshl_add_u64 v[4:5], s[20:21], 0, v[0:1]
	global_load_lds_dwordx4 v0, s[20:21]
	v_readfirstlane_b32 s20, v136
	v_lshl_add_u64 v[12:13], v[4:5], 0, s[36:37]
	s_mov_b32 m0, s20
	s_mov_b64 s[20:21], 0xb0000
	v_add_u32_e32 v138, s60, v11
	global_load_lds_dwordx4 v[12:13], off
	v_lshl_add_u64 v[12:13], v[2:3], 0, s[20:21]
	v_readfirstlane_b32 s20, v138
	s_mov_b32 m0, s20
	s_mov_b64 s[20:21], 0x108000
	v_add_u32_e32 v14, s60, v14
	global_load_lds_dwordx4 v[12:13], off
	v_lshl_add_u64 v[12:13], v[2:3], 0, s[20:21]
	v_readfirstlane_b32 s20, v14
	s_mul_hi_i32 s21, s18, 0x1600
	s_mulk_i32 s18, 0x1600
	s_mov_b32 m0, s20
	s_add_u32 s20, s23, s18
	v_add_u32_e32 v139, 0x4000, v135
	s_addc_u32 s21, s28, s21
	v_readfirstlane_b32 s18, v139
	v_add_u32_e32 v140, 0x6000, v135
	global_load_lds_dwordx4 v[12:13], off
	v_lshl_add_u64 v[130:131], s[20:21], 0, v[0:1]
	s_mov_b32 m0, s18
	v_readfirstlane_b32 s18, v140
	global_load_lds_dwordx4 v0, s[20:21]
	v_lshl_add_u64 v[12:13], v[130:131], 0, s[36:37]
	s_mov_b32 m0, s18
	s_cmp_lg_u32 s0, 1
	global_load_lds_dwordx4 v[12:13], off
	v_mov_b32_e32 v16, 0
	v_mov_b32_e32 v17, 0
	v_mov_b32_e32 v18, 0
	v_mov_b32_e32 v19, 0
	v_mov_b32_e32 v20, 0
	v_mov_b32_e32 v21, 0
	v_mov_b32_e32 v22, 0
	v_mov_b32_e32 v23, 0
	v_mov_b32_e32 v24, 0
	v_mov_b32_e32 v25, 0
	v_mov_b32_e32 v26, 0
	v_mov_b32_e32 v27, 0
	v_mov_b32_e32 v28, 0
	v_mov_b32_e32 v29, 0
	v_mov_b32_e32 v30, 0
	v_mov_b32_e32 v31, 0
	v_mov_b32_e32 v32, 0
	v_mov_b32_e32 v33, 0
	v_mov_b32_e32 v34, 0
	v_mov_b32_e32 v35, 0
	v_mov_b32_e32 v36, 0
	v_mov_b32_e32 v37, 0
	v_mov_b32_e32 v38, 0
	v_mov_b32_e32 v39, 0
	v_mov_b32_e32 v40, 0
	v_mov_b32_e32 v41, 0
	v_mov_b32_e32 v42, 0
	v_mov_b32_e32 v43, 0
	v_mov_b32_e32 v44, 0
	v_mov_b32_e32 v45, 0
	v_mov_b32_e32 v46, 0
	v_mov_b32_e32 v47, 0
	v_mov_b32_e32 v48, 0
	v_mov_b32_e32 v49, 0
	v_mov_b32_e32 v50, 0
	v_mov_b32_e32 v51, 0
	v_mov_b32_e32 v52, 0
	v_mov_b32_e32 v53, 0
	v_mov_b32_e32 v54, 0
	v_mov_b32_e32 v55, 0
	v_mov_b32_e32 v56, 0
	v_mov_b32_e32 v57, 0
	v_mov_b32_e32 v58, 0
	v_mov_b32_e32 v59, 0
	v_mov_b32_e32 v60, 0
	v_mov_b32_e32 v61, 0
	v_mov_b32_e32 v62, 0
	v_mov_b32_e32 v63, 0
	v_mov_b32_e32 v64, 0
	v_mov_b32_e32 v65, 0
	v_mov_b32_e32 v66, 0
	v_mov_b32_e32 v67, 0
	v_mov_b32_e32 v68, 0
	v_mov_b32_e32 v69, 0
	v_mov_b32_e32 v70, 0
	v_mov_b32_e32 v71, 0
	v_mov_b32_e32 v72, 0
	v_mov_b32_e32 v73, 0
	v_mov_b32_e32 v74, 0
	v_mov_b32_e32 v75, 0
	v_mov_b32_e32 v76, 0
	v_mov_b32_e32 v77, 0
	v_mov_b32_e32 v78, 0
	v_mov_b32_e32 v79, 0
	v_mov_b32_e32 v80, 0
	v_mov_b32_e32 v81, 0
	v_mov_b32_e32 v82, 0
	v_mov_b32_e32 v83, 0
	v_mov_b32_e32 v84, 0
	v_mov_b32_e32 v85, 0
	v_mov_b32_e32 v86, 0
	v_mov_b32_e32 v87, 0
	v_mov_b32_e32 v88, 0
	v_mov_b32_e32 v89, 0
	v_mov_b32_e32 v90, 0
	v_mov_b32_e32 v91, 0
	v_mov_b32_e32 v92, 0
	v_mov_b32_e32 v93, 0
	v_mov_b32_e32 v94, 0
	v_mov_b32_e32 v95, 0
	v_mov_b32_e32 v96, 0
	v_mov_b32_e32 v97, 0
	v_mov_b32_e32 v98, 0
	v_mov_b32_e32 v99, 0
	v_mov_b32_e32 v100, 0
	v_mov_b32_e32 v101, 0
	v_mov_b32_e32 v102, 0
	v_mov_b32_e32 v103, 0
	v_mov_b32_e32 v104, 0
	v_mov_b32_e32 v105, 0
	v_mov_b32_e32 v106, 0
	v_mov_b32_e32 v107, 0
	v_mov_b32_e32 v108, 0
	v_mov_b32_e32 v109, 0
	v_mov_b32_e32 v110, 0
	v_mov_b32_e32 v111, 0
	v_mov_b32_e32 v112, 0
	v_mov_b32_e32 v113, 0
	v_mov_b32_e32 v114, 0
	v_mov_b32_e32 v115, 0
	v_mov_b32_e32 v116, 0
	v_mov_b32_e32 v117, 0
	v_mov_b32_e32 v118, 0
	v_mov_b32_e32 v119, 0
	v_mov_b32_e32 v120, 0
	v_mov_b32_e32 v121, 0
	v_mov_b32_e32 v122, 0
	v_mov_b32_e32 v123, 0
	v_mov_b32_e32 v124, 0
	v_mov_b32_e32 v125, 0
	v_mov_b32_e32 v126, 0
	v_mov_b32_e32 v127, 0
	v_mov_b32_e32 v128, 0
	v_mov_b32_e32 v129, 0
	s_cbranch_scc1 .LBB0_93
	s_setprio 1
	s_barrier

; #define STAGE_A(P, br, kt) do { const char* _g = (const char*)(A + (long)(br) * lda + (long)(kt) * BK); \
;     __builtin_amdgcn_global_load_lds((const unsigned*)(_g + (size_t)offA0), (unsigned*)((char*)(P) + sb0), 16, 0, 0); \
;     __builtin_amdgcn_global_load_lds((const unsigned*)(_g + (size_t)lda * 128 + (size_t)offA0), (unsigned*)((char*)(P) + sb1), 16, 0, 0); } while (0)
; #define STAGE_B(P, br, kt) do { const char* _g = (const char*)(B + (long)(br) * ldb + (long)(kt) * BK); \
;     __builtin_amdgcn_global_load_lds((const unsigned*)(_g + (size_t)offB0), (unsigned*)((char*)(P) + sb0), 16, 0, 0); \
;     __builtin_amdgcn_global_load_lds((const unsigned*)(_g + (size_t)ldb * 128 + (size_t)offB0), (unsigned*)((char*)(P) + sb1), 16, 0, 0); } while (0)
; #define LDA(dst, b, h) for (int m = 0; m < 4; ++m) for (int k = 0; k < 2; ++k) \
;     dst[m][k] = *reinterpret_cast<const bf16x8*>((char*)SA(b, h) + lds_byte(wr * 64 + m * 16 + fr, k * 32 + fq * 8))
; #define LDB(dst, b, h) for (int n = 0; n < 2; ++n) for (int k = 0; k < 2; ++k) \
;     dst[n][k] = *reinterpret_cast<const bf16x8*>((char*)SB(b, h) + lds_byte(wc * 32 + n * 16 + fr, k * 32 + fq * 8))
; #define MMA(ai, bj, At_, Bt_) do { __builtin_amdgcn_s_setprio(1); \
;     for (int m = 0; m < 4; ++m) for (int n = 0; n < 2; ++n) for (int k = 0; k < 2; ++k) \
;       acc[ai][bj][m][n] = MFMA16(At_[m][k], Bt_[n][k], acc[ai][bj][m][n]); \
;     __builtin_amdgcn_s_setprio(0); } while (0)
; #define WAIT_V(n) asm volatile("s_waitcnt vmcnt(" #n ")" ::: "memory")
; #define WAIT_L(n) asm volatile("s_waitcnt lgkmcnt(" #n ")" ::: "memory")
; #define BAR __builtin_amdgcn_s_barrier()
; #define SCHED __builtin_amdgcn_sched_barrier(0)
; DI void gemm_core(WVP char* smem, const u16* __restrict__ A, int lda, int ar0, int ar1,
;                   const u16* __restrict__ B, int ldb, int bc0, int K, AccT& acc) {
;     ...
;     LDB(B0, 0, 0); SCHED; LDA(At, 0, 0); STAGE_A(SA(1, 1), ac1, t + 1);
;     WAIT_L(8); BAR; WAIT_L(0); MMA(0, 0, At, B0); BAR; SCHED;
;     LDB(B1, 0, 1); STAGE_B(SB(0, 0), bb0, t + 2);
;     BAR; WAIT_L(0); MMA(0, 1, At, B1); BAR;
;     LDA(At, 0, 1); STAGE_A(SA(0, 0), ac0, t + 2);
;     BAR; WAIT_L(0); MMA(1, 0, At, B0); BAR; SCHED;
;     STAGE_B(SB(0, 1), bb1, t + 2);
;     WAIT_V(6); BAR; MMA(1, 1, At, B1); BAR;
.LBB0_94:
	v_add_u32_e32 v150, s0, v148
	v_add_u32_e32 v151, s1, v148
	v_add_u32_e32 v152, s19, v148
	ds_read_b128 v[156:159], v149
	ds_read_b128 v[160:163], v149 offset:1024
	ds_read_b128 v[164:167], v149 offset:2048
	ds_read_b128 v[168:171], v149 offset:3072
	ds_read_b128 v[172:175], v132
	ds_read_b128 v[176:179], v132 offset:1024
	ds_read_b128 v[180:183], v150
	ds_read_b128 v[184:187], v150 offset:1024
	ds_read_b128 v[188:191], v151
	ds_read_b128 v[192:195], v151 offset:1024
	ds_read_b128 v[196:199], v152
	ds_read_b128 v[200:203], v152 offset:1024
	ds_read_b128 v[206:209], v146
	ds_read_b128 v[210:213], v146 offset:1024
	ds_read_b128 v[214:217], v146 offset:2048
	ds_read_b128 v[218:221], v146 offset:3072
	v_add_u32_e32 v153, 0xc000, v135
	v_lshl_add_u64 v[224:225], s[16:17], 0, v[0:1]
	s_mov_b64 s[22:23], 0x1f430080
	v_lshl_add_u64 v[222:223], v[224:225], 0, s[22:23]
	v_readfirstlane_b32 s21, v153
	s_mov_b32 m0, s21
	s_nop 0
	global_load_lds_dwordx4 v[222:223], off
	v_add_u32_e32 v154, 0xe000, v135
	v_lshl_add_u64 v[224:225], s[16:17], 0, v[0:1]
	s_mov_b64 s[22:23], 0x1f488080
	v_lshl_add_u64 v[222:223], v[224:225], 0, s[22:23]
	v_readfirstlane_b32 s21, v154
	s_mov_b32 m0, s21
	s_nop 0
	global_load_lds_dwordx4 v[222:223], off
	s_waitcnt vmcnt(8)
	s_waitcnt lgkmcnt(0)
	s_barrier
	v_mfma_f32_16x16x32_bf16 v[126:129], v[172:175], v[156:159], v[126:129]
	v_mfma_f32_16x16x32_bf16 v[122:125], v[172:175], v[164:167], v[122:125]
	v_mfma_f32_16x16x32_bf16 v[118:121], v[180:183], v[156:159], v[118:121]
	v_mfma_f32_16x16x32_bf16 v[114:117], v[180:183], v[164:167], v[114:117]
	v_mfma_f32_16x16x32_bf16 v[110:113], v[188:191], v[156:159], v[110:113]
	v_mfma_f32_16x16x32_bf16 v[106:109], v[188:191], v[164:167], v[106:109]
	v_mfma_f32_16x16x32_bf16 v[102:105], v[196:199], v[156:159], v[102:105]
	v_mfma_f32_16x16x32_bf16 v[98:101], v[196:199], v[164:167], v[98:101]
	v_mfma_f32_16x16x32_bf16 v[126:129], v[176:179], v[160:163], v[126:129]
	v_mfma_f32_16x16x32_bf16 v[122:125], v[176:179], v[168:171], v[122:125]
	v_mfma_f32_16x16x32_bf16 v[118:121], v[184:187], v[160:163], v[118:121]
	v_mfma_f32_16x16x32_bf16 v[114:117], v[184:187], v[168:171], v[114:117]
	v_mfma_f32_16x16x32_bf16 v[110:113], v[192:195], v[160:163], v[110:113]
	v_mfma_f32_16x16x32_bf16 v[106:109], v[192:195], v[168:171], v[106:109]
	v_mfma_f32_16x16x32_bf16 v[102:105], v[200:203], v[160:163], v[102:105]
	v_mfma_f32_16x16x32_bf16 v[98:101], v[200:203], v[168:171], v[98:101]
	v_mfma_f32_16x16x32_bf16 v[94:97], v[172:175], v[206:209], v[94:97]
	v_mfma_f32_16x16x32_bf16 v[90:93], v[172:175], v[214:217], v[90:93]
	v_mfma_f32_16x16x32_bf16 v[86:89], v[180:183], v[206:209], v[86:89]
	v_mfma_f32_16x16x32_bf16 v[82:85], v[180:183], v[214:217], v[82:85]
	v_mfma_f32_16x16x32_bf16 v[78:81], v[188:191], v[206:209], v[78:81]
	v_mfma_f32_16x16x32_bf16 v[74:77], v[188:191], v[214:217], v[74:77]
	v_mfma_f32_16x16x32_bf16 v[70:73], v[196:199], v[206:209], v[70:73]
	v_mfma_f32_16x16x32_bf16 v[66:69], v[196:199], v[214:217], v[66:69]
	v_mfma_f32_16x16x32_bf16 v[94:97], v[176:179], v[210:213], v[94:97]
	v_mfma_f32_16x16x32_bf16 v[90:93], v[176:179], v[218:221], v[90:93]
	v_mfma_f32_16x16x32_bf16 v[86:89], v[184:187], v[210:213], v[86:89]
	v_mfma_f32_16x16x32_bf16 v[82:85], v[184:187], v[218:221], v[82:85]
	v_mfma_f32_16x16x32_bf16 v[78:81], v[192:195], v[210:213], v[78:81]
	v_mfma_f32_16x16x32_bf16 v[74:77], v[192:195], v[218:221], v[74:77]
	v_mfma_f32_16x16x32_bf16 v[70:73], v[200:203], v[210:213], v[70:73]
	v_mfma_f32_16x16x32_bf16 v[66:69], v[200:203], v[218:221], v[66:69]
	s_barrier
	ds_read_b128 v[172:175], v132 offset:16384
	ds_read_b128 v[176:179], v132 offset:17408
	ds_read_b128 v[180:183], v150 offset:16384
	ds_read_b128 v[184:187], v150 offset:17408
	ds_read_b128 v[188:191], v151 offset:16384
	ds_read_b128 v[192:195], v151 offset:17408
	ds_read_b128 v[196:199], v152 offset:16384
	ds_read_b128 v[200:203], v152 offset:17408
	v_lshl_add_u64 v[224:225], s[8:9], 0, v[0:1]
	v_lshl_add_u64 v[222:223], v[224:225], 0, s[68:69]
	v_readfirstlane_b32 s21, v134
	s_mov_b32 m0, s21
	s_nop 0
	global_load_lds_dwordx4 v[222:223], off
	v_add_u32_e32 v155, 0x2000, v134
	v_lshl_add_u64 v[224:225], s[8:9], 0, v[0:1]
	s_mov_b64 s[22:23], 0x58100
	v_lshl_add_u64 v[222:223], v[224:225], 0, s[22:23]
	v_readfirstlane_b32 s21, v155
	s_mov_b32 m0, s21
	s_nop 0
	global_load_lds_dwordx4 v[222:223], off
	v_lshl_add_u64 v[224:225], s[16:17], 0, v[0:1]
	s_mov_b64 s[22:23], 0x1f380100
	v_lshl_add_u64 v[222:223], v[224:225], 0, s[22:23]
	v_readfirstlane_b32 s21, v135
	s_mov_b32 m0, s21
	s_nop 0
	global_load_lds_dwordx4 v[222:223], off
	v_lshl_add_u64 v[224:225], s[16:17], 0, v[0:1]
	s_mov_b64 s[22:23], 0x1f3d8100
	v_lshl_add_u64 v[222:223], v[224:225], 0, s[22:23]
	v_readfirstlane_b32 s21, v136
	s_mov_b32 m0, s21
	s_nop 0
	global_load_lds_dwordx4 v[222:223], off
	v_lshl_add_u64 v[224:225], s[8:9], 0, v[0:1]
	s_mov_b64 s[22:23], 0xb0100
	v_lshl_add_u64 v[222:223], v[224:225], 0, s[22:23]
	v_readfirstlane_b32 s21, v138
	s_mov_b32 m0, s21
	s_nop 0
	global_load_lds_dwordx4 v[222:223], off
	v_add_u32_e32 v155, 0x2000, v138
	v_lshl_add_u64 v[224:225], s[8:9], 0, v[0:1]
	s_mov_b64 s[22:23], 0x108100
	v_lshl_add_u64 v[222:223], v[224:225], 0, s[22:23]
	v_readfirstlane_b32 s21, v155
	s_mov_b32 m0, s21
	s_nop 0
	global_load_lds_dwordx4 v[222:223], off
	s_waitcnt vmcnt(8)
	s_waitcnt lgkmcnt(0)
	s_barrier
; #define STAGE_A(P, br, kt) do { const char* _g = (const char*)(A + (long)(br) * lda + (long)(kt) * BK); \
;     __builtin_amdgcn_global_load_lds((const unsigned*)(_g + (size_t)offA0), (unsigned*)((char*)(P) + sb0), 16, 0, 0); \
;     __builtin_amdgcn_global_load_lds((const unsigned*)(_g + (size_t)lda * 128 + (size_t)offA0), (unsigned*)((char*)(P) + sb1), 16, 0, 0); } while (0)
; #define STAGE_B(P, br, kt) do { const char* _g = (const char*)(B + (long)(br) * ldb + (long)(kt) * BK); \
;     __builtin_amdgcn_global_load_lds((const unsigned*)(_g + (size_t)offB0), (unsigned*)((char*)(P) + sb0), 16, 0, 0); \
;     __builtin_amdgcn_global_load_lds((const unsigned*)(_g + (size_t)ldb * 128 + (size_t)offB0), (unsigned*)((char*)(P) + sb1), 16, 0, 0); } while (0)
; #define LDA(dst, b, h) for (int m = 0; m < 4; ++m) for (int k = 0; k < 2; ++k) \
;     dst[m][k] = *reinterpret_cast<const bf16x8*>((char*)SA(b, h) + lds_byte(wr * 64 + m * 16 + fr, k * 32 + fq * 8))
; #define LDB(dst, b, h) for (int n = 0; n < 2; ++n) for (int k = 0; k < 2; ++k) \
;     dst[n][k] = *reinterpret_cast<const bf16x8*>((char*)SB(b, h) + lds_byte(wc * 32 + n * 16 + fr, k * 32 + fq * 8))
; #define MMA(ai, bj, At_, Bt_) do { __builtin_amdgcn_s_setprio(1); \
;     for (int m = 0; m < 4; ++m) for (int n = 0; n < 2; ++n) for (int k = 0; k < 2; ++k) \
;       acc[ai][bj][m][n] = MFMA16(At_[m][k], Bt_[n][k], acc[ai][bj][m][n]); \
;     __builtin_amdgcn_s_setprio(0); } while (0)
; #define WAIT_V(n) asm volatile("s_waitcnt vmcnt(" #n ")" ::: "memory")
; #define WAIT_L(n) asm volatile("s_waitcnt lgkmcnt(" #n ")" ::: "memory")
; #define BAR __builtin_amdgcn_s_barrier()
; #define SCHED __builtin_amdgcn_sched_barrier(0)
; DI void gemm_core(WVP char* smem, const u16* __restrict__ A, int lda, int ar0, int ar1,
;                   const u16* __restrict__ B, int ldb, int bc0, int K, AccT& acc) {
;     ...
;     WAIT_V(6); BAR; MMA(1, 1, At, B1); BAR;
;     LDB(B0, 1, 0); SCHED; LDA(At, 1, 0); STAGE_A(SA(0, 1), ac1, t + 2);
;     WAIT_L(8); BAR; WAIT_L(0); MMA(0, 0, At, B0); BAR; SCHED;
;     LDB(B1, 1, 1); STAGE_B(SB(1, 0), bb0, t + 3);
;     BAR; WAIT_L(0); MMA(0, 1, At, B1); BAR;
	v_mfma_f32_16x16x32_bf16 v[62:65], v[172:175], v[156:159], v[62:65]
	v_mfma_f32_16x16x32_bf16 v[58:61], v[172:175], v[164:167], v[58:61]
	v_mfma_f32_16x16x32_bf16 v[54:57], v[180:183], v[156:159], v[54:57]
	v_mfma_f32_16x16x32_bf16 v[50:53], v[180:183], v[164:167], v[50:53]
	v_mfma_f32_16x16x32_bf16 v[46:49], v[188:191], v[156:159], v[46:49]
	v_mfma_f32_16x16x32_bf16 v[42:45], v[188:191], v[164:167], v[42:45]
	v_mfma_f32_16x16x32_bf16 v[38:41], v[196:199], v[156:159], v[38:41]
	v_mfma_f32_16x16x32_bf16 v[34:37], v[196:199], v[164:167], v[34:37]
	v_mfma_f32_16x16x32_bf16 v[62:65], v[176:179], v[160:163], v[62:65]
	v_mfma_f32_16x16x32_bf16 v[58:61], v[176:179], v[168:171], v[58:61]
	v_mfma_f32_16x16x32_bf16 v[54:57], v[184:187], v[160:163], v[54:57]
	v_mfma_f32_16x16x32_bf16 v[50:53], v[184:187], v[168:171], v[50:53]
	v_mfma_f32_16x16x32_bf16 v[46:49], v[192:195], v[160:163], v[46:49]
	v_mfma_f32_16x16x32_bf16 v[42:45], v[192:195], v[168:171], v[42:45]
	v_mfma_f32_16x16x32_bf16 v[38:41], v[200:203], v[160:163], v[38:41]
	v_mfma_f32_16x16x32_bf16 v[34:37], v[200:203], v[168:171], v[34:37]
	v_mfma_f32_16x16x32_bf16 v[30:33], v[172:175], v[206:209], v[30:33]
	v_mfma_f32_16x16x32_bf16 v[26:29], v[172:175], v[214:217], v[26:29]
	v_mfma_f32_16x16x32_bf16 v[22:25], v[180:183], v[206:209], v[22:25]
	v_mfma_f32_16x16x32_bf16 v[18:21], v[180:183], v[214:217], v[18:21]
	v_mfma_f32_16x16x32_bf16 v[14:17], v[188:191], v[206:209], v[14:17]
	v_mfma_f32_16x16x32_bf16 v[10:13], v[188:191], v[214:217], v[10:13]
	v_mfma_f32_16x16x32_bf16 v[6:9], v[196:199], v[206:209], v[6:9]
	v_mfma_f32_16x16x32_bf16 v[2:5], v[196:199], v[214:217], v[2:5]
	v_mfma_f32_16x16x32_bf16 v[30:33], v[176:179], v[210:213], v[30:33]
	v_mfma_f32_16x16x32_bf16 v[26:29], v[176:179], v[218:221], v[26:29]
	v_mfma_f32_16x16x32_bf16 v[22:25], v[184:187], v[210:213], v[22:25]
	v_mfma_f32_16x16x32_bf16 v[18:21], v[184:187], v[218:221], v[18:21]
	v_mfma_f32_16x16x32_bf16 v[14:17], v[192:195], v[210:213], v[14:17]
	v_mfma_f32_16x16x32_bf16 v[10:13], v[192:195], v[218:221], v[10:13]
	v_mfma_f32_16x16x32_bf16 v[6:9], v[200:203], v[210:213], v[6:9]
	v_mfma_f32_16x16x32_bf16 v[2:5], v[200:203], v[218:221], v[2:5]
	s_barrier
	ds_read_b128 v[156:159], v137
	ds_read_b128 v[160:163], v137 offset:1024
	ds_read_b128 v[164:167], v137 offset:2048
	ds_read_b128 v[168:171], v137 offset:3072
	ds_read_b128 v[172:175], v132 offset:32768
	ds_read_b128 v[176:179], v132 offset:33792
	ds_read_b128 v[180:183], v150 offset:32768
	ds_read_b128 v[184:187], v150 offset:33792
	ds_read_b128 v[188:191], v151 offset:32768
	ds_read_b128 v[192:195], v151 offset:33792
	ds_read_b128 v[196:199], v152 offset:32768
	ds_read_b128 v[200:203], v152 offset:33792
	ds_read_b128 v[206:209], v133
	ds_read_b128 v[210:213], v133 offset:1024
	ds_read_b128 v[214:217], v133 offset:2048
	ds_read_b128 v[218:221], v133 offset:3072
	v_lshl_add_u64 v[224:225], s[16:17], 0, v[0:1]
	s_mov_b64 s[22:23], 0x1f430100
	v_lshl_add_u64 v[222:223], v[224:225], 0, s[22:23]
	v_readfirstlane_b32 s21, v139
	s_mov_b32 m0, s21
	s_nop 0
	global_load_lds_dwordx4 v[222:223], off
	v_lshl_add_u64 v[224:225], s[16:17], 0, v[0:1]
	s_mov_b64 s[22:23], 0x1f488100
	v_lshl_add_u64 v[222:223], v[224:225], 0, s[22:23]
	v_readfirstlane_b32 s21, v140
	s_mov_b32 m0, s21
	s_nop 0
	global_load_lds_dwordx4 v[222:223], off
	s_waitcnt vmcnt(8)
	s_waitcnt lgkmcnt(0)
	s_barrier
	v_mfma_f32_16x16x32_bf16 v[126:129], v[172:175], v[156:159], v[126:129]
	v_mfma_f32_16x16x32_bf16 v[122:125], v[172:175], v[164:167], v[122:125]
	v_mfma_f32_16x16x32_bf16 v[118:121], v[180:183], v[156:159], v[118:121]
	v_mfma_f32_16x16x32_bf16 v[114:117], v[180:183], v[164:167], v[114:117]
	v_mfma_f32_16x16x32_bf16 v[110:113], v[188:191], v[156:159], v[110:113]
	v_mfma_f32_16x16x32_bf16 v[106:109], v[188:191], v[164:167], v[106:109]
	v_mfma_f32_16x16x32_bf16 v[102:105], v[196:199], v[156:159], v[102:105]
	v_mfma_f32_16x16x32_bf16 v[98:101], v[196:199], v[164:167], v[98:101]
	v_mfma_f32_16x16x32_bf16 v[126:129], v[176:179], v[160:163], v[126:129]
	v_mfma_f32_16x16x32_bf16 v[122:125], v[176:179], v[168:171], v[122:125]
	v_mfma_f32_16x16x32_bf16 v[118:121], v[184:187], v[160:163], v[118:121]
	v_mfma_f32_16x16x32_bf16 v[114:117], v[184:187], v[168:171], v[114:117]
	v_mfma_f32_16x16x32_bf16 v[110:113], v[192:195], v[160:163], v[110:113]
	v_mfma_f32_16x16x32_bf16 v[106:109], v[192:195], v[168:171], v[106:109]
	v_mfma_f32_16x16x32_bf16 v[102:105], v[200:203], v[160:163], v[102:105]
	v_mfma_f32_16x16x32_bf16 v[98:101], v[200:203], v[168:171], v[98:101]
	v_mfma_f32_16x16x32_bf16 v[94:97], v[172:175], v[206:209], v[94:97]
	v_mfma_f32_16x16x32_bf16 v[90:93], v[172:175], v[214:217], v[90:93]
	v_mfma_f32_16x16x32_bf16 v[86:89], v[180:183], v[206:209], v[86:89]
	v_mfma_f32_16x16x32_bf16 v[82:85], v[180:183], v[214:217], v[82:85]
	v_mfma_f32_16x16x32_bf16 v[78:81], v[188:191], v[206:209], v[78:81]
	v_mfma_f32_16x16x32_bf16 v[74:77], v[188:191], v[214:217], v[74:77]
	v_mfma_f32_16x16x32_bf16 v[70:73], v[196:199], v[206:209], v[70:73]
	v_mfma_f32_16x16x32_bf16 v[66:69], v[196:199], v[214:217], v[66:69]
	v_mfma_f32_16x16x32_bf16 v[94:97], v[176:179], v[210:213], v[94:97]
	v_mfma_f32_16x16x32_bf16 v[90:93], v[176:179], v[218:221], v[90:93]
	v_mfma_f32_16x16x32_bf16 v[86:89], v[184:187], v[210:213], v[86:89]
	v_mfma_f32_16x16x32_bf16 v[82:85], v[184:187], v[218:221], v[82:85]
	v_mfma_f32_16x16x32_bf16 v[78:81], v[192:195], v[210:213], v[78:81]
	v_mfma_f32_16x16x32_bf16 v[74:77], v[192:195], v[218:221], v[74:77]
	v_mfma_f32_16x16x32_bf16 v[70:73], v[200:203], v[210:213], v[70:73]
	v_mfma_f32_16x16x32_bf16 v[66:69], v[200:203], v[218:221], v[66:69]
	s_barrier
; #define STAGE_A(P, br, kt) do { const char* _g = (const char*)(A + (long)(br) * lda + (long)(kt) * BK); \
;     __builtin_amdgcn_global_load_lds((const unsigned*)(_g + (size_t)offA0), (unsigned*)((char*)(P) + sb0), 16, 0, 0); \
;     __builtin_amdgcn_global_load_lds((const unsigned*)(_g + (size_t)lda * 128 + (size_t)offA0), (unsigned*)((char*)(P) + sb1), 16, 0, 0); } while (0)
; #define STAGE_B(P, br, kt) do { const char* _g = (const char*)(B + (long)(br) * ldb + (long)(kt) * BK); \
;     __builtin_amdgcn_global_load_lds((const unsigned*)(_g + (size_t)offB0), (unsigned*)((char*)(P) + sb0), 16, 0, 0); \
;     __builtin_amdgcn_global_load_lds((const unsigned*)(_g + (size_t)ldb * 128 + (size_t)offB0), (unsigned*)((char*)(P) + sb1), 16, 0, 0); } while (0)
; #define LDA(dst, b, h) for (int m = 0; m < 4; ++m) for (int k = 0; k < 2; ++k) \
;     dst[m][k] = *reinterpret_cast<const bf16x8*>((char*)SA(b, h) + lds_byte(wr * 64 + m * 16 + fr, k * 32 + fq * 8))
; #define LDB(dst, b, h) for (int n = 0; n < 2; ++n) for (int k = 0; k < 2; ++k) \
;     dst[n][k] = *reinterpret_cast<const bf16x8*>((char*)SB(b, h) + lds_byte(wc * 32 + n * 16 + fr, k * 32 + fq * 8))
; #define MMA(ai, bj, At_, Bt_) do { __builtin_amdgcn_s_setprio(1); \
;     for (int m = 0; m < 4; ++m) for (int n = 0; n < 2; ++n) for (int k = 0; k < 2; ++k) \
;       acc[ai][bj][m][n] = MFMA16(At_[m][k], Bt_[n][k], acc[ai][bj][m][n]); \
;     __builtin_amdgcn_s_setprio(0); } while (0)
; #define WAIT_V(n) asm volatile("s_waitcnt vmcnt(" #n ")" ::: "memory")
; #define WAIT_L(n) asm volatile("s_waitcnt lgkmcnt(" #n ")" ::: "memory")
; #define BAR __builtin_amdgcn_s_barrier()
; #define SCHED __builtin_amdgcn_sched_barrier(0)
; DI void gemm_core(WVP char* smem, const u16* __restrict__ A, int lda, int ar0, int ar1,
;                   const u16* __restrict__ B, int ldb, int bc0, int K, AccT& acc) {
;     ...
;     LDA(At, 1, 1); STAGE_A(SA(1, 0), ac0, t + 3);
;     BAR; WAIT_L(0); MMA(1, 0, At, B0); BAR; SCHED;
;     STAGE_B(SB(1, 1), bb1, t + 3);
;     WAIT_V(6); BAR; MMA(1, 1, At, B1); BAR;
;   }
;   { LDB(B0, 0, 0); LDA(At, 0, 0); STAGE_A(SA(1, 1), ac1, nt - 1);
;     BAR; WAIT_L(0); MMA(0, 0, At, B0); BAR;
	ds_read_b128 v[172:175], v132 offset:49152
	ds_read_b128 v[176:179], v132 offset:50176
	ds_read_b128 v[180:183], v150 offset:49152
	ds_read_b128 v[184:187], v150 offset:50176
	ds_read_b128 v[188:191], v151 offset:49152
	ds_read_b128 v[192:195], v151 offset:50176
	ds_read_b128 v[196:199], v152 offset:49152
	ds_read_b128 v[200:203], v152 offset:50176
	v_lshl_add_u64 v[224:225], s[8:9], 0, v[0:1]
	v_lshl_add_u64 v[222:223], v[224:225], 0, s[70:71]
	v_readfirstlane_b32 s21, v141
	s_mov_b32 m0, s21
	s_nop 0
	global_load_lds_dwordx4 v[222:223], off
	v_lshl_add_u64 v[224:225], s[8:9], 0, v[0:1]
	s_mov_b64 s[22:23], 0x58180
	v_lshl_add_u64 v[222:223], v[224:225], 0, s[22:23]
	v_readfirstlane_b32 s21, v142
	s_mov_b32 m0, s21
	s_nop 0
	global_load_lds_dwordx4 v[222:223], off
	v_lshl_add_u64 v[224:225], s[16:17], 0, v[0:1]
	s_mov_b64 s[22:23], 0x1f380180
	v_lshl_add_u64 v[222:223], v[224:225], 0, s[22:23]
	v_readfirstlane_b32 s21, v143
	s_mov_b32 m0, s21
	s_nop 0
	global_load_lds_dwordx4 v[222:223], off
	v_lshl_add_u64 v[224:225], s[16:17], 0, v[0:1]
	s_mov_b64 s[22:23], 0x1f3d8180
	v_lshl_add_u64 v[222:223], v[224:225], 0, s[22:23]
	v_readfirstlane_b32 s21, v144
	s_mov_b32 m0, s21
	s_nop 0
	global_load_lds_dwordx4 v[222:223], off
	v_lshl_add_u64 v[224:225], s[8:9], 0, v[0:1]
	s_mov_b64 s[22:23], 0xb0180
	v_lshl_add_u64 v[222:223], v[224:225], 0, s[22:23]
	v_readfirstlane_b32 s21, v145
	s_mov_b32 m0, s21
	s_nop 0
	global_load_lds_dwordx4 v[222:223], off
	v_lshl_add_u64 v[224:225], s[8:9], 0, v[0:1]
	s_mov_b64 s[22:23], 0x108180
	v_lshl_add_u64 v[222:223], v[224:225], 0, s[22:23]
	v_readfirstlane_b32 s21, v147
	s_mov_b32 m0, s21
	s_nop 0
	global_load_lds_dwordx4 v[222:223], off
	s_waitcnt vmcnt(8)
	s_waitcnt lgkmcnt(0)
	s_barrier
	v_mfma_f32_16x16x32_bf16 v[62:65], v[172:175], v[156:159], v[62:65]
	v_mfma_f32_16x16x32_bf16 v[58:61], v[172:175], v[164:167], v[58:61]
	v_mfma_f32_16x16x32_bf16 v[54:57], v[180:183], v[156:159], v[54:57]
	v_mfma_f32_16x16x32_bf16 v[50:53], v[180:183], v[164:167], v[50:53]
	v_mfma_f32_16x16x32_bf16 v[46:49], v[188:191], v[156:159], v[46:49]
	v_mfma_f32_16x16x32_bf16 v[42:45], v[188:191], v[164:167], v[42:45]
	v_mfma_f32_16x16x32_bf16 v[38:41], v[196:199], v[156:159], v[38:41]
	v_mfma_f32_16x16x32_bf16 v[34:37], v[196:199], v[164:167], v[34:37]
	v_mfma_f32_16x16x32_bf16 v[62:65], v[176:179], v[160:163], v[62:65]
	v_mfma_f32_16x16x32_bf16 v[58:61], v[176:179], v[168:171], v[58:61]
	v_mfma_f32_16x16x32_bf16 v[54:57], v[184:187], v[160:163], v[54:57]
	v_mfma_f32_16x16x32_bf16 v[50:53], v[184:187], v[168:171], v[50:53]
	v_mfma_f32_16x16x32_bf16 v[46:49], v[192:195], v[160:163], v[46:49]
	v_mfma_f32_16x16x32_bf16 v[42:45], v[192:195], v[168:171], v[42:45]
	v_mfma_f32_16x16x32_bf16 v[38:41], v[200:203], v[160:163], v[38:41]
	v_mfma_f32_16x16x32_bf16 v[34:37], v[200:203], v[168:171], v[34:37]
	v_mfma_f32_16x16x32_bf16 v[30:33], v[172:175], v[206:209], v[30:33]
	v_mfma_f32_16x16x32_bf16 v[26:29], v[172:175], v[214:217], v[26:29]
	v_mfma_f32_16x16x32_bf16 v[22:25], v[180:183], v[206:209], v[22:25]
	v_mfma_f32_16x16x32_bf16 v[18:21], v[180:183], v[214:217], v[18:21]
	v_mfma_f32_16x16x32_bf16 v[14:17], v[188:191], v[206:209], v[14:17]
	v_mfma_f32_16x16x32_bf16 v[10:13], v[188:191], v[214:217], v[10:13]
	v_mfma_f32_16x16x32_bf16 v[6:9], v[196:199], v[206:209], v[6:9]
	v_mfma_f32_16x16x32_bf16 v[2:5], v[196:199], v[214:217], v[2:5]
	v_mfma_f32_16x16x32_bf16 v[30:33], v[176:179], v[210:213], v[30:33]
	v_mfma_f32_16x16x32_bf16 v[26:29], v[176:179], v[218:221], v[26:29]
	v_mfma_f32_16x16x32_bf16 v[22:25], v[184:187], v[210:213], v[22:25]
	v_mfma_f32_16x16x32_bf16 v[18:21], v[184:187], v[218:221], v[18:21]
	v_mfma_f32_16x16x32_bf16 v[14:17], v[192:195], v[210:213], v[14:17]
	v_mfma_f32_16x16x32_bf16 v[10:13], v[192:195], v[218:221], v[10:13]
	v_mfma_f32_16x16x32_bf16 v[6:9], v[200:203], v[210:213], v[6:9]
	v_mfma_f32_16x16x32_bf16 v[2:5], v[200:203], v[218:221], v[2:5]
	s_add_i32 s20, s20, 2
	s_add_u32 s8, s8, 0x100
	s_addc_u32 s9, s9, 0
	s_add_u32 s16, s16, 0x100
	s_addc_u32 s17, s17, 0
	s_cmp_lt_u32 s20, 40
	s_barrier
	s_cbranch_scc1 .LBB0_94
	s_mov_b64 s[0:1], 0x1580
	v_lshl_add_u64 v[134:135], v[130:131], 0, s[0:1]
	v_readfirstlane_b32 s0, v153
	s_mov_b32 m0, s0
	s_mov_b64 s[0:1], 0x59580
	v_lshl_add_u64 v[130:131], v[130:131], 0, s[0:1]
	v_readfirstlane_b32 s0, v154
	ds_read_b128 v[138:141], v149
	ds_read_b128 v[142:145], v149 offset:1024
	ds_read_b128 v[156:159], v149 offset:2048
	ds_read_b128 v[160:163], v149 offset:3072
	ds_read_b128 v[164:167], v132
	ds_read_b128 v[168:171], v132 offset:1024
	ds_read_b128 v[172:175], v150
	ds_read_b128 v[176:179], v150 offset:1024
	ds_read_b128 v[180:183], v151
	ds_read_b128 v[184:187], v151 offset:1024
	ds_read_b128 v[188:191], v152
	ds_read_b128 v[192:195], v152 offset:1024
	global_load_lds_dwordx4 v[134:135], off
	s_mov_b32 m0, s0
	s_nop 0
	global_load_lds_dwordx4 v[130:131], off
	s_waitcnt vmcnt(8)
	s_barrier
	s_waitcnt lgkmcnt(0)
	s_setprio 1
	s_waitcnt lgkmcnt(0)
	v_mfma_f32_16x16x32_bf16 v[126:129], v[164:167], v[138:141], v[126:129]
	v_mfma_f32_16x16x32_bf16 v[118:121], v[172:175], v[138:141], v[118:121]
	v_mfma_f32_16x16x32_bf16 v[110:113], v[180:183], v[138:141], v[110:113]
	v_mfma_f32_16x16x32_bf16 v[102:105], v[188:191], v[138:141], v[102:105]
	v_mfma_f32_16x16x32_bf16 v[126:129], v[168:171], v[142:145], v[126:129]
	v_mfma_f32_16x16x32_bf16 v[122:125], v[164:167], v[156:159], v[122:125]
	v_mfma_f32_16x16x32_bf16 v[118:121], v[176:179], v[142:145], v[118:121]
	v_mfma_f32_16x16x32_bf16 v[114:117], v[172:175], v[156:159], v[114:117]
	v_mfma_f32_16x16x32_bf16 v[110:113], v[184:187], v[142:145], v[110:113]
	v_mfma_f32_16x16x32_bf16 v[106:109], v[180:183], v[156:159], v[106:109]
	v_mfma_f32_16x16x32_bf16 v[102:105], v[192:195], v[142:145], v[102:105]
	v_mfma_f32_16x16x32_bf16 v[98:101], v[188:191], v[156:159], v[98:101]
	v_mfma_f32_16x16x32_bf16 v[122:125], v[168:171], v[160:163], v[122:125]
	v_mfma_f32_16x16x32_bf16 v[196:199], v[176:179], v[160:163], v[114:117]
	v_mfma_f32_16x16x32_bf16 v[200:203], v[184:187], v[160:163], v[106:109]
	v_mfma_f32_16x16x32_bf16 v[206:209], v[192:195], v[160:163], v[98:101]
	s_setprio 0
	s_barrier
; #define LDA(dst, b, h) for (int m = 0; m < 4; ++m) for (int k = 0; k < 2; ++k) \
;     dst[m][k] = *reinterpret_cast<const bf16x8*>((char*)SA(b, h) + lds_byte(wr * 64 + m * 16 + fr, k * 32 + fq * 8))
; #define LDB(dst, b, h) for (int n = 0; n < 2; ++n) for (int k = 0; k < 2; ++k) \
;     dst[n][k] = *reinterpret_cast<const bf16x8*>((char*)SB(b, h) + lds_byte(wc * 32 + n * 16 + fr, k * 32 + fq * 8))
; #define MMA(ai, bj, At_, Bt_) do { __builtin_amdgcn_s_setprio(1); \
;     for (int m = 0; m < 4; ++m) for (int n = 0; n < 2; ++n) for (int k = 0; k < 2; ++k) \
;       acc[ai][bj][m][n] = MFMA16(At_[m][k], Bt_[n][k], acc[ai][bj][m][n]); \
;     __builtin_amdgcn_s_setprio(0); } while (0)
; #define WAIT_V(n) asm volatile("s_waitcnt vmcnt(" #n ")" ::: "memory")
; #define WAIT_L(n) asm volatile("s_waitcnt lgkmcnt(" #n ")" ::: "memory")
; #define BAR __builtin_amdgcn_s_barrier()
; DI void gemm_core(WVP char* smem, const u16* __restrict__ A, int lda, int ar0, int ar1,
;                   const u16* __restrict__ B, int ldb, int bc0, int K, AccT& acc) {
;     ...
;     LDB(B1, 0, 1); BAR; WAIT_L(0); MMA(0, 1, At, B1); BAR;
;     LDA(At, 0, 1); WAIT_V(4); BAR; WAIT_L(0); MMA(1, 0, At, B0); MMA(1, 1, At, B1); BAR; }
;   { LDB(B0, 1, 0); LDA(At, 1, 0); WAIT_V(2); BAR; WAIT_L(0); MMA(0, 0, At, B0); BAR;
	s_nop 1
	ds_read_b128 v[98:101], v146
	ds_read_b128 v[106:109], v146 offset:1024
	ds_read_b128 v[114:117], v146 offset:2048
	ds_read_b128 v[146:149], v146 offset:3072
	s_barrier
	s_waitcnt lgkmcnt(0)
	s_setprio 1
	s_waitcnt lgkmcnt(0)
	v_mfma_f32_16x16x32_bf16 v[94:97], v[164:167], v[98:101], v[94:97]
	v_mfma_f32_16x16x32_bf16 v[86:89], v[172:175], v[98:101], v[86:89]
	v_mfma_f32_16x16x32_bf16 v[78:81], v[180:183], v[98:101], v[78:81]
	v_mfma_f32_16x16x32_bf16 v[70:73], v[188:191], v[98:101], v[70:73]
	v_mfma_f32_16x16x32_bf16 v[94:97], v[168:171], v[106:109], v[94:97]
	v_mfma_f32_16x16x32_bf16 v[90:93], v[164:167], v[114:117], v[90:93]
	v_mfma_f32_16x16x32_bf16 v[86:89], v[176:179], v[106:109], v[86:89]
	v_mfma_f32_16x16x32_bf16 v[82:85], v[172:175], v[114:117], v[82:85]
	v_mfma_f32_16x16x32_bf16 v[78:81], v[184:187], v[106:109], v[78:81]
	v_mfma_f32_16x16x32_bf16 v[74:77], v[180:183], v[114:117], v[74:77]
	v_mfma_f32_16x16x32_bf16 v[70:73], v[192:195], v[106:109], v[70:73]
	v_mfma_f32_16x16x32_bf16 v[66:69], v[188:191], v[114:117], v[66:69]
	v_mfma_f32_16x16x32_bf16 v[164:167], v[168:171], v[146:149], v[90:93]
	v_mfma_f32_16x16x32_bf16 v[168:171], v[176:179], v[146:149], v[82:85]
	v_mfma_f32_16x16x32_bf16 v[172:175], v[184:187], v[146:149], v[74:77]
	v_mfma_f32_16x16x32_bf16 v[176:179], v[192:195], v[146:149], v[66:69]
	s_setprio 0
	s_barrier
	s_nop 1
	ds_read_b128 v[66:69], v132 offset:16384
	ds_read_b128 v[74:77], v132 offset:17408
	ds_read_b128 v[82:85], v150 offset:16384
	ds_read_b128 v[90:93], v150 offset:17408
	ds_read_b128 v[180:183], v151 offset:16384
	ds_read_b128 v[184:187], v151 offset:17408
	ds_read_b128 v[188:191], v152 offset:16384
	ds_read_b128 v[192:195], v152 offset:17408
	s_waitcnt vmcnt(4)
	s_barrier
	s_waitcnt lgkmcnt(0)
	s_setprio 1
	s_waitcnt lgkmcnt(0)
	v_mfma_f32_16x16x32_bf16 v[62:65], v[66:69], v[138:141], v[62:65]
	v_mfma_f32_16x16x32_bf16 v[54:57], v[82:85], v[138:141], v[54:57]
	v_mfma_f32_16x16x32_bf16 v[42:45], v[180:183], v[156:159], v[42:45]
	v_mfma_f32_16x16x32_bf16 v[38:41], v[188:191], v[138:141], v[38:41]
	v_mfma_f32_16x16x32_bf16 v[62:65], v[74:77], v[142:145], v[62:65]
	v_mfma_f32_16x16x32_bf16 v[58:61], v[66:69], v[156:159], v[58:61]
	v_mfma_f32_16x16x32_bf16 v[54:57], v[90:93], v[142:145], v[54:57]
	v_mfma_f32_16x16x32_bf16 v[50:53], v[82:85], v[156:159], v[50:53]
	v_mfma_f32_16x16x32_bf16 v[46:49], v[180:183], v[138:141], v[46:49]
	v_mfma_f32_16x16x32_bf16 v[42:45], v[184:187], v[160:163], v[42:45]
	v_mfma_f32_16x16x32_bf16 v[38:41], v[192:195], v[142:145], v[38:41]
	v_mfma_f32_16x16x32_bf16 v[34:37], v[188:191], v[156:159], v[34:37]
	v_mfma_f32_16x16x32_bf16 v[210:213], v[74:77], v[160:163], v[58:61]
	v_mfma_f32_16x16x32_bf16 v[214:217], v[90:93], v[160:163], v[50:53]
	v_mfma_f32_16x16x32_bf16 v[218:221], v[184:187], v[142:145], v[46:49]
	v_mfma_f32_16x16x32_bf16 v[138:141], v[192:195], v[160:163], v[34:37]
	s_setprio 0
	s_setprio 1
	v_mfma_f32_16x16x32_bf16 v[30:33], v[66:69], v[98:101], v[30:33]
	v_mfma_f32_16x16x32_bf16 v[22:25], v[82:85], v[98:101], v[22:25]
	v_mfma_f32_16x16x32_bf16 v[10:13], v[180:183], v[114:117], v[10:13]
	v_mfma_f32_16x16x32_bf16 v[30:33], v[74:77], v[106:109], v[30:33]
	v_mfma_f32_16x16x32_bf16 v[26:29], v[66:69], v[114:117], v[26:29]
	v_mfma_f32_16x16x32_bf16 v[22:25], v[90:93], v[106:109], v[22:25]
	v_mfma_f32_16x16x32_bf16 v[18:21], v[82:85], v[114:117], v[18:21]
	v_mfma_f32_16x16x32_bf16 v[14:17], v[180:183], v[98:101], v[14:17]
	v_mfma_f32_16x16x32_bf16 v[10:13], v[184:187], v[146:149], v[10:13]
	v_mfma_f32_16x16x32_bf16 v[6:9], v[188:191], v[98:101], v[6:9]
	v_mfma_f32_16x16x32_bf16 v[2:5], v[188:191], v[114:117], v[2:5]
	v_mfma_f32_16x16x32_bf16 v[142:145], v[74:77], v[146:149], v[26:29]
	v_mfma_f32_16x16x32_bf16 v[154:157], v[90:93], v[146:149], v[18:21]
	v_mfma_f32_16x16x32_bf16 v[158:161], v[184:187], v[106:109], v[14:17]
	v_mfma_f32_16x16x32_bf16 v[180:183], v[192:195], v[106:109], v[6:9]
	v_mfma_f32_16x16x32_bf16 v[146:149], v[192:195], v[146:149], v[2:5]
	s_setprio 0
	s_barrier
	ds_read_b128 v[184:187], v137
	ds_read_b128 v[188:191], v137 offset:1024
	ds_read_b128 v[192:195], v137 offset:2048
	ds_read_b128 v[134:137], v137 offset:3072
	ds_read_b128 v[2:5], v132 offset:32768
	ds_read_b128 v[6:9], v132 offset:33792
	ds_read_b128 v[14:17], v150 offset:32768
	ds_read_b128 v[18:21], v150 offset:33792
	ds_read_b128 v[222:225], v151 offset:32768
	ds_read_b128 v[226:229], v151 offset:33792
	ds_read_b128 v[230:233], v152 offset:32768
	ds_read_b128 v[234:237], v152 offset:33792
	s_waitcnt vmcnt(2)
	s_barrier
; #define LDA(dst, b, h) for (int m = 0; m < 4; ++m) for (int k = 0; k < 2; ++k) \
;     dst[m][k] = *reinterpret_cast<const bf16x8*>((char*)SA(b, h) + lds_byte(wr * 64 + m * 16 + fr, k * 32 + fq * 8))
; #define LDB(dst, b, h) for (int n = 0; n < 2; ++n) for (int k = 0; k < 2; ++k) \
;     dst[n][k] = *reinterpret_cast<const bf16x8*>((char*)SB(b, h) + lds_byte(wc * 32 + n * 16 + fr, k * 32 + fq * 8))
; #define MMA(ai, bj, At_, Bt_) do { __builtin_amdgcn_s_setprio(1); \
;     for (int m = 0; m < 4; ++m) for (int n = 0; n < 2; ++n) for (int k = 0; k < 2; ++k) \
;       acc[ai][bj][m][n] = MFMA16(At_[m][k], Bt_[n][k], acc[ai][bj][m][n]); \
;     __builtin_amdgcn_s_setprio(0); } while (0)
; #define WAIT_V(n) asm volatile("s_waitcnt vmcnt(" #n ")" ::: "memory")
; #define WAIT_L(n) asm volatile("s_waitcnt lgkmcnt(" #n ")" ::: "memory")
; #define BAR __builtin_amdgcn_s_barrier()
; DI void gemm_core(WVP char* smem, const u16* __restrict__ A, int lda, int ar0, int ar1,
;                   const u16* __restrict__ B, int ldb, int bc0, int K, AccT& acc) {
;     ...
;   { LDB(B0, 1, 0); LDA(At, 1, 0); WAIT_V(2); BAR; WAIT_L(0); MMA(0, 0, At, B0); BAR;
;     LDB(B1, 1, 1); WAIT_V(0); BAR; WAIT_L(0); MMA(0, 1, At, B1); BAR;
;     LDA(At, 1, 1); BAR; WAIT_L(0); MMA(1, 0, At, B0); MMA(1, 1, At, B1); BAR; }
;   if (wr == 0) BAR;
	s_waitcnt lgkmcnt(0)
	s_setprio 1
	s_waitcnt lgkmcnt(0)
	v_mfma_f32_16x16x32_bf16 v[26:29], v[2:5], v[184:187], v[126:129]
	v_mfma_f32_16x16x32_bf16 v[114:117], v[6:9], v[188:191], v[26:29]
	v_mfma_f32_16x16x32_bf16 v[26:29], v[2:5], v[192:195], v[122:125]
	v_mfma_f32_16x16x32_bf16 v[106:109], v[6:9], v[134:137], v[26:29]
	v_mfma_f32_16x16x32_bf16 v[26:29], v[14:17], v[184:187], v[118:121]
	v_mfma_f32_16x16x32_bf16 v[98:101], v[18:21], v[188:191], v[26:29]
	v_mfma_f32_16x16x32_bf16 v[26:29], v[14:17], v[192:195], v[196:199]
	v_mfma_f32_16x16x32_bf16 v[90:93], v[18:21], v[134:137], v[26:29]
	v_mfma_f32_16x16x32_bf16 v[26:29], v[222:225], v[184:187], v[110:113]
	v_mfma_f32_16x16x32_bf16 v[82:85], v[226:229], v[188:191], v[26:29]
	v_mfma_f32_16x16x32_bf16 v[26:29], v[222:225], v[192:195], v[200:203]
	v_mfma_f32_16x16x32_bf16 v[74:77], v[226:229], v[134:137], v[26:29]
	v_mfma_f32_16x16x32_bf16 v[26:29], v[230:233], v[184:187], v[102:105]
	v_mfma_f32_16x16x32_bf16 v[66:69], v[234:237], v[188:191], v[26:29]
	v_mfma_f32_16x16x32_bf16 v[26:29], v[230:233], v[192:195], v[206:209]
	v_mfma_f32_16x16x32_bf16 v[58:61], v[234:237], v[134:137], v[26:29]
	s_setprio 0
	s_barrier
	ds_read_b128 v[122:125], v133
	ds_read_b128 v[196:199], v133 offset:1024
	ds_read_b128 v[200:203], v133 offset:2048
	ds_read_b128 v[206:209], v133 offset:3072
	s_waitcnt vmcnt(0)
	s_barrier
	s_waitcnt lgkmcnt(0)
	s_setprio 1
	s_waitcnt lgkmcnt(0)
	v_mfma_f32_16x16x32_bf16 v[26:29], v[2:5], v[122:125], v[94:97]
	v_mfma_f32_16x16x32_bf16 v[2:5], v[2:5], v[200:203], v[164:167]
	v_mfma_f32_16x16x32_bf16 v[46:49], v[6:9], v[206:209], v[2:5]
	v_mfma_f32_16x16x32_bf16 v[2:5], v[14:17], v[122:125], v[86:89]
	v_mfma_f32_16x16x32_bf16 v[34:37], v[18:21], v[196:199], v[2:5]
	v_mfma_f32_16x16x32_bf16 v[2:5], v[14:17], v[200:203], v[168:171]
	v_mfma_f32_16x16x32_bf16 v[50:53], v[6:9], v[196:199], v[26:29]
	v_mfma_f32_16x16x32_bf16 v[26:29], v[18:21], v[206:209], v[2:5]
	v_mfma_f32_16x16x32_bf16 v[2:5], v[222:225], v[122:125], v[78:81]
	v_mfma_f32_16x16x32_bf16 v[18:21], v[226:229], v[196:199], v[2:5]
	v_mfma_f32_16x16x32_bf16 v[2:5], v[222:225], v[200:203], v[172:175]
	v_mfma_f32_16x16x32_bf16 v[14:17], v[226:229], v[206:209], v[2:5]
	v_mfma_f32_16x16x32_bf16 v[2:5], v[230:233], v[122:125], v[70:73]
	v_mfma_f32_16x16x32_bf16 v[6:9], v[234:237], v[196:199], v[2:5]
	v_mfma_f32_16x16x32_bf16 v[2:5], v[230:233], v[200:203], v[176:179]
	v_mfma_f32_16x16x32_bf16 v[2:5], v[234:237], v[206:209], v[2:5]
	s_setprio 0
	s_barrier
	ds_read_b128 v[162:165], v132 offset:49152
	ds_read_b128 v[130:133], v132 offset:50176
	ds_read_b128 v[166:169], v150 offset:49152
	ds_read_b128 v[170:173], v150 offset:50176
	ds_read_b128 v[174:177], v151 offset:49152
	ds_read_b128 v[222:225], v151 offset:50176
	ds_read_b128 v[226:229], v152 offset:49152
	ds_read_b128 v[150:153], v152 offset:50176
	s_barrier
	s_waitcnt lgkmcnt(0)
	s_setprio 1
	s_waitcnt lgkmcnt(0)
	v_mfma_f32_16x16x32_bf16 v[54:57], v[166:169], v[184:187], v[54:57]
	v_mfma_f32_16x16x32_bf16 v[62:65], v[162:165], v[184:187], v[62:65]
	v_mfma_f32_16x16x32_bf16 v[110:113], v[170:173], v[188:191], v[54:57]
	v_mfma_f32_16x16x32_bf16 v[54:57], v[166:169], v[192:195], v[214:217]
	v_mfma_f32_16x16x32_bf16 v[38:41], v[226:229], v[184:187], v[38:41]
	v_mfma_f32_16x16x32_bf16 v[118:121], v[130:133], v[188:191], v[62:65]
	v_mfma_f32_16x16x32_bf16 v[62:65], v[162:165], v[192:195], v[210:213]
	v_mfma_f32_16x16x32_bf16 v[102:105], v[170:173], v[134:137], v[54:57]
	v_mfma_f32_16x16x32_bf16 v[54:57], v[174:177], v[184:187], v[218:221]
	v_mfma_f32_16x16x32_bf16 v[42:45], v[174:177], v[192:195], v[42:45]
	v_mfma_f32_16x16x32_bf16 v[78:81], v[150:153], v[188:191], v[38:41]
	v_mfma_f32_16x16x32_bf16 v[38:41], v[226:229], v[192:195], v[138:141]
	v_mfma_f32_16x16x32_bf16 v[126:129], v[130:133], v[134:137], v[62:65]
	v_mfma_f32_16x16x32_bf16 v[86:89], v[222:225], v[188:191], v[54:57]
	v_mfma_f32_16x16x32_bf16 v[94:97], v[222:225], v[134:137], v[42:45]
	v_mfma_f32_16x16x32_bf16 v[70:73], v[150:153], v[134:137], v[38:41]
	s_setprio 0
	s_setprio 1
	v_mfma_f32_16x16x32_bf16 v[30:33], v[162:165], v[122:125], v[30:33]
	v_mfma_f32_16x16x32_bf16 v[22:25], v[166:169], v[122:125], v[22:25]
	v_mfma_f32_16x16x32_bf16 v[54:57], v[130:133], v[196:199], v[30:33]
	v_mfma_f32_16x16x32_bf16 v[30:33], v[162:165], v[200:203], v[142:145]
	v_mfma_f32_16x16x32_bf16 v[42:45], v[170:173], v[196:199], v[22:25]
	v_mfma_f32_16x16x32_bf16 v[22:25], v[166:169], v[200:203], v[154:157]
	v_mfma_f32_16x16x32_bf16 v[10:13], v[174:177], v[200:203], v[10:13]
	v_mfma_f32_16x16x32_bf16 v[62:65], v[130:133], v[206:209], v[30:33]
	v_mfma_f32_16x16x32_bf16 v[38:41], v[170:173], v[206:209], v[22:25]
	v_mfma_f32_16x16x32_bf16 v[22:25], v[174:177], v[122:125], v[158:161]
	v_mfma_f32_16x16x32_bf16 v[30:33], v[222:225], v[206:209], v[10:13]
	v_mfma_f32_16x16x32_bf16 v[10:13], v[226:229], v[122:125], v[180:183]
	v_mfma_f32_16x16x32_bf16 v[122:125], v[226:229], v[200:203], v[146:149]
	v_mfma_f32_16x16x32_bf16 v[22:25], v[222:225], v[196:199], v[22:25]
	v_mfma_f32_16x16x32_bf16 v[10:13], v[150:153], v[196:199], v[10:13]
	v_mfma_f32_16x16x32_bf16 v[130:133], v[150:153], v[206:209], v[122:125]
	s_setprio 0
	s_cmp_gt_u32 s18, 3
	s_barrier
	s_cbranch_scc0 .LBB0_144
	s_mov_b64 s[8:9], -1
	s_and_b64 vcc, exec, s[12:13]
	s_cbranch_vccnz .LBB0_145

; DI int get_tid(int wv) { int l; asm volatile("v_mbcnt_lo_u32_b32 %0, -1, 0\n\tv_mbcnt_hi_u32_b32 %0, -1, %0" : "=v"(l)); return wv * 64 + l; }
; DI int wave_of(int tid) { return __builtin_amdgcn_readfirstlane(tid >> 6); }
; #define STAGE_A(P, br, kt) do { const char* _g = (const char*)(A + (long)(br) * lda + (long)(kt) * BK); \
;     __builtin_amdgcn_global_load_lds((const unsigned*)(_g + (size_t)offA0), (unsigned*)((char*)(P) + sb0), 16, 0, 0); \
;     __builtin_amdgcn_global_load_lds((const unsigned*)(_g + (size_t)lda * 128 + (size_t)offA0), (unsigned*)((char*)(P) + sb1), 16, 0, 0); } while (0)
; #define STAGE_B(P, br, kt) do { const char* _g = (const char*)(B + (long)(br) * ldb + (long)(kt) * BK); \
;     __builtin_amdgcn_global_load_lds((const unsigned*)(_g + (size_t)offB0), (unsigned*)((char*)(P) + sb0), 16, 0, 0); \
;     __builtin_amdgcn_global_load_lds((const unsigned*)(_g + (size_t)ldb * 128 + (size_t)offB0), (unsigned*)((char*)(P) + sb1), 16, 0, 0); } while (0)
; #define BAR __builtin_amdgcn_s_barrier()
; DI void gemm_core(WVP char* smem, const u16* __restrict__ A, int lda, int ar0, int ar1,
;                   const u16* __restrict__ B, int ldb, int bc0, int K, AccT& acc) {
;     ...
;   const int tid = get_tid(WV);
;   const int wid = wave_of(tid), lane = tid & 63, wr = wid >> 2, wc = wid & 3, fr = lane & 15, fq = lane >> 4;
;   const int sb0 = tid * 16, sb1 = sb0 + 8192;
;   int R0, C0; stage_rc(sb0, R0, C0);
;   const unsigned offA0 = (unsigned)(R0 * lda + C0) * 2u, offB0 = (unsigned)(R0 * ldb + C0) * 2u;
;   const int ac0 = ar0, ac1 = ar1, bb0 = bc0, bb1 = bc0 + HALF;
;   bf16x8 At[4][2], B0[2][2], B1[2][2];
;   const int nt = K / BK;
;   __syncthreads();
;   STAGE_B(SB(0, 0), bb0, 0); STAGE_A(SA(0, 0), ac0, 0);
;   STAGE_B(SB(0, 1), bb1, 0); STAGE_A(SA(0, 1), ac1, 0);
;   if (wr == 1) BAR;
.LBB0_165:
	s_cmpk_gt_i32 s4, 0xaff
	s_cbranch_scc1 .LBB0_172
	s_ashr_i32 s0, s4, 31
	s_lshr_b32 s0, s0, 29
	s_add_i32 s0, s4, s0
	s_ashr_i32 s1, s0, 3
	s_and_b32 s0, s0, -8
	s_sub_i32 s0, s4, s0
	s_cmp_lt_i32 s0, 0
	s_movk_i32 s5, 0x161
	s_cselect_b32 s5, s5, 0x160
	s_mul_i32 s14, s0, s5
	s_add_i32 s14, s14, s1
	s_ashr_i32 s0, s14, 31
	s_lshr_b32 s0, s0, 23
	s_add_i32 s0, s14, s0
	s_ashr_i32 s15, s0, 9
	s_lshl_b32 s5, s15, 2
	s_sub_i32 s1, 22, s5
	s_min_u32 s8, s1, 4
	s_and_b32 s16, s0, 0xfffffe00
	s_sub_i32 s9, s14, s16
	v_cvt_f32_ubyte0_e32 v2, s8
	v_cvt_f32_i32_e32 v0, s9
	v_rcp_iflag_f32_e32 v3, v2
	s_ashr_i32 s0, s9, 30
	s_or_b32 s10, s0, 1
	v_mbcnt_lo_u32_b32 v9, -1, 0
	v_mbcnt_hi_u32_b32 v9, -1, v9
	v_mul_f32_e32 v3, v0, v3
	v_trunc_f32_e32 v3, v3
	v_fma_f32 v0, -v3, v2, v0
	v_cvt_i32_f32_e32 v3, v3
	v_cmp_ge_f32_e64 s[0:1], |v0|, v2
	s_and_b64 s[0:1], s[0:1], exec
	s_cselect_b32 s0, s10, 0
	v_readfirstlane_b32 s1, v3
	s_add_i32 s17, s1, s0
	s_sext_i32_i16 s0, s17
	s_mul_i32 s17, s17, s8
	v_add_u32_e32 v0, s3, v9
	s_sub_i32 s1, s9, s17
	v_ashrrev_i32_e32 v2, 31, v0
	s_sext_i32_i16 s1, s1
	v_lshrrev_b32_e32 v2, 26, v2
	s_add_i32 s5, s5, s1
	v_readfirstlane_b32 s1, v0
	v_lshlrev_b32_e32 v12, 4, v0
	v_add_u32_e32 v2, v0, v2
	v_bfe_i32 v0, v0, 27, 1
	v_lshrrev_b32_e32 v0, 22, v0
	v_add_u32_e32 v0, v12, v0
	v_and_b32_e32 v0, 0xfffffc00, v0
	v_sub_u32_e32 v0, v12, v0
	v_ashrrev_i32_e32 v8, 6, v2
	v_lshrrev_b32_e32 v2, 4, v0
	v_bitop3_b32 v0, v2, v0, 32 bitop3:0x6c
	v_ashrrev_i32_e32 v3, 31, v0
	s_lshl_b32 s8, s0, 8
	v_lshrrev_b32_e32 v3, 26, v3
	v_add_u32_e32 v3, v0, v3
	s_ashr_i32 s9, s8, 31
	s_lshl_b32 s10, s5, 7
	s_ashr_i32 s0, s1, 8
	v_ashrrev_i32_e32 v10, 6, v3
	v_and_b32_e32 v3, 0xc0, v3
	s_or_b32 s18, s8, 0x80
	s_lshl_b64 s[12:13], s[8:9], 11
	v_readlane_b32 s22, v255, 29
	v_sub_u32_e32 v0, v0, v3
	v_readlane_b32 s23, v255, 30
	s_add_u32 s20, s22, s12
	v_lshlrev_b32_e32 v2, 3, v8
	v_lshlrev_b32_e32 v4, 5, v8
	v_ashrrev_i16_sdwa v0, v254, sext(v0) dst_sel:DWORD dst_unused:UNUSED_PAD src0_sel:DWORD src1_sel:BYTE_0
	s_addc_u32 s21, s23, s13
	s_add_i32 s9, 0, 0x10000
	v_add_u32_e32 v13, 0x2000, v12
	v_and_b32_e32 v2, 0x1ffff0, v2
	v_and_b32_e32 v4, 32, v4
	v_bfe_i32 v11, v0, 0, 16
	v_add_u32_e32 v133, s9, v12
	v_add_u32_e32 v0, v4, v11
	v_add_lshl_u32 v2, v10, v2, 11
	v_readfirstlane_b32 s5, v133
	v_add_u32_e32 v6, s9, v13
	v_lshl_add_u32 v0, v0, 1, v2
	s_mov_b32 m0, s5
	v_readfirstlane_b32 s5, v6
	s_ashr_i32 s11, s10, 31
	s_barrier
	v_lshl_add_u64 v[2:3], s[20:21], 0, v[0:1]
	global_load_lds_dwordx4 v0, s[20:21]
	s_mov_b32 m0, s5
	s_lshl_b64 s[20:21], s[10:11], 11
	v_readlane_b32 s5, v255, 38
	s_add_u32 s20, s5, s20
	v_readlane_b32 s5, v255, 39
	v_add_u32_e32 v135, 0, v12
	v_lshl_add_u64 v[4:5], v[2:3], 0, s[76:77]
	s_addc_u32 s21, s5, s21
	v_readfirstlane_b32 s5, v135
	v_add_u32_e32 v136, 0x2000, v135
	s_ashr_i32 s19, s18, 31
	global_load_lds_dwordx4 v[4:5], off
	v_lshl_add_u64 v[4:5], s[20:21], 0, v[0:1]
	s_mov_b32 m0, s5
	v_readfirstlane_b32 s5, v136
	s_lshl_b64 s[18:19], s[18:19], 11
	v_add_u32_e32 v138, s60, v12
	global_load_lds_dwordx4 v0, s[20:21]
	v_lshl_add_u64 v[6:7], v[4:5], 0, s[76:77]
	s_mov_b32 m0, s5
	s_add_u32 s18, s22, s18
	v_readfirstlane_b32 s5, v138
	global_load_lds_dwordx4 v[6:7], off
	s_addc_u32 s19, s23, s19
	s_mov_b32 m0, s5
	v_add_u32_e32 v13, s60, v13
	v_lshl_add_u64 v[6:7], s[18:19], 0, v[0:1]
	global_load_lds_dwordx4 v0, s[18:19]
	v_readfirstlane_b32 s5, v13
	s_add_u32 s18, s20, 0x580000
	v_add_u32_e32 v139, 0x4000, v135
	v_lshl_add_u64 v[14:15], v[6:7], 0, s[76:77]
	s_mov_b32 m0, s5
	s_addc_u32 s19, s21, 0
	v_readfirstlane_b32 s5, v139
	v_add_u32_e32 v140, 0x6000, v135
	global_load_lds_dwordx4 v[14:15], off
	v_lshl_add_u64 v[130:131], s[18:19], 0, v[0:1]
	s_mov_b32 m0, s5
	v_readfirstlane_b32 s5, v140
	global_load_lds_dwordx4 v0, s[18:19]
	v_lshl_add_u64 v[14:15], v[130:131], 0, s[76:77]
	s_mov_b32 m0, s5
	s_cmp_lg_u32 s0, 1
	global_load_lds_dwordx4 v[14:15], off
	v_mov_b32_e32 v16, 0
	v_mov_b32_e32 v17, 0
	v_mov_b32_e32 v18, 0
	v_mov_b32_e32 v19, 0
	v_mov_b32_e32 v20, 0
	v_mov_b32_e32 v21, 0
	v_mov_b32_e32 v22, 0
	v_mov_b32_e32 v23, 0
	v_mov_b32_e32 v24, 0
	v_mov_b32_e32 v25, 0
	v_mov_b32_e32 v26, 0
	v_mov_b32_e32 v27, 0
	v_mov_b32_e32 v28, 0
	v_mov_b32_e32 v29, 0
	v_mov_b32_e32 v30, 0
	v_mov_b32_e32 v31, 0
	v_mov_b32_e32 v32, 0
	v_mov_b32_e32 v33, 0
	v_mov_b32_e32 v34, 0
	v_mov_b32_e32 v35, 0
	v_mov_b32_e32 v36, 0
	v_mov_b32_e32 v37, 0
	v_mov_b32_e32 v38, 0
	v_mov_b32_e32 v39, 0
	v_mov_b32_e32 v40, 0
	v_mov_b32_e32 v41, 0
	v_mov_b32_e32 v42, 0
	v_mov_b32_e32 v43, 0
	v_mov_b32_e32 v44, 0
	v_mov_b32_e32 v45, 0
	v_mov_b32_e32 v46, 0
	v_mov_b32_e32 v47, 0
	v_mov_b32_e32 v48, 0
	v_mov_b32_e32 v49, 0
	v_mov_b32_e32 v50, 0
	v_mov_b32_e32 v51, 0
	v_mov_b32_e32 v52, 0
	v_mov_b32_e32 v53, 0
	v_mov_b32_e32 v54, 0
	v_mov_b32_e32 v55, 0
	v_mov_b32_e32 v56, 0
	v_mov_b32_e32 v57, 0
	v_mov_b32_e32 v58, 0
	v_mov_b32_e32 v59, 0
	v_mov_b32_e32 v60, 0
	v_mov_b32_e32 v61, 0
	v_mov_b32_e32 v62, 0
	v_mov_b32_e32 v63, 0
	v_mov_b32_e32 v64, 0
	v_mov_b32_e32 v65, 0
	v_mov_b32_e32 v66, 0
	v_mov_b32_e32 v67, 0
	v_mov_b32_e32 v68, 0
	v_mov_b32_e32 v69, 0
	v_mov_b32_e32 v70, 0
	v_mov_b32_e32 v71, 0
	v_mov_b32_e32 v72, 0
	v_mov_b32_e32 v73, 0
	v_mov_b32_e32 v74, 0
	v_mov_b32_e32 v75, 0
	v_mov_b32_e32 v76, 0
	v_mov_b32_e32 v77, 0
	v_mov_b32_e32 v78, 0
	v_mov_b32_e32 v79, 0
	v_mov_b32_e32 v80, 0
	v_mov_b32_e32 v81, 0
	v_mov_b32_e32 v82, 0
	v_mov_b32_e32 v83, 0
	v_mov_b32_e32 v84, 0
	v_mov_b32_e32 v85, 0
	v_mov_b32_e32 v86, 0
	v_mov_b32_e32 v87, 0
	v_mov_b32_e32 v88, 0
	v_mov_b32_e32 v89, 0
	v_mov_b32_e32 v90, 0
	v_mov_b32_e32 v91, 0
	v_mov_b32_e32 v92, 0
	v_mov_b32_e32 v93, 0
	v_mov_b32_e32 v94, 0
	v_mov_b32_e32 v95, 0
	v_mov_b32_e32 v96, 0
	v_mov_b32_e32 v97, 0
	v_mov_b32_e32 v98, 0
	v_mov_b32_e32 v99, 0
	v_mov_b32_e32 v100, 0
	v_mov_b32_e32 v101, 0
	v_mov_b32_e32 v102, 0
	v_mov_b32_e32 v103, 0
	v_mov_b32_e32 v104, 0
	v_mov_b32_e32 v105, 0
	v_mov_b32_e32 v106, 0
	v_mov_b32_e32 v107, 0
	v_mov_b32_e32 v108, 0
	v_mov_b32_e32 v109, 0
	v_mov_b32_e32 v110, 0
	v_mov_b32_e32 v111, 0
	v_mov_b32_e32 v112, 0
	v_mov_b32_e32 v113, 0
	v_mov_b32_e32 v114, 0
	v_mov_b32_e32 v115, 0
	v_mov_b32_e32 v116, 0
	v_mov_b32_e32 v117, 0
	v_mov_b32_e32 v118, 0
	v_mov_b32_e32 v119, 0
	v_mov_b32_e32 v120, 0
	v_mov_b32_e32 v121, 0
	v_mov_b32_e32 v122, 0
	v_mov_b32_e32 v123, 0
	v_mov_b32_e32 v124, 0
	v_mov_b32_e32 v125, 0
	v_mov_b32_e32 v126, 0
	v_mov_b32_e32 v127, 0
	v_mov_b32_e32 v128, 0
	v_mov_b32_e32 v129, 0
	s_cbranch_scc1 .LBB0_168
	s_setprio 1
	s_barrier

; #define STAGE_A(P, br, kt) do { const char* _g = (const char*)(A + (long)(br) * lda + (long)(kt) * BK); \
;     __builtin_amdgcn_global_load_lds((const unsigned*)(_g + (size_t)offA0), (unsigned*)((char*)(P) + sb0), 16, 0, 0); \
;     __builtin_amdgcn_global_load_lds((const unsigned*)(_g + (size_t)lda * 128 + (size_t)offA0), (unsigned*)((char*)(P) + sb1), 16, 0, 0); } while (0)
; #define STAGE_B(P, br, kt) do { const char* _g = (const char*)(B + (long)(br) * ldb + (long)(kt) * BK); \
;     __builtin_amdgcn_global_load_lds((const unsigned*)(_g + (size_t)offB0), (unsigned*)((char*)(P) + sb0), 16, 0, 0); \
;     __builtin_amdgcn_global_load_lds((const unsigned*)(_g + (size_t)ldb * 128 + (size_t)offB0), (unsigned*)((char*)(P) + sb1), 16, 0, 0); } while (0)
; #define LDA(dst, b, h) for (int m = 0; m < 4; ++m) for (int k = 0; k < 2; ++k) \
;     dst[m][k] = *reinterpret_cast<const bf16x8*>((char*)SA(b, h) + lds_byte(wr * 64 + m * 16 + fr, k * 32 + fq * 8))
; #define LDB(dst, b, h) for (int n = 0; n < 2; ++n) for (int k = 0; k < 2; ++k) \
;     dst[n][k] = *reinterpret_cast<const bf16x8*>((char*)SB(b, h) + lds_byte(wc * 32 + n * 16 + fr, k * 32 + fq * 8))
; #define MMA(ai, bj, At_, Bt_) do { __builtin_amdgcn_s_setprio(1); \
;     for (int m = 0; m < 4; ++m) for (int n = 0; n < 2; ++n) for (int k = 0; k < 2; ++k) \
;       acc[ai][bj][m][n] = MFMA16(At_[m][k], Bt_[n][k], acc[ai][bj][m][n]); \
;     __builtin_amdgcn_s_setprio(0); } while (0)
; #define WAIT_V(n) asm volatile("s_waitcnt vmcnt(" #n ")" ::: "memory")
; #define WAIT_L(n) asm volatile("s_waitcnt lgkmcnt(" #n ")" ::: "memory")
; #define BAR __builtin_amdgcn_s_barrier()
; #define SCHED __builtin_amdgcn_sched_barrier(0)
; DI void gemm_core(WVP char* smem, const u16* __restrict__ A, int lda, int ar0, int ar1,
;                   const u16* __restrict__ B, int ldb, int bc0, int K, AccT& acc) {
;     ...
;     LDB(B0, 0, 0); SCHED; LDA(At, 0, 0); STAGE_A(SA(1, 1), ac1, t + 1);
;     WAIT_L(8); BAR; WAIT_L(0); MMA(0, 0, At, B0); BAR; SCHED;
;     LDB(B1, 0, 1); STAGE_B(SB(0, 0), bb0, t + 2);
;     BAR; WAIT_L(0); MMA(0, 1, At, B1); BAR;
;     LDA(At, 0, 1); STAGE_A(SA(0, 0), ac0, t + 2);
;     BAR; WAIT_L(0); MMA(1, 0, At, B0); BAR; SCHED;
;     STAGE_B(SB(0, 1), bb1, t + 2);
;     WAIT_V(6); BAR; MMA(1, 1, At, B1); BAR;
.LBB0_169:
	v_add_u32_e32 v150, s0, v148
	v_add_u32_e32 v151, s1, v148
	v_add_u32_e32 v152, s9, v148
	ds_read_b128 v[156:159], v149
	ds_read_b128 v[160:163], v149 offset:1024
	ds_read_b128 v[164:167], v149 offset:2048
	ds_read_b128 v[168:171], v149 offset:3072
	ds_read_b128 v[172:175], v132
	ds_read_b128 v[176:179], v132 offset:1024
	ds_read_b128 v[180:183], v150
	ds_read_b128 v[184:187], v150 offset:1024
	ds_read_b128 v[188:191], v151
	ds_read_b128 v[192:195], v151 offset:1024
	ds_read_b128 v[196:199], v152
	ds_read_b128 v[200:203], v152 offset:1024
	ds_read_b128 v[206:209], v147
	ds_read_b128 v[210:213], v147 offset:1024
	ds_read_b128 v[214:217], v147 offset:2048
	ds_read_b128 v[218:221], v147 offset:3072
	v_add_u32_e32 v153, 0xc000, v135
	v_lshl_add_u64 v[224:225], s[16:17], 0, v[0:1]
	s_mov_b64 s[20:21], 0x1e880080
	v_lshl_add_u64 v[222:223], v[224:225], 0, s[20:21]
	v_readfirstlane_b32 s19, v153
	s_mov_b32 m0, s19
	s_nop 0
	global_load_lds_dwordx4 v[222:223], off
	v_add_u32_e32 v154, 0xe000, v135
	v_lshl_add_u64 v[224:225], s[16:17], 0, v[0:1]
	s_mov_b64 s[20:21], 0x1e8a0080
	v_lshl_add_u64 v[222:223], v[224:225], 0, s[20:21]
	v_readfirstlane_b32 s19, v154
	s_mov_b32 m0, s19
	s_nop 0
	global_load_lds_dwordx4 v[222:223], off
	s_waitcnt vmcnt(8)
	s_waitcnt lgkmcnt(0)
	s_barrier
	v_mfma_f32_16x16x32_bf16 v[126:129], v[172:175], v[156:159], v[126:129]
	v_mfma_f32_16x16x32_bf16 v[122:125], v[172:175], v[164:167], v[122:125]
	v_mfma_f32_16x16x32_bf16 v[118:121], v[180:183], v[156:159], v[118:121]
	v_mfma_f32_16x16x32_bf16 v[114:117], v[180:183], v[164:167], v[114:117]
	v_mfma_f32_16x16x32_bf16 v[110:113], v[188:191], v[156:159], v[110:113]
	v_mfma_f32_16x16x32_bf16 v[106:109], v[188:191], v[164:167], v[106:109]
	v_mfma_f32_16x16x32_bf16 v[102:105], v[196:199], v[156:159], v[102:105]
	v_mfma_f32_16x16x32_bf16 v[98:101], v[196:199], v[164:167], v[98:101]
	v_mfma_f32_16x16x32_bf16 v[126:129], v[176:179], v[160:163], v[126:129]
	v_mfma_f32_16x16x32_bf16 v[122:125], v[176:179], v[168:171], v[122:125]
	v_mfma_f32_16x16x32_bf16 v[118:121], v[184:187], v[160:163], v[118:121]
	v_mfma_f32_16x16x32_bf16 v[114:117], v[184:187], v[168:171], v[114:117]
	v_mfma_f32_16x16x32_bf16 v[110:113], v[192:195], v[160:163], v[110:113]
	v_mfma_f32_16x16x32_bf16 v[106:109], v[192:195], v[168:171], v[106:109]
	v_mfma_f32_16x16x32_bf16 v[102:105], v[200:203], v[160:163], v[102:105]
	v_mfma_f32_16x16x32_bf16 v[98:101], v[200:203], v[168:171], v[98:101]
	v_mfma_f32_16x16x32_bf16 v[94:97], v[172:175], v[206:209], v[94:97]
	v_mfma_f32_16x16x32_bf16 v[90:93], v[172:175], v[214:217], v[90:93]
	v_mfma_f32_16x16x32_bf16 v[86:89], v[180:183], v[206:209], v[86:89]
	v_mfma_f32_16x16x32_bf16 v[82:85], v[180:183], v[214:217], v[82:85]
	v_mfma_f32_16x16x32_bf16 v[78:81], v[188:191], v[206:209], v[78:81]
	v_mfma_f32_16x16x32_bf16 v[74:77], v[188:191], v[214:217], v[74:77]
	v_mfma_f32_16x16x32_bf16 v[70:73], v[196:199], v[206:209], v[70:73]
	v_mfma_f32_16x16x32_bf16 v[66:69], v[196:199], v[214:217], v[66:69]
	v_mfma_f32_16x16x32_bf16 v[94:97], v[176:179], v[210:213], v[94:97]
	v_mfma_f32_16x16x32_bf16 v[90:93], v[176:179], v[218:221], v[90:93]
	v_mfma_f32_16x16x32_bf16 v[86:89], v[184:187], v[210:213], v[86:89]
	v_mfma_f32_16x16x32_bf16 v[82:85], v[184:187], v[218:221], v[82:85]
	v_mfma_f32_16x16x32_bf16 v[78:81], v[192:195], v[210:213], v[78:81]
	v_mfma_f32_16x16x32_bf16 v[74:77], v[192:195], v[218:221], v[74:77]
	v_mfma_f32_16x16x32_bf16 v[70:73], v[200:203], v[210:213], v[70:73]
	v_mfma_f32_16x16x32_bf16 v[66:69], v[200:203], v[218:221], v[66:69]
	s_barrier
	ds_read_b128 v[172:175], v132 offset:16384
	ds_read_b128 v[176:179], v132 offset:17408
	ds_read_b128 v[180:183], v150 offset:16384
	ds_read_b128 v[184:187], v150 offset:17408
	ds_read_b128 v[188:191], v151 offset:16384
	ds_read_b128 v[192:195], v151 offset:17408
	ds_read_b128 v[196:199], v152 offset:16384
	ds_read_b128 v[200:203], v152 offset:17408
	v_lshl_add_u64 v[224:225], s[12:13], 0, v[0:1]
	v_lshl_add_u64 v[222:223], v[224:225], 0, s[80:81]
	v_readfirstlane_b32 s19, v133
	s_mov_b32 m0, s19
	s_nop 0
	global_load_lds_dwordx4 v[222:223], off
	v_add_u32_e32 v155, 0x2000, v133
	v_lshl_add_u64 v[224:225], s[12:13], 0, v[0:1]
	v_lshl_add_u64 v[222:223], v[224:225], 0, s[82:83]
	v_readfirstlane_b32 s19, v155
	s_mov_b32 m0, s19
	s_nop 0
	global_load_lds_dwordx4 v[222:223], off
	v_lshl_add_u64 v[224:225], s[14:15], 0, v[0:1]
	v_lshl_add_u64 v[222:223], v[224:225], 0, s[22:23]
	v_readfirstlane_b32 s19, v135
	s_mov_b32 m0, s19
	s_nop 0
	global_load_lds_dwordx4 v[222:223], off
	v_lshl_add_u64 v[224:225], s[14:15], 0, v[0:1]
	v_lshl_add_u64 v[222:223], v[224:225], 0, s[24:25]
	v_readfirstlane_b32 s19, v136
	s_mov_b32 m0, s19
	s_nop 0
	global_load_lds_dwordx4 v[222:223], off
	v_lshl_add_u64 v[224:225], s[12:13], 0, v[0:1]
	v_lshl_add_u64 v[222:223], v[224:225], 0, s[88:89]
	v_readfirstlane_b32 s19, v138
	s_mov_b32 m0, s19
	s_nop 0
	global_load_lds_dwordx4 v[222:223], off
	v_add_u32_e32 v155, 0x2000, v138
	v_lshl_add_u64 v[224:225], s[12:13], 0, v[0:1]
	v_lshl_add_u64 v[222:223], v[224:225], 0, s[90:91]
	v_readfirstlane_b32 s19, v155
	s_mov_b32 m0, s19
	s_nop 0
	global_load_lds_dwordx4 v[222:223], off
	s_waitcnt vmcnt(8)
	s_waitcnt lgkmcnt(0)
	s_barrier
; #define STAGE_A(P, br, kt) do { const char* _g = (const char*)(A + (long)(br) * lda + (long)(kt) * BK); \
;     __builtin_amdgcn_global_load_lds((const unsigned*)(_g + (size_t)offA0), (unsigned*)((char*)(P) + sb0), 16, 0, 0); \
;     __builtin_amdgcn_global_load_lds((const unsigned*)(_g + (size_t)lda * 128 + (size_t)offA0), (unsigned*)((char*)(P) + sb1), 16, 0, 0); } while (0)
; #define STAGE_B(P, br, kt) do { const char* _g = (const char*)(B + (long)(br) * ldb + (long)(kt) * BK); \
;     __builtin_amdgcn_global_load_lds((const unsigned*)(_g + (size_t)offB0), (unsigned*)((char*)(P) + sb0), 16, 0, 0); \
;     __builtin_amdgcn_global_load_lds((const unsigned*)(_g + (size_t)ldb * 128 + (size_t)offB0), (unsigned*)((char*)(P) + sb1), 16, 0, 0); } while (0)
; #define LDA(dst, b, h) for (int m = 0; m < 4; ++m) for (int k = 0; k < 2; ++k) \
;     dst[m][k] = *reinterpret_cast<const bf16x8*>((char*)SA(b, h) + lds_byte(wr * 64 + m * 16 + fr, k * 32 + fq * 8))
; #define LDB(dst, b, h) for (int n = 0; n < 2; ++n) for (int k = 0; k < 2; ++k) \
;     dst[n][k] = *reinterpret_cast<const bf16x8*>((char*)SB(b, h) + lds_byte(wc * 32 + n * 16 + fr, k * 32 + fq * 8))
; #define MMA(ai, bj, At_, Bt_) do { __builtin_amdgcn_s_setprio(1); \
;     for (int m = 0; m < 4; ++m) for (int n = 0; n < 2; ++n) for (int k = 0; k < 2; ++k) \
;       acc[ai][bj][m][n] = MFMA16(At_[m][k], Bt_[n][k], acc[ai][bj][m][n]); \
;     __builtin_amdgcn_s_setprio(0); } while (0)
; #define WAIT_V(n) asm volatile("s_waitcnt vmcnt(" #n ")" ::: "memory")
; #define WAIT_L(n) asm volatile("s_waitcnt lgkmcnt(" #n ")" ::: "memory")
; #define BAR __builtin_amdgcn_s_barrier()
; #define SCHED __builtin_amdgcn_sched_barrier(0)
; DI void gemm_core(WVP char* smem, const u16* __restrict__ A, int lda, int ar0, int ar1,
;                   const u16* __restrict__ B, int ldb, int bc0, int K, AccT& acc) {
;     ...
;     WAIT_V(6); BAR; MMA(1, 1, At, B1); BAR;
;     LDB(B0, 1, 0); SCHED; LDA(At, 1, 0); STAGE_A(SA(0, 1), ac1, t + 2);
;     WAIT_L(8); BAR; WAIT_L(0); MMA(0, 0, At, B0); BAR; SCHED;
;     LDB(B1, 1, 1); STAGE_B(SB(1, 0), bb0, t + 3);
;     BAR; WAIT_L(0); MMA(0, 1, At, B1); BAR;
	v_mfma_f32_16x16x32_bf16 v[62:65], v[172:175], v[156:159], v[62:65]
	v_mfma_f32_16x16x32_bf16 v[58:61], v[172:175], v[164:167], v[58:61]
	v_mfma_f32_16x16x32_bf16 v[54:57], v[180:183], v[156:159], v[54:57]
	v_mfma_f32_16x16x32_bf16 v[50:53], v[180:183], v[164:167], v[50:53]
	v_mfma_f32_16x16x32_bf16 v[46:49], v[188:191], v[156:159], v[46:49]
	v_mfma_f32_16x16x32_bf16 v[42:45], v[188:191], v[164:167], v[42:45]
	v_mfma_f32_16x16x32_bf16 v[38:41], v[196:199], v[156:159], v[38:41]
	v_mfma_f32_16x16x32_bf16 v[34:37], v[196:199], v[164:167], v[34:37]
	v_mfma_f32_16x16x32_bf16 v[62:65], v[176:179], v[160:163], v[62:65]
	v_mfma_f32_16x16x32_bf16 v[58:61], v[176:179], v[168:171], v[58:61]
	v_mfma_f32_16x16x32_bf16 v[54:57], v[184:187], v[160:163], v[54:57]
	v_mfma_f32_16x16x32_bf16 v[50:53], v[184:187], v[168:171], v[50:53]
	v_mfma_f32_16x16x32_bf16 v[46:49], v[192:195], v[160:163], v[46:49]
	v_mfma_f32_16x16x32_bf16 v[42:45], v[192:195], v[168:171], v[42:45]
	v_mfma_f32_16x16x32_bf16 v[38:41], v[200:203], v[160:163], v[38:41]
	v_mfma_f32_16x16x32_bf16 v[34:37], v[200:203], v[168:171], v[34:37]
	v_mfma_f32_16x16x32_bf16 v[30:33], v[172:175], v[206:209], v[30:33]
	v_mfma_f32_16x16x32_bf16 v[26:29], v[172:175], v[214:217], v[26:29]
	v_mfma_f32_16x16x32_bf16 v[22:25], v[180:183], v[206:209], v[22:25]
	v_mfma_f32_16x16x32_bf16 v[18:21], v[180:183], v[214:217], v[18:21]
	v_mfma_f32_16x16x32_bf16 v[14:17], v[188:191], v[206:209], v[14:17]
	v_mfma_f32_16x16x32_bf16 v[10:13], v[188:191], v[214:217], v[10:13]
	v_mfma_f32_16x16x32_bf16 v[6:9], v[196:199], v[206:209], v[6:9]
	v_mfma_f32_16x16x32_bf16 v[2:5], v[196:199], v[214:217], v[2:5]
	v_mfma_f32_16x16x32_bf16 v[30:33], v[176:179], v[210:213], v[30:33]
	v_mfma_f32_16x16x32_bf16 v[26:29], v[176:179], v[218:221], v[26:29]
	v_mfma_f32_16x16x32_bf16 v[22:25], v[184:187], v[210:213], v[22:25]
	v_mfma_f32_16x16x32_bf16 v[18:21], v[184:187], v[218:221], v[18:21]
	v_mfma_f32_16x16x32_bf16 v[14:17], v[192:195], v[210:213], v[14:17]
	v_mfma_f32_16x16x32_bf16 v[10:13], v[192:195], v[218:221], v[10:13]
	v_mfma_f32_16x16x32_bf16 v[6:9], v[200:203], v[210:213], v[6:9]
	v_mfma_f32_16x16x32_bf16 v[2:5], v[200:203], v[218:221], v[2:5]
	s_barrier
	ds_read_b128 v[156:159], v137
	ds_read_b128 v[160:163], v137 offset:1024
	ds_read_b128 v[164:167], v137 offset:2048
	ds_read_b128 v[168:171], v137 offset:3072
	ds_read_b128 v[172:175], v132 offset:32768
	ds_read_b128 v[176:179], v132 offset:33792
	ds_read_b128 v[180:183], v150 offset:32768
	ds_read_b128 v[184:187], v150 offset:33792
	ds_read_b128 v[188:191], v151 offset:32768
	ds_read_b128 v[192:195], v151 offset:33792
	ds_read_b128 v[196:199], v152 offset:32768
	ds_read_b128 v[200:203], v152 offset:33792
	ds_read_b128 v[206:209], v134
	ds_read_b128 v[210:213], v134 offset:1024
	ds_read_b128 v[214:217], v134 offset:2048
	ds_read_b128 v[218:221], v134 offset:3072
	v_lshl_add_u64 v[224:225], s[16:17], 0, v[0:1]
	v_lshl_add_u64 v[222:223], v[224:225], 0, s[22:23]
	v_readfirstlane_b32 s19, v139
	s_mov_b32 m0, s19
	s_nop 0
	global_load_lds_dwordx4 v[222:223], off
	v_lshl_add_u64 v[224:225], s[16:17], 0, v[0:1]
	v_lshl_add_u64 v[222:223], v[224:225], 0, s[24:25]
	v_readfirstlane_b32 s19, v140
	s_mov_b32 m0, s19
	s_nop 0
	global_load_lds_dwordx4 v[222:223], off
	s_waitcnt vmcnt(8)
	s_waitcnt lgkmcnt(0)
	s_barrier
	v_mfma_f32_16x16x32_bf16 v[126:129], v[172:175], v[156:159], v[126:129]
	v_mfma_f32_16x16x32_bf16 v[122:125], v[172:175], v[164:167], v[122:125]
	v_mfma_f32_16x16x32_bf16 v[118:121], v[180:183], v[156:159], v[118:121]
	v_mfma_f32_16x16x32_bf16 v[114:117], v[180:183], v[164:167], v[114:117]
	v_mfma_f32_16x16x32_bf16 v[110:113], v[188:191], v[156:159], v[110:113]
	v_mfma_f32_16x16x32_bf16 v[106:109], v[188:191], v[164:167], v[106:109]
	v_mfma_f32_16x16x32_bf16 v[102:105], v[196:199], v[156:159], v[102:105]
	v_mfma_f32_16x16x32_bf16 v[98:101], v[196:199], v[164:167], v[98:101]
	v_mfma_f32_16x16x32_bf16 v[126:129], v[176:179], v[160:163], v[126:129]
	v_mfma_f32_16x16x32_bf16 v[122:125], v[176:179], v[168:171], v[122:125]
	v_mfma_f32_16x16x32_bf16 v[118:121], v[184:187], v[160:163], v[118:121]
	v_mfma_f32_16x16x32_bf16 v[114:117], v[184:187], v[168:171], v[114:117]
	v_mfma_f32_16x16x32_bf16 v[110:113], v[192:195], v[160:163], v[110:113]
	v_mfma_f32_16x16x32_bf16 v[106:109], v[192:195], v[168:171], v[106:109]
	v_mfma_f32_16x16x32_bf16 v[102:105], v[200:203], v[160:163], v[102:105]
	v_mfma_f32_16x16x32_bf16 v[98:101], v[200:203], v[168:171], v[98:101]
	v_mfma_f32_16x16x32_bf16 v[94:97], v[172:175], v[206:209], v[94:97]
	v_mfma_f32_16x16x32_bf16 v[90:93], v[172:175], v[214:217], v[90:93]
	v_mfma_f32_16x16x32_bf16 v[86:89], v[180:183], v[206:209], v[86:89]
	v_mfma_f32_16x16x32_bf16 v[82:85], v[180:183], v[214:217], v[82:85]
	v_mfma_f32_16x16x32_bf16 v[78:81], v[188:191], v[206:209], v[78:81]
	v_mfma_f32_16x16x32_bf16 v[74:77], v[188:191], v[214:217], v[74:77]
	v_mfma_f32_16x16x32_bf16 v[70:73], v[196:199], v[206:209], v[70:73]
	v_mfma_f32_16x16x32_bf16 v[66:69], v[196:199], v[214:217], v[66:69]
	v_mfma_f32_16x16x32_bf16 v[94:97], v[176:179], v[210:213], v[94:97]
	v_mfma_f32_16x16x32_bf16 v[90:93], v[176:179], v[218:221], v[90:93]
	v_mfma_f32_16x16x32_bf16 v[86:89], v[184:187], v[210:213], v[86:89]
	v_mfma_f32_16x16x32_bf16 v[82:85], v[184:187], v[218:221], v[82:85]
	v_mfma_f32_16x16x32_bf16 v[78:81], v[192:195], v[210:213], v[78:81]
	v_mfma_f32_16x16x32_bf16 v[74:77], v[192:195], v[218:221], v[74:77]
	v_mfma_f32_16x16x32_bf16 v[70:73], v[200:203], v[210:213], v[70:73]
	v_mfma_f32_16x16x32_bf16 v[66:69], v[200:203], v[218:221], v[66:69]
	s_barrier
; #define STAGE_A(P, br, kt) do { const char* _g = (const char*)(A + (long)(br) * lda + (long)(kt) * BK); \
;     __builtin_amdgcn_global_load_lds((const unsigned*)(_g + (size_t)offA0), (unsigned*)((char*)(P) + sb0), 16, 0, 0); \
;     __builtin_amdgcn_global_load_lds((const unsigned*)(_g + (size_t)lda * 128 + (size_t)offA0), (unsigned*)((char*)(P) + sb1), 16, 0, 0); } while (0)
; #define STAGE_B(P, br, kt) do { const char* _g = (const char*)(B + (long)(br) * ldb + (long)(kt) * BK); \
;     __builtin_amdgcn_global_load_lds((const unsigned*)(_g + (size_t)offB0), (unsigned*)((char*)(P) + sb0), 16, 0, 0); \
;     __builtin_amdgcn_global_load_lds((const unsigned*)(_g + (size_t)ldb * 128 + (size_t)offB0), (unsigned*)((char*)(P) + sb1), 16, 0, 0); } while (0)
; #define LDA(dst, b, h) for (int m = 0; m < 4; ++m) for (int k = 0; k < 2; ++k) \
;     dst[m][k] = *reinterpret_cast<const bf16x8*>((char*)SA(b, h) + lds_byte(wr * 64 + m * 16 + fr, k * 32 + fq * 8))
; #define LDB(dst, b, h) for (int n = 0; n < 2; ++n) for (int k = 0; k < 2; ++k) \
;     dst[n][k] = *reinterpret_cast<const bf16x8*>((char*)SB(b, h) + lds_byte(wc * 32 + n * 16 + fr, k * 32 + fq * 8))
; #define MMA(ai, bj, At_, Bt_) do { __builtin_amdgcn_s_setprio(1); \
;     for (int m = 0; m < 4; ++m) for (int n = 0; n < 2; ++n) for (int k = 0; k < 2; ++k) \
;       acc[ai][bj][m][n] = MFMA16(At_[m][k], Bt_[n][k], acc[ai][bj][m][n]); \
;     __builtin_amdgcn_s_setprio(0); } while (0)
; #define WAIT_V(n) asm volatile("s_waitcnt vmcnt(" #n ")" ::: "memory")
; #define WAIT_L(n) asm volatile("s_waitcnt lgkmcnt(" #n ")" ::: "memory")
; #define BAR __builtin_amdgcn_s_barrier()
; #define SCHED __builtin_amdgcn_sched_barrier(0)
; DI void gemm_core(WVP char* smem, const u16* __restrict__ A, int lda, int ar0, int ar1,
;                   const u16* __restrict__ B, int ldb, int bc0, int K, AccT& acc) {
;     ...
;     LDA(At, 1, 1); STAGE_A(SA(1, 0), ac0, t + 3);
;     BAR; WAIT_L(0); MMA(1, 0, At, B0); BAR; SCHED;
;     STAGE_B(SB(1, 1), bb1, t + 3);
;     WAIT_V(6); BAR; MMA(1, 1, At, B1); BAR;
;   }
;   { LDB(B0, 0, 0); LDA(At, 0, 0); STAGE_A(SA(1, 1), ac1, nt - 1);
;     BAR; WAIT_L(0); MMA(0, 0, At, B0); BAR;
	ds_read_b128 v[172:175], v132 offset:49152
	ds_read_b128 v[176:179], v132 offset:50176
	ds_read_b128 v[180:183], v150 offset:49152
	ds_read_b128 v[184:187], v150 offset:50176
	ds_read_b128 v[188:191], v151 offset:49152
	ds_read_b128 v[192:195], v151 offset:50176
	ds_read_b128 v[196:199], v152 offset:49152
	ds_read_b128 v[200:203], v152 offset:50176
	v_lshl_add_u64 v[224:225], s[12:13], 0, v[0:1]
	v_lshl_add_u64 v[222:223], v[224:225], 0, s[92:93]
	v_readfirstlane_b32 s19, v141
	s_mov_b32 m0, s19
	s_nop 0
	global_load_lds_dwordx4 v[222:223], off
	v_lshl_add_u64 v[224:225], s[12:13], 0, v[0:1]
	v_lshl_add_u64 v[222:223], v[224:225], 0, s[94:95]
	v_readfirstlane_b32 s19, v142
	s_mov_b32 m0, s19
	s_nop 0
	global_load_lds_dwordx4 v[222:223], off
	v_lshl_add_u64 v[224:225], s[14:15], 0, v[0:1]
	s_mov_b64 s[20:21], 0x1e880180
	v_lshl_add_u64 v[222:223], v[224:225], 0, s[20:21]
	v_readfirstlane_b32 s19, v143
	s_mov_b32 m0, s19
	s_nop 0
	global_load_lds_dwordx4 v[222:223], off
	v_lshl_add_u64 v[224:225], s[14:15], 0, v[0:1]
	s_mov_b64 s[20:21], 0x1e8a0180
	v_lshl_add_u64 v[222:223], v[224:225], 0, s[20:21]
	v_readfirstlane_b32 s19, v144
	s_mov_b32 m0, s19
	s_nop 0
	global_load_lds_dwordx4 v[222:223], off
	v_lshl_add_u64 v[224:225], s[12:13], 0, v[0:1]
	v_lshl_add_u64 v[222:223], v[224:225], 0, s[96:97]
	v_readfirstlane_b32 s19, v145
	s_mov_b32 m0, s19
	s_nop 0
	global_load_lds_dwordx4 v[222:223], off
	v_lshl_add_u64 v[224:225], s[12:13], 0, v[0:1]
	v_lshl_add_u64 v[222:223], v[224:225], 0, s[72:73]
	v_readfirstlane_b32 s19, v146
	s_mov_b32 m0, s19
	s_nop 0
	global_load_lds_dwordx4 v[222:223], off
	s_waitcnt vmcnt(8)
	s_waitcnt lgkmcnt(0)
	s_barrier
	v_mfma_f32_16x16x32_bf16 v[62:65], v[172:175], v[156:159], v[62:65]
	v_mfma_f32_16x16x32_bf16 v[58:61], v[172:175], v[164:167], v[58:61]
	v_mfma_f32_16x16x32_bf16 v[54:57], v[180:183], v[156:159], v[54:57]
	v_mfma_f32_16x16x32_bf16 v[50:53], v[180:183], v[164:167], v[50:53]
	v_mfma_f32_16x16x32_bf16 v[46:49], v[188:191], v[156:159], v[46:49]
	v_mfma_f32_16x16x32_bf16 v[42:45], v[188:191], v[164:167], v[42:45]
	v_mfma_f32_16x16x32_bf16 v[38:41], v[196:199], v[156:159], v[38:41]
	v_mfma_f32_16x16x32_bf16 v[34:37], v[196:199], v[164:167], v[34:37]
	v_mfma_f32_16x16x32_bf16 v[62:65], v[176:179], v[160:163], v[62:65]
	v_mfma_f32_16x16x32_bf16 v[58:61], v[176:179], v[168:171], v[58:61]
	v_mfma_f32_16x16x32_bf16 v[54:57], v[184:187], v[160:163], v[54:57]
	v_mfma_f32_16x16x32_bf16 v[50:53], v[184:187], v[168:171], v[50:53]
	v_mfma_f32_16x16x32_bf16 v[46:49], v[192:195], v[160:163], v[46:49]
	v_mfma_f32_16x16x32_bf16 v[42:45], v[192:195], v[168:171], v[42:45]
	v_mfma_f32_16x16x32_bf16 v[38:41], v[200:203], v[160:163], v[38:41]
	v_mfma_f32_16x16x32_bf16 v[34:37], v[200:203], v[168:171], v[34:37]
	v_mfma_f32_16x16x32_bf16 v[30:33], v[172:175], v[206:209], v[30:33]
	v_mfma_f32_16x16x32_bf16 v[26:29], v[172:175], v[214:217], v[26:29]
	v_mfma_f32_16x16x32_bf16 v[22:25], v[180:183], v[206:209], v[22:25]
	v_mfma_f32_16x16x32_bf16 v[18:21], v[180:183], v[214:217], v[18:21]
	v_mfma_f32_16x16x32_bf16 v[14:17], v[188:191], v[206:209], v[14:17]
	v_mfma_f32_16x16x32_bf16 v[10:13], v[188:191], v[214:217], v[10:13]
	v_mfma_f32_16x16x32_bf16 v[6:9], v[196:199], v[206:209], v[6:9]
	v_mfma_f32_16x16x32_bf16 v[2:5], v[196:199], v[214:217], v[2:5]
	v_mfma_f32_16x16x32_bf16 v[30:33], v[176:179], v[210:213], v[30:33]
	v_mfma_f32_16x16x32_bf16 v[26:29], v[176:179], v[218:221], v[26:29]
	v_mfma_f32_16x16x32_bf16 v[22:25], v[184:187], v[210:213], v[22:25]
	v_mfma_f32_16x16x32_bf16 v[18:21], v[184:187], v[218:221], v[18:21]
	v_mfma_f32_16x16x32_bf16 v[14:17], v[192:195], v[210:213], v[14:17]
	v_mfma_f32_16x16x32_bf16 v[10:13], v[192:195], v[218:221], v[10:13]
	v_mfma_f32_16x16x32_bf16 v[6:9], v[200:203], v[210:213], v[6:9]
	v_mfma_f32_16x16x32_bf16 v[2:5], v[200:203], v[218:221], v[2:5]
	s_add_i32 s18, s18, 2
	s_add_u32 s12, s12, 0x100
	s_addc_u32 s13, s13, 0
	s_add_u32 s14, s14, 0x100
	s_addc_u32 s15, s15, 0
	s_add_u32 s16, s16, 0x100
	s_addc_u32 s17, s17, 0
	s_cmp_lt_u32 s18, 12
	s_barrier
	s_cbranch_scc1 .LBB0_169
	s_mov_b64 s[0:1], 0x780
	ds_read_b128 v[138:141], v149
	ds_read_b128 v[142:145], v149 offset:1024
	ds_read_b128 v[156:159], v149 offset:2048
	ds_read_b128 v[160:163], v149 offset:3072
	ds_read_b128 v[164:167], v132
	ds_read_b128 v[168:171], v132 offset:1024
	ds_read_b128 v[172:175], v150
	ds_read_b128 v[176:179], v150 offset:1024
	ds_read_b128 v[180:183], v151
	ds_read_b128 v[184:187], v151 offset:1024
	ds_read_b128 v[188:191], v152
	ds_read_b128 v[192:195], v152 offset:1024
	v_lshl_add_u64 v[148:149], v[130:131], 0, s[0:1]
	v_readfirstlane_b32 s0, v153
	s_mov_b32 m0, s0
	s_mov_b64 s[0:1], 0x20780
	v_lshl_add_u64 v[130:131], v[130:131], 0, s[0:1]
	v_readfirstlane_b32 s0, v154
	global_load_lds_dwordx4 v[148:149], off
	s_mov_b32 m0, s0
	s_nop 0
	global_load_lds_dwordx4 v[130:131], off
	s_waitcnt vmcnt(8)
	s_barrier
	s_waitcnt lgkmcnt(0)
	s_setprio 1
	s_waitcnt lgkmcnt(0)
	v_mfma_f32_16x16x32_bf16 v[126:129], v[164:167], v[138:141], v[126:129]
	v_mfma_f32_16x16x32_bf16 v[118:121], v[172:175], v[138:141], v[118:121]
	v_mfma_f32_16x16x32_bf16 v[110:113], v[180:183], v[138:141], v[110:113]
	v_mfma_f32_16x16x32_bf16 v[102:105], v[188:191], v[138:141], v[102:105]
	v_mfma_f32_16x16x32_bf16 v[126:129], v[168:171], v[142:145], v[126:129]
	v_mfma_f32_16x16x32_bf16 v[122:125], v[164:167], v[156:159], v[122:125]
	v_mfma_f32_16x16x32_bf16 v[118:121], v[176:179], v[142:145], v[118:121]
	v_mfma_f32_16x16x32_bf16 v[114:117], v[172:175], v[156:159], v[114:117]
	v_mfma_f32_16x16x32_bf16 v[110:113], v[184:187], v[142:145], v[110:113]
	v_mfma_f32_16x16x32_bf16 v[106:109], v[180:183], v[156:159], v[106:109]
	v_mfma_f32_16x16x32_bf16 v[102:105], v[192:195], v[142:145], v[102:105]
	v_mfma_f32_16x16x32_bf16 v[98:101], v[188:191], v[156:159], v[98:101]
	v_mfma_f32_16x16x32_bf16 v[196:199], v[168:171], v[160:163], v[122:125]
	v_mfma_f32_16x16x32_bf16 v[200:203], v[176:179], v[160:163], v[114:117]
	v_mfma_f32_16x16x32_bf16 v[206:209], v[184:187], v[160:163], v[106:109]
	v_mfma_f32_16x16x32_bf16 v[210:213], v[192:195], v[160:163], v[98:101]
	s_setprio 0
	s_barrier
; #define LDA(dst, b, h) for (int m = 0; m < 4; ++m) for (int k = 0; k < 2; ++k) \
;     dst[m][k] = *reinterpret_cast<const bf16x8*>((char*)SA(b, h) + lds_byte(wr * 64 + m * 16 + fr, k * 32 + fq * 8))
; #define LDB(dst, b, h) for (int n = 0; n < 2; ++n) for (int k = 0; k < 2; ++k) \
;     dst[n][k] = *reinterpret_cast<const bf16x8*>((char*)SB(b, h) + lds_byte(wc * 32 + n * 16 + fr, k * 32 + fq * 8))
; #define MMA(ai, bj, At_, Bt_) do { __builtin_amdgcn_s_setprio(1); \
;     for (int m = 0; m < 4; ++m) for (int n = 0; n < 2; ++n) for (int k = 0; k < 2; ++k) \
;       acc[ai][bj][m][n] = MFMA16(At_[m][k], Bt_[n][k], acc[ai][bj][m][n]); \
;     __builtin_amdgcn_s_setprio(0); } while (0)
; #define WAIT_V(n) asm volatile("s_waitcnt vmcnt(" #n ")" ::: "memory")
; #define WAIT_L(n) asm volatile("s_waitcnt lgkmcnt(" #n ")" ::: "memory")
; #define BAR __builtin_amdgcn_s_barrier()
; DI void gemm_core(WVP char* smem, const u16* __restrict__ A, int lda, int ar0, int ar1,
;                   const u16* __restrict__ B, int ldb, int bc0, int K, AccT& acc) {
;     ...
;     LDB(B1, 0, 1); BAR; WAIT_L(0); MMA(0, 1, At, B1); BAR;
;     LDA(At, 0, 1); WAIT_V(4); BAR; WAIT_L(0); MMA(1, 0, At, B0); MMA(1, 1, At, B1); BAR; }
;   { LDB(B0, 1, 0); LDA(At, 1, 0); WAIT_V(2); BAR; WAIT_L(0); MMA(0, 0, At, B0); BAR;
	s_nop 1
	ds_read_b128 v[98:101], v147
	ds_read_b128 v[106:109], v147 offset:1024
	ds_read_b128 v[114:117], v147 offset:2048
	ds_read_b128 v[122:125], v147 offset:3072
	s_barrier
	s_waitcnt lgkmcnt(0)
	s_setprio 1
	s_waitcnt lgkmcnt(0)
	v_mfma_f32_16x16x32_bf16 v[94:97], v[164:167], v[98:101], v[94:97]
	v_mfma_f32_16x16x32_bf16 v[86:89], v[172:175], v[98:101], v[86:89]
	v_mfma_f32_16x16x32_bf16 v[78:81], v[180:183], v[98:101], v[78:81]
	v_mfma_f32_16x16x32_bf16 v[70:73], v[188:191], v[98:101], v[70:73]
	v_mfma_f32_16x16x32_bf16 v[94:97], v[168:171], v[106:109], v[94:97]
	v_mfma_f32_16x16x32_bf16 v[90:93], v[164:167], v[114:117], v[90:93]
	v_mfma_f32_16x16x32_bf16 v[86:89], v[176:179], v[106:109], v[86:89]
	v_mfma_f32_16x16x32_bf16 v[82:85], v[172:175], v[114:117], v[82:85]
	v_mfma_f32_16x16x32_bf16 v[78:81], v[184:187], v[106:109], v[78:81]
	v_mfma_f32_16x16x32_bf16 v[74:77], v[180:183], v[114:117], v[74:77]
	v_mfma_f32_16x16x32_bf16 v[70:73], v[192:195], v[106:109], v[70:73]
	v_mfma_f32_16x16x32_bf16 v[66:69], v[188:191], v[114:117], v[66:69]
	v_mfma_f32_16x16x32_bf16 v[146:149], v[168:171], v[122:125], v[90:93]
	v_mfma_f32_16x16x32_bf16 v[164:167], v[176:179], v[122:125], v[82:85]
	v_mfma_f32_16x16x32_bf16 v[168:171], v[184:187], v[122:125], v[74:77]
	v_mfma_f32_16x16x32_bf16 v[172:175], v[192:195], v[122:125], v[66:69]
	s_setprio 0
	s_barrier
	s_nop 1
	ds_read_b128 v[66:69], v132 offset:16384
	ds_read_b128 v[74:77], v132 offset:17408
	ds_read_b128 v[82:85], v150 offset:16384
	ds_read_b128 v[90:93], v150 offset:17408
	ds_read_b128 v[176:179], v151 offset:16384
	ds_read_b128 v[180:183], v151 offset:17408
	ds_read_b128 v[184:187], v152 offset:16384
	ds_read_b128 v[188:191], v152 offset:17408
	s_waitcnt vmcnt(4)
	s_barrier
	s_waitcnt lgkmcnt(0)
	s_setprio 1
	s_waitcnt lgkmcnt(0)
	v_mfma_f32_16x16x32_bf16 v[62:65], v[66:69], v[138:141], v[62:65]
	v_mfma_f32_16x16x32_bf16 v[54:57], v[82:85], v[138:141], v[54:57]
	v_mfma_f32_16x16x32_bf16 v[46:49], v[176:179], v[138:141], v[46:49]
	v_mfma_f32_16x16x32_bf16 v[38:41], v[184:187], v[138:141], v[38:41]
	v_mfma_f32_16x16x32_bf16 v[62:65], v[74:77], v[142:145], v[62:65]
	v_mfma_f32_16x16x32_bf16 v[58:61], v[66:69], v[156:159], v[58:61]
	v_mfma_f32_16x16x32_bf16 v[54:57], v[90:93], v[142:145], v[54:57]
	v_mfma_f32_16x16x32_bf16 v[50:53], v[82:85], v[156:159], v[50:53]
	v_mfma_f32_16x16x32_bf16 v[46:49], v[180:183], v[142:145], v[46:49]
	v_mfma_f32_16x16x32_bf16 v[42:45], v[176:179], v[156:159], v[42:45]
	v_mfma_f32_16x16x32_bf16 v[38:41], v[188:191], v[142:145], v[38:41]
	v_mfma_f32_16x16x32_bf16 v[34:37], v[184:187], v[156:159], v[34:37]
	v_mfma_f32_16x16x32_bf16 v[192:195], v[74:77], v[160:163], v[58:61]
	v_mfma_f32_16x16x32_bf16 v[214:217], v[90:93], v[160:163], v[50:53]
	v_mfma_f32_16x16x32_bf16 v[218:221], v[180:183], v[160:163], v[42:45]
	v_mfma_f32_16x16x32_bf16 v[138:141], v[188:191], v[160:163], v[34:37]
	s_setprio 0
	s_setprio 1
	v_mfma_f32_16x16x32_bf16 v[30:33], v[66:69], v[98:101], v[30:33]
	v_mfma_f32_16x16x32_bf16 v[22:25], v[82:85], v[98:101], v[22:25]
	v_mfma_f32_16x16x32_bf16 v[14:17], v[176:179], v[98:101], v[14:17]
	v_mfma_f32_16x16x32_bf16 v[6:9], v[184:187], v[98:101], v[6:9]
	v_mfma_f32_16x16x32_bf16 v[30:33], v[74:77], v[106:109], v[30:33]
	v_mfma_f32_16x16x32_bf16 v[26:29], v[66:69], v[114:117], v[26:29]
	v_mfma_f32_16x16x32_bf16 v[22:25], v[90:93], v[106:109], v[22:25]
	v_mfma_f32_16x16x32_bf16 v[18:21], v[82:85], v[114:117], v[18:21]
	v_mfma_f32_16x16x32_bf16 v[14:17], v[180:183], v[106:109], v[14:17]
	v_mfma_f32_16x16x32_bf16 v[10:13], v[176:179], v[114:117], v[10:13]
	v_mfma_f32_16x16x32_bf16 v[6:9], v[188:191], v[106:109], v[6:9]
	v_mfma_f32_16x16x32_bf16 v[2:5], v[184:187], v[114:117], v[2:5]
	v_mfma_f32_16x16x32_bf16 v[142:145], v[74:77], v[122:125], v[26:29]
	v_mfma_f32_16x16x32_bf16 v[154:157], v[90:93], v[122:125], v[18:21]
	v_mfma_f32_16x16x32_bf16 v[158:161], v[180:183], v[122:125], v[10:13]
	v_mfma_f32_16x16x32_bf16 v[176:179], v[188:191], v[122:125], v[2:5]
	s_setprio 0
	s_barrier
	ds_read_b128 v[180:183], v137
	ds_read_b128 v[184:187], v137 offset:1024
	ds_read_b128 v[188:191], v137 offset:2048
	ds_read_b128 v[222:225], v137 offset:3072
	ds_read_b128 v[2:5], v132 offset:32768
	ds_read_b128 v[10:13], v132 offset:33792
	ds_read_b128 v[18:21], v150 offset:32768
	ds_read_b128 v[26:29], v150 offset:33792
	ds_read_b128 v[226:229], v151 offset:32768
	ds_read_b128 v[230:233], v151 offset:33792
	ds_read_b128 v[234:237], v152 offset:32768
	ds_read_b128 v[238:241], v152 offset:33792
	s_waitcnt vmcnt(2)
	s_barrier
; #define LDA(dst, b, h) for (int m = 0; m < 4; ++m) for (int k = 0; k < 2; ++k) \
;     dst[m][k] = *reinterpret_cast<const bf16x8*>((char*)SA(b, h) + lds_byte(wr * 64 + m * 16 + fr, k * 32 + fq * 8))
; #define LDB(dst, b, h) for (int n = 0; n < 2; ++n) for (int k = 0; k < 2; ++k) \
;     dst[n][k] = *reinterpret_cast<const bf16x8*>((char*)SB(b, h) + lds_byte(wc * 32 + n * 16 + fr, k * 32 + fq * 8))
; #define MMA(ai, bj, At_, Bt_) do { __builtin_amdgcn_s_setprio(1); \
;     for (int m = 0; m < 4; ++m) for (int n = 0; n < 2; ++n) for (int k = 0; k < 2; ++k) \
;       acc[ai][bj][m][n] = MFMA16(At_[m][k], Bt_[n][k], acc[ai][bj][m][n]); \
;     __builtin_amdgcn_s_setprio(0); } while (0)
; #define WAIT_V(n) asm volatile("s_waitcnt vmcnt(" #n ")" ::: "memory")
; #define WAIT_L(n) asm volatile("s_waitcnt lgkmcnt(" #n ")" ::: "memory")
; #define BAR __builtin_amdgcn_s_barrier()
; DI void gemm_core(WVP char* smem, const u16* __restrict__ A, int lda, int ar0, int ar1,
;                   const u16* __restrict__ B, int ldb, int bc0, int K, AccT& acc) {
;     ...
;   { LDB(B0, 1, 0); LDA(At, 1, 0); WAIT_V(2); BAR; WAIT_L(0); MMA(0, 0, At, B0); BAR;
;     LDB(B1, 1, 1); WAIT_V(0); BAR; WAIT_L(0); MMA(0, 1, At, B1); BAR;
;     LDA(At, 1, 1); BAR; WAIT_L(0); MMA(1, 0, At, B0); MMA(1, 1, At, B1); BAR; }
;   if (wr == 0) BAR;
	s_waitcnt lgkmcnt(0)
	s_setprio 1
	s_waitcnt lgkmcnt(0)
	v_mfma_f32_16x16x32_bf16 v[34:37], v[2:5], v[180:183], v[126:129]
	v_mfma_f32_16x16x32_bf16 v[122:125], v[10:13], v[184:187], v[34:37]
	v_mfma_f32_16x16x32_bf16 v[34:37], v[2:5], v[188:191], v[196:199]
	v_mfma_f32_16x16x32_bf16 v[114:117], v[10:13], v[222:225], v[34:37]
	v_mfma_f32_16x16x32_bf16 v[34:37], v[18:21], v[180:183], v[118:121]
	v_mfma_f32_16x16x32_bf16 v[106:109], v[26:29], v[184:187], v[34:37]
	v_mfma_f32_16x16x32_bf16 v[34:37], v[18:21], v[188:191], v[200:203]
	v_mfma_f32_16x16x32_bf16 v[98:101], v[26:29], v[222:225], v[34:37]
	v_mfma_f32_16x16x32_bf16 v[34:37], v[226:229], v[180:183], v[110:113]
	v_mfma_f32_16x16x32_bf16 v[90:93], v[230:233], v[184:187], v[34:37]
	v_mfma_f32_16x16x32_bf16 v[34:37], v[226:229], v[188:191], v[206:209]
	v_mfma_f32_16x16x32_bf16 v[82:85], v[230:233], v[222:225], v[34:37]
	v_mfma_f32_16x16x32_bf16 v[34:37], v[234:237], v[180:183], v[102:105]
	v_mfma_f32_16x16x32_bf16 v[74:77], v[238:241], v[184:187], v[34:37]
	v_mfma_f32_16x16x32_bf16 v[34:37], v[234:237], v[188:191], v[210:213]
	v_mfma_f32_16x16x32_bf16 v[66:69], v[238:241], v[222:225], v[34:37]
	s_setprio 0
	s_barrier
	ds_read_b128 v[196:199], v134
	ds_read_b128 v[200:203], v134 offset:1024
	ds_read_b128 v[206:209], v134 offset:2048
	ds_read_b128 v[134:137], v134 offset:3072
	s_waitcnt vmcnt(0)
	s_barrier
	s_waitcnt lgkmcnt(0)
	s_setprio 1
	s_waitcnt lgkmcnt(0)
	v_mfma_f32_16x16x32_bf16 v[34:37], v[2:5], v[196:199], v[94:97]
	v_mfma_f32_16x16x32_bf16 v[2:5], v[2:5], v[206:209], v[146:149]
	v_mfma_f32_16x16x32_bf16 v[50:53], v[10:13], v[134:137], v[2:5]
	v_mfma_f32_16x16x32_bf16 v[2:5], v[18:21], v[196:199], v[86:89]
	v_mfma_f32_16x16x32_bf16 v[42:45], v[26:29], v[200:203], v[2:5]
	v_mfma_f32_16x16x32_bf16 v[2:5], v[18:21], v[206:209], v[164:167]
	v_mfma_f32_16x16x32_bf16 v[58:61], v[10:13], v[200:203], v[34:37]
	v_mfma_f32_16x16x32_bf16 v[34:37], v[26:29], v[134:137], v[2:5]
	v_mfma_f32_16x16x32_bf16 v[2:5], v[226:229], v[196:199], v[78:81]
	v_mfma_f32_16x16x32_bf16 v[26:29], v[230:233], v[200:203], v[2:5]
	v_mfma_f32_16x16x32_bf16 v[2:5], v[226:229], v[206:209], v[168:171]
	v_mfma_f32_16x16x32_bf16 v[18:21], v[230:233], v[134:137], v[2:5]
	v_mfma_f32_16x16x32_bf16 v[2:5], v[234:237], v[196:199], v[70:73]
	v_mfma_f32_16x16x32_bf16 v[10:13], v[238:241], v[200:203], v[2:5]
	v_mfma_f32_16x16x32_bf16 v[2:5], v[234:237], v[206:209], v[172:175]
	v_mfma_f32_16x16x32_bf16 v[2:5], v[238:241], v[134:137], v[2:5]
	s_setprio 0
	s_barrier
	ds_read_b128 v[146:149], v132 offset:49152
	ds_read_b128 v[130:133], v132 offset:50176
	ds_read_b128 v[162:165], v150 offset:49152
	ds_read_b128 v[166:169], v150 offset:50176
	ds_read_b128 v[170:173], v151 offset:49152
	ds_read_b128 v[210:213], v151 offset:50176
	ds_read_b128 v[226:229], v152 offset:49152
	ds_read_b128 v[150:153], v152 offset:50176
	s_barrier
	s_waitcnt lgkmcnt(0)
	s_setprio 1
	s_waitcnt lgkmcnt(0)
	v_mfma_f32_16x16x32_bf16 v[62:65], v[146:149], v[180:183], v[62:65]
	v_mfma_f32_16x16x32_bf16 v[54:57], v[162:165], v[180:183], v[54:57]
	v_mfma_f32_16x16x32_bf16 v[46:49], v[170:173], v[180:183], v[46:49]
	v_mfma_f32_16x16x32_bf16 v[38:41], v[226:229], v[180:183], v[38:41]
	v_mfma_f32_16x16x32_bf16 v[126:129], v[130:133], v[184:187], v[62:65]
	v_mfma_f32_16x16x32_bf16 v[62:65], v[146:149], v[188:191], v[192:195]
	v_mfma_f32_16x16x32_bf16 v[110:113], v[166:169], v[184:187], v[54:57]
	v_mfma_f32_16x16x32_bf16 v[54:57], v[162:165], v[188:191], v[214:217]
	v_mfma_f32_16x16x32_bf16 v[94:97], v[210:213], v[184:187], v[46:49]
	v_mfma_f32_16x16x32_bf16 v[46:49], v[170:173], v[188:191], v[218:221]
	v_mfma_f32_16x16x32_bf16 v[78:81], v[150:153], v[184:187], v[38:41]
	v_mfma_f32_16x16x32_bf16 v[38:41], v[226:229], v[188:191], v[138:141]
	v_mfma_f32_16x16x32_bf16 v[118:121], v[130:133], v[222:225], v[62:65]
	v_mfma_f32_16x16x32_bf16 v[102:105], v[166:169], v[222:225], v[54:57]
	v_mfma_f32_16x16x32_bf16 v[86:89], v[210:213], v[222:225], v[46:49]
	v_mfma_f32_16x16x32_bf16 v[70:73], v[150:153], v[222:225], v[38:41]
	s_setprio 0
	s_setprio 1
	v_mfma_f32_16x16x32_bf16 v[30:33], v[146:149], v[196:199], v[30:33]
	v_mfma_f32_16x16x32_bf16 v[62:65], v[130:133], v[200:203], v[30:33]
	v_mfma_f32_16x16x32_bf16 v[30:33], v[146:149], v[206:209], v[142:145]
	v_mfma_f32_16x16x32_bf16 v[22:25], v[162:165], v[196:199], v[22:25]
	v_mfma_f32_16x16x32_bf16 v[14:17], v[170:173], v[196:199], v[14:17]
	v_mfma_f32_16x16x32_bf16 v[54:57], v[130:133], v[134:137], v[30:33]
	v_mfma_f32_16x16x32_bf16 v[46:49], v[166:169], v[200:203], v[22:25]
	v_mfma_f32_16x16x32_bf16 v[22:25], v[162:165], v[206:209], v[154:157]
	v_mfma_f32_16x16x32_bf16 v[30:33], v[210:213], v[200:203], v[14:17]
	v_mfma_f32_16x16x32_bf16 v[14:17], v[170:173], v[206:209], v[158:161]
	v_mfma_f32_16x16x32_bf16 v[6:9], v[226:229], v[196:199], v[6:9]
	v_mfma_f32_16x16x32_bf16 v[38:41], v[166:169], v[134:137], v[22:25]
	v_mfma_f32_16x16x32_bf16 v[22:25], v[210:213], v[134:137], v[14:17]
	v_mfma_f32_16x16x32_bf16 v[14:17], v[150:153], v[200:203], v[6:9]
	v_mfma_f32_16x16x32_bf16 v[6:9], v[226:229], v[206:209], v[176:179]
	v_mfma_f32_16x16x32_bf16 v[6:9], v[150:153], v[134:137], v[6:9]
	s_setprio 0
	s_cmp_gt_u32 s5, 3
	s_movk_i32 s5, 0x1600
	s_barrier
	s_cbranch_scc1 .LBB0_164
	s_barrier
	s_branch .LBB0_164

; DI int get_tid(int wv) { int l; asm volatile("v_mbcnt_lo_u32_b32 %0, -1, 0\n\tv_mbcnt_hi_u32_b32 %0, -1, %0" : "=v"(l)); return wv * 64 + l; }
; DI int wave_of(int tid) { return __builtin_amdgcn_readfirstlane(tid >> 6); }
; #define STAGE_A(P, br, kt) do { const char* _g = (const char*)(A + (long)(br) * lda + (long)(kt) * BK); \
;     __builtin_amdgcn_global_load_lds((const unsigned*)(_g + (size_t)offA0), (unsigned*)((char*)(P) + sb0), 16, 0, 0); \
;     __builtin_amdgcn_global_load_lds((const unsigned*)(_g + (size_t)lda * 128 + (size_t)offA0), (unsigned*)((char*)(P) + sb1), 16, 0, 0); } while (0)
; #define STAGE_B(P, br, kt) do { const char* _g = (const char*)(B + (long)(br) * ldb + (long)(kt) * BK); \
;     __builtin_amdgcn_global_load_lds((const unsigned*)(_g + (size_t)offB0), (unsigned*)((char*)(P) + sb0), 16, 0, 0); \
;     __builtin_amdgcn_global_load_lds((const unsigned*)(_g + (size_t)ldb * 128 + (size_t)offB0), (unsigned*)((char*)(P) + sb1), 16, 0, 0); } while (0)
; #define BAR __builtin_amdgcn_s_barrier()
; DI void gemm_core(WVP char* smem, const u16* __restrict__ A, int lda, int ar0, int ar1,
;                   const u16* __restrict__ B, int ldb, int bc0, int K, AccT& acc) {
;     ...
;   const int tid = get_tid(WV);
;   const int wid = wave_of(tid), lane = tid & 63, wr = wid >> 2, wc = wid & 3, fr = lane & 15, fq = lane >> 4;
;   const int sb0 = tid * 16, sb1 = sb0 + 8192;
;   int R0, C0; stage_rc(sb0, R0, C0);
;   const unsigned offA0 = (unsigned)(R0 * lda + C0) * 2u, offB0 = (unsigned)(R0 * ldb + C0) * 2u;
;   const int ac0 = ar0, ac1 = ar1, bb0 = bc0, bb1 = bc0 + HALF;
;   bf16x8 At[4][2], B0[2][2], B1[2][2];
;   const int nt = K / BK;
;   __syncthreads();
;   STAGE_B(SB(0, 0), bb0, 0); STAGE_A(SA(0, 0), ac0, 0);
;   STAGE_B(SB(0, 1), bb1, 0); STAGE_A(SA(0, 1), ac1, 0);
;   if (wr == 1) BAR;
.LBB0_184:
	s_add_i32 s0, s1, s8
	s_ashr_i32 s1, s0, 31
	s_lshr_b32 s1, s1, 23
	s_add_i32 s1, s0, s1
	s_ashr_i32 s8, s1, 9
	s_and_b32 s1, s1, 0xfe00
	s_sub_i32 s0, s0, s1
	s_sext_i32_i16 s1, s0
	s_bfe_u32 s1, s1, 0x2001d
	v_mbcnt_lo_u32_b32 v9, -1, 0
	v_mbcnt_hi_u32_b32 v9, -1, v9
	s_add_i32 s1, s0, s1
	v_add_u32_e32 v0, s3, v9
	v_ashrrev_i32_e32 v2, 31, v0
	s_lshl_b32 s26, s8, 2
	s_sext_i32_i16 s8, s1
	s_and_b32 s1, s1, 0xfffc
	v_lshrrev_b32_e32 v2, 26, v2
	s_sub_i32 s0, s0, s1
	v_readfirstlane_b32 s1, v0
	v_lshlrev_b32_e32 v12, 4, v0
	v_add_u32_e32 v2, v0, v2
	v_bfe_i32 v0, v0, 27, 1
	v_lshrrev_b32_e32 v0, 22, v0
	v_add_u32_e32 v0, v12, v0
	v_and_b32_e32 v0, 0xfffffc00, v0
	v_sub_u32_e32 v0, v12, v0
	v_ashrrev_i32_e32 v8, 6, v2
	v_lshrrev_b32_e32 v2, 4, v0
	v_bitop3_b32 v0, v2, v0, 32 bitop3:0x6c
	s_sext_i32_i16 s0, s0
	s_ashr_i32 s27, s8, 2
	v_ashrrev_i32_e32 v3, 31, v0
	s_add_i32 s26, s26, s0
	s_lshl_b32 s14, s27, 8
	v_lshrrev_b32_e32 v3, 26, v3
	s_lshl_b32 s16, s26, 8
	v_add_u32_e32 v3, v0, v3
	s_ashr_i32 s15, s14, 31
	s_or_b32 s22, s16, 0x80
	s_ashr_i32 s0, s1, 8
	v_ashrrev_i32_e32 v10, 6, v3
	v_and_b32_e32 v3, 0xc0, v3
	s_or_b32 s28, s14, 0x80
	s_lshl_b64 s[8:9], s[14:15], 11
	v_sub_u32_e32 v0, v0, v3
	s_add_u32 s18, s10, s8
	v_lshlrev_b32_e32 v2, 3, v8
	v_lshlrev_b32_e32 v4, 5, v8
	v_ashrrev_i16_sdwa v0, v254, sext(v0) dst_sel:DWORD dst_unused:UNUSED_PAD src0_sel:DWORD src1_sel:BYTE_0
	s_addc_u32 s19, s11, s9
	s_add_i32 s20, 0, 0x10000
	v_and_b32_e32 v2, 0x1ffff0, v2
	v_and_b32_e32 v4, 32, v4
	v_bfe_i32 v11, v0, 0, 16
	v_add_u32_e32 v134, s20, v12
	v_add_u32_e32 v0, v4, v11
	v_add_lshl_u32 v2, v10, v2, 11
	v_readfirstlane_b32 s15, v134
	v_lshl_add_u32 v0, v0, 1, v2
	s_mov_b32 m0, s15
	s_ashr_i32 s17, s16, 31
	s_barrier
	v_lshl_add_u64 v[2:3], s[18:19], 0, v[0:1]
	global_load_lds_dwordx4 v0, s[18:19]
	s_lshl_b64 s[18:19], s[16:17], 11
	v_add_u32_e32 v13, 0x2000, v12
	s_add_u32 s30, s75, s18
	v_readlane_b32 s21, v255, 37
	v_add_u32_e32 v6, s20, v13
	s_addc_u32 s31, s21, s19
	s_ashr_i32 s29, s28, 31
	v_readfirstlane_b32 s15, v6
	v_add_u32_e32 v135, 0, v12
	s_lshl_b64 s[28:29], s[28:29], 11
	v_lshl_add_u64 v[4:5], v[2:3], 0, s[76:77]
	s_mov_b32 m0, s15
	v_readfirstlane_b32 s15, v135
	v_add_u32_e32 v136, 0x2000, v135
	s_add_u32 s28, s10, s28
	global_load_lds_dwordx4 v[4:5], off
	v_lshl_add_u64 v[4:5], s[30:31], 0, v[0:1]
	s_mov_b32 m0, s15
	v_readfirstlane_b32 s15, v136
	s_addc_u32 s29, s11, s29
	v_add_u32_e32 v138, s60, v12
	s_ashr_i32 s23, s22, 31
	global_load_lds_dwordx4 v0, s[30:31]
	v_lshl_add_u64 v[6:7], v[4:5], 0, s[76:77]
	s_mov_b32 m0, s15
	v_readfirstlane_b32 s15, v138
	v_add_u32_e32 v13, s60, v13
	s_lshl_b64 s[22:23], s[22:23], 11
	global_load_lds_dwordx4 v[6:7], off
	v_lshl_add_u64 v[6:7], s[28:29], 0, v[0:1]
	s_mov_b32 m0, s15
	v_readfirstlane_b32 s15, v13
	s_add_u32 s22, s75, s22
	v_add_u32_e32 v139, 0x4000, v135
	global_load_lds_dwordx4 v0, s[28:29]
	v_lshl_add_u64 v[14:15], v[6:7], 0, s[76:77]
	s_mov_b32 m0, s15
	s_addc_u32 s23, s21, s23
	v_readfirstlane_b32 s15, v139
	v_add_u32_e32 v140, 0x6000, v135
	global_load_lds_dwordx4 v[14:15], off
	v_lshl_add_u64 v[130:131], s[22:23], 0, v[0:1]
	s_mov_b32 m0, s15
	v_readfirstlane_b32 s15, v140
	global_load_lds_dwordx4 v0, s[22:23]
	v_lshl_add_u64 v[14:15], v[130:131], 0, s[76:77]
	s_mov_b32 m0, s15
	s_cmp_lg_u32 s0, 1
	global_load_lds_dwordx4 v[14:15], off
	v_mov_b32_e32 v16, 0
	v_mov_b32_e32 v17, 0
	v_mov_b32_e32 v18, 0
	v_mov_b32_e32 v19, 0
	v_mov_b32_e32 v20, 0
	v_mov_b32_e32 v21, 0
	v_mov_b32_e32 v22, 0
	v_mov_b32_e32 v23, 0
	v_mov_b32_e32 v24, 0
	v_mov_b32_e32 v25, 0
	v_mov_b32_e32 v26, 0
	v_mov_b32_e32 v27, 0
	v_mov_b32_e32 v28, 0
	v_mov_b32_e32 v29, 0
	v_mov_b32_e32 v30, 0
	v_mov_b32_e32 v31, 0
	v_mov_b32_e32 v32, 0
	v_mov_b32_e32 v33, 0
	v_mov_b32_e32 v34, 0
	v_mov_b32_e32 v35, 0
	v_mov_b32_e32 v36, 0
	v_mov_b32_e32 v37, 0
	v_mov_b32_e32 v38, 0
	v_mov_b32_e32 v39, 0
	v_mov_b32_e32 v40, 0
	v_mov_b32_e32 v41, 0
	v_mov_b32_e32 v42, 0
	v_mov_b32_e32 v43, 0
	v_mov_b32_e32 v44, 0
	v_mov_b32_e32 v45, 0
	v_mov_b32_e32 v46, 0
	v_mov_b32_e32 v47, 0
	v_mov_b32_e32 v48, 0
	v_mov_b32_e32 v49, 0
	v_mov_b32_e32 v50, 0
	v_mov_b32_e32 v51, 0
	v_mov_b32_e32 v52, 0
	v_mov_b32_e32 v53, 0
	v_mov_b32_e32 v54, 0
	v_mov_b32_e32 v55, 0
	v_mov_b32_e32 v56, 0
	v_mov_b32_e32 v57, 0
	v_mov_b32_e32 v58, 0
	v_mov_b32_e32 v59, 0
	v_mov_b32_e32 v60, 0
	v_mov_b32_e32 v61, 0
	v_mov_b32_e32 v62, 0
	v_mov_b32_e32 v63, 0
	v_mov_b32_e32 v64, 0
	v_mov_b32_e32 v65, 0
	v_mov_b32_e32 v66, 0
	v_mov_b32_e32 v67, 0
	v_mov_b32_e32 v68, 0
	v_mov_b32_e32 v69, 0
	v_mov_b32_e32 v70, 0
	v_mov_b32_e32 v71, 0
	v_mov_b32_e32 v72, 0
	v_mov_b32_e32 v73, 0
	v_mov_b32_e32 v74, 0
	v_mov_b32_e32 v75, 0
	v_mov_b32_e32 v76, 0
	v_mov_b32_e32 v77, 0
	v_mov_b32_e32 v78, 0
	v_mov_b32_e32 v79, 0
	v_mov_b32_e32 v80, 0
	v_mov_b32_e32 v81, 0
	v_mov_b32_e32 v82, 0
	v_mov_b32_e32 v83, 0
	v_mov_b32_e32 v84, 0
	v_mov_b32_e32 v85, 0
	v_mov_b32_e32 v86, 0
	v_mov_b32_e32 v87, 0
	v_mov_b32_e32 v88, 0
	v_mov_b32_e32 v89, 0
	v_mov_b32_e32 v90, 0
	v_mov_b32_e32 v91, 0
	v_mov_b32_e32 v92, 0
	v_mov_b32_e32 v93, 0
	v_mov_b32_e32 v94, 0
	v_mov_b32_e32 v95, 0
	v_mov_b32_e32 v96, 0
	v_mov_b32_e32 v97, 0
	v_mov_b32_e32 v98, 0
	v_mov_b32_e32 v99, 0
	v_mov_b32_e32 v100, 0
	v_mov_b32_e32 v101, 0
	v_mov_b32_e32 v102, 0
	v_mov_b32_e32 v103, 0
	v_mov_b32_e32 v104, 0
	v_mov_b32_e32 v105, 0
	v_mov_b32_e32 v106, 0
	v_mov_b32_e32 v107, 0
	v_mov_b32_e32 v108, 0
	v_mov_b32_e32 v109, 0
	v_mov_b32_e32 v110, 0
	v_mov_b32_e32 v111, 0
	v_mov_b32_e32 v112, 0
	v_mov_b32_e32 v113, 0
	v_mov_b32_e32 v114, 0
	v_mov_b32_e32 v115, 0
	v_mov_b32_e32 v116, 0
	v_mov_b32_e32 v117, 0
	v_mov_b32_e32 v118, 0
	v_mov_b32_e32 v119, 0
	v_mov_b32_e32 v120, 0
	v_mov_b32_e32 v121, 0
	v_mov_b32_e32 v122, 0
	v_mov_b32_e32 v123, 0
	v_mov_b32_e32 v124, 0
	v_mov_b32_e32 v125, 0
	v_mov_b32_e32 v126, 0
	v_mov_b32_e32 v127, 0
	v_mov_b32_e32 v128, 0
	v_mov_b32_e32 v129, 0
	s_cbranch_scc1 .LBB0_186
	s_setprio 1
	s_barrier

; #define STAGE_A(P, br, kt) do { const char* _g = (const char*)(A + (long)(br) * lda + (long)(kt) * BK); \
;     __builtin_amdgcn_global_load_lds((const unsigned*)(_g + (size_t)offA0), (unsigned*)((char*)(P) + sb0), 16, 0, 0); \
;     __builtin_amdgcn_global_load_lds((const unsigned*)(_g + (size_t)lda * 128 + (size_t)offA0), (unsigned*)((char*)(P) + sb1), 16, 0, 0); } while (0)
; #define STAGE_B(P, br, kt) do { const char* _g = (const char*)(B + (long)(br) * ldb + (long)(kt) * BK); \
;     __builtin_amdgcn_global_load_lds((const unsigned*)(_g + (size_t)offB0), (unsigned*)((char*)(P) + sb0), 16, 0, 0); \
;     __builtin_amdgcn_global_load_lds((const unsigned*)(_g + (size_t)ldb * 128 + (size_t)offB0), (unsigned*)((char*)(P) + sb1), 16, 0, 0); } while (0)
; #define LDA(dst, b, h) for (int m = 0; m < 4; ++m) for (int k = 0; k < 2; ++k) \
;     dst[m][k] = *reinterpret_cast<const bf16x8*>((char*)SA(b, h) + lds_byte(wr * 64 + m * 16 + fr, k * 32 + fq * 8))
; #define LDB(dst, b, h) for (int n = 0; n < 2; ++n) for (int k = 0; k < 2; ++k) \
;     dst[n][k] = *reinterpret_cast<const bf16x8*>((char*)SB(b, h) + lds_byte(wc * 32 + n * 16 + fr, k * 32 + fq * 8))
; #define MMA(ai, bj, At_, Bt_) do { __builtin_amdgcn_s_setprio(1); \
;     for (int m = 0; m < 4; ++m) for (int n = 0; n < 2; ++n) for (int k = 0; k < 2; ++k) \
;       acc[ai][bj][m][n] = MFMA16(At_[m][k], Bt_[n][k], acc[ai][bj][m][n]); \
;     __builtin_amdgcn_s_setprio(0); } while (0)
; #define WAIT_V(n) asm volatile("s_waitcnt vmcnt(" #n ")" ::: "memory")
; #define WAIT_L(n) asm volatile("s_waitcnt lgkmcnt(" #n ")" ::: "memory")
; #define BAR __builtin_amdgcn_s_barrier()
; #define SCHED __builtin_amdgcn_sched_barrier(0)
; DI void gemm_core(WVP char* smem, const u16* __restrict__ A, int lda, int ar0, int ar1,
;                   const u16* __restrict__ B, int ldb, int bc0, int K, AccT& acc) {
;     ...
;     LDB(B0, 0, 0); SCHED; LDA(At, 0, 0); STAGE_A(SA(1, 1), ac1, t + 1);
;     WAIT_L(8); BAR; WAIT_L(0); MMA(0, 0, At, B0); BAR; SCHED;
;     LDB(B1, 0, 1); STAGE_B(SB(0, 0), bb0, t + 2);
;     BAR; WAIT_L(0); MMA(0, 1, At, B1); BAR;
;     LDA(At, 0, 1); STAGE_A(SA(0, 0), ac0, t + 2);
;     BAR; WAIT_L(0); MMA(1, 0, At, B0); BAR; SCHED;
;     STAGE_B(SB(0, 1), bb1, t + 2);
;     WAIT_V(6); BAR; MMA(1, 1, At, B1); BAR;
.LBB0_187:
	v_add_u32_e32 v150, s0, v148
	v_add_u32_e32 v151, s1, v148
	v_add_u32_e32 v152, s20, v148
	ds_read_b128 v[156:159], v149
	ds_read_b128 v[160:163], v149 offset:1024
	ds_read_b128 v[164:167], v149 offset:2048
	ds_read_b128 v[168:171], v149 offset:3072
	ds_read_b128 v[172:175], v132
	ds_read_b128 v[176:179], v132 offset:1024
	ds_read_b128 v[180:183], v150
	ds_read_b128 v[184:187], v150 offset:1024
	ds_read_b128 v[188:191], v151
	ds_read_b128 v[192:195], v151 offset:1024
	ds_read_b128 v[196:199], v152
	ds_read_b128 v[200:203], v152 offset:1024
	ds_read_b128 v[206:209], v146
	ds_read_b128 v[210:213], v146 offset:1024
	ds_read_b128 v[214:217], v146 offset:2048
	ds_read_b128 v[218:221], v146 offset:3072
	v_add_u32_e32 v153, 0xc000, v135
	v_lshl_add_u64 v[224:225], s[18:19], 0, v[0:1]
	s_mov_b64 s[22:23], 0x1e6c0080
	v_lshl_add_u64 v[222:223], v[224:225], 0, s[22:23]
	v_readfirstlane_b32 s22, v153
	s_mov_b32 m0, s22
	s_nop 0
	global_load_lds_dwordx4 v[222:223], off
	v_add_u32_e32 v154, 0xe000, v135
	v_lshl_add_u64 v[224:225], s[18:19], 0, v[0:1]
	s_mov_b64 s[22:23], 0x1e6e0080
	v_lshl_add_u64 v[222:223], v[224:225], 0, s[22:23]
	v_readfirstlane_b32 s22, v154
	s_mov_b32 m0, s22
	s_nop 0
	global_load_lds_dwordx4 v[222:223], off
	s_waitcnt vmcnt(8)
	s_waitcnt lgkmcnt(0)
	s_barrier
	v_mfma_f32_16x16x32_bf16 v[126:129], v[172:175], v[156:159], v[126:129]
	v_mfma_f32_16x16x32_bf16 v[122:125], v[172:175], v[164:167], v[122:125]
	v_mfma_f32_16x16x32_bf16 v[118:121], v[180:183], v[156:159], v[118:121]
	v_mfma_f32_16x16x32_bf16 v[114:117], v[180:183], v[164:167], v[114:117]
	v_mfma_f32_16x16x32_bf16 v[110:113], v[188:191], v[156:159], v[110:113]
	v_mfma_f32_16x16x32_bf16 v[106:109], v[188:191], v[164:167], v[106:109]
	v_mfma_f32_16x16x32_bf16 v[102:105], v[196:199], v[156:159], v[102:105]
	v_mfma_f32_16x16x32_bf16 v[98:101], v[196:199], v[164:167], v[98:101]
	v_mfma_f32_16x16x32_bf16 v[126:129], v[176:179], v[160:163], v[126:129]
	v_mfma_f32_16x16x32_bf16 v[122:125], v[176:179], v[168:171], v[122:125]
	v_mfma_f32_16x16x32_bf16 v[118:121], v[184:187], v[160:163], v[118:121]
	v_mfma_f32_16x16x32_bf16 v[114:117], v[184:187], v[168:171], v[114:117]
	v_mfma_f32_16x16x32_bf16 v[110:113], v[192:195], v[160:163], v[110:113]
	v_mfma_f32_16x16x32_bf16 v[106:109], v[192:195], v[168:171], v[106:109]
	v_mfma_f32_16x16x32_bf16 v[102:105], v[200:203], v[160:163], v[102:105]
	v_mfma_f32_16x16x32_bf16 v[98:101], v[200:203], v[168:171], v[98:101]
	v_mfma_f32_16x16x32_bf16 v[94:97], v[172:175], v[206:209], v[94:97]
	v_mfma_f32_16x16x32_bf16 v[82:85], v[172:175], v[214:217], v[82:85]
	v_mfma_f32_16x16x32_bf16 v[66:69], v[180:183], v[206:209], v[66:69]
	v_mfma_f32_16x16x32_bf16 v[54:57], v[180:183], v[214:217], v[54:57]
	v_mfma_f32_16x16x32_bf16 v[50:53], v[188:191], v[206:209], v[50:53]
	v_mfma_f32_16x16x32_bf16 v[46:49], v[188:191], v[214:217], v[46:49]
	v_mfma_f32_16x16x32_bf16 v[42:45], v[196:199], v[206:209], v[42:45]
	v_mfma_f32_16x16x32_bf16 v[38:41], v[196:199], v[214:217], v[38:41]
	v_mfma_f32_16x16x32_bf16 v[94:97], v[176:179], v[210:213], v[94:97]
	v_mfma_f32_16x16x32_bf16 v[82:85], v[176:179], v[218:221], v[82:85]
	v_mfma_f32_16x16x32_bf16 v[66:69], v[184:187], v[210:213], v[66:69]
	v_mfma_f32_16x16x32_bf16 v[54:57], v[184:187], v[218:221], v[54:57]
	v_mfma_f32_16x16x32_bf16 v[50:53], v[192:195], v[210:213], v[50:53]
	v_mfma_f32_16x16x32_bf16 v[46:49], v[192:195], v[218:221], v[46:49]
	v_mfma_f32_16x16x32_bf16 v[42:45], v[200:203], v[210:213], v[42:45]
	v_mfma_f32_16x16x32_bf16 v[38:41], v[200:203], v[218:221], v[38:41]
	s_barrier
	ds_read_b128 v[172:175], v132 offset:16384
	ds_read_b128 v[176:179], v132 offset:17408
	ds_read_b128 v[180:183], v150 offset:16384
	ds_read_b128 v[184:187], v150 offset:17408
	ds_read_b128 v[188:191], v151 offset:16384
	ds_read_b128 v[192:195], v151 offset:17408
	ds_read_b128 v[196:199], v152 offset:16384
	ds_read_b128 v[200:203], v152 offset:17408
	v_lshl_add_u64 v[224:225], s[8:9], 0, v[0:1]
	s_mov_b64 s[22:23], 0x19000100
	v_lshl_add_u64 v[222:223], v[224:225], 0, s[22:23]
	v_readfirstlane_b32 s22, v134
	s_mov_b32 m0, s22
	s_nop 0
	global_load_lds_dwordx4 v[222:223], off
	v_add_u32_e32 v155, 0x2000, v134
	v_lshl_add_u64 v[224:225], s[8:9], 0, v[0:1]
	s_mov_b64 s[22:23], 0x19020100
	v_lshl_add_u64 v[222:223], v[224:225], 0, s[22:23]
	v_readfirstlane_b32 s22, v155
	s_mov_b32 m0, s22
	s_nop 0
	global_load_lds_dwordx4 v[222:223], off
	v_lshl_add_u64 v[224:225], s[18:19], 0, v[0:1]
	s_mov_b64 s[22:23], 0x1e680100
	v_lshl_add_u64 v[222:223], v[224:225], 0, s[22:23]
	v_readfirstlane_b32 s22, v135
	s_mov_b32 m0, s22
	s_nop 0
	global_load_lds_dwordx4 v[222:223], off
	v_lshl_add_u64 v[224:225], s[18:19], 0, v[0:1]
	s_mov_b64 s[22:23], 0x1e6a0100
	v_lshl_add_u64 v[222:223], v[224:225], 0, s[22:23]
	v_readfirstlane_b32 s22, v136
	s_mov_b32 m0, s22
	s_nop 0
	global_load_lds_dwordx4 v[222:223], off
	v_lshl_add_u64 v[224:225], s[8:9], 0, v[0:1]
	s_mov_b64 s[22:23], 0x19040100
	v_lshl_add_u64 v[222:223], v[224:225], 0, s[22:23]
	v_readfirstlane_b32 s22, v138
	s_mov_b32 m0, s22
	s_nop 0
	global_load_lds_dwordx4 v[222:223], off
	v_add_u32_e32 v155, 0x2000, v138
	v_lshl_add_u64 v[224:225], s[8:9], 0, v[0:1]
	s_mov_b64 s[22:23], 0x19060100
	v_lshl_add_u64 v[222:223], v[224:225], 0, s[22:23]
	v_readfirstlane_b32 s22, v155
	s_mov_b32 m0, s22
	s_nop 0
	global_load_lds_dwordx4 v[222:223], off
	s_waitcnt vmcnt(8)
	s_waitcnt lgkmcnt(0)
	s_barrier
; #define STAGE_A(P, br, kt) do { const char* _g = (const char*)(A + (long)(br) * lda + (long)(kt) * BK); \
;     __builtin_amdgcn_global_load_lds((const unsigned*)(_g + (size_t)offA0), (unsigned*)((char*)(P) + sb0), 16, 0, 0); \
;     __builtin_amdgcn_global_load_lds((const unsigned*)(_g + (size_t)lda * 128 + (size_t)offA0), (unsigned*)((char*)(P) + sb1), 16, 0, 0); } while (0)
; #define STAGE_B(P, br, kt) do { const char* _g = (const char*)(B + (long)(br) * ldb + (long)(kt) * BK); \
;     __builtin_amdgcn_global_load_lds((const unsigned*)(_g + (size_t)offB0), (unsigned*)((char*)(P) + sb0), 16, 0, 0); \
;     __builtin_amdgcn_global_load_lds((const unsigned*)(_g + (size_t)ldb * 128 + (size_t)offB0), (unsigned*)((char*)(P) + sb1), 16, 0, 0); } while (0)
; #define LDA(dst, b, h) for (int m = 0; m < 4; ++m) for (int k = 0; k < 2; ++k) \
;     dst[m][k] = *reinterpret_cast<const bf16x8*>((char*)SA(b, h) + lds_byte(wr * 64 + m * 16 + fr, k * 32 + fq * 8))
; #define LDB(dst, b, h) for (int n = 0; n < 2; ++n) for (int k = 0; k < 2; ++k) \
;     dst[n][k] = *reinterpret_cast<const bf16x8*>((char*)SB(b, h) + lds_byte(wc * 32 + n * 16 + fr, k * 32 + fq * 8))
; #define MMA(ai, bj, At_, Bt_) do { __builtin_amdgcn_s_setprio(1); \
;     for (int m = 0; m < 4; ++m) for (int n = 0; n < 2; ++n) for (int k = 0; k < 2; ++k) \
;       acc[ai][bj][m][n] = MFMA16(At_[m][k], Bt_[n][k], acc[ai][bj][m][n]); \
;     __builtin_amdgcn_s_setprio(0); } while (0)
; #define WAIT_V(n) asm volatile("s_waitcnt vmcnt(" #n ")" ::: "memory")
; #define WAIT_L(n) asm volatile("s_waitcnt lgkmcnt(" #n ")" ::: "memory")
; #define BAR __builtin_amdgcn_s_barrier()
; #define SCHED __builtin_amdgcn_sched_barrier(0)
; DI void gemm_core(WVP char* smem, const u16* __restrict__ A, int lda, int ar0, int ar1,
;                   const u16* __restrict__ B, int ldb, int bc0, int K, AccT& acc) {
;     ...
;     WAIT_V(6); BAR; MMA(1, 1, At, B1); BAR;
;     LDB(B0, 1, 0); SCHED; LDA(At, 1, 0); STAGE_A(SA(0, 1), ac1, t + 2);
;     WAIT_L(8); BAR; WAIT_L(0); MMA(0, 0, At, B0); BAR; SCHED;
;     LDB(B1, 1, 1); STAGE_B(SB(1, 0), bb0, t + 3);
;     BAR; WAIT_L(0); MMA(0, 1, At, B1); BAR;
	v_mfma_f32_16x16x32_bf16 v[34:37], v[172:175], v[156:159], v[34:37]
	v_mfma_f32_16x16x32_bf16 v[30:33], v[172:175], v[164:167], v[30:33]
	v_mfma_f32_16x16x32_bf16 v[26:29], v[180:183], v[156:159], v[26:29]
	v_mfma_f32_16x16x32_bf16 v[22:25], v[180:183], v[164:167], v[22:25]
	v_mfma_f32_16x16x32_bf16 v[18:21], v[188:191], v[156:159], v[18:21]
	v_mfma_f32_16x16x32_bf16 v[14:17], v[188:191], v[164:167], v[14:17]
	v_mfma_f32_16x16x32_bf16 v[10:13], v[196:199], v[156:159], v[10:13]
	v_mfma_f32_16x16x32_bf16 v[6:9], v[196:199], v[164:167], v[6:9]
	v_mfma_f32_16x16x32_bf16 v[34:37], v[176:179], v[160:163], v[34:37]
	v_mfma_f32_16x16x32_bf16 v[30:33], v[176:179], v[168:171], v[30:33]
	v_mfma_f32_16x16x32_bf16 v[26:29], v[184:187], v[160:163], v[26:29]
	v_mfma_f32_16x16x32_bf16 v[22:25], v[184:187], v[168:171], v[22:25]
	v_mfma_f32_16x16x32_bf16 v[18:21], v[192:195], v[160:163], v[18:21]
	v_mfma_f32_16x16x32_bf16 v[14:17], v[192:195], v[168:171], v[14:17]
	v_mfma_f32_16x16x32_bf16 v[10:13], v[200:203], v[160:163], v[10:13]
	v_mfma_f32_16x16x32_bf16 v[6:9], v[200:203], v[168:171], v[6:9]
	v_mfma_f32_16x16x32_bf16 v[2:5], v[172:175], v[206:209], v[2:5]
	v_mfma_f32_16x16x32_bf16 v[58:61], v[172:175], v[214:217], v[58:61]
	v_mfma_f32_16x16x32_bf16 v[62:65], v[180:183], v[206:209], v[62:65]
	v_mfma_f32_16x16x32_bf16 v[70:73], v[180:183], v[214:217], v[70:73]
	v_mfma_f32_16x16x32_bf16 v[74:77], v[188:191], v[206:209], v[74:77]
	v_mfma_f32_16x16x32_bf16 v[78:81], v[188:191], v[214:217], v[78:81]
	v_mfma_f32_16x16x32_bf16 v[86:89], v[196:199], v[206:209], v[86:89]
	v_mfma_f32_16x16x32_bf16 v[90:93], v[196:199], v[214:217], v[90:93]
	v_mfma_f32_16x16x32_bf16 v[2:5], v[176:179], v[210:213], v[2:5]
	v_mfma_f32_16x16x32_bf16 v[58:61], v[176:179], v[218:221], v[58:61]
	v_mfma_f32_16x16x32_bf16 v[62:65], v[184:187], v[210:213], v[62:65]
	v_mfma_f32_16x16x32_bf16 v[70:73], v[184:187], v[218:221], v[70:73]
	v_mfma_f32_16x16x32_bf16 v[74:77], v[192:195], v[210:213], v[74:77]
	v_mfma_f32_16x16x32_bf16 v[78:81], v[192:195], v[218:221], v[78:81]
	v_mfma_f32_16x16x32_bf16 v[86:89], v[200:203], v[210:213], v[86:89]
	v_mfma_f32_16x16x32_bf16 v[90:93], v[200:203], v[218:221], v[90:93]
	s_barrier
	ds_read_b128 v[156:159], v137
	ds_read_b128 v[160:163], v137 offset:1024
	ds_read_b128 v[164:167], v137 offset:2048
	ds_read_b128 v[168:171], v137 offset:3072
	ds_read_b128 v[172:175], v132 offset:32768
	ds_read_b128 v[176:179], v132 offset:33792
	ds_read_b128 v[180:183], v150 offset:32768
	ds_read_b128 v[184:187], v150 offset:33792
	ds_read_b128 v[188:191], v151 offset:32768
	ds_read_b128 v[192:195], v151 offset:33792
	ds_read_b128 v[196:199], v152 offset:32768
	ds_read_b128 v[200:203], v152 offset:33792
	ds_read_b128 v[206:209], v133
	ds_read_b128 v[210:213], v133 offset:1024
	ds_read_b128 v[214:217], v133 offset:2048
	ds_read_b128 v[218:221], v133 offset:3072
	v_lshl_add_u64 v[224:225], s[18:19], 0, v[0:1]
	s_mov_b64 s[22:23], 0x1e6c0100
	v_lshl_add_u64 v[222:223], v[224:225], 0, s[22:23]
	v_readfirstlane_b32 s22, v139
	s_mov_b32 m0, s22
	s_nop 0
	global_load_lds_dwordx4 v[222:223], off
	v_lshl_add_u64 v[224:225], s[18:19], 0, v[0:1]
	s_mov_b64 s[22:23], 0x1e6e0100
	v_lshl_add_u64 v[222:223], v[224:225], 0, s[22:23]
	v_readfirstlane_b32 s22, v140
	s_mov_b32 m0, s22
	s_nop 0
	global_load_lds_dwordx4 v[222:223], off
	s_waitcnt vmcnt(8)
	s_waitcnt lgkmcnt(0)
	s_barrier
	v_mfma_f32_16x16x32_bf16 v[126:129], v[172:175], v[156:159], v[126:129]
	v_mfma_f32_16x16x32_bf16 v[122:125], v[172:175], v[164:167], v[122:125]
	v_mfma_f32_16x16x32_bf16 v[118:121], v[180:183], v[156:159], v[118:121]
	v_mfma_f32_16x16x32_bf16 v[114:117], v[180:183], v[164:167], v[114:117]
	v_mfma_f32_16x16x32_bf16 v[110:113], v[188:191], v[156:159], v[110:113]
	v_mfma_f32_16x16x32_bf16 v[106:109], v[188:191], v[164:167], v[106:109]
	v_mfma_f32_16x16x32_bf16 v[102:105], v[196:199], v[156:159], v[102:105]
	v_mfma_f32_16x16x32_bf16 v[98:101], v[196:199], v[164:167], v[98:101]
	v_mfma_f32_16x16x32_bf16 v[126:129], v[176:179], v[160:163], v[126:129]
	v_mfma_f32_16x16x32_bf16 v[122:125], v[176:179], v[168:171], v[122:125]
	v_mfma_f32_16x16x32_bf16 v[118:121], v[184:187], v[160:163], v[118:121]
	v_mfma_f32_16x16x32_bf16 v[114:117], v[184:187], v[168:171], v[114:117]
	v_mfma_f32_16x16x32_bf16 v[110:113], v[192:195], v[160:163], v[110:113]
	v_mfma_f32_16x16x32_bf16 v[106:109], v[192:195], v[168:171], v[106:109]
	v_mfma_f32_16x16x32_bf16 v[102:105], v[200:203], v[160:163], v[102:105]
	v_mfma_f32_16x16x32_bf16 v[98:101], v[200:203], v[168:171], v[98:101]
	v_mfma_f32_16x16x32_bf16 v[94:97], v[172:175], v[206:209], v[94:97]
	v_mfma_f32_16x16x32_bf16 v[82:85], v[172:175], v[214:217], v[82:85]
	v_mfma_f32_16x16x32_bf16 v[66:69], v[180:183], v[206:209], v[66:69]
	v_mfma_f32_16x16x32_bf16 v[54:57], v[180:183], v[214:217], v[54:57]
	v_mfma_f32_16x16x32_bf16 v[50:53], v[188:191], v[206:209], v[50:53]
	v_mfma_f32_16x16x32_bf16 v[46:49], v[188:191], v[214:217], v[46:49]
	v_mfma_f32_16x16x32_bf16 v[42:45], v[196:199], v[206:209], v[42:45]
	v_mfma_f32_16x16x32_bf16 v[38:41], v[196:199], v[214:217], v[38:41]
	v_mfma_f32_16x16x32_bf16 v[94:97], v[176:179], v[210:213], v[94:97]
	v_mfma_f32_16x16x32_bf16 v[82:85], v[176:179], v[218:221], v[82:85]
	v_mfma_f32_16x16x32_bf16 v[66:69], v[184:187], v[210:213], v[66:69]
	v_mfma_f32_16x16x32_bf16 v[54:57], v[184:187], v[218:221], v[54:57]
	v_mfma_f32_16x16x32_bf16 v[50:53], v[192:195], v[210:213], v[50:53]
	v_mfma_f32_16x16x32_bf16 v[46:49], v[192:195], v[218:221], v[46:49]
	v_mfma_f32_16x16x32_bf16 v[42:45], v[200:203], v[210:213], v[42:45]
	v_mfma_f32_16x16x32_bf16 v[38:41], v[200:203], v[218:221], v[38:41]
	s_barrier
; #define STAGE_A(P, br, kt) do { const char* _g = (const char*)(A + (long)(br) * lda + (long)(kt) * BK); \
;     __builtin_amdgcn_global_load_lds((const unsigned*)(_g + (size_t)offA0), (unsigned*)((char*)(P) + sb0), 16, 0, 0); \
;     __builtin_amdgcn_global_load_lds((const unsigned*)(_g + (size_t)lda * 128 + (size_t)offA0), (unsigned*)((char*)(P) + sb1), 16, 0, 0); } while (0)
; #define STAGE_B(P, br, kt) do { const char* _g = (const char*)(B + (long)(br) * ldb + (long)(kt) * BK); \
;     __builtin_amdgcn_global_load_lds((const unsigned*)(_g + (size_t)offB0), (unsigned*)((char*)(P) + sb0), 16, 0, 0); \
;     __builtin_amdgcn_global_load_lds((const unsigned*)(_g + (size_t)ldb * 128 + (size_t)offB0), (unsigned*)((char*)(P) + sb1), 16, 0, 0); } while (0)
; #define LDA(dst, b, h) for (int m = 0; m < 4; ++m) for (int k = 0; k < 2; ++k) \
;     dst[m][k] = *reinterpret_cast<const bf16x8*>((char*)SA(b, h) + lds_byte(wr * 64 + m * 16 + fr, k * 32 + fq * 8))
; #define LDB(dst, b, h) for (int n = 0; n < 2; ++n) for (int k = 0; k < 2; ++k) \
;     dst[n][k] = *reinterpret_cast<const bf16x8*>((char*)SB(b, h) + lds_byte(wc * 32 + n * 16 + fr, k * 32 + fq * 8))
; #define MMA(ai, bj, At_, Bt_) do { __builtin_amdgcn_s_setprio(1); \
;     for (int m = 0; m < 4; ++m) for (int n = 0; n < 2; ++n) for (int k = 0; k < 2; ++k) \
;       acc[ai][bj][m][n] = MFMA16(At_[m][k], Bt_[n][k], acc[ai][bj][m][n]); \
;     __builtin_amdgcn_s_setprio(0); } while (0)
; #define WAIT_V(n) asm volatile("s_waitcnt vmcnt(" #n ")" ::: "memory")
; #define WAIT_L(n) asm volatile("s_waitcnt lgkmcnt(" #n ")" ::: "memory")
; #define BAR __builtin_amdgcn_s_barrier()
; #define SCHED __builtin_amdgcn_sched_barrier(0)
; DI void gemm_core(WVP char* smem, const u16* __restrict__ A, int lda, int ar0, int ar1,
;                   const u16* __restrict__ B, int ldb, int bc0, int K, AccT& acc) {
;     ...
;     LDA(At, 1, 1); STAGE_A(SA(1, 0), ac0, t + 3);
;     BAR; WAIT_L(0); MMA(1, 0, At, B0); BAR; SCHED;
;     STAGE_B(SB(1, 1), bb1, t + 3);
;     WAIT_V(6); BAR; MMA(1, 1, At, B1); BAR;
;   }
;   { LDB(B0, 0, 0); LDA(At, 0, 0); STAGE_A(SA(1, 1), ac1, nt - 1);
;     BAR; WAIT_L(0); MMA(0, 0, At, B0); BAR;
	ds_read_b128 v[172:175], v132 offset:49152
	ds_read_b128 v[176:179], v132 offset:50176
	ds_read_b128 v[180:183], v150 offset:49152
	ds_read_b128 v[184:187], v150 offset:50176
	ds_read_b128 v[188:191], v151 offset:49152
	ds_read_b128 v[192:195], v151 offset:50176
	ds_read_b128 v[196:199], v152 offset:49152
	ds_read_b128 v[200:203], v152 offset:50176
	v_lshl_add_u64 v[224:225], s[8:9], 0, v[0:1]
	s_mov_b64 s[22:23], 0x19000180
	v_lshl_add_u64 v[222:223], v[224:225], 0, s[22:23]
	v_readfirstlane_b32 s22, v141
	s_mov_b32 m0, s22
	s_nop 0
	global_load_lds_dwordx4 v[222:223], off
	v_lshl_add_u64 v[224:225], s[8:9], 0, v[0:1]
	s_mov_b64 s[22:23], 0x19020180
	v_lshl_add_u64 v[222:223], v[224:225], 0, s[22:23]
	v_readfirstlane_b32 s22, v142
	s_mov_b32 m0, s22
	s_nop 0
	global_load_lds_dwordx4 v[222:223], off
	v_lshl_add_u64 v[224:225], s[18:19], 0, v[0:1]
	s_mov_b64 s[22:23], 0x1e680180
	v_lshl_add_u64 v[222:223], v[224:225], 0, s[22:23]
	v_readfirstlane_b32 s22, v143
	s_mov_b32 m0, s22
	s_nop 0
	global_load_lds_dwordx4 v[222:223], off
	v_lshl_add_u64 v[224:225], s[18:19], 0, v[0:1]
	s_mov_b64 s[22:23], 0x1e6a0180
	v_lshl_add_u64 v[222:223], v[224:225], 0, s[22:23]
	v_readfirstlane_b32 s22, v144
	s_mov_b32 m0, s22
	s_nop 0
	global_load_lds_dwordx4 v[222:223], off
	v_lshl_add_u64 v[224:225], s[8:9], 0, v[0:1]
	s_mov_b64 s[22:23], 0x19040180
	v_lshl_add_u64 v[222:223], v[224:225], 0, s[22:23]
	v_readfirstlane_b32 s22, v145
	s_mov_b32 m0, s22
	s_nop 0
	global_load_lds_dwordx4 v[222:223], off
	v_lshl_add_u64 v[224:225], s[8:9], 0, v[0:1]
	s_mov_b64 s[22:23], 0x19060180
	v_lshl_add_u64 v[222:223], v[224:225], 0, s[22:23]
	v_readfirstlane_b32 s22, v147
	s_mov_b32 m0, s22
	s_nop 0
	global_load_lds_dwordx4 v[222:223], off
	s_waitcnt vmcnt(8)
	s_waitcnt lgkmcnt(0)
	s_barrier
	v_mfma_f32_16x16x32_bf16 v[34:37], v[172:175], v[156:159], v[34:37]
	v_mfma_f32_16x16x32_bf16 v[30:33], v[172:175], v[164:167], v[30:33]
	v_mfma_f32_16x16x32_bf16 v[26:29], v[180:183], v[156:159], v[26:29]
	v_mfma_f32_16x16x32_bf16 v[22:25], v[180:183], v[164:167], v[22:25]
	v_mfma_f32_16x16x32_bf16 v[18:21], v[188:191], v[156:159], v[18:21]
	v_mfma_f32_16x16x32_bf16 v[14:17], v[188:191], v[164:167], v[14:17]
	v_mfma_f32_16x16x32_bf16 v[10:13], v[196:199], v[156:159], v[10:13]
	v_mfma_f32_16x16x32_bf16 v[6:9], v[196:199], v[164:167], v[6:9]
	v_mfma_f32_16x16x32_bf16 v[34:37], v[176:179], v[160:163], v[34:37]
	v_mfma_f32_16x16x32_bf16 v[30:33], v[176:179], v[168:171], v[30:33]
	v_mfma_f32_16x16x32_bf16 v[26:29], v[184:187], v[160:163], v[26:29]
	v_mfma_f32_16x16x32_bf16 v[22:25], v[184:187], v[168:171], v[22:25]
	v_mfma_f32_16x16x32_bf16 v[18:21], v[192:195], v[160:163], v[18:21]
	v_mfma_f32_16x16x32_bf16 v[14:17], v[192:195], v[168:171], v[14:17]
	v_mfma_f32_16x16x32_bf16 v[10:13], v[200:203], v[160:163], v[10:13]
	v_mfma_f32_16x16x32_bf16 v[6:9], v[200:203], v[168:171], v[6:9]
	v_mfma_f32_16x16x32_bf16 v[2:5], v[172:175], v[206:209], v[2:5]
	v_mfma_f32_16x16x32_bf16 v[58:61], v[172:175], v[214:217], v[58:61]
	v_mfma_f32_16x16x32_bf16 v[62:65], v[180:183], v[206:209], v[62:65]
	v_mfma_f32_16x16x32_bf16 v[70:73], v[180:183], v[214:217], v[70:73]
	v_mfma_f32_16x16x32_bf16 v[74:77], v[188:191], v[206:209], v[74:77]
	v_mfma_f32_16x16x32_bf16 v[78:81], v[188:191], v[214:217], v[78:81]
	v_mfma_f32_16x16x32_bf16 v[86:89], v[196:199], v[206:209], v[86:89]
	v_mfma_f32_16x16x32_bf16 v[90:93], v[196:199], v[214:217], v[90:93]
	v_mfma_f32_16x16x32_bf16 v[2:5], v[176:179], v[210:213], v[2:5]
	v_mfma_f32_16x16x32_bf16 v[58:61], v[176:179], v[218:221], v[58:61]
	v_mfma_f32_16x16x32_bf16 v[62:65], v[184:187], v[210:213], v[62:65]
	v_mfma_f32_16x16x32_bf16 v[70:73], v[184:187], v[218:221], v[70:73]
	v_mfma_f32_16x16x32_bf16 v[74:77], v[192:195], v[210:213], v[74:77]
	v_mfma_f32_16x16x32_bf16 v[78:81], v[192:195], v[218:221], v[78:81]
	v_mfma_f32_16x16x32_bf16 v[86:89], v[200:203], v[210:213], v[86:89]
	v_mfma_f32_16x16x32_bf16 v[90:93], v[200:203], v[218:221], v[90:93]
	s_add_i32 s21, s21, 2
	s_add_u32 s8, s8, 0x100
	s_addc_u32 s9, s9, 0
	s_add_u32 s18, s18, 0x100
	s_addc_u32 s19, s19, 0
	s_cmp_lt_u32 s21, 12
	s_barrier
	s_cbranch_scc1 .LBB0_187
	s_mov_b64 s[0:1], 0x780
	v_lshl_add_u64 v[134:135], v[130:131], 0, s[0:1]
	v_readfirstlane_b32 s0, v153
	s_mov_b32 m0, s0
	s_mov_b64 s[0:1], 0x20780
	v_lshl_add_u64 v[130:131], v[130:131], 0, s[0:1]
	v_readfirstlane_b32 s0, v154
	ds_read_b128 v[138:141], v149
	ds_read_b128 v[142:145], v149 offset:1024
	ds_read_b128 v[156:159], v149 offset:2048
	ds_read_b128 v[160:163], v149 offset:3072
	ds_read_b128 v[164:167], v132
	ds_read_b128 v[168:171], v132 offset:1024
	ds_read_b128 v[172:175], v150
	ds_read_b128 v[176:179], v150 offset:1024
	ds_read_b128 v[180:183], v151
	ds_read_b128 v[184:187], v151 offset:1024
	ds_read_b128 v[188:191], v152
	ds_read_b128 v[192:195], v152 offset:1024
	global_load_lds_dwordx4 v[134:135], off
	s_mov_b32 m0, s0
	s_nop 0
	global_load_lds_dwordx4 v[130:131], off
	s_waitcnt vmcnt(8)
	s_barrier
	s_waitcnt lgkmcnt(0)
	s_setprio 1
	s_waitcnt lgkmcnt(0)
	v_mfma_f32_16x16x32_bf16 v[126:129], v[164:167], v[138:141], v[126:129]
	v_mfma_f32_16x16x32_bf16 v[122:125], v[164:167], v[156:159], v[122:125]
	v_mfma_f32_16x16x32_bf16 v[118:121], v[172:175], v[138:141], v[118:121]
	v_mfma_f32_16x16x32_bf16 v[114:117], v[172:175], v[156:159], v[114:117]
	v_mfma_f32_16x16x32_bf16 v[106:109], v[180:183], v[156:159], v[106:109]
	v_mfma_f32_16x16x32_bf16 v[126:129], v[168:171], v[142:145], v[126:129]
	v_mfma_f32_16x16x32_bf16 v[122:125], v[168:171], v[160:163], v[122:125]
	v_mfma_f32_16x16x32_bf16 v[118:121], v[176:179], v[142:145], v[118:121]
	v_mfma_f32_16x16x32_bf16 v[114:117], v[176:179], v[160:163], v[114:117]
	v_mfma_f32_16x16x32_bf16 v[110:113], v[180:183], v[138:141], v[110:113]
	v_mfma_f32_16x16x32_bf16 v[106:109], v[184:187], v[160:163], v[106:109]
	v_mfma_f32_16x16x32_bf16 v[102:105], v[188:191], v[138:141], v[102:105]
	v_mfma_f32_16x16x32_bf16 v[98:101], v[188:191], v[156:159], v[98:101]
	v_mfma_f32_16x16x32_bf16 v[196:199], v[184:187], v[142:145], v[110:113]
	v_mfma_f32_16x16x32_bf16 v[200:203], v[192:195], v[142:145], v[102:105]
	v_mfma_f32_16x16x32_bf16 v[206:209], v[192:195], v[160:163], v[98:101]
	s_setprio 0
	s_barrier
; #define LDA(dst, b, h) for (int m = 0; m < 4; ++m) for (int k = 0; k < 2; ++k) \
;     dst[m][k] = *reinterpret_cast<const bf16x8*>((char*)SA(b, h) + lds_byte(wr * 64 + m * 16 + fr, k * 32 + fq * 8))
; #define LDB(dst, b, h) for (int n = 0; n < 2; ++n) for (int k = 0; k < 2; ++k) \
;     dst[n][k] = *reinterpret_cast<const bf16x8*>((char*)SB(b, h) + lds_byte(wc * 32 + n * 16 + fr, k * 32 + fq * 8))
; #define MMA(ai, bj, At_, Bt_) do { __builtin_amdgcn_s_setprio(1); \
;     for (int m = 0; m < 4; ++m) for (int n = 0; n < 2; ++n) for (int k = 0; k < 2; ++k) \
;       acc[ai][bj][m][n] = MFMA16(At_[m][k], Bt_[n][k], acc[ai][bj][m][n]); \
;     __builtin_amdgcn_s_setprio(0); } while (0)
; #define WAIT_V(n) asm volatile("s_waitcnt vmcnt(" #n ")" ::: "memory")
; #define WAIT_L(n) asm volatile("s_waitcnt lgkmcnt(" #n ")" ::: "memory")
; #define BAR __builtin_amdgcn_s_barrier()
; DI void gemm_core(WVP char* smem, const u16* __restrict__ A, int lda, int ar0, int ar1,
;                   const u16* __restrict__ B, int ldb, int bc0, int K, AccT& acc) {
;     ...
;     LDB(B1, 0, 1); BAR; WAIT_L(0); MMA(0, 1, At, B1); BAR;
;     LDA(At, 0, 1); WAIT_V(4); BAR; WAIT_L(0); MMA(1, 0, At, B0); MMA(1, 1, At, B1); BAR; }
;   { LDB(B0, 1, 0); LDA(At, 1, 0); WAIT_V(2); BAR; WAIT_L(0); MMA(0, 0, At, B0); BAR;
	s_nop 2
	ds_read_b128 v[98:101], v146
	ds_read_b128 v[102:105], v146 offset:1024
	ds_read_b128 v[110:113], v146 offset:2048
	ds_read_b128 v[146:149], v146 offset:3072
	s_barrier
	s_waitcnt lgkmcnt(0)
	s_setprio 1
	s_waitcnt lgkmcnt(0)
	v_mfma_f32_16x16x32_bf16 v[94:97], v[164:167], v[98:101], v[94:97]
	v_mfma_f32_16x16x32_bf16 v[82:85], v[164:167], v[110:113], v[82:85]
	v_mfma_f32_16x16x32_bf16 v[54:57], v[172:175], v[110:113], v[54:57]
	v_mfma_f32_16x16x32_bf16 v[46:49], v[180:183], v[110:113], v[46:49]
	v_mfma_f32_16x16x32_bf16 v[38:41], v[188:191], v[110:113], v[38:41]
	v_mfma_f32_16x16x32_bf16 v[94:97], v[168:171], v[102:105], v[94:97]
	v_mfma_f32_16x16x32_bf16 v[82:85], v[168:171], v[146:149], v[82:85]
	v_mfma_f32_16x16x32_bf16 v[66:69], v[172:175], v[98:101], v[66:69]
	v_mfma_f32_16x16x32_bf16 v[54:57], v[176:179], v[146:149], v[54:57]
	v_mfma_f32_16x16x32_bf16 v[50:53], v[180:183], v[98:101], v[50:53]
	v_mfma_f32_16x16x32_bf16 v[46:49], v[184:187], v[146:149], v[46:49]
	v_mfma_f32_16x16x32_bf16 v[42:45], v[188:191], v[98:101], v[42:45]
	v_mfma_f32_16x16x32_bf16 v[38:41], v[192:195], v[146:149], v[38:41]
	v_mfma_f32_16x16x32_bf16 v[164:167], v[176:179], v[102:105], v[66:69]
	v_mfma_f32_16x16x32_bf16 v[168:171], v[184:187], v[102:105], v[50:53]
	v_mfma_f32_16x16x32_bf16 v[172:175], v[192:195], v[102:105], v[42:45]
	s_setprio 0
	s_barrier
	s_nop 1
	ds_read_b128 v[42:45], v132 offset:16384
	ds_read_b128 v[50:53], v132 offset:17408
	ds_read_b128 v[66:69], v150 offset:16384
	ds_read_b128 v[176:179], v150 offset:17408
	ds_read_b128 v[180:183], v151 offset:16384
	ds_read_b128 v[184:187], v151 offset:17408
	ds_read_b128 v[188:191], v152 offset:16384
	ds_read_b128 v[192:195], v152 offset:17408
	s_waitcnt vmcnt(4)
	s_barrier
	s_waitcnt lgkmcnt(0)
	s_setprio 1
	s_waitcnt lgkmcnt(0)
	v_mfma_f32_16x16x32_bf16 v[30:33], v[42:45], v[156:159], v[30:33]
	v_mfma_f32_16x16x32_bf16 v[26:29], v[66:69], v[138:141], v[26:29]
	v_mfma_f32_16x16x32_bf16 v[14:17], v[180:183], v[156:159], v[14:17]
	v_mfma_f32_16x16x32_bf16 v[6:9], v[188:191], v[156:159], v[6:9]
	v_mfma_f32_16x16x32_bf16 v[34:37], v[42:45], v[138:141], v[34:37]
	v_mfma_f32_16x16x32_bf16 v[30:33], v[50:53], v[160:163], v[30:33]
	v_mfma_f32_16x16x32_bf16 v[26:29], v[176:179], v[142:145], v[26:29]
	v_mfma_f32_16x16x32_bf16 v[22:25], v[66:69], v[156:159], v[22:25]
	v_mfma_f32_16x16x32_bf16 v[18:21], v[180:183], v[138:141], v[18:21]
	v_mfma_f32_16x16x32_bf16 v[14:17], v[184:187], v[160:163], v[14:17]
	v_mfma_f32_16x16x32_bf16 v[10:13], v[188:191], v[138:141], v[10:13]
	v_mfma_f32_16x16x32_bf16 v[6:9], v[192:195], v[160:163], v[6:9]
	v_mfma_f32_16x16x32_bf16 v[210:213], v[50:53], v[142:145], v[34:37]
	v_mfma_f32_16x16x32_bf16 v[214:217], v[176:179], v[160:163], v[22:25]
	v_mfma_f32_16x16x32_bf16 v[218:221], v[184:187], v[142:145], v[18:21]
	v_mfma_f32_16x16x32_bf16 v[138:141], v[192:195], v[142:145], v[10:13]
	s_setprio 0
	s_setprio 1
	v_mfma_f32_16x16x32_bf16 v[2:5], v[42:45], v[98:101], v[2:5]
	v_mfma_f32_16x16x32_bf16 v[142:145], v[50:53], v[102:105], v[2:5]
	v_mfma_f32_16x16x32_bf16 v[2:5], v[42:45], v[110:113], v[58:61]
	v_mfma_f32_16x16x32_bf16 v[154:157], v[50:53], v[146:149], v[2:5]
	v_mfma_f32_16x16x32_bf16 v[2:5], v[66:69], v[98:101], v[62:65]
	v_mfma_f32_16x16x32_bf16 v[158:161], v[176:179], v[102:105], v[2:5]
	v_mfma_f32_16x16x32_bf16 v[2:5], v[66:69], v[110:113], v[70:73]
	v_mfma_f32_16x16x32_bf16 v[176:179], v[176:179], v[146:149], v[2:5]
	v_mfma_f32_16x16x32_bf16 v[2:5], v[180:183], v[98:101], v[74:77]
	v_mfma_f32_16x16x32_bf16 v[222:225], v[184:187], v[102:105], v[2:5]
	v_mfma_f32_16x16x32_bf16 v[2:5], v[180:183], v[110:113], v[78:81]
	v_mfma_f32_16x16x32_bf16 v[180:183], v[184:187], v[146:149], v[2:5]
	v_mfma_f32_16x16x32_bf16 v[2:5], v[188:191], v[98:101], v[86:89]
	v_mfma_f32_16x16x32_bf16 v[184:187], v[192:195], v[102:105], v[2:5]
	v_mfma_f32_16x16x32_bf16 v[2:5], v[188:191], v[110:113], v[90:93]
	v_mfma_f32_16x16x32_bf16 v[146:149], v[192:195], v[146:149], v[2:5]
	s_setprio 0
	s_barrier
	ds_read_b128 v[62:65], v137
	ds_read_b128 v[74:77], v137 offset:1024
	ds_read_b128 v[86:89], v137 offset:2048
	ds_read_b128 v[134:137], v137 offset:3072
	s_nop 0
	ds_read_b128 v[2:5], v132 offset:32768
	ds_read_b128 v[10:13], v132 offset:33792
	ds_read_b128 v[18:21], v150 offset:32768
	ds_read_b128 v[22:25], v150 offset:33792
	ds_read_b128 v[188:191], v151 offset:32768
	ds_read_b128 v[192:195], v151 offset:33792
	ds_read_b128 v[226:229], v152 offset:32768
	ds_read_b128 v[230:233], v152 offset:33792
	s_waitcnt vmcnt(2)
	s_barrier
; #define LDA(dst, b, h) for (int m = 0; m < 4; ++m) for (int k = 0; k < 2; ++k) \
;     dst[m][k] = *reinterpret_cast<const bf16x8*>((char*)SA(b, h) + lds_byte(wr * 64 + m * 16 + fr, k * 32 + fq * 8))
; #define LDB(dst, b, h) for (int n = 0; n < 2; ++n) for (int k = 0; k < 2; ++k) \
;     dst[n][k] = *reinterpret_cast<const bf16x8*>((char*)SB(b, h) + lds_byte(wc * 32 + n * 16 + fr, k * 32 + fq * 8))
; #define MMA(ai, bj, At_, Bt_) do { __builtin_amdgcn_s_setprio(1); \
;     for (int m = 0; m < 4; ++m) for (int n = 0; n < 2; ++n) for (int k = 0; k < 2; ++k) \
;       acc[ai][bj][m][n] = MFMA16(At_[m][k], Bt_[n][k], acc[ai][bj][m][n]); \
;     __builtin_amdgcn_s_setprio(0); } while (0)
; #define WAIT_V(n) asm volatile("s_waitcnt vmcnt(" #n ")" ::: "memory")
; #define WAIT_L(n) asm volatile("s_waitcnt lgkmcnt(" #n ")" ::: "memory")
; #define BAR __builtin_amdgcn_s_barrier()
; DI void gemm_core(WVP char* smem, const u16* __restrict__ A, int lda, int ar0, int ar1,
;                   const u16* __restrict__ B, int ldb, int bc0, int K, AccT& acc) {
;     ...
;   { LDB(B0, 1, 0); LDA(At, 1, 0); WAIT_V(2); BAR; WAIT_L(0); MMA(0, 0, At, B0); BAR;
;     LDB(B1, 1, 1); WAIT_V(0); BAR; WAIT_L(0); MMA(0, 1, At, B1); BAR;
;     LDA(At, 1, 1); BAR; WAIT_L(0); MMA(1, 0, At, B0); MMA(1, 1, At, B1); BAR; }
;   if (wr == 0) BAR;
	s_waitcnt lgkmcnt(0)
	s_setprio 1
	s_waitcnt lgkmcnt(0)
	v_mfma_f32_16x16x32_bf16 v[34:37], v[2:5], v[62:65], v[126:129]
	v_mfma_f32_16x16x32_bf16 v[98:101], v[10:13], v[74:77], v[34:37]
	v_mfma_f32_16x16x32_bf16 v[34:37], v[2:5], v[86:89], v[122:125]
	v_mfma_f32_16x16x32_bf16 v[122:125], v[10:13], v[134:137], v[34:37]
	v_mfma_f32_16x16x32_bf16 v[34:37], v[18:21], v[62:65], v[118:121]
	v_mfma_f32_16x16x32_bf16 v[110:113], v[22:25], v[74:77], v[34:37]
	v_mfma_f32_16x16x32_bf16 v[34:37], v[18:21], v[86:89], v[114:117]
	v_mfma_f32_16x16x32_bf16 v[102:105], v[22:25], v[134:137], v[34:37]
	v_mfma_f32_16x16x32_bf16 v[34:37], v[188:191], v[62:65], v[196:199]
	v_mfma_f32_16x16x32_bf16 v[78:81], v[192:195], v[74:77], v[34:37]
	v_mfma_f32_16x16x32_bf16 v[34:37], v[188:191], v[86:89], v[106:109]
	v_mfma_f32_16x16x32_bf16 v[90:93], v[192:195], v[134:137], v[34:37]
	v_mfma_f32_16x16x32_bf16 v[34:37], v[226:229], v[62:65], v[200:203]
	v_mfma_f32_16x16x32_bf16 v[66:69], v[230:233], v[74:77], v[34:37]
	v_mfma_f32_16x16x32_bf16 v[34:37], v[226:229], v[86:89], v[206:209]
	v_mfma_f32_16x16x32_bf16 v[70:73], v[230:233], v[134:137], v[34:37]
	s_setprio 0
	s_barrier
	ds_read_b128 v[196:199], v133
	ds_read_b128 v[200:203], v133 offset:1024
	ds_read_b128 v[206:209], v133 offset:2048
	ds_read_b128 v[234:237], v133 offset:3072
	s_waitcnt vmcnt(0)
	s_barrier
	s_waitcnt lgkmcnt(0)
	s_setprio 1
	s_waitcnt lgkmcnt(0)
	v_mfma_f32_16x16x32_bf16 v[34:37], v[2:5], v[196:199], v[94:97]
	v_mfma_f32_16x16x32_bf16 v[2:5], v[2:5], v[206:209], v[82:85]
	v_mfma_f32_16x16x32_bf16 v[58:61], v[10:13], v[234:237], v[2:5]
	v_mfma_f32_16x16x32_bf16 v[2:5], v[18:21], v[196:199], v[164:167]
	v_mfma_f32_16x16x32_bf16 v[42:45], v[22:25], v[200:203], v[2:5]
	v_mfma_f32_16x16x32_bf16 v[2:5], v[18:21], v[206:209], v[54:57]
	v_mfma_f32_16x16x32_bf16 v[50:53], v[10:13], v[200:203], v[34:37]
	v_mfma_f32_16x16x32_bf16 v[34:37], v[22:25], v[234:237], v[2:5]
	v_mfma_f32_16x16x32_bf16 v[2:5], v[188:191], v[196:199], v[168:171]
	v_mfma_f32_16x16x32_bf16 v[18:21], v[192:195], v[200:203], v[2:5]
	v_mfma_f32_16x16x32_bf16 v[2:5], v[188:191], v[206:209], v[46:49]
	v_mfma_f32_16x16x32_bf16 v[22:25], v[192:195], v[234:237], v[2:5]
	v_mfma_f32_16x16x32_bf16 v[2:5], v[226:229], v[196:199], v[172:175]
	v_mfma_f32_16x16x32_bf16 v[10:13], v[230:233], v[200:203], v[2:5]
	v_mfma_f32_16x16x32_bf16 v[2:5], v[226:229], v[206:209], v[38:41]
	v_mfma_f32_16x16x32_bf16 v[2:5], v[230:233], v[234:237], v[2:5]
	s_setprio 0
	s_barrier
	ds_read_b128 v[38:41], v132 offset:49152
	ds_read_b128 v[46:49], v132 offset:50176
	ds_read_b128 v[130:133], v150 offset:49152
	ds_read_b128 v[162:165], v150 offset:50176
	ds_read_b128 v[166:169], v151 offset:49152
	ds_read_b128 v[170:173], v151 offset:50176
	ds_read_b128 v[188:191], v152 offset:49152
	ds_read_b128 v[150:153], v152 offset:50176
	s_barrier
	s_waitcnt lgkmcnt(0)
	s_setprio 1
	s_waitcnt lgkmcnt(0)
	v_mfma_f32_16x16x32_bf16 v[26:29], v[130:133], v[62:65], v[26:29]
	v_mfma_f32_16x16x32_bf16 v[114:117], v[162:165], v[74:77], v[26:29]
	v_mfma_f32_16x16x32_bf16 v[26:29], v[130:133], v[86:89], v[214:217]
	v_mfma_f32_16x16x32_bf16 v[14:17], v[166:169], v[86:89], v[14:17]
	v_mfma_f32_16x16x32_bf16 v[54:57], v[38:41], v[62:65], v[210:213]
	v_mfma_f32_16x16x32_bf16 v[30:33], v[38:41], v[86:89], v[30:33]
	v_mfma_f32_16x16x32_bf16 v[118:121], v[162:165], v[134:137], v[26:29]
	v_mfma_f32_16x16x32_bf16 v[26:29], v[166:169], v[62:65], v[218:221]
	v_mfma_f32_16x16x32_bf16 v[94:97], v[170:173], v[134:137], v[14:17]
	v_mfma_f32_16x16x32_bf16 v[14:17], v[188:191], v[62:65], v[138:141]
	v_mfma_f32_16x16x32_bf16 v[6:9], v[188:191], v[86:89], v[6:9]
	v_mfma_f32_16x16x32_bf16 v[106:109], v[46:49], v[74:77], v[54:57]
	v_mfma_f32_16x16x32_bf16 v[126:129], v[46:49], v[134:137], v[30:33]
	v_mfma_f32_16x16x32_bf16 v[82:85], v[170:173], v[74:77], v[26:29]
	v_mfma_f32_16x16x32_bf16 v[74:77], v[150:153], v[74:77], v[14:17]
	v_mfma_f32_16x16x32_bf16 v[86:89], v[150:153], v[134:137], v[6:9]
	s_setprio 0
	s_setprio 1
	v_mfma_f32_16x16x32_bf16 v[6:9], v[38:41], v[196:199], v[142:145]
	v_mfma_f32_16x16x32_bf16 v[54:57], v[46:49], v[200:203], v[6:9]
	v_mfma_f32_16x16x32_bf16 v[6:9], v[38:41], v[206:209], v[154:157]
	v_mfma_f32_16x16x32_bf16 v[62:65], v[46:49], v[234:237], v[6:9]
	v_mfma_f32_16x16x32_bf16 v[6:9], v[130:133], v[196:199], v[158:161]
	v_mfma_f32_16x16x32_bf16 v[46:49], v[162:165], v[200:203], v[6:9]
	v_mfma_f32_16x16x32_bf16 v[6:9], v[130:133], v[206:209], v[176:179]
	v_mfma_f32_16x16x32_bf16 v[38:41], v[162:165], v[234:237], v[6:9]
	v_mfma_f32_16x16x32_bf16 v[6:9], v[166:169], v[196:199], v[222:225]
	v_mfma_f32_16x16x32_bf16 v[26:29], v[170:173], v[200:203], v[6:9]
	v_mfma_f32_16x16x32_bf16 v[6:9], v[166:169], v[206:209], v[180:183]
	v_mfma_f32_16x16x32_bf16 v[30:33], v[170:173], v[234:237], v[6:9]
	v_mfma_f32_16x16x32_bf16 v[6:9], v[188:191], v[196:199], v[184:187]
	v_mfma_f32_16x16x32_bf16 v[14:17], v[150:153], v[200:203], v[6:9]
	v_mfma_f32_16x16x32_bf16 v[6:9], v[188:191], v[206:209], v[146:149]
	v_mfma_f32_16x16x32_bf16 v[6:9], v[150:153], v[234:237], v[6:9]
	s_setprio 0
	s_cmp_gt_u32 s15, 3
	s_barrier
	s_cbranch_scc1 .LBB0_190
	s_barrier

; DI int get_tid(int wv) { int l; asm volatile("v_mbcnt_lo_u32_b32 %0, -1, 0\n\tv_mbcnt_hi_u32_b32 %0, -1, %0" : "=v"(l)); return wv * 64 + l; }
; DI int wave_of(int tid) { return __builtin_amdgcn_readfirstlane(tid >> 6); }
; #define STAGE_A(P, br, kt) do { const char* _g = (const char*)(A + (long)(br) * lda + (long)(kt) * BK); \
;     __builtin_amdgcn_global_load_lds((const unsigned*)(_g + (size_t)offA0), (unsigned*)((char*)(P) + sb0), 16, 0, 0); \
;     __builtin_amdgcn_global_load_lds((const unsigned*)(_g + (size_t)lda * 128 + (size_t)offA0), (unsigned*)((char*)(P) + sb1), 16, 0, 0); } while (0)
; #define STAGE_B(P, br, kt) do { const char* _g = (const char*)(B + (long)(br) * ldb + (long)(kt) * BK); \
;     __builtin_amdgcn_global_load_lds((const unsigned*)(_g + (size_t)offB0), (unsigned*)((char*)(P) + sb0), 16, 0, 0); \
;     __builtin_amdgcn_global_load_lds((const unsigned*)(_g + (size_t)ldb * 128 + (size_t)offB0), (unsigned*)((char*)(P) + sb1), 16, 0, 0); } while (0)
; #define BAR __builtin_amdgcn_s_barrier()
; DI void gemm_core(WVP char* smem, const u16* __restrict__ A, int lda, int ar0, int ar1,
;                   const u16* __restrict__ B, int ldb, int bc0, int K, AccT& acc) {
;     ...
;   const int tid = get_tid(WV);
;   const int wid = wave_of(tid), lane = tid & 63, wr = wid >> 2, wc = wid & 3, fr = lane & 15, fq = lane >> 4;
;   const int sb0 = tid * 16, sb1 = sb0 + 8192;
;   int R0, C0; stage_rc(sb0, R0, C0);
;   const unsigned offA0 = (unsigned)(R0 * lda + C0) * 2u, offB0 = (unsigned)(R0 * ldb + C0) * 2u;
;   const int ac0 = ar0, ac1 = ar1, bb0 = bc0, bb1 = bc0 + HALF;
;   bf16x8 At[4][2], B0[2][2], B1[2][2];
;   const int nt = K / BK;
;   __syncthreads();
;   STAGE_B(SB(0, 0), bb0, 0); STAGE_A(SA(0, 0), ac0, 0);
;   STAGE_B(SB(0, 1), bb1, 0); STAGE_A(SA(0, 1), ac1, 0);
;   if (wr == 1) BAR;
; __global__ void __launch_bounds__(NTHR) mega(Params p) {
;     ...
;           for (int b = 0; b < 4; ++b) {
;             const int q = pr * 3 + b;
;             u16* sd = (b == 3) ? mg + pr * 256 : proj + (q < 8 ? 768 + 256 * q : (q < 10 ? 256 * (q - 8) : 3840 + 256 * (q - 10)));
;             EpiSig E1{sd, b == 3 ? DM : INW, pc * 256};
;             gemm_tile(WV, smem, WG + (size_t)b * DM * DM, DM, pr * 256, pr * 256 + 128, xn, DM, pc * 256, DM, E1);
.LBB0_224:
	v_mbcnt_lo_u32_b32 v5, -1, 0
	v_mbcnt_hi_u32_b32 v5, -1, v5
	s_lshl_b32 s0, s21, 21
	v_add_u32_e32 v0, s3, v5
	v_ashrrev_i32_e32 v2, 31, v0
	v_lshrrev_b32_e32 v2, 26, v2
	v_readfirstlane_b32 s1, v0
	v_lshlrev_b32_e32 v8, 4, v0
	v_add_u32_e32 v2, v0, v2
	v_bfe_i32 v0, v0, 27, 1
	v_lshrrev_b32_e32 v0, 22, v0
	v_add_u32_e32 v0, v8, v0
	v_and_b32_e32 v0, 0xfffffc00, v0
	v_sub_u32_e32 v0, v8, v0
	v_ashrrev_i32_e32 v4, 6, v2
	v_lshrrev_b32_e32 v2, 4, v0
	v_bitop3_b32 v0, v2, v0, 32 bitop3:0x6c
	v_ashrrev_i32_e32 v3, 31, v0
	v_lshrrev_b32_e32 v3, 26, v3
	v_add_u32_e32 v3, v0, v3
	v_ashrrev_i32_e32 v6, 6, v3
	v_and_b32_e32 v3, 0xc0, v3
	v_sub_u32_e32 v0, v0, v3
	s_add_u32 s47, s5, s0
	v_lshlrev_b32_e32 v2, 3, v4
	v_lshlrev_b32_e32 v7, 5, v4
	v_ashrrev_i16_sdwa v0, v254, sext(v0) dst_sel:DWORD dst_unused:UNUSED_PAD src0_sel:DWORD src1_sel:BYTE_0
	s_addc_u32 s50, s50, 0
	v_and_b32_e32 v2, 0x1ffff0, v2
	v_and_b32_e32 v10, 32, v7
	v_bfe_i32 v7, v0, 0, 16
	s_add_i32 s5, 0, 0x10000
	v_add_u32_e32 v9, 0x2000, v8
	v_add_u32_e32 v0, v10, v7
	v_add_lshl_u32 v2, v6, v2, 11
	v_add_u32_e32 v134, s5, v8
	v_lshl_add_u32 v0, v0, 1, v2
	v_readfirstlane_b32 s52, v134
	v_add_u32_e32 v2, s5, v9
	s_ashr_i32 s0, s1, 8
	s_mov_b32 m0, s52
	v_readfirstlane_b32 s52, v2
	v_add_u32_e32 v136, 0, v8
	s_barrier
	global_load_lds_dwordx4 v0, s[22:23]
	s_mov_b32 m0, s52
	s_add_u32 s52, s47, s26
	v_readfirstlane_b32 s57, v136
	global_load_lds_dwordx4 v0, s[24:25]
	s_addc_u32 s53, s50, s27
	s_mov_b32 m0, s57
	v_add_u32_e32 v137, 0x2000, v136
	v_lshl_add_u64 v[2:3], s[52:53], 0, v[0:1]
	global_load_lds_dwordx4 v0, s[52:53]
	v_readfirstlane_b32 s52, v137
	v_add_u32_e32 v138, s60, v8
	v_lshl_add_u64 v[10:11], v[2:3], 0, s[76:77]
	s_mov_b32 m0, s52
	v_readfirstlane_b32 s52, v138
	v_add_u32_e32 v9, s60, v9
	global_load_lds_dwordx4 v[10:11], off
	s_mov_b32 m0, s52
	v_readfirstlane_b32 s52, v9
	global_load_lds_dwordx4 v0, s[28:29]
	s_mov_b32 m0, s52
	s_add_u32 s52, s47, s34
	v_add_u32_e32 v139, 0x4000, v136
	s_addc_u32 s53, s50, s35
	v_readfirstlane_b32 s47, v139
	v_add_u32_e32 v140, 0x6000, v136
	global_load_lds_dwordx4 v0, s[30:31]
	v_lshl_add_u64 v[130:131], s[52:53], 0, v[0:1]
	s_mov_b32 m0, s47
	v_readfirstlane_b32 s47, v140
	global_load_lds_dwordx4 v0, s[52:53]
	v_lshl_add_u64 v[10:11], v[130:131], 0, s[76:77]
	s_mov_b32 m0, s47
	s_cmp_lg_u32 s0, 1
	global_load_lds_dwordx4 v[10:11], off
	v_mov_b32_e32 v16, 0
	v_mov_b32_e32 v17, 0
	v_mov_b32_e32 v18, 0
	v_mov_b32_e32 v19, 0
	v_mov_b32_e32 v20, 0
	v_mov_b32_e32 v21, 0
	v_mov_b32_e32 v22, 0
	v_mov_b32_e32 v23, 0
	v_mov_b32_e32 v24, 0
	v_mov_b32_e32 v25, 0
	v_mov_b32_e32 v26, 0
	v_mov_b32_e32 v27, 0
	v_mov_b32_e32 v28, 0
	v_mov_b32_e32 v29, 0
	v_mov_b32_e32 v30, 0
	v_mov_b32_e32 v31, 0
	v_mov_b32_e32 v32, 0
	v_mov_b32_e32 v33, 0
	v_mov_b32_e32 v34, 0
	v_mov_b32_e32 v35, 0
	v_mov_b32_e32 v36, 0
	v_mov_b32_e32 v37, 0
	v_mov_b32_e32 v38, 0
	v_mov_b32_e32 v39, 0
	v_mov_b32_e32 v40, 0
	v_mov_b32_e32 v41, 0
	v_mov_b32_e32 v42, 0
	v_mov_b32_e32 v43, 0
	v_mov_b32_e32 v44, 0
	v_mov_b32_e32 v45, 0
	v_mov_b32_e32 v46, 0
	v_mov_b32_e32 v47, 0
	v_mov_b32_e32 v48, 0
	v_mov_b32_e32 v49, 0
	v_mov_b32_e32 v50, 0
	v_mov_b32_e32 v51, 0
	v_mov_b32_e32 v52, 0
	v_mov_b32_e32 v53, 0
	v_mov_b32_e32 v54, 0
	v_mov_b32_e32 v55, 0
	v_mov_b32_e32 v56, 0
	v_mov_b32_e32 v57, 0
	v_mov_b32_e32 v58, 0
	v_mov_b32_e32 v59, 0
	v_mov_b32_e32 v60, 0
	v_mov_b32_e32 v61, 0
	v_mov_b32_e32 v62, 0
	v_mov_b32_e32 v63, 0
	v_mov_b32_e32 v64, 0
	v_mov_b32_e32 v65, 0
	v_mov_b32_e32 v66, 0
	v_mov_b32_e32 v67, 0
	v_mov_b32_e32 v68, 0
	v_mov_b32_e32 v69, 0
	v_mov_b32_e32 v70, 0
	v_mov_b32_e32 v71, 0
	v_mov_b32_e32 v72, 0
	v_mov_b32_e32 v73, 0
	v_mov_b32_e32 v74, 0
	v_mov_b32_e32 v75, 0
	v_mov_b32_e32 v76, 0
	v_mov_b32_e32 v77, 0
	v_mov_b32_e32 v78, 0
	v_mov_b32_e32 v79, 0
	v_mov_b32_e32 v80, 0
	v_mov_b32_e32 v81, 0
	v_mov_b32_e32 v82, 0
	v_mov_b32_e32 v83, 0
	v_mov_b32_e32 v84, 0
	v_mov_b32_e32 v85, 0
	v_mov_b32_e32 v86, 0
	v_mov_b32_e32 v87, 0
	v_mov_b32_e32 v88, 0
	v_mov_b32_e32 v89, 0
	v_mov_b32_e32 v90, 0
	v_mov_b32_e32 v91, 0
	v_mov_b32_e32 v92, 0
	v_mov_b32_e32 v93, 0
	v_mov_b32_e32 v94, 0
	v_mov_b32_e32 v95, 0
	v_mov_b32_e32 v96, 0
	v_mov_b32_e32 v97, 0
	v_mov_b32_e32 v98, 0
	v_mov_b32_e32 v99, 0
	v_mov_b32_e32 v100, 0
	v_mov_b32_e32 v101, 0
	v_mov_b32_e32 v102, 0
	v_mov_b32_e32 v103, 0
	v_mov_b32_e32 v104, 0
	v_mov_b32_e32 v105, 0
	v_mov_b32_e32 v106, 0
	v_mov_b32_e32 v107, 0
	v_mov_b32_e32 v108, 0
	v_mov_b32_e32 v109, 0
	v_mov_b32_e32 v110, 0
	v_mov_b32_e32 v111, 0
	v_mov_b32_e32 v112, 0
	v_mov_b32_e32 v113, 0
	v_mov_b32_e32 v114, 0
	v_mov_b32_e32 v115, 0
	v_mov_b32_e32 v116, 0
	v_mov_b32_e32 v117, 0
	v_mov_b32_e32 v118, 0
	v_mov_b32_e32 v119, 0
	v_mov_b32_e32 v120, 0
	v_mov_b32_e32 v121, 0
	v_mov_b32_e32 v122, 0
	v_mov_b32_e32 v123, 0
	v_mov_b32_e32 v124, 0
	v_mov_b32_e32 v125, 0
	v_mov_b32_e32 v126, 0
	v_mov_b32_e32 v127, 0
	v_mov_b32_e32 v128, 0
	v_mov_b32_e32 v129, 0
	s_cbranch_scc1 .LBB0_226
	s_setprio 1
	s_barrier

; #define STAGE_A(P, br, kt) do { const char* _g = (const char*)(A + (long)(br) * lda + (long)(kt) * BK); \
;     __builtin_amdgcn_global_load_lds((const unsigned*)(_g + (size_t)offA0), (unsigned*)((char*)(P) + sb0), 16, 0, 0); \
;     __builtin_amdgcn_global_load_lds((const unsigned*)(_g + (size_t)lda * 128 + (size_t)offA0), (unsigned*)((char*)(P) + sb1), 16, 0, 0); } while (0)
; #define STAGE_B(P, br, kt) do { const char* _g = (const char*)(B + (long)(br) * ldb + (long)(kt) * BK); \
;     __builtin_amdgcn_global_load_lds((const unsigned*)(_g + (size_t)offB0), (unsigned*)((char*)(P) + sb0), 16, 0, 0); \
;     __builtin_amdgcn_global_load_lds((const unsigned*)(_g + (size_t)ldb * 128 + (size_t)offB0), (unsigned*)((char*)(P) + sb1), 16, 0, 0); } while (0)
; #define LDA(dst, b, h) for (int m = 0; m < 4; ++m) for (int k = 0; k < 2; ++k) \
;     dst[m][k] = *reinterpret_cast<const bf16x8*>((char*)SA(b, h) + lds_byte(wr * 64 + m * 16 + fr, k * 32 + fq * 8))
; #define LDB(dst, b, h) for (int n = 0; n < 2; ++n) for (int k = 0; k < 2; ++k) \
;     dst[n][k] = *reinterpret_cast<const bf16x8*>((char*)SB(b, h) + lds_byte(wc * 32 + n * 16 + fr, k * 32 + fq * 8))
; #define MMA(ai, bj, At_, Bt_) do { __builtin_amdgcn_s_setprio(1); \
;     for (int m = 0; m < 4; ++m) for (int n = 0; n < 2; ++n) for (int k = 0; k < 2; ++k) \
;       acc[ai][bj][m][n] = MFMA16(At_[m][k], Bt_[n][k], acc[ai][bj][m][n]); \
;     __builtin_amdgcn_s_setprio(0); } while (0)
; #define WAIT_V(n) asm volatile("s_waitcnt vmcnt(" #n ")" ::: "memory")
; #define WAIT_L(n) asm volatile("s_waitcnt lgkmcnt(" #n ")" ::: "memory")
; #define BAR __builtin_amdgcn_s_barrier()
; #define SCHED __builtin_amdgcn_sched_barrier(0)
; DI void gemm_core(WVP char* smem, const u16* __restrict__ A, int lda, int ar0, int ar1,
;                   const u16* __restrict__ B, int ldb, int bc0, int K, AccT& acc) {
;     ...
;     LDB(B0, 0, 0); SCHED; LDA(At, 0, 0); STAGE_A(SA(1, 1), ac1, t + 1);
;     WAIT_L(8); BAR; WAIT_L(0); MMA(0, 0, At, B0); BAR; SCHED;
;     LDB(B1, 0, 1); STAGE_B(SB(0, 0), bb0, t + 2);
;     BAR; WAIT_L(0); MMA(0, 1, At, B1); BAR;
;     LDA(At, 0, 1); STAGE_A(SA(0, 0), ac0, t + 2);
;     BAR; WAIT_L(0); MMA(1, 0, At, B0); BAR; SCHED;
;     STAGE_B(SB(0, 1), bb1, t + 2);
;     WAIT_V(6); BAR; MMA(1, 1, At, B1); BAR;
.LBB0_227:
	v_add_u32_e32 v150, s0, v148
	v_add_u32_e32 v151, s1, v148
	v_add_u32_e32 v152, s50, v148
	ds_read_b128 v[156:159], v149
	ds_read_b128 v[160:163], v149 offset:1024
	ds_read_b128 v[164:167], v149 offset:2048
	ds_read_b128 v[168:171], v149 offset:3072
	ds_read_b128 v[172:175], v132
	ds_read_b128 v[176:179], v132 offset:1024
	ds_read_b128 v[180:183], v150
	ds_read_b128 v[184:187], v150 offset:1024
	ds_read_b128 v[188:191], v151
	ds_read_b128 v[192:195], v151 offset:1024
	ds_read_b128 v[196:199], v152
	ds_read_b128 v[200:203], v152 offset:1024
	ds_read_b128 v[206:209], v144
	ds_read_b128 v[210:213], v144 offset:1024
	ds_read_b128 v[214:217], v144 offset:2048
	ds_read_b128 v[218:221], v144 offset:3072
	v_add_u32_e32 v153, 0xc000, v136
	v_lshl_add_u64 v[224:225], s[52:53], 0, v[0:1]
	s_mov_b64 s[74:75], 0x3ff80
	v_lshl_add_u64 v[222:223], v[224:225], 0, s[74:75]
	v_readfirstlane_b32 s58, v153
	s_mov_b32 m0, s58
	s_nop 0
	global_load_lds_dwordx4 v[222:223], off
	v_add_u32_e32 v154, 0xe000, v136
	v_lshl_add_u64 v[224:225], s[52:53], 0, v[0:1]
	s_mov_b64 s[74:75], 0x5ff80
	v_lshl_add_u64 v[222:223], v[224:225], 0, s[74:75]
	v_readfirstlane_b32 s58, v154
	s_mov_b32 m0, s58
	s_nop 0
	global_load_lds_dwordx4 v[222:223], off
	s_waitcnt vmcnt(8)
	s_waitcnt lgkmcnt(0)
	s_barrier
	v_mfma_f32_16x16x32_bf16 v[126:129], v[172:175], v[156:159], v[126:129]
	v_mfma_f32_16x16x32_bf16 v[122:125], v[172:175], v[164:167], v[122:125]
	v_mfma_f32_16x16x32_bf16 v[118:121], v[180:183], v[156:159], v[118:121]
	v_mfma_f32_16x16x32_bf16 v[114:117], v[180:183], v[164:167], v[114:117]
	v_mfma_f32_16x16x32_bf16 v[110:113], v[188:191], v[156:159], v[110:113]
	v_mfma_f32_16x16x32_bf16 v[106:109], v[188:191], v[164:167], v[106:109]
	v_mfma_f32_16x16x32_bf16 v[102:105], v[196:199], v[156:159], v[102:105]
	v_mfma_f32_16x16x32_bf16 v[98:101], v[196:199], v[164:167], v[98:101]
	v_mfma_f32_16x16x32_bf16 v[126:129], v[176:179], v[160:163], v[126:129]
	v_mfma_f32_16x16x32_bf16 v[122:125], v[176:179], v[168:171], v[122:125]
	v_mfma_f32_16x16x32_bf16 v[118:121], v[184:187], v[160:163], v[118:121]
	v_mfma_f32_16x16x32_bf16 v[114:117], v[184:187], v[168:171], v[114:117]
	v_mfma_f32_16x16x32_bf16 v[110:113], v[192:195], v[160:163], v[110:113]
	v_mfma_f32_16x16x32_bf16 v[106:109], v[192:195], v[168:171], v[106:109]
	v_mfma_f32_16x16x32_bf16 v[102:105], v[200:203], v[160:163], v[102:105]
	v_mfma_f32_16x16x32_bf16 v[98:101], v[200:203], v[168:171], v[98:101]
	v_mfma_f32_16x16x32_bf16 v[94:97], v[172:175], v[206:209], v[94:97]
	v_mfma_f32_16x16x32_bf16 v[90:93], v[172:175], v[214:217], v[90:93]
	v_mfma_f32_16x16x32_bf16 v[86:89], v[180:183], v[206:209], v[86:89]
	v_mfma_f32_16x16x32_bf16 v[82:85], v[180:183], v[214:217], v[82:85]
	v_mfma_f32_16x16x32_bf16 v[78:81], v[188:191], v[206:209], v[78:81]
	v_mfma_f32_16x16x32_bf16 v[74:77], v[188:191], v[214:217], v[74:77]
	v_mfma_f32_16x16x32_bf16 v[70:73], v[196:199], v[206:209], v[70:73]
	v_mfma_f32_16x16x32_bf16 v[66:69], v[196:199], v[214:217], v[66:69]
	v_mfma_f32_16x16x32_bf16 v[94:97], v[176:179], v[210:213], v[94:97]
	v_mfma_f32_16x16x32_bf16 v[90:93], v[176:179], v[218:221], v[90:93]
	v_mfma_f32_16x16x32_bf16 v[86:89], v[184:187], v[210:213], v[86:89]
	v_mfma_f32_16x16x32_bf16 v[82:85], v[184:187], v[218:221], v[82:85]
	v_mfma_f32_16x16x32_bf16 v[78:81], v[192:195], v[210:213], v[78:81]
	v_mfma_f32_16x16x32_bf16 v[74:77], v[192:195], v[218:221], v[74:77]
	v_mfma_f32_16x16x32_bf16 v[70:73], v[200:203], v[210:213], v[70:73]
	v_mfma_f32_16x16x32_bf16 v[66:69], v[200:203], v[218:221], v[66:69]
	s_barrier
	ds_read_b128 v[172:175], v132 offset:16384
	ds_read_b128 v[176:179], v132 offset:17408
	ds_read_b128 v[180:183], v150 offset:16384
	ds_read_b128 v[184:187], v150 offset:17408
	ds_read_b128 v[188:191], v151 offset:16384
	ds_read_b128 v[192:195], v151 offset:17408
	ds_read_b128 v[196:199], v152 offset:16384
	ds_read_b128 v[200:203], v152 offset:17408
	v_lshl_add_u64 v[224:225], vcc, 0, v[0:1]
	v_lshl_add_u64 v[222:223], v[224:225], 0, s[80:81]
	v_readfirstlane_b32 s58, v134
	s_mov_b32 m0, s58
	s_nop 0
	global_load_lds_dwordx4 v[222:223], off
	v_add_u32_e32 v155, 0x2000, v134
	v_lshl_add_u64 v[224:225], vcc, 0, v[0:1]
	v_lshl_add_u64 v[222:223], v[224:225], 0, s[82:83]
	v_readfirstlane_b32 s58, v155
	s_mov_b32 m0, s58
	s_nop 0
	global_load_lds_dwordx4 v[222:223], off
	v_lshl_add_u64 v[222:223], s[52:53], 0, v[0:1]
	v_readfirstlane_b32 s58, v136
	s_mov_b32 m0, s58
	s_nop 0
	global_load_lds_dwordx4 v[222:223], off
	v_lshl_add_u64 v[224:225], s[52:53], 0, v[0:1]
	v_lshl_add_u64 v[222:223], v[224:225], 0, s[76:77]
	v_readfirstlane_b32 s58, v137
	s_mov_b32 m0, s58
	s_nop 0
	global_load_lds_dwordx4 v[222:223], off
	v_lshl_add_u64 v[224:225], vcc, 0, v[0:1]
	v_lshl_add_u64 v[222:223], v[224:225], 0, s[88:89]
	v_readfirstlane_b32 s58, v138
	s_mov_b32 m0, s58
	s_nop 0
	global_load_lds_dwordx4 v[222:223], off
	v_add_u32_e32 v155, 0x2000, v138
	v_lshl_add_u64 v[224:225], vcc, 0, v[0:1]
	v_lshl_add_u64 v[222:223], v[224:225], 0, s[90:91]
	v_readfirstlane_b32 s58, v155
	s_mov_b32 m0, s58
	s_nop 0
	global_load_lds_dwordx4 v[222:223], off
	s_waitcnt vmcnt(8)
	s_waitcnt lgkmcnt(0)
	s_barrier
; #define STAGE_A(P, br, kt) do { const char* _g = (const char*)(A + (long)(br) * lda + (long)(kt) * BK); \
;     __builtin_amdgcn_global_load_lds((const unsigned*)(_g + (size_t)offA0), (unsigned*)((char*)(P) + sb0), 16, 0, 0); \
;     __builtin_amdgcn_global_load_lds((const unsigned*)(_g + (size_t)lda * 128 + (size_t)offA0), (unsigned*)((char*)(P) + sb1), 16, 0, 0); } while (0)
; #define STAGE_B(P, br, kt) do { const char* _g = (const char*)(B + (long)(br) * ldb + (long)(kt) * BK); \
;     __builtin_amdgcn_global_load_lds((const unsigned*)(_g + (size_t)offB0), (unsigned*)((char*)(P) + sb0), 16, 0, 0); \
;     __builtin_amdgcn_global_load_lds((const unsigned*)(_g + (size_t)ldb * 128 + (size_t)offB0), (unsigned*)((char*)(P) + sb1), 16, 0, 0); } while (0)
; #define LDA(dst, b, h) for (int m = 0; m < 4; ++m) for (int k = 0; k < 2; ++k) \
;     dst[m][k] = *reinterpret_cast<const bf16x8*>((char*)SA(b, h) + lds_byte(wr * 64 + m * 16 + fr, k * 32 + fq * 8))
; #define LDB(dst, b, h) for (int n = 0; n < 2; ++n) for (int k = 0; k < 2; ++k) \
;     dst[n][k] = *reinterpret_cast<const bf16x8*>((char*)SB(b, h) + lds_byte(wc * 32 + n * 16 + fr, k * 32 + fq * 8))
; #define MMA(ai, bj, At_, Bt_) do { __builtin_amdgcn_s_setprio(1); \
;     for (int m = 0; m < 4; ++m) for (int n = 0; n < 2; ++n) for (int k = 0; k < 2; ++k) \
;       acc[ai][bj][m][n] = MFMA16(At_[m][k], Bt_[n][k], acc[ai][bj][m][n]); \
;     __builtin_amdgcn_s_setprio(0); } while (0)
; #define WAIT_V(n) asm volatile("s_waitcnt vmcnt(" #n ")" ::: "memory")
; #define WAIT_L(n) asm volatile("s_waitcnt lgkmcnt(" #n ")" ::: "memory")
; #define BAR __builtin_amdgcn_s_barrier()
; #define SCHED __builtin_amdgcn_sched_barrier(0)
; DI void gemm_core(WVP char* smem, const u16* __restrict__ A, int lda, int ar0, int ar1,
;                   const u16* __restrict__ B, int ldb, int bc0, int K, AccT& acc) {
;     ...
;     WAIT_V(6); BAR; MMA(1, 1, At, B1); BAR;
;     LDB(B0, 1, 0); SCHED; LDA(At, 1, 0); STAGE_A(SA(0, 1), ac1, t + 2);
;     WAIT_L(8); BAR; WAIT_L(0); MMA(0, 0, At, B0); BAR; SCHED;
;     LDB(B1, 1, 1); STAGE_B(SB(1, 0), bb0, t + 3);
;     BAR; WAIT_L(0); MMA(0, 1, At, B1); BAR;
	v_mfma_f32_16x16x32_bf16 v[62:65], v[172:175], v[156:159], v[62:65]
	v_mfma_f32_16x16x32_bf16 v[58:61], v[172:175], v[164:167], v[58:61]
	v_mfma_f32_16x16x32_bf16 v[54:57], v[180:183], v[156:159], v[54:57]
	v_mfma_f32_16x16x32_bf16 v[50:53], v[180:183], v[164:167], v[50:53]
	v_mfma_f32_16x16x32_bf16 v[46:49], v[188:191], v[156:159], v[46:49]
	v_mfma_f32_16x16x32_bf16 v[42:45], v[188:191], v[164:167], v[42:45]
	v_mfma_f32_16x16x32_bf16 v[38:41], v[196:199], v[156:159], v[38:41]
	v_mfma_f32_16x16x32_bf16 v[34:37], v[196:199], v[164:167], v[34:37]
	v_mfma_f32_16x16x32_bf16 v[62:65], v[176:179], v[160:163], v[62:65]
	v_mfma_f32_16x16x32_bf16 v[58:61], v[176:179], v[168:171], v[58:61]
	v_mfma_f32_16x16x32_bf16 v[54:57], v[184:187], v[160:163], v[54:57]
	v_mfma_f32_16x16x32_bf16 v[50:53], v[184:187], v[168:171], v[50:53]
	v_mfma_f32_16x16x32_bf16 v[46:49], v[192:195], v[160:163], v[46:49]
	v_mfma_f32_16x16x32_bf16 v[42:45], v[192:195], v[168:171], v[42:45]
	v_mfma_f32_16x16x32_bf16 v[38:41], v[200:203], v[160:163], v[38:41]
	v_mfma_f32_16x16x32_bf16 v[34:37], v[200:203], v[168:171], v[34:37]
	v_mfma_f32_16x16x32_bf16 v[30:33], v[172:175], v[206:209], v[30:33]
	v_mfma_f32_16x16x32_bf16 v[26:29], v[172:175], v[214:217], v[26:29]
	v_mfma_f32_16x16x32_bf16 v[22:25], v[180:183], v[206:209], v[22:25]
	v_mfma_f32_16x16x32_bf16 v[18:21], v[180:183], v[214:217], v[18:21]
	v_mfma_f32_16x16x32_bf16 v[14:17], v[188:191], v[206:209], v[14:17]
	v_mfma_f32_16x16x32_bf16 v[10:13], v[188:191], v[214:217], v[10:13]
	v_mfma_f32_16x16x32_bf16 v[6:9], v[196:199], v[206:209], v[6:9]
	v_mfma_f32_16x16x32_bf16 v[2:5], v[196:199], v[214:217], v[2:5]
	v_mfma_f32_16x16x32_bf16 v[30:33], v[176:179], v[210:213], v[30:33]
	v_mfma_f32_16x16x32_bf16 v[26:29], v[176:179], v[218:221], v[26:29]
	v_mfma_f32_16x16x32_bf16 v[22:25], v[184:187], v[210:213], v[22:25]
	v_mfma_f32_16x16x32_bf16 v[18:21], v[184:187], v[218:221], v[18:21]
	v_mfma_f32_16x16x32_bf16 v[14:17], v[192:195], v[210:213], v[14:17]
	v_mfma_f32_16x16x32_bf16 v[10:13], v[192:195], v[218:221], v[10:13]
	v_mfma_f32_16x16x32_bf16 v[6:9], v[200:203], v[210:213], v[6:9]
	v_mfma_f32_16x16x32_bf16 v[2:5], v[200:203], v[218:221], v[2:5]
	s_barrier
	ds_read_b128 v[156:159], v135
	ds_read_b128 v[160:163], v135 offset:1024
	ds_read_b128 v[164:167], v135 offset:2048
	ds_read_b128 v[168:171], v135 offset:3072
	ds_read_b128 v[172:175], v132 offset:32768
	ds_read_b128 v[176:179], v132 offset:33792
	ds_read_b128 v[180:183], v150 offset:32768
	ds_read_b128 v[184:187], v150 offset:33792
	ds_read_b128 v[188:191], v151 offset:32768
	ds_read_b128 v[192:195], v151 offset:33792
	ds_read_b128 v[196:199], v152 offset:32768
	ds_read_b128 v[200:203], v152 offset:33792
	ds_read_b128 v[206:209], v133
	ds_read_b128 v[210:213], v133 offset:1024
	ds_read_b128 v[214:217], v133 offset:2048
	ds_read_b128 v[218:221], v133 offset:3072
	v_lshl_add_u64 v[224:225], s[52:53], 0, v[0:1]
	s_mov_b64 s[74:75], 0x40000
	v_lshl_add_u64 v[222:223], v[224:225], 0, s[74:75]
	v_readfirstlane_b32 s58, v139
	s_mov_b32 m0, s58
	s_nop 0
	global_load_lds_dwordx4 v[222:223], off
	v_lshl_add_u64 v[224:225], s[52:53], 0, v[0:1]
	s_mov_b64 s[74:75], 0x60000
	v_lshl_add_u64 v[222:223], v[224:225], 0, s[74:75]
	v_readfirstlane_b32 s58, v140
	s_mov_b32 m0, s58
	s_nop 0
	global_load_lds_dwordx4 v[222:223], off
	s_waitcnt vmcnt(8)
	s_waitcnt lgkmcnt(0)
	s_barrier
	v_mfma_f32_16x16x32_bf16 v[126:129], v[172:175], v[156:159], v[126:129]
	v_mfma_f32_16x16x32_bf16 v[122:125], v[172:175], v[164:167], v[122:125]
	v_mfma_f32_16x16x32_bf16 v[118:121], v[180:183], v[156:159], v[118:121]
	v_mfma_f32_16x16x32_bf16 v[114:117], v[180:183], v[164:167], v[114:117]
	v_mfma_f32_16x16x32_bf16 v[110:113], v[188:191], v[156:159], v[110:113]
	v_mfma_f32_16x16x32_bf16 v[106:109], v[188:191], v[164:167], v[106:109]
	v_mfma_f32_16x16x32_bf16 v[102:105], v[196:199], v[156:159], v[102:105]
	v_mfma_f32_16x16x32_bf16 v[98:101], v[196:199], v[164:167], v[98:101]
	v_mfma_f32_16x16x32_bf16 v[126:129], v[176:179], v[160:163], v[126:129]
	v_mfma_f32_16x16x32_bf16 v[122:125], v[176:179], v[168:171], v[122:125]
	v_mfma_f32_16x16x32_bf16 v[118:121], v[184:187], v[160:163], v[118:121]
	v_mfma_f32_16x16x32_bf16 v[114:117], v[184:187], v[168:171], v[114:117]
	v_mfma_f32_16x16x32_bf16 v[110:113], v[192:195], v[160:163], v[110:113]
	v_mfma_f32_16x16x32_bf16 v[106:109], v[192:195], v[168:171], v[106:109]
	v_mfma_f32_16x16x32_bf16 v[102:105], v[200:203], v[160:163], v[102:105]
	v_mfma_f32_16x16x32_bf16 v[98:101], v[200:203], v[168:171], v[98:101]
	v_mfma_f32_16x16x32_bf16 v[94:97], v[172:175], v[206:209], v[94:97]
	v_mfma_f32_16x16x32_bf16 v[90:93], v[172:175], v[214:217], v[90:93]
	v_mfma_f32_16x16x32_bf16 v[86:89], v[180:183], v[206:209], v[86:89]
	v_mfma_f32_16x16x32_bf16 v[82:85], v[180:183], v[214:217], v[82:85]
	v_mfma_f32_16x16x32_bf16 v[78:81], v[188:191], v[206:209], v[78:81]
	v_mfma_f32_16x16x32_bf16 v[74:77], v[188:191], v[214:217], v[74:77]
	v_mfma_f32_16x16x32_bf16 v[70:73], v[196:199], v[206:209], v[70:73]
	v_mfma_f32_16x16x32_bf16 v[66:69], v[196:199], v[214:217], v[66:69]
	v_mfma_f32_16x16x32_bf16 v[94:97], v[176:179], v[210:213], v[94:97]
	v_mfma_f32_16x16x32_bf16 v[90:93], v[176:179], v[218:221], v[90:93]
	v_mfma_f32_16x16x32_bf16 v[86:89], v[184:187], v[210:213], v[86:89]
	v_mfma_f32_16x16x32_bf16 v[82:85], v[184:187], v[218:221], v[82:85]
	v_mfma_f32_16x16x32_bf16 v[78:81], v[192:195], v[210:213], v[78:81]
	v_mfma_f32_16x16x32_bf16 v[74:77], v[192:195], v[218:221], v[74:77]
	v_mfma_f32_16x16x32_bf16 v[70:73], v[200:203], v[210:213], v[70:73]
	v_mfma_f32_16x16x32_bf16 v[66:69], v[200:203], v[218:221], v[66:69]
	s_barrier
; #define STAGE_A(P, br, kt) do { const char* _g = (const char*)(A + (long)(br) * lda + (long)(kt) * BK); \
;     __builtin_amdgcn_global_load_lds((const unsigned*)(_g + (size_t)offA0), (unsigned*)((char*)(P) + sb0), 16, 0, 0); \
;     __builtin_amdgcn_global_load_lds((const unsigned*)(_g + (size_t)lda * 128 + (size_t)offA0), (unsigned*)((char*)(P) + sb1), 16, 0, 0); } while (0)
; #define STAGE_B(P, br, kt) do { const char* _g = (const char*)(B + (long)(br) * ldb + (long)(kt) * BK); \
;     __builtin_amdgcn_global_load_lds((const unsigned*)(_g + (size_t)offB0), (unsigned*)((char*)(P) + sb0), 16, 0, 0); \
;     __builtin_amdgcn_global_load_lds((const unsigned*)(_g + (size_t)ldb * 128 + (size_t)offB0), (unsigned*)((char*)(P) + sb1), 16, 0, 0); } while (0)
; #define LDA(dst, b, h) for (int m = 0; m < 4; ++m) for (int k = 0; k < 2; ++k) \
;     dst[m][k] = *reinterpret_cast<const bf16x8*>((char*)SA(b, h) + lds_byte(wr * 64 + m * 16 + fr, k * 32 + fq * 8))
; #define LDB(dst, b, h) for (int n = 0; n < 2; ++n) for (int k = 0; k < 2; ++k) \
;     dst[n][k] = *reinterpret_cast<const bf16x8*>((char*)SB(b, h) + lds_byte(wc * 32 + n * 16 + fr, k * 32 + fq * 8))
; #define MMA(ai, bj, At_, Bt_) do { __builtin_amdgcn_s_setprio(1); \
;     for (int m = 0; m < 4; ++m) for (int n = 0; n < 2; ++n) for (int k = 0; k < 2; ++k) \
;       acc[ai][bj][m][n] = MFMA16(At_[m][k], Bt_[n][k], acc[ai][bj][m][n]); \
;     __builtin_amdgcn_s_setprio(0); } while (0)
; #define WAIT_V(n) asm volatile("s_waitcnt vmcnt(" #n ")" ::: "memory")
; #define WAIT_L(n) asm volatile("s_waitcnt lgkmcnt(" #n ")" ::: "memory")
; #define BAR __builtin_amdgcn_s_barrier()
; #define SCHED __builtin_amdgcn_sched_barrier(0)
; DI void gemm_core(WVP char* smem, const u16* __restrict__ A, int lda, int ar0, int ar1,
;                   const u16* __restrict__ B, int ldb, int bc0, int K, AccT& acc) {
;     ...
;     LDA(At, 1, 1); STAGE_A(SA(1, 0), ac0, t + 3);
;     BAR; WAIT_L(0); MMA(1, 0, At, B0); BAR; SCHED;
;     STAGE_B(SB(1, 1), bb1, t + 3);
;     WAIT_V(6); BAR; MMA(1, 1, At, B1); BAR;
;   }
;   { LDB(B0, 0, 0); LDA(At, 0, 0); STAGE_A(SA(1, 1), ac1, nt - 1);
;     BAR; WAIT_L(0); MMA(0, 0, At, B0); BAR;
	ds_read_b128 v[172:175], v132 offset:49152
	ds_read_b128 v[176:179], v132 offset:50176
	ds_read_b128 v[180:183], v150 offset:49152
	ds_read_b128 v[184:187], v150 offset:50176
	ds_read_b128 v[188:191], v151 offset:49152
	ds_read_b128 v[192:195], v151 offset:50176
	ds_read_b128 v[196:199], v152 offset:49152
	ds_read_b128 v[200:203], v152 offset:50176
	v_lshl_add_u64 v[224:225], vcc, 0, v[0:1]
	v_lshl_add_u64 v[222:223], v[224:225], 0, s[92:93]
	v_readfirstlane_b32 s58, v141
	s_mov_b32 m0, s58
	s_nop 0
	global_load_lds_dwordx4 v[222:223], off
	v_lshl_add_u64 v[224:225], vcc, 0, v[0:1]
	v_lshl_add_u64 v[222:223], v[224:225], 0, s[94:95]
	v_readfirstlane_b32 s58, v142
	s_mov_b32 m0, s58
	s_nop 0
	global_load_lds_dwordx4 v[222:223], off
	v_lshl_add_u64 v[224:225], s[52:53], 0, v[0:1]
	v_lshl_add_u64 v[222:223], v[224:225], 0, s[64:65]
	v_readfirstlane_b32 s58, v143
	s_mov_b32 m0, s58
	s_nop 0
	global_load_lds_dwordx4 v[222:223], off
	v_lshl_add_u64 v[224:225], s[52:53], 0, v[0:1]
	v_lshl_add_u64 v[222:223], v[224:225], 0, s[78:79]
	v_readfirstlane_b32 s58, v145
	s_mov_b32 m0, s58
	s_nop 0
	global_load_lds_dwordx4 v[222:223], off
	v_lshl_add_u64 v[224:225], vcc, 0, v[0:1]
	v_lshl_add_u64 v[222:223], v[224:225], 0, s[96:97]
	v_readfirstlane_b32 s58, v146
	s_mov_b32 m0, s58
	s_nop 0
	global_load_lds_dwordx4 v[222:223], off
	v_lshl_add_u64 v[224:225], vcc, 0, v[0:1]
	v_lshl_add_u64 v[222:223], v[224:225], 0, s[72:73]
	v_readfirstlane_b32 s58, v147
	s_mov_b32 m0, s58
	s_nop 0
	global_load_lds_dwordx4 v[222:223], off
	s_waitcnt vmcnt(8)
	s_waitcnt lgkmcnt(0)
	s_barrier
	v_mfma_f32_16x16x32_bf16 v[62:65], v[172:175], v[156:159], v[62:65]
	v_mfma_f32_16x16x32_bf16 v[58:61], v[172:175], v[164:167], v[58:61]
	v_mfma_f32_16x16x32_bf16 v[54:57], v[180:183], v[156:159], v[54:57]
	v_mfma_f32_16x16x32_bf16 v[50:53], v[180:183], v[164:167], v[50:53]
	v_mfma_f32_16x16x32_bf16 v[46:49], v[188:191], v[156:159], v[46:49]
	v_mfma_f32_16x16x32_bf16 v[42:45], v[188:191], v[164:167], v[42:45]
	v_mfma_f32_16x16x32_bf16 v[38:41], v[196:199], v[156:159], v[38:41]
	v_mfma_f32_16x16x32_bf16 v[34:37], v[196:199], v[164:167], v[34:37]
	v_mfma_f32_16x16x32_bf16 v[62:65], v[176:179], v[160:163], v[62:65]
	v_mfma_f32_16x16x32_bf16 v[58:61], v[176:179], v[168:171], v[58:61]
	v_mfma_f32_16x16x32_bf16 v[54:57], v[184:187], v[160:163], v[54:57]
	v_mfma_f32_16x16x32_bf16 v[50:53], v[184:187], v[168:171], v[50:53]
	v_mfma_f32_16x16x32_bf16 v[46:49], v[192:195], v[160:163], v[46:49]
	v_mfma_f32_16x16x32_bf16 v[42:45], v[192:195], v[168:171], v[42:45]
	v_mfma_f32_16x16x32_bf16 v[38:41], v[200:203], v[160:163], v[38:41]
	v_mfma_f32_16x16x32_bf16 v[34:37], v[200:203], v[168:171], v[34:37]
	v_mfma_f32_16x16x32_bf16 v[30:33], v[172:175], v[206:209], v[30:33]
	v_mfma_f32_16x16x32_bf16 v[26:29], v[172:175], v[214:217], v[26:29]
	v_mfma_f32_16x16x32_bf16 v[22:25], v[180:183], v[206:209], v[22:25]
	v_mfma_f32_16x16x32_bf16 v[18:21], v[180:183], v[214:217], v[18:21]
	v_mfma_f32_16x16x32_bf16 v[14:17], v[188:191], v[206:209], v[14:17]
	v_mfma_f32_16x16x32_bf16 v[10:13], v[188:191], v[214:217], v[10:13]
	v_mfma_f32_16x16x32_bf16 v[6:9], v[196:199], v[206:209], v[6:9]
	v_mfma_f32_16x16x32_bf16 v[2:5], v[196:199], v[214:217], v[2:5]
	v_mfma_f32_16x16x32_bf16 v[30:33], v[176:179], v[210:213], v[30:33]
	v_mfma_f32_16x16x32_bf16 v[26:29], v[176:179], v[218:221], v[26:29]
	v_mfma_f32_16x16x32_bf16 v[22:25], v[184:187], v[210:213], v[22:25]
	v_mfma_f32_16x16x32_bf16 v[18:21], v[184:187], v[218:221], v[18:21]
	v_mfma_f32_16x16x32_bf16 v[14:17], v[192:195], v[210:213], v[14:17]
	v_mfma_f32_16x16x32_bf16 v[10:13], v[192:195], v[218:221], v[10:13]
	v_mfma_f32_16x16x32_bf16 v[6:9], v[200:203], v[210:213], v[6:9]
	v_mfma_f32_16x16x32_bf16 v[2:5], v[200:203], v[218:221], v[2:5]
	s_add_i32 s57, s57, 2
	s_add_u32 vcc_lo, vcc_lo, 0x100
	s_addc_u32 vcc_hi, vcc_hi, 0
	s_add_u32 s52, s52, 0x100
	s_addc_u32 s53, s53, 0
	s_cmp_lt_u32 s57, 12
	s_barrier
	s_cbranch_scc1 .LBB0_227
	s_mov_b64 s[0:1], 0x780
	v_lshl_add_u64 v[192:193], v[130:131], 0, s[0:1]
	v_readfirstlane_b32 s0, v153
	s_mov_b32 m0, s0
	s_mov_b64 s[0:1], 0x20780
	v_lshl_add_u64 v[130:131], v[130:131], 0, s[0:1]
	v_readfirstlane_b32 s0, v154
	ds_read_b128 v[136:139], v149
	ds_read_b128 v[140:143], v149 offset:1024
	ds_read_b128 v[156:159], v149 offset:2048
	ds_read_b128 v[146:149], v149 offset:3072
	ds_read_b128 v[160:163], v132
	ds_read_b128 v[164:167], v132 offset:1024
	ds_read_b128 v[168:171], v150
	ds_read_b128 v[172:175], v150 offset:1024
	ds_read_b128 v[176:179], v151
	ds_read_b128 v[180:183], v151 offset:1024
	ds_read_b128 v[184:187], v152
	ds_read_b128 v[188:191], v152 offset:1024
	global_load_lds_dwordx4 v[192:193], off
	s_mov_b32 m0, s0
	s_nop 0
	global_load_lds_dwordx4 v[130:131], off
	s_waitcnt vmcnt(8)
	s_barrier
	s_waitcnt lgkmcnt(0)
	s_setprio 1
	s_waitcnt lgkmcnt(0)
	v_mfma_f32_16x16x32_bf16 v[126:129], v[160:163], v[136:139], v[126:129]
	v_mfma_f32_16x16x32_bf16 v[118:121], v[168:171], v[136:139], v[118:121]
	v_mfma_f32_16x16x32_bf16 v[110:113], v[176:179], v[136:139], v[110:113]
	v_mfma_f32_16x16x32_bf16 v[102:105], v[184:187], v[136:139], v[102:105]
	v_mfma_f32_16x16x32_bf16 v[126:129], v[164:167], v[140:143], v[126:129]
	v_mfma_f32_16x16x32_bf16 v[122:125], v[160:163], v[156:159], v[122:125]
	v_mfma_f32_16x16x32_bf16 v[118:121], v[172:175], v[140:143], v[118:121]
	v_mfma_f32_16x16x32_bf16 v[114:117], v[168:171], v[156:159], v[114:117]
	v_mfma_f32_16x16x32_bf16 v[110:113], v[180:183], v[140:143], v[110:113]
	v_mfma_f32_16x16x32_bf16 v[106:109], v[176:179], v[156:159], v[106:109]
	v_mfma_f32_16x16x32_bf16 v[102:105], v[188:191], v[140:143], v[102:105]
	v_mfma_f32_16x16x32_bf16 v[98:101], v[184:187], v[156:159], v[98:101]
	v_mfma_f32_16x16x32_bf16 v[192:195], v[164:167], v[146:149], v[122:125]
	v_mfma_f32_16x16x32_bf16 v[196:199], v[172:175], v[146:149], v[114:117]
	v_mfma_f32_16x16x32_bf16 v[200:203], v[180:183], v[146:149], v[106:109]
	v_mfma_f32_16x16x32_bf16 v[206:209], v[188:191], v[146:149], v[98:101]
	s_setprio 0
	s_barrier
; #define STAGE_A(P, br, kt) do { const char* _g = (const char*)(A + (long)(br) * lda + (long)(kt) * BK); \
;     __builtin_amdgcn_global_load_lds((const unsigned*)(_g + (size_t)offA0), (unsigned*)((char*)(P) + sb0), 16, 0, 0); \
;     __builtin_amdgcn_global_load_lds((const unsigned*)(_g + (size_t)lda * 128 + (size_t)offA0), (unsigned*)((char*)(P) + sb1), 16, 0, 0); } while (0)
; #define LDA(dst, b, h) for (int m = 0; m < 4; ++m) for (int k = 0; k < 2; ++k) \
;     dst[m][k] = *reinterpret_cast<const bf16x8*>((char*)SA(b, h) + lds_byte(wr * 64 + m * 16 + fr, k * 32 + fq * 8))
; #define LDB(dst, b, h) for (int n = 0; n < 2; ++n) for (int k = 0; k < 2; ++k) \
;     dst[n][k] = *reinterpret_cast<const bf16x8*>((char*)SB(b, h) + lds_byte(wc * 32 + n * 16 + fr, k * 32 + fq * 8))
; #define MMA(ai, bj, At_, Bt_) do { __builtin_amdgcn_s_setprio(1); \
;     for (int m = 0; m < 4; ++m) for (int n = 0; n < 2; ++n) for (int k = 0; k < 2; ++k) \
;       acc[ai][bj][m][n] = MFMA16(At_[m][k], Bt_[n][k], acc[ai][bj][m][n]); \
;     __builtin_amdgcn_s_setprio(0); } while (0)
; #define WAIT_V(n) asm volatile("s_waitcnt vmcnt(" #n ")" ::: "memory")
; #define WAIT_L(n) asm volatile("s_waitcnt lgkmcnt(" #n ")" ::: "memory")
; #define BAR __builtin_amdgcn_s_barrier()
; DI void gemm_core(WVP char* smem, const u16* __restrict__ A, int lda, int ar0, int ar1,
;                   const u16* __restrict__ B, int ldb, int bc0, int K, AccT& acc) {
;     ...
;   { LDB(B0, 0, 0); LDA(At, 0, 0); STAGE_A(SA(1, 1), ac1, nt - 1);
;     BAR; WAIT_L(0); MMA(0, 0, At, B0); BAR;
;     LDB(B1, 0, 1); BAR; WAIT_L(0); MMA(0, 1, At, B1); BAR;
;     LDA(At, 0, 1); WAIT_V(4); BAR; WAIT_L(0); MMA(1, 0, At, B0); MMA(1, 1, At, B1); BAR; }
;   { LDB(B0, 1, 0); LDA(At, 1, 0); WAIT_V(2); BAR; WAIT_L(0); MMA(0, 0, At, B0); BAR;
;     LDB(B1, 1, 1); WAIT_V(0); BAR; WAIT_L(0); MMA(0, 1, At, B1); BAR;
;     LDA(At, 1, 1); BAR; WAIT_L(0); MMA(1, 0, At, B0); MMA(1, 1, At, B1); BAR; }
	s_nop 1
	ds_read_b128 v[98:101], v144
	ds_read_b128 v[106:109], v144 offset:1024
	ds_read_b128 v[114:117], v144 offset:2048
	ds_read_b128 v[122:125], v144 offset:3072
	s_barrier
	s_waitcnt lgkmcnt(0)
	s_setprio 1
	s_waitcnt lgkmcnt(0)
	v_mfma_f32_16x16x32_bf16 v[94:97], v[160:163], v[98:101], v[94:97]
	v_mfma_f32_16x16x32_bf16 v[86:89], v[168:171], v[98:101], v[86:89]
	v_mfma_f32_16x16x32_bf16 v[78:81], v[176:179], v[98:101], v[78:81]
	v_mfma_f32_16x16x32_bf16 v[70:73], v[184:187], v[98:101], v[70:73]
	v_mfma_f32_16x16x32_bf16 v[94:97], v[164:167], v[106:109], v[94:97]
	v_mfma_f32_16x16x32_bf16 v[90:93], v[160:163], v[114:117], v[90:93]
	v_mfma_f32_16x16x32_bf16 v[86:89], v[172:175], v[106:109], v[86:89]
	v_mfma_f32_16x16x32_bf16 v[82:85], v[168:171], v[114:117], v[82:85]
	v_mfma_f32_16x16x32_bf16 v[78:81], v[180:183], v[106:109], v[78:81]
	v_mfma_f32_16x16x32_bf16 v[74:77], v[176:179], v[114:117], v[74:77]
	v_mfma_f32_16x16x32_bf16 v[70:73], v[188:191], v[106:109], v[70:73]
	v_mfma_f32_16x16x32_bf16 v[66:69], v[184:187], v[114:117], v[66:69]
	v_mfma_f32_16x16x32_bf16 v[160:163], v[164:167], v[122:125], v[90:93]
	v_mfma_f32_16x16x32_bf16 v[164:167], v[172:175], v[122:125], v[82:85]
	v_mfma_f32_16x16x32_bf16 v[168:171], v[180:183], v[122:125], v[74:77]
	v_mfma_f32_16x16x32_bf16 v[172:175], v[188:191], v[122:125], v[66:69]
	s_setprio 0
	s_barrier
	s_nop 1
	ds_read_b128 v[66:69], v132 offset:16384
	ds_read_b128 v[74:77], v132 offset:17408
	ds_read_b128 v[82:85], v150 offset:16384
	ds_read_b128 v[90:93], v150 offset:17408
	ds_read_b128 v[176:179], v151 offset:16384
	ds_read_b128 v[180:183], v151 offset:17408
	ds_read_b128 v[184:187], v152 offset:16384
	ds_read_b128 v[188:191], v152 offset:17408
	s_waitcnt vmcnt(4)
	s_barrier
	s_waitcnt lgkmcnt(0)
	s_setprio 1
	s_waitcnt lgkmcnt(0)
	v_mfma_f32_16x16x32_bf16 v[62:65], v[66:69], v[136:139], v[62:65]
	v_mfma_f32_16x16x32_bf16 v[54:57], v[82:85], v[136:139], v[54:57]
	v_mfma_f32_16x16x32_bf16 v[46:49], v[176:179], v[136:139], v[46:49]
	v_mfma_f32_16x16x32_bf16 v[38:41], v[184:187], v[136:139], v[38:41]
	v_mfma_f32_16x16x32_bf16 v[62:65], v[74:77], v[140:143], v[62:65]
	v_mfma_f32_16x16x32_bf16 v[58:61], v[66:69], v[156:159], v[58:61]
	v_mfma_f32_16x16x32_bf16 v[54:57], v[90:93], v[140:143], v[54:57]
	v_mfma_f32_16x16x32_bf16 v[50:53], v[82:85], v[156:159], v[50:53]
	v_mfma_f32_16x16x32_bf16 v[46:49], v[180:183], v[140:143], v[46:49]
	v_mfma_f32_16x16x32_bf16 v[42:45], v[176:179], v[156:159], v[42:45]
	v_mfma_f32_16x16x32_bf16 v[38:41], v[188:191], v[140:143], v[38:41]
	v_mfma_f32_16x16x32_bf16 v[34:37], v[184:187], v[156:159], v[34:37]
	v_mfma_f32_16x16x32_bf16 v[210:213], v[74:77], v[146:149], v[58:61]
	v_mfma_f32_16x16x32_bf16 v[214:217], v[90:93], v[146:149], v[50:53]
	v_mfma_f32_16x16x32_bf16 v[218:221], v[180:183], v[146:149], v[42:45]
	v_mfma_f32_16x16x32_bf16 v[136:139], v[188:191], v[146:149], v[34:37]
	s_setprio 0
	s_setprio 1
	v_mfma_f32_16x16x32_bf16 v[30:33], v[66:69], v[98:101], v[30:33]
	v_mfma_f32_16x16x32_bf16 v[22:25], v[82:85], v[98:101], v[22:25]
	v_mfma_f32_16x16x32_bf16 v[14:17], v[176:179], v[98:101], v[14:17]
	v_mfma_f32_16x16x32_bf16 v[6:9], v[184:187], v[98:101], v[6:9]
	v_mfma_f32_16x16x32_bf16 v[30:33], v[74:77], v[106:109], v[30:33]
	v_mfma_f32_16x16x32_bf16 v[26:29], v[66:69], v[114:117], v[26:29]
	v_mfma_f32_16x16x32_bf16 v[22:25], v[90:93], v[106:109], v[22:25]
	v_mfma_f32_16x16x32_bf16 v[18:21], v[82:85], v[114:117], v[18:21]
	v_mfma_f32_16x16x32_bf16 v[14:17], v[180:183], v[106:109], v[14:17]
	v_mfma_f32_16x16x32_bf16 v[10:13], v[176:179], v[114:117], v[10:13]
	v_mfma_f32_16x16x32_bf16 v[6:9], v[188:191], v[106:109], v[6:9]
	v_mfma_f32_16x16x32_bf16 v[2:5], v[184:187], v[114:117], v[2:5]
	v_mfma_f32_16x16x32_bf16 v[140:143], v[74:77], v[122:125], v[26:29]
	v_mfma_f32_16x16x32_bf16 v[144:147], v[90:93], v[122:125], v[18:21]
	v_mfma_f32_16x16x32_bf16 v[154:157], v[180:183], v[122:125], v[10:13]
	v_mfma_f32_16x16x32_bf16 v[176:179], v[188:191], v[122:125], v[2:5]
	s_setprio 0
	s_barrier
	ds_read_b128 v[180:183], v135
	ds_read_b128 v[184:187], v135 offset:1024
	ds_read_b128 v[188:191], v135 offset:2048
	ds_read_b128 v[222:225], v135 offset:3072
	ds_read_b128 v[2:5], v132 offset:32768
	ds_read_b128 v[10:13], v132 offset:33792
	ds_read_b128 v[18:21], v150 offset:32768
	ds_read_b128 v[26:29], v150 offset:33792
	ds_read_b128 v[226:229], v151 offset:32768
	ds_read_b128 v[230:233], v151 offset:33792
	ds_read_b128 v[234:237], v152 offset:32768
	ds_read_b128 v[238:241], v152 offset:33792
	s_waitcnt vmcnt(2)
	s_barrier
; #define LDA(dst, b, h) for (int m = 0; m < 4; ++m) for (int k = 0; k < 2; ++k) \
;     dst[m][k] = *reinterpret_cast<const bf16x8*>((char*)SA(b, h) + lds_byte(wr * 64 + m * 16 + fr, k * 32 + fq * 8))
; #define LDB(dst, b, h) for (int n = 0; n < 2; ++n) for (int k = 0; k < 2; ++k) \
;     dst[n][k] = *reinterpret_cast<const bf16x8*>((char*)SB(b, h) + lds_byte(wc * 32 + n * 16 + fr, k * 32 + fq * 8))
; #define MMA(ai, bj, At_, Bt_) do { __builtin_amdgcn_s_setprio(1); \
;     for (int m = 0; m < 4; ++m) for (int n = 0; n < 2; ++n) for (int k = 0; k < 2; ++k) \
;       acc[ai][bj][m][n] = MFMA16(At_[m][k], Bt_[n][k], acc[ai][bj][m][n]); \
;     __builtin_amdgcn_s_setprio(0); } while (0)
; #define WAIT_V(n) asm volatile("s_waitcnt vmcnt(" #n ")" ::: "memory")
; #define WAIT_L(n) asm volatile("s_waitcnt lgkmcnt(" #n ")" ::: "memory")
; #define BAR __builtin_amdgcn_s_barrier()
; DI void gemm_core(WVP char* smem, const u16* __restrict__ A, int lda, int ar0, int ar1,
;                   const u16* __restrict__ B, int ldb, int bc0, int K, AccT& acc) {
;     ...
;   { LDB(B0, 1, 0); LDA(At, 1, 0); WAIT_V(2); BAR; WAIT_L(0); MMA(0, 0, At, B0); BAR;
;     LDB(B1, 1, 1); WAIT_V(0); BAR; WAIT_L(0); MMA(0, 1, At, B1); BAR;
;     LDA(At, 1, 1); BAR; WAIT_L(0); MMA(1, 0, At, B0); MMA(1, 1, At, B1); BAR; }
;   if (wr == 0) BAR;
	s_waitcnt lgkmcnt(0)
	s_setprio 1
	s_waitcnt lgkmcnt(0)
	v_mfma_f32_16x16x32_bf16 v[34:37], v[2:5], v[180:183], v[126:129]
	v_mfma_f32_16x16x32_bf16 v[122:125], v[10:13], v[184:187], v[34:37]
	v_mfma_f32_16x16x32_bf16 v[34:37], v[2:5], v[188:191], v[192:195]
	v_mfma_f32_16x16x32_bf16 v[114:117], v[10:13], v[222:225], v[34:37]
	v_mfma_f32_16x16x32_bf16 v[34:37], v[18:21], v[180:183], v[118:121]
	v_mfma_f32_16x16x32_bf16 v[106:109], v[26:29], v[184:187], v[34:37]
	v_mfma_f32_16x16x32_bf16 v[34:37], v[18:21], v[188:191], v[196:199]
	v_mfma_f32_16x16x32_bf16 v[98:101], v[26:29], v[222:225], v[34:37]
	v_mfma_f32_16x16x32_bf16 v[34:37], v[226:229], v[180:183], v[110:113]
	v_mfma_f32_16x16x32_bf16 v[90:93], v[230:233], v[184:187], v[34:37]
	v_mfma_f32_16x16x32_bf16 v[34:37], v[226:229], v[188:191], v[200:203]
	v_mfma_f32_16x16x32_bf16 v[82:85], v[230:233], v[222:225], v[34:37]
	v_mfma_f32_16x16x32_bf16 v[34:37], v[234:237], v[180:183], v[102:105]
	v_mfma_f32_16x16x32_bf16 v[74:77], v[238:241], v[184:187], v[34:37]
	v_mfma_f32_16x16x32_bf16 v[34:37], v[234:237], v[188:191], v[206:209]
	v_mfma_f32_16x16x32_bf16 v[66:69], v[238:241], v[222:225], v[34:37]
	s_setprio 0
	s_barrier
	ds_read_b128 v[192:195], v133
	ds_read_b128 v[196:199], v133 offset:1024
	ds_read_b128 v[200:203], v133 offset:2048
	ds_read_b128 v[206:209], v133 offset:3072
	s_waitcnt vmcnt(0)
	s_barrier
	s_waitcnt lgkmcnt(0)
	s_setprio 1
	s_waitcnt lgkmcnt(0)
	v_mfma_f32_16x16x32_bf16 v[34:37], v[2:5], v[192:195], v[94:97]
	v_mfma_f32_16x16x32_bf16 v[2:5], v[2:5], v[200:203], v[160:163]
	v_mfma_f32_16x16x32_bf16 v[50:53], v[10:13], v[206:209], v[2:5]
	v_mfma_f32_16x16x32_bf16 v[2:5], v[18:21], v[192:195], v[86:89]
	v_mfma_f32_16x16x32_bf16 v[42:45], v[26:29], v[196:199], v[2:5]
	v_mfma_f32_16x16x32_bf16 v[2:5], v[18:21], v[200:203], v[164:167]
	v_mfma_f32_16x16x32_bf16 v[58:61], v[10:13], v[196:199], v[34:37]
	v_mfma_f32_16x16x32_bf16 v[34:37], v[26:29], v[206:209], v[2:5]
	v_mfma_f32_16x16x32_bf16 v[2:5], v[226:229], v[192:195], v[78:81]
	v_mfma_f32_16x16x32_bf16 v[26:29], v[230:233], v[196:199], v[2:5]
	v_mfma_f32_16x16x32_bf16 v[2:5], v[226:229], v[200:203], v[168:171]
	v_mfma_f32_16x16x32_bf16 v[18:21], v[230:233], v[206:209], v[2:5]
	v_mfma_f32_16x16x32_bf16 v[2:5], v[234:237], v[192:195], v[70:73]
	v_mfma_f32_16x16x32_bf16 v[10:13], v[238:241], v[196:199], v[2:5]
	v_mfma_f32_16x16x32_bf16 v[2:5], v[234:237], v[200:203], v[172:175]
	v_mfma_f32_16x16x32_bf16 v[2:5], v[238:241], v[206:209], v[2:5]
	s_setprio 0
	s_barrier
	ds_read_b128 v[158:161], v132 offset:49152
	ds_read_b128 v[130:133], v132 offset:50176
	ds_read_b128 v[162:165], v150 offset:49152
	ds_read_b128 v[166:169], v150 offset:50176
	ds_read_b128 v[170:173], v151 offset:49152
	ds_read_b128 v[148:151], v151 offset:50176
	ds_read_b128 v[226:229], v152 offset:49152
	ds_read_b128 v[230:233], v152 offset:50176
	s_barrier
	s_waitcnt lgkmcnt(0)
	s_setprio 1
	s_waitcnt lgkmcnt(0)
	v_mfma_f32_16x16x32_bf16 v[62:65], v[158:161], v[180:183], v[62:65]
	v_mfma_f32_16x16x32_bf16 v[54:57], v[162:165], v[180:183], v[54:57]
	v_mfma_f32_16x16x32_bf16 v[46:49], v[170:173], v[180:183], v[46:49]
	v_mfma_f32_16x16x32_bf16 v[38:41], v[226:229], v[180:183], v[38:41]
	v_mfma_f32_16x16x32_bf16 v[126:129], v[130:133], v[184:187], v[62:65]
	v_mfma_f32_16x16x32_bf16 v[62:65], v[158:161], v[188:191], v[210:213]
	v_mfma_f32_16x16x32_bf16 v[110:113], v[166:169], v[184:187], v[54:57]
	v_mfma_f32_16x16x32_bf16 v[54:57], v[162:165], v[188:191], v[214:217]
	v_mfma_f32_16x16x32_bf16 v[94:97], v[148:151], v[184:187], v[46:49]
	v_mfma_f32_16x16x32_bf16 v[46:49], v[170:173], v[188:191], v[218:221]
	v_mfma_f32_16x16x32_bf16 v[78:81], v[230:233], v[184:187], v[38:41]
	v_mfma_f32_16x16x32_bf16 v[38:41], v[226:229], v[188:191], v[136:139]
	v_mfma_f32_16x16x32_bf16 v[118:121], v[130:133], v[222:225], v[62:65]
	v_mfma_f32_16x16x32_bf16 v[102:105], v[166:169], v[222:225], v[54:57]
	v_mfma_f32_16x16x32_bf16 v[86:89], v[148:151], v[222:225], v[46:49]
	v_mfma_f32_16x16x32_bf16 v[70:73], v[230:233], v[222:225], v[38:41]
	s_setprio 0
	s_setprio 1
	v_mfma_f32_16x16x32_bf16 v[30:33], v[158:161], v[192:195], v[30:33]
	v_mfma_f32_16x16x32_bf16 v[62:65], v[130:133], v[196:199], v[30:33]
	v_mfma_f32_16x16x32_bf16 v[30:33], v[158:161], v[200:203], v[140:143]
	v_mfma_f32_16x16x32_bf16 v[22:25], v[162:165], v[192:195], v[22:25]
	v_mfma_f32_16x16x32_bf16 v[14:17], v[170:173], v[192:195], v[14:17]
	v_mfma_f32_16x16x32_bf16 v[54:57], v[130:133], v[206:209], v[30:33]
	v_mfma_f32_16x16x32_bf16 v[46:49], v[166:169], v[196:199], v[22:25]
	v_mfma_f32_16x16x32_bf16 v[22:25], v[162:165], v[200:203], v[144:147]
	v_mfma_f32_16x16x32_bf16 v[30:33], v[148:151], v[196:199], v[14:17]
	v_mfma_f32_16x16x32_bf16 v[14:17], v[170:173], v[200:203], v[154:157]
	v_mfma_f32_16x16x32_bf16 v[6:9], v[226:229], v[192:195], v[6:9]
	v_mfma_f32_16x16x32_bf16 v[38:41], v[166:169], v[206:209], v[22:25]
	v_mfma_f32_16x16x32_bf16 v[22:25], v[148:151], v[206:209], v[14:17]
	v_mfma_f32_16x16x32_bf16 v[14:17], v[230:233], v[196:199], v[6:9]
	v_mfma_f32_16x16x32_bf16 v[6:9], v[226:229], v[200:203], v[176:179]
	v_mfma_f32_16x16x32_bf16 v[6:9], v[230:233], v[206:209], v[6:9]
	s_setprio 0
	s_cmp_gt_u32 s47, 3
	s_barrier
	s_cbranch_scc1 .LBB0_213
	s_barrier
	s_branch .LBB0_213

; DI int get_tid(int wv) { int l; asm volatile("v_mbcnt_lo_u32_b32 %0, -1, 0\n\tv_mbcnt_hi_u32_b32 %0, -1, %0" : "=v"(l)); return wv * 64 + l; }
; DI int wave_of(int tid) { return __builtin_amdgcn_readfirstlane(tid >> 6); }
; #define STAGE_A(P, br, kt) do { const char* _g = (const char*)(A + (long)(br) * lda + (long)(kt) * BK); \
;     __builtin_amdgcn_global_load_lds((const unsigned*)(_g + (size_t)offA0), (unsigned*)((char*)(P) + sb0), 16, 0, 0); \
;     __builtin_amdgcn_global_load_lds((const unsigned*)(_g + (size_t)lda * 128 + (size_t)offA0), (unsigned*)((char*)(P) + sb1), 16, 0, 0); } while (0)
; #define STAGE_B(P, br, kt) do { const char* _g = (const char*)(B + (long)(br) * ldb + (long)(kt) * BK); \
;     __builtin_amdgcn_global_load_lds((const unsigned*)(_g + (size_t)offB0), (unsigned*)((char*)(P) + sb0), 16, 0, 0); \
;     __builtin_amdgcn_global_load_lds((const unsigned*)(_g + (size_t)ldb * 128 + (size_t)offB0), (unsigned*)((char*)(P) + sb1), 16, 0, 0); } while (0)
; #define BAR __builtin_amdgcn_s_barrier()
; DI void gemm_core(WVP char* smem, const u16* __restrict__ A, int lda, int ar0, int ar1,
;                   const u16* __restrict__ B, int ldb, int bc0, int K, AccT& acc) {
;     ...
;   const int tid = get_tid(WV);
;   const int wid = wave_of(tid), lane = tid & 63, wr = wid >> 2, wc = wid & 3, fr = lane & 15, fq = lane >> 4;
;   const int sb0 = tid * 16, sb1 = sb0 + 8192;
;   int R0, C0; stage_rc(sb0, R0, C0);
;   const unsigned offA0 = (unsigned)(R0 * lda + C0) * 2u, offB0 = (unsigned)(R0 * ldb + C0) * 2u;
;   const int ac0 = ar0, ac1 = ar1, bb0 = bc0, bb1 = bc0 + HALF;
;   bf16x8 At[4][2], B0[2][2], B1[2][2];
;   const int nt = K / BK;
;   __syncthreads();
;   STAGE_B(SB(0, 0), bb0, 0); STAGE_A(SA(0, 0), ac0, 0);
;   STAGE_B(SB(0, 1), bb1, 0); STAGE_A(SA(0, 1), ac1, 0);
;   if (wr == 1) BAR;
; __global__ void __launch_bounds__(NTHR) mega(Params p) {
;     ...
;           for (int b = 0; b < 4; ++b) {
;             const int Kb = (b == 1) ? 256 : 512, ldy = (b == 0) ? 512 : INW;
;             const u16* yb = (b == 0) ? pb : proj + (b == 1 ? O1 : (b == 2 ? O2 : O2 + 512));
;             const u16* wb = WB + DM * (b == 0 ? 0 : (b == 1 ? 512 : (b == 2 ? 768 : 1280)));
;             gemm_core(WV, smem, wb, Kb, pr * 256, pr * 256 + 128, yb, ldy, pc * 256, Kb, acc);
.LBB0_234:
	s_cmp_eq_u32 s34, 2
	s_movk_i32 s0, 0xd00
	s_cselect_b32 s1, 0xb00, s0
	s_cmp_eq_u32 s34, 1
	s_movk_i32 s0, 0x200
	s_cselect_b32 s0, 0x100, s0
	s_cselect_b32 s1, 0x200, s1
	s_cselect_b32 s30, 8, 9
	s_cmp_eq_u32 s34, 2
	s_mov_b32 s24, 0xc0000
	s_cselect_b32 s24, s24, 0x140000
	s_cmp_lg_u32 s34, 2
	s_cselect_b64 s[26:27], -1, 0
	s_lshl_b32 s1, s1, 1
	s_add_u32 s1, s54, s1
	s_addc_u32 s25, s55, 0
	s_cmp_eq_u32 s34, 0
	s_movk_i32 s28, 0x1300
	v_mbcnt_lo_u32_b32 v142, -1, 0
	v_mbcnt_hi_u32_b32 v142, -1, v142
	s_cselect_b32 s41, 0x200, s28
	v_add_u32_e32 v0, s3, v142
	s_cselect_b32 s40, s67, s25
	s_cselect_b32 s42, s66, s1
	s_cselect_b32 s1, 0, 0x80000
	s_cmp_lt_u32 s34, 2
	v_ashrrev_i32_e32 v130, 31, v0
	s_cselect_b32 s1, s1, s24
	v_lshrrev_b32_e32 v130, 26, v130
	s_lshl_b32 s43, s1, 1
	v_readfirstlane_b32 s1, v0
	v_lshlrev_b32_e32 v150, 4, v0
	v_add_u32_e32 v130, v0, v130
	v_bfe_i32 v0, v0, 27, 1
	v_lshrrev_b32_e32 v0, 22, v0
	v_add_u32_e32 v0, v150, v0
	v_and_b32_e32 v0, 0xfffffc00, v0
	v_sub_u32_e32 v0, v150, v0
	v_lshrrev_b32_e32 v131, 4, v0
	v_bitop3_b32 v0, v131, v0, 32 bitop3:0x6c
	v_ashrrev_i32_e32 v132, 31, v0
	v_ashrrev_i32_e32 v130, 6, v130
	v_lshrrev_b32_e32 v132, 26, v132
	v_lshlrev_b32_e32 v131, 3, v130
	v_add_u32_e32 v132, v0, v132
	v_lshlrev_b32_e32 v130, 5, v130
	v_readlane_b32 s24, v255, 35
	v_and_b32_e32 v143, 32, v130
	v_and_b32_e32 v130, 0xc0, v132
	v_readlane_b32 s25, v255, 36
	s_add_u32 s35, s24, s43
	v_sub_u32_e32 v0, v0, v130
	s_addc_u32 s38, s25, 0
	v_and_b32_e32 v131, -16, v131
	v_ashrrev_i32_e32 v133, 6, v132
	v_ashrrev_i16_sdwa v0, v254, sext(v0) dst_sel:DWORD dst_unused:UNUSED_PAD src0_sel:DWORD src1_sel:BYTE_0
	s_mul_hi_i32 s25, s41, s12
	s_mul_i32 s24, s41, s12
	s_ashr_i32 s37, s1, 8
	v_add_u32_e32 v131, v133, v131
	v_bfe_i32 v144, v0, 0, 16
	s_lshl_b64 s[24:25], s[24:25], 1
	v_add_u32_e32 v146, s5, v150
	v_add_u32_e32 v151, 0x2000, v150
	v_add_u32_e32 v130, v143, v144
	v_mul_lo_u32 v145, v131, s41
	s_add_u32 s24, s42, s24
	v_readfirstlane_b32 s28, v146
	v_lshlrev_b32_e32 v0, s30, v131
	v_add_lshl_u32 v152, v130, v145, 1
	s_addc_u32 s25, s40, s25
	v_mov_b32_e32 v153, v1
	s_mov_b32 m0, s28
	s_lshl_b32 s31, s41, 7
	v_add_u32_e32 v134, s5, v151
	v_add_lshl_u32 v0, v130, v0, 1
	s_waitcnt vmcnt(0)
	s_barrier
	v_lshl_add_u64 v[130:131], s[24:25], 0, v[152:153]
	global_load_lds_dwordx4 v152, s[24:25]
	s_add_u32 s24, s24, s31
	v_readfirstlane_b32 s28, v134
	s_addc_u32 s25, s25, 0
	s_mov_b32 m0, s28
	v_lshl_add_u64 v[132:133], s[24:25], 0, v[152:153]
	global_load_lds_dwordx4 v152, s[24:25]
	s_lshl_b64 s[24:25], s[16:17], s30
	s_lshl_b64 s[28:29], s[24:25], 1
	v_add_u32_e32 v147, 0, v150
	s_add_u32 s24, s35, s28
	v_readfirstlane_b32 s36, v147
	s_addc_u32 s25, s38, s29
	s_mov_b32 m0, s36
	s_lshl_b32 s36, s0, 7
	v_add_u32_e32 v148, 0x2000, v147
	v_lshl_add_u64 v[134:135], s[24:25], 0, v[0:1]
	global_load_lds_dwordx4 v0, s[24:25]
	s_add_u32 s24, s24, s36
	v_readfirstlane_b32 s39, v148
	s_addc_u32 s25, s25, 0
	s_mov_b32 m0, s39
	v_lshl_add_u64 v[136:137], s[24:25], 0, v[0:1]
	global_load_lds_dwordx4 v0, s[24:25]
	s_mul_hi_i32 s25, s41, s20
	s_mul_i32 s24, s41, s20
	s_lshl_b64 s[24:25], s[24:25], 1
	v_add_u32_e32 v149, s60, v150
	s_add_u32 s24, s42, s24
	v_readfirstlane_b32 s39, v149
	s_addc_u32 s25, s40, s25
	s_mov_b32 m0, s39
	v_add_u32_e32 v151, s60, v151
	v_lshl_add_u64 v[138:139], s[24:25], 0, v[152:153]
	global_load_lds_dwordx4 v152, s[24:25]
	s_add_u32 s24, s24, s31
	v_readfirstlane_b32 s31, v151
	s_addc_u32 s25, s25, 0
	s_mov_b32 m0, s31
	v_lshl_add_u64 v[140:141], s[24:25], 0, v[152:153]
	global_load_lds_dwordx4 v152, s[24:25]
	s_lshl_b64 s[24:25], s[18:19], s30
	s_lshl_b64 s[30:31], s[24:25], 1
	s_add_u32 s24, s35, s30
	v_add_u32_e32 v151, 0x4000, v147
	s_addc_u32 s25, s38, s31
	v_readfirstlane_b32 s35, v151
	v_add_u32_e32 v152, 0x6000, v147
	s_mov_b32 m0, s35
	s_add_u32 s38, s24, s36
	v_readfirstlane_b32 s35, v152
	global_load_lds_dwordx4 v0, s[24:25]
	s_addc_u32 s39, s25, 0
	s_mov_b32 m0, s35
	s_cmp_lg_u32 s37, 1
	global_load_lds_dwordx4 v0, s[38:39]
	s_cbranch_scc1 .LBB0_236
	s_setprio 1
	s_barrier

; #define STAGE_A(P, br, kt) do { const char* _g = (const char*)(A + (long)(br) * lda + (long)(kt) * BK); \
;     __builtin_amdgcn_global_load_lds((const unsigned*)(_g + (size_t)offA0), (unsigned*)((char*)(P) + sb0), 16, 0, 0); \
;     __builtin_amdgcn_global_load_lds((const unsigned*)(_g + (size_t)lda * 128 + (size_t)offA0), (unsigned*)((char*)(P) + sb1), 16, 0, 0); } while (0)
; #define STAGE_B(P, br, kt) do { const char* _g = (const char*)(B + (long)(br) * ldb + (long)(kt) * BK); \
;     __builtin_amdgcn_global_load_lds((const unsigned*)(_g + (size_t)offB0), (unsigned*)((char*)(P) + sb0), 16, 0, 0); \
;     __builtin_amdgcn_global_load_lds((const unsigned*)(_g + (size_t)ldb * 128 + (size_t)offB0), (unsigned*)((char*)(P) + sb1), 16, 0, 0); } while (0)
; #define LDA(dst, b, h) for (int m = 0; m < 4; ++m) for (int k = 0; k < 2; ++k) \
;     dst[m][k] = *reinterpret_cast<const bf16x8*>((char*)SA(b, h) + lds_byte(wr * 64 + m * 16 + fr, k * 32 + fq * 8))
; #define LDB(dst, b, h) for (int n = 0; n < 2; ++n) for (int k = 0; k < 2; ++k) \
;     dst[n][k] = *reinterpret_cast<const bf16x8*>((char*)SB(b, h) + lds_byte(wc * 32 + n * 16 + fr, k * 32 + fq * 8))
; #define WAIT_V(n) asm volatile("s_waitcnt vmcnt(" #n ")" ::: "memory")
; #define WAIT_L(n) asm volatile("s_waitcnt lgkmcnt(" #n ")" ::: "memory")
; DI void gemm_core(WVP char* smem, const u16* __restrict__ A, int lda, int ar0, int ar1,
;                   const u16* __restrict__ B, int ldb, int bc0, int K, AccT& acc) {
;     ...
;   for (int t = 0; t < nt - 2; t += 2) {
;     LDB(B0, 0, 0); SCHED; LDA(At, 0, 0); STAGE_A(SA(1, 1), ac1, t + 1);
;     WAIT_L(8); BAR; WAIT_L(0); MMA(0, 0, At, B0); BAR; SCHED;
;     LDB(B1, 0, 1); STAGE_B(SB(0, 0), bb0, t + 2);
;     BAR; WAIT_L(0); MMA(0, 1, At, B1); BAR;
;     LDA(At, 0, 1); STAGE_A(SA(0, 0), ac0, t + 2);
;     BAR; WAIT_L(0); MMA(1, 0, At, B0); BAR; SCHED;
;     STAGE_B(SB(0, 1), bb1, t + 2);
;     WAIT_V(6); BAR; MMA(1, 1, At, B1); BAR;
;     LDB(B0, 1, 0); SCHED; LDA(At, 1, 0); STAGE_A(SA(0, 1), ac1, t + 2);
;     WAIT_L(8); BAR; WAIT_L(0); MMA(0, 0, At, B0); BAR; SCHED;
;     LDB(B1, 1, 1); STAGE_B(SB(1, 0), bb0, t + 3);
;     BAR; WAIT_L(0); MMA(0, 1, At, B1); BAR;
;     LDA(At, 1, 1); STAGE_A(SA(1, 0), ac0, t + 3);
;     BAR; WAIT_L(0); MMA(1, 0, At, B0); BAR; SCHED;
;     STAGE_B(SB(1, 1), bb1, t + 3);
;     WAIT_V(6); BAR; MMA(1, 1, At, B1); BAR;
;   }
.LBB0_237:
	v_add_u32_e32 v164, s37, v161
	v_add_u32_e32 v165, s38, v161
	v_add_u32_e32 v166, s39, v161
	ds_read_b128 v[170:173], v163
	ds_read_b128 v[174:177], v163 offset:1024
	ds_read_b128 v[178:181], v163 offset:2048
	ds_read_b128 v[182:185], v163 offset:3072
	ds_read_b128 v[186:189], v150
	ds_read_b128 v[190:193], v150 offset:1024
	ds_read_b128 v[194:197], v164
	ds_read_b128 v[198:201], v164 offset:1024
	ds_read_b128 v[206:209], v165
	ds_read_b128 v[210:213], v165 offset:1024
	ds_read_b128 v[214:217], v166
	ds_read_b128 v[218:221], v166 offset:1024
	ds_read_b128 v[222:225], v162
	ds_read_b128 v[226:229], v162 offset:1024
	ds_read_b128 v[230:233], v162 offset:2048
	ds_read_b128 v[234:237], v162 offset:3072
	v_add_u32_e32 v168, 0xc000, v147
	v_lshl_add_u64 v[238:239], v[142:143], 0, s[28:29]
	v_lshl_add_u64 v[202:203], v[238:239], 0, s[6:7]
	v_readfirstlane_b32 s31, v168
	s_mov_b32 m0, s31
	s_nop 0
	global_load_lds_dwordx4 v[202:203], off
	v_add_u32_e32 v167, 0xe000, v147
	v_lshl_add_u64 v[238:239], v[144:145], 0, s[28:29]
	v_lshl_add_u64 v[202:203], v[238:239], 0, s[6:7]
	v_readfirstlane_b32 s31, v167
	s_mov_b32 m0, s31
	s_nop 0
	global_load_lds_dwordx4 v[202:203], off
	s_waitcnt vmcnt(8)
	s_waitcnt lgkmcnt(0)
	s_barrier
	v_mfma_f32_16x16x32_bf16 v[126:129], v[186:189], v[170:173], v[126:129]
	v_mfma_f32_16x16x32_bf16 v[118:121], v[186:189], v[178:181], v[118:121]
	v_mfma_f32_16x16x32_bf16 v[110:113], v[194:197], v[170:173], v[110:113]
	v_mfma_f32_16x16x32_bf16 v[102:105], v[194:197], v[178:181], v[102:105]
	v_mfma_f32_16x16x32_bf16 v[98:101], v[206:209], v[170:173], v[98:101]
	v_mfma_f32_16x16x32_bf16 v[86:89], v[206:209], v[178:181], v[86:89]
	v_mfma_f32_16x16x32_bf16 v[78:81], v[214:217], v[170:173], v[78:81]
	v_mfma_f32_16x16x32_bf16 v[70:73], v[214:217], v[178:181], v[70:73]
	v_mfma_f32_16x16x32_bf16 v[126:129], v[190:193], v[174:177], v[126:129]
	v_mfma_f32_16x16x32_bf16 v[118:121], v[190:193], v[182:185], v[118:121]
	v_mfma_f32_16x16x32_bf16 v[110:113], v[198:201], v[174:177], v[110:113]
	v_mfma_f32_16x16x32_bf16 v[102:105], v[198:201], v[182:185], v[102:105]
	v_mfma_f32_16x16x32_bf16 v[98:101], v[210:213], v[174:177], v[98:101]
	v_mfma_f32_16x16x32_bf16 v[86:89], v[210:213], v[182:185], v[86:89]
	v_mfma_f32_16x16x32_bf16 v[78:81], v[218:221], v[174:177], v[78:81]
	v_mfma_f32_16x16x32_bf16 v[70:73], v[218:221], v[182:185], v[70:73]
	v_mfma_f32_16x16x32_bf16 v[66:69], v[186:189], v[222:225], v[66:69]
	v_mfma_f32_16x16x32_bf16 v[54:57], v[186:189], v[230:233], v[54:57]
	v_mfma_f32_16x16x32_bf16 v[46:49], v[194:197], v[222:225], v[46:49]
	v_mfma_f32_16x16x32_bf16 v[38:41], v[194:197], v[230:233], v[38:41]
	v_mfma_f32_16x16x32_bf16 v[34:37], v[206:209], v[222:225], v[34:37]
	v_mfma_f32_16x16x32_bf16 v[22:25], v[206:209], v[230:233], v[22:25]
	v_mfma_f32_16x16x32_bf16 v[14:17], v[214:217], v[222:225], v[14:17]
	v_mfma_f32_16x16x32_bf16 v[6:9], v[214:217], v[230:233], v[6:9]
	v_mfma_f32_16x16x32_bf16 v[66:69], v[190:193], v[226:229], v[66:69]
	v_mfma_f32_16x16x32_bf16 v[54:57], v[190:193], v[234:237], v[54:57]
	v_mfma_f32_16x16x32_bf16 v[46:49], v[198:201], v[226:229], v[46:49]
	v_mfma_f32_16x16x32_bf16 v[38:41], v[198:201], v[234:237], v[38:41]
	v_mfma_f32_16x16x32_bf16 v[34:37], v[210:213], v[226:229], v[34:37]
	v_mfma_f32_16x16x32_bf16 v[22:25], v[210:213], v[234:237], v[22:25]
	v_mfma_f32_16x16x32_bf16 v[14:17], v[218:221], v[226:229], v[14:17]
	v_mfma_f32_16x16x32_bf16 v[6:9], v[218:221], v[234:237], v[6:9]
	s_barrier
	ds_read_b128 v[186:189], v150 offset:16384
	ds_read_b128 v[190:193], v150 offset:17408
	ds_read_b128 v[194:197], v164 offset:16384
	ds_read_b128 v[198:201], v164 offset:17408
	ds_read_b128 v[206:209], v165 offset:16384
	ds_read_b128 v[210:213], v165 offset:17408
	ds_read_b128 v[214:217], v166 offset:16384
	ds_read_b128 v[218:221], v166 offset:17408
	v_lshl_add_u64 v[238:239], v[130:131], 0, s[28:29]
	v_lshl_add_u64 v[202:203], v[238:239], 0, s[68:69]
	v_readfirstlane_b32 s31, v146
	s_mov_b32 m0, s31
	s_nop 0
	global_load_lds_dwordx4 v[202:203], off
	v_add_u32_e32 v169, 0x2000, v146
	v_lshl_add_u64 v[238:239], v[132:133], 0, s[28:29]
	v_lshl_add_u64 v[202:203], v[238:239], 0, s[68:69]
	v_readfirstlane_b32 s31, v169
	s_mov_b32 m0, s31
	s_nop 0
	global_load_lds_dwordx4 v[202:203], off
	v_lshl_add_u64 v[238:239], v[134:135], 0, s[28:29]
	v_lshl_add_u64 v[202:203], v[238:239], 0, s[48:49]
	v_readfirstlane_b32 s31, v147
	s_mov_b32 m0, s31
	s_nop 0
	global_load_lds_dwordx4 v[202:203], off
	v_lshl_add_u64 v[238:239], v[136:137], 0, s[28:29]
	v_lshl_add_u64 v[202:203], v[238:239], 0, s[48:49]
	v_readfirstlane_b32 s31, v148
	s_mov_b32 m0, s31
	s_nop 0
	global_load_lds_dwordx4 v[202:203], off
	v_lshl_add_u64 v[238:239], v[138:139], 0, s[28:29]
	v_lshl_add_u64 v[202:203], v[238:239], 0, s[68:69]
	v_readfirstlane_b32 s31, v149
	s_mov_b32 m0, s31
	s_nop 0
	global_load_lds_dwordx4 v[202:203], off
	v_add_u32_e32 v169, 0x2000, v149
	v_lshl_add_u64 v[238:239], v[140:141], 0, s[28:29]
	v_lshl_add_u64 v[202:203], v[238:239], 0, s[68:69]
	v_readfirstlane_b32 s31, v169
	s_mov_b32 m0, s31
	s_nop 0
	global_load_lds_dwordx4 v[202:203], off
	s_waitcnt vmcnt(8)
	s_waitcnt lgkmcnt(0)
	s_barrier
; #define STAGE_A(P, br, kt) do { const char* _g = (const char*)(A + (long)(br) * lda + (long)(kt) * BK); \
;     __builtin_amdgcn_global_load_lds((const unsigned*)(_g + (size_t)offA0), (unsigned*)((char*)(P) + sb0), 16, 0, 0); \
;     __builtin_amdgcn_global_load_lds((const unsigned*)(_g + (size_t)lda * 128 + (size_t)offA0), (unsigned*)((char*)(P) + sb1), 16, 0, 0); } while (0)
; #define STAGE_B(P, br, kt) do { const char* _g = (const char*)(B + (long)(br) * ldb + (long)(kt) * BK); \
;     __builtin_amdgcn_global_load_lds((const unsigned*)(_g + (size_t)offB0), (unsigned*)((char*)(P) + sb0), 16, 0, 0); \
;     __builtin_amdgcn_global_load_lds((const unsigned*)(_g + (size_t)ldb * 128 + (size_t)offB0), (unsigned*)((char*)(P) + sb1), 16, 0, 0); } while (0)
; #define LDA(dst, b, h) for (int m = 0; m < 4; ++m) for (int k = 0; k < 2; ++k) \
;     dst[m][k] = *reinterpret_cast<const bf16x8*>((char*)SA(b, h) + lds_byte(wr * 64 + m * 16 + fr, k * 32 + fq * 8))
; #define LDB(dst, b, h) for (int n = 0; n < 2; ++n) for (int k = 0; k < 2; ++k) \
;     dst[n][k] = *reinterpret_cast<const bf16x8*>((char*)SB(b, h) + lds_byte(wc * 32 + n * 16 + fr, k * 32 + fq * 8))
; #define WAIT_V(n) asm volatile("s_waitcnt vmcnt(" #n ")" ::: "memory")
; #define WAIT_L(n) asm volatile("s_waitcnt lgkmcnt(" #n ")" ::: "memory")
; DI void gemm_core(WVP char* smem, const u16* __restrict__ A, int lda, int ar0, int ar1,
;                   const u16* __restrict__ B, int ldb, int bc0, int K, AccT& acc) {
;     ...
;   for (int t = 0; t < nt - 2; t += 2) {
;     LDB(B0, 0, 0); SCHED; LDA(At, 0, 0); STAGE_A(SA(1, 1), ac1, t + 1);
;     WAIT_L(8); BAR; WAIT_L(0); MMA(0, 0, At, B0); BAR; SCHED;
;     LDB(B1, 0, 1); STAGE_B(SB(0, 0), bb0, t + 2);
;     BAR; WAIT_L(0); MMA(0, 1, At, B1); BAR;
;     LDA(At, 0, 1); STAGE_A(SA(0, 0), ac0, t + 2);
;     BAR; WAIT_L(0); MMA(1, 0, At, B0); BAR; SCHED;
;     STAGE_B(SB(0, 1), bb1, t + 2);
;     WAIT_V(6); BAR; MMA(1, 1, At, B1); BAR;
;     LDB(B0, 1, 0); SCHED; LDA(At, 1, 0); STAGE_A(SA(0, 1), ac1, t + 2);
;     WAIT_L(8); BAR; WAIT_L(0); MMA(0, 0, At, B0); BAR; SCHED;
;     LDB(B1, 1, 1); STAGE_B(SB(1, 0), bb0, t + 3);
;     BAR; WAIT_L(0); MMA(0, 1, At, B1); BAR;
;     LDA(At, 1, 1); STAGE_A(SA(1, 0), ac0, t + 3);
;     BAR; WAIT_L(0); MMA(1, 0, At, B0); BAR; SCHED;
;     STAGE_B(SB(1, 1), bb1, t + 3);
;     WAIT_V(6); BAR; MMA(1, 1, At, B1); BAR;
;   }
	v_mfma_f32_16x16x32_bf16 v[122:125], v[186:189], v[170:173], v[122:125]
	v_mfma_f32_16x16x32_bf16 v[114:117], v[186:189], v[178:181], v[114:117]
	v_mfma_f32_16x16x32_bf16 v[106:109], v[194:197], v[170:173], v[106:109]
	v_mfma_f32_16x16x32_bf16 v[94:97], v[194:197], v[178:181], v[94:97]
	v_mfma_f32_16x16x32_bf16 v[90:93], v[206:209], v[170:173], v[90:93]
	v_mfma_f32_16x16x32_bf16 v[82:85], v[206:209], v[178:181], v[82:85]
	v_mfma_f32_16x16x32_bf16 v[74:77], v[214:217], v[170:173], v[74:77]
	v_mfma_f32_16x16x32_bf16 v[62:65], v[214:217], v[178:181], v[62:65]
	v_mfma_f32_16x16x32_bf16 v[122:125], v[190:193], v[174:177], v[122:125]
	v_mfma_f32_16x16x32_bf16 v[114:117], v[190:193], v[182:185], v[114:117]
	v_mfma_f32_16x16x32_bf16 v[106:109], v[198:201], v[174:177], v[106:109]
	v_mfma_f32_16x16x32_bf16 v[94:97], v[198:201], v[182:185], v[94:97]
	v_mfma_f32_16x16x32_bf16 v[90:93], v[210:213], v[174:177], v[90:93]
	v_mfma_f32_16x16x32_bf16 v[82:85], v[210:213], v[182:185], v[82:85]
	v_mfma_f32_16x16x32_bf16 v[74:77], v[218:221], v[174:177], v[74:77]
	v_mfma_f32_16x16x32_bf16 v[62:65], v[218:221], v[182:185], v[62:65]
	v_mfma_f32_16x16x32_bf16 v[58:61], v[186:189], v[222:225], v[58:61]
	v_mfma_f32_16x16x32_bf16 v[50:53], v[186:189], v[230:233], v[50:53]
	v_mfma_f32_16x16x32_bf16 v[42:45], v[194:197], v[222:225], v[42:45]
	v_mfma_f32_16x16x32_bf16 v[30:33], v[194:197], v[230:233], v[30:33]
	v_mfma_f32_16x16x32_bf16 v[26:29], v[206:209], v[222:225], v[26:29]
	v_mfma_f32_16x16x32_bf16 v[18:21], v[206:209], v[230:233], v[18:21]
	v_mfma_f32_16x16x32_bf16 v[10:13], v[214:217], v[222:225], v[10:13]
	v_mfma_f32_16x16x32_bf16 v[2:5], v[214:217], v[230:233], v[2:5]
	v_mfma_f32_16x16x32_bf16 v[58:61], v[190:193], v[226:229], v[58:61]
	v_mfma_f32_16x16x32_bf16 v[50:53], v[190:193], v[234:237], v[50:53]
	v_mfma_f32_16x16x32_bf16 v[42:45], v[198:201], v[226:229], v[42:45]
	v_mfma_f32_16x16x32_bf16 v[30:33], v[198:201], v[234:237], v[30:33]
	v_mfma_f32_16x16x32_bf16 v[26:29], v[210:213], v[226:229], v[26:29]
	v_mfma_f32_16x16x32_bf16 v[18:21], v[210:213], v[234:237], v[18:21]
	v_mfma_f32_16x16x32_bf16 v[10:13], v[218:221], v[226:229], v[10:13]
	v_mfma_f32_16x16x32_bf16 v[2:5], v[218:221], v[234:237], v[2:5]
	s_barrier
	ds_read_b128 v[170:173], v154
	ds_read_b128 v[174:177], v154 offset:1024
	ds_read_b128 v[178:181], v154 offset:2048
	ds_read_b128 v[182:185], v154 offset:3072
	ds_read_b128 v[186:189], v150 offset:32768
	ds_read_b128 v[190:193], v150 offset:33792
	ds_read_b128 v[194:197], v164 offset:32768
	ds_read_b128 v[198:201], v164 offset:33792
	ds_read_b128 v[206:209], v165 offset:32768
	ds_read_b128 v[210:213], v165 offset:33792
	ds_read_b128 v[214:217], v166 offset:32768
	ds_read_b128 v[218:221], v166 offset:33792
	ds_read_b128 v[222:225], v153
	ds_read_b128 v[226:229], v153 offset:1024
	ds_read_b128 v[230:233], v153 offset:2048
	ds_read_b128 v[234:237], v153 offset:3072
	v_lshl_add_u64 v[238:239], v[142:143], 0, s[28:29]
	v_lshl_add_u64 v[202:203], v[238:239], 0, s[48:49]
	v_readfirstlane_b32 s31, v151
	s_mov_b32 m0, s31
	s_nop 0
	global_load_lds_dwordx4 v[202:203], off
	v_lshl_add_u64 v[238:239], v[144:145], 0, s[28:29]
	v_lshl_add_u64 v[202:203], v[238:239], 0, s[48:49]
	v_readfirstlane_b32 s31, v152
	s_mov_b32 m0, s31
	s_nop 0
	global_load_lds_dwordx4 v[202:203], off
	s_waitcnt vmcnt(8)
	s_waitcnt lgkmcnt(0)
	s_barrier
	v_mfma_f32_16x16x32_bf16 v[126:129], v[186:189], v[170:173], v[126:129]
	v_mfma_f32_16x16x32_bf16 v[118:121], v[186:189], v[178:181], v[118:121]
	v_mfma_f32_16x16x32_bf16 v[110:113], v[194:197], v[170:173], v[110:113]
	v_mfma_f32_16x16x32_bf16 v[102:105], v[194:197], v[178:181], v[102:105]
	v_mfma_f32_16x16x32_bf16 v[98:101], v[206:209], v[170:173], v[98:101]
	v_mfma_f32_16x16x32_bf16 v[86:89], v[206:209], v[178:181], v[86:89]
	v_mfma_f32_16x16x32_bf16 v[78:81], v[214:217], v[170:173], v[78:81]
	v_mfma_f32_16x16x32_bf16 v[70:73], v[214:217], v[178:181], v[70:73]
	v_mfma_f32_16x16x32_bf16 v[126:129], v[190:193], v[174:177], v[126:129]
	v_mfma_f32_16x16x32_bf16 v[118:121], v[190:193], v[182:185], v[118:121]
	v_mfma_f32_16x16x32_bf16 v[110:113], v[198:201], v[174:177], v[110:113]
	v_mfma_f32_16x16x32_bf16 v[102:105], v[198:201], v[182:185], v[102:105]
	v_mfma_f32_16x16x32_bf16 v[98:101], v[210:213], v[174:177], v[98:101]
	v_mfma_f32_16x16x32_bf16 v[86:89], v[210:213], v[182:185], v[86:89]
	v_mfma_f32_16x16x32_bf16 v[78:81], v[218:221], v[174:177], v[78:81]
	v_mfma_f32_16x16x32_bf16 v[70:73], v[218:221], v[182:185], v[70:73]
	v_mfma_f32_16x16x32_bf16 v[66:69], v[186:189], v[222:225], v[66:69]
	v_mfma_f32_16x16x32_bf16 v[54:57], v[186:189], v[230:233], v[54:57]
	v_mfma_f32_16x16x32_bf16 v[46:49], v[194:197], v[222:225], v[46:49]
	v_mfma_f32_16x16x32_bf16 v[38:41], v[194:197], v[230:233], v[38:41]
	v_mfma_f32_16x16x32_bf16 v[34:37], v[206:209], v[222:225], v[34:37]
	v_mfma_f32_16x16x32_bf16 v[22:25], v[206:209], v[230:233], v[22:25]
	v_mfma_f32_16x16x32_bf16 v[14:17], v[214:217], v[222:225], v[14:17]
	v_mfma_f32_16x16x32_bf16 v[6:9], v[214:217], v[230:233], v[6:9]
	v_mfma_f32_16x16x32_bf16 v[66:69], v[190:193], v[226:229], v[66:69]
	v_mfma_f32_16x16x32_bf16 v[54:57], v[190:193], v[234:237], v[54:57]
	v_mfma_f32_16x16x32_bf16 v[46:49], v[198:201], v[226:229], v[46:49]
	v_mfma_f32_16x16x32_bf16 v[38:41], v[198:201], v[234:237], v[38:41]
	v_mfma_f32_16x16x32_bf16 v[34:37], v[210:213], v[226:229], v[34:37]
	v_mfma_f32_16x16x32_bf16 v[22:25], v[210:213], v[234:237], v[22:25]
	v_mfma_f32_16x16x32_bf16 v[14:17], v[218:221], v[226:229], v[14:17]
	v_mfma_f32_16x16x32_bf16 v[6:9], v[218:221], v[234:237], v[6:9]
	s_barrier
; #define STAGE_A(P, br, kt) do { const char* _g = (const char*)(A + (long)(br) * lda + (long)(kt) * BK); \
;     __builtin_amdgcn_global_load_lds((const unsigned*)(_g + (size_t)offA0), (unsigned*)((char*)(P) + sb0), 16, 0, 0); \
;     __builtin_amdgcn_global_load_lds((const unsigned*)(_g + (size_t)lda * 128 + (size_t)offA0), (unsigned*)((char*)(P) + sb1), 16, 0, 0); } while (0)
; #define STAGE_B(P, br, kt) do { const char* _g = (const char*)(B + (long)(br) * ldb + (long)(kt) * BK); \
;     __builtin_amdgcn_global_load_lds((const unsigned*)(_g + (size_t)offB0), (unsigned*)((char*)(P) + sb0), 16, 0, 0); \
;     __builtin_amdgcn_global_load_lds((const unsigned*)(_g + (size_t)ldb * 128 + (size_t)offB0), (unsigned*)((char*)(P) + sb1), 16, 0, 0); } while (0)
; #define LDA(dst, b, h) for (int m = 0; m < 4; ++m) for (int k = 0; k < 2; ++k) \
;     dst[m][k] = *reinterpret_cast<const bf16x8*>((char*)SA(b, h) + lds_byte(wr * 64 + m * 16 + fr, k * 32 + fq * 8))
; #define WAIT_V(n) asm volatile("s_waitcnt vmcnt(" #n ")" ::: "memory")
; DI void gemm_core(WVP char* smem, const u16* __restrict__ A, int lda, int ar0, int ar1,
;                   const u16* __restrict__ B, int ldb, int bc0, int K, AccT& acc) {
;     ...
;   for (int t = 0; t < nt - 2; t += 2) {
;     LDB(B0, 0, 0); SCHED; LDA(At, 0, 0); STAGE_A(SA(1, 1), ac1, t + 1);
;     WAIT_L(8); BAR; WAIT_L(0); MMA(0, 0, At, B0); BAR; SCHED;
;     LDB(B1, 0, 1); STAGE_B(SB(0, 0), bb0, t + 2);
;     BAR; WAIT_L(0); MMA(0, 1, At, B1); BAR;
;     LDA(At, 0, 1); STAGE_A(SA(0, 0), ac0, t + 2);
;     BAR; WAIT_L(0); MMA(1, 0, At, B0); BAR; SCHED;
;     STAGE_B(SB(0, 1), bb1, t + 2);
;     WAIT_V(6); BAR; MMA(1, 1, At, B1); BAR;
;     LDB(B0, 1, 0); SCHED; LDA(At, 1, 0); STAGE_A(SA(0, 1), ac1, t + 2);
;     WAIT_L(8); BAR; WAIT_L(0); MMA(0, 0, At, B0); BAR; SCHED;
;     LDB(B1, 1, 1); STAGE_B(SB(1, 0), bb0, t + 3);
;     BAR; WAIT_L(0); MMA(0, 1, At, B1); BAR;
;     LDA(At, 1, 1); STAGE_A(SA(1, 0), ac0, t + 3);
;     BAR; WAIT_L(0); MMA(1, 0, At, B0); BAR; SCHED;
;     STAGE_B(SB(1, 1), bb1, t + 3);
;     WAIT_V(6); BAR; MMA(1, 1, At, B1); BAR;
;   }
;   { LDB(B0, 0, 0); LDA(At, 0, 0); STAGE_A(SA(1, 1), ac1, nt - 1);
;     BAR; WAIT_L(0); MMA(0, 0, At, B0); BAR;
;     LDB(B1, 0, 1); BAR; WAIT_L(0); MMA(0, 1, At, B1); BAR;
;     LDA(At, 0, 1); WAIT_V(4); BAR; WAIT_L(0); MMA(1, 0, At, B0); MMA(1, 1, At, B1); BAR; }
	ds_read_b128 v[186:189], v150 offset:49152
	ds_read_b128 v[190:193], v150 offset:50176
	ds_read_b128 v[194:197], v164 offset:49152
	ds_read_b128 v[198:201], v164 offset:50176
	ds_read_b128 v[206:209], v165 offset:49152
	ds_read_b128 v[210:213], v165 offset:50176
	ds_read_b128 v[214:217], v166 offset:49152
	ds_read_b128 v[218:221], v166 offset:50176
	v_lshl_add_u64 v[238:239], v[130:131], 0, s[28:29]
	v_lshl_add_u64 v[202:203], v[238:239], 0, s[70:71]
	v_readfirstlane_b32 s31, v155
	s_mov_b32 m0, s31
	s_nop 0
	global_load_lds_dwordx4 v[202:203], off
	v_lshl_add_u64 v[238:239], v[132:133], 0, s[28:29]
	v_lshl_add_u64 v[202:203], v[238:239], 0, s[70:71]
	v_readfirstlane_b32 s31, v156
	s_mov_b32 m0, s31
	s_nop 0
	global_load_lds_dwordx4 v[202:203], off
	v_lshl_add_u64 v[238:239], v[134:135], 0, s[28:29]
	v_lshl_add_u64 v[202:203], v[238:239], 0, s[62:63]
	v_readfirstlane_b32 s31, v157
	s_mov_b32 m0, s31
	s_nop 0
	global_load_lds_dwordx4 v[202:203], off
	v_lshl_add_u64 v[238:239], v[136:137], 0, s[28:29]
	v_lshl_add_u64 v[202:203], v[238:239], 0, s[62:63]
	v_readfirstlane_b32 s31, v158
	s_mov_b32 m0, s31
	s_nop 0
	global_load_lds_dwordx4 v[202:203], off
	v_lshl_add_u64 v[238:239], v[138:139], 0, s[28:29]
	v_lshl_add_u64 v[202:203], v[238:239], 0, s[70:71]
	v_readfirstlane_b32 s31, v159
	s_mov_b32 m0, s31
	s_nop 0
	global_load_lds_dwordx4 v[202:203], off
	v_lshl_add_u64 v[238:239], v[140:141], 0, s[28:29]
	v_lshl_add_u64 v[202:203], v[238:239], 0, s[70:71]
	v_readfirstlane_b32 s31, v160
	s_mov_b32 m0, s31
	s_nop 0
	global_load_lds_dwordx4 v[202:203], off
	s_waitcnt vmcnt(8)
	s_waitcnt lgkmcnt(0)
	s_barrier
	v_mfma_f32_16x16x32_bf16 v[122:125], v[186:189], v[170:173], v[122:125]
	v_mfma_f32_16x16x32_bf16 v[114:117], v[186:189], v[178:181], v[114:117]
	v_mfma_f32_16x16x32_bf16 v[106:109], v[194:197], v[170:173], v[106:109]
	v_mfma_f32_16x16x32_bf16 v[94:97], v[194:197], v[178:181], v[94:97]
	v_mfma_f32_16x16x32_bf16 v[90:93], v[206:209], v[170:173], v[90:93]
	v_mfma_f32_16x16x32_bf16 v[82:85], v[206:209], v[178:181], v[82:85]
	v_mfma_f32_16x16x32_bf16 v[74:77], v[214:217], v[170:173], v[74:77]
	v_mfma_f32_16x16x32_bf16 v[62:65], v[214:217], v[178:181], v[62:65]
	v_mfma_f32_16x16x32_bf16 v[122:125], v[190:193], v[174:177], v[122:125]
	v_mfma_f32_16x16x32_bf16 v[114:117], v[190:193], v[182:185], v[114:117]
	v_mfma_f32_16x16x32_bf16 v[106:109], v[198:201], v[174:177], v[106:109]
	v_mfma_f32_16x16x32_bf16 v[94:97], v[198:201], v[182:185], v[94:97]
	v_mfma_f32_16x16x32_bf16 v[90:93], v[210:213], v[174:177], v[90:93]
	v_mfma_f32_16x16x32_bf16 v[82:85], v[210:213], v[182:185], v[82:85]
	v_mfma_f32_16x16x32_bf16 v[74:77], v[218:221], v[174:177], v[74:77]
	v_mfma_f32_16x16x32_bf16 v[62:65], v[218:221], v[182:185], v[62:65]
	v_mfma_f32_16x16x32_bf16 v[58:61], v[186:189], v[222:225], v[58:61]
	v_mfma_f32_16x16x32_bf16 v[50:53], v[186:189], v[230:233], v[50:53]
	v_mfma_f32_16x16x32_bf16 v[42:45], v[194:197], v[222:225], v[42:45]
	v_mfma_f32_16x16x32_bf16 v[30:33], v[194:197], v[230:233], v[30:33]
	v_mfma_f32_16x16x32_bf16 v[26:29], v[206:209], v[222:225], v[26:29]
	v_mfma_f32_16x16x32_bf16 v[18:21], v[206:209], v[230:233], v[18:21]
	v_mfma_f32_16x16x32_bf16 v[10:13], v[214:217], v[222:225], v[10:13]
	v_mfma_f32_16x16x32_bf16 v[2:5], v[214:217], v[230:233], v[2:5]
	v_mfma_f32_16x16x32_bf16 v[58:61], v[190:193], v[226:229], v[58:61]
	v_mfma_f32_16x16x32_bf16 v[50:53], v[190:193], v[234:237], v[50:53]
	v_mfma_f32_16x16x32_bf16 v[42:45], v[198:201], v[226:229], v[42:45]
	v_mfma_f32_16x16x32_bf16 v[30:33], v[198:201], v[234:237], v[30:33]
	v_mfma_f32_16x16x32_bf16 v[26:29], v[210:213], v[226:229], v[26:29]
	v_mfma_f32_16x16x32_bf16 v[18:21], v[210:213], v[234:237], v[18:21]
	v_mfma_f32_16x16x32_bf16 v[10:13], v[218:221], v[226:229], v[10:13]
	v_mfma_f32_16x16x32_bf16 v[2:5], v[218:221], v[234:237], v[2:5]
	s_add_i32 s30, s30, 2
	s_add_u32 s28, s28, 0x100
	s_addc_u32 s29, s29, 0
	s_cmp_lt_u32 s30, s1
	s_barrier
	s_cbranch_scc1 .LBB0_237
	s_add_i32 s58, s0, -1
	s_lshl_b64 s[0:1], s[58:59], 7
	s_add_u32 s0, s24, s0
	s_addc_u32 s1, s25, s1
	v_lshl_add_u64 v[160:161], s[0:1], 0, v[0:1]
	v_readfirstlane_b32 s24, v168
	s_add_u32 s0, s0, s36
	s_mov_b32 m0, s24
	s_addc_u32 s1, s1, 0
	ds_read_b128 v[130:133], v163
	ds_read_b128 v[134:137], v163 offset:1024
	ds_read_b128 v[138:141], v163 offset:2048
	ds_read_b128 v[142:145], v163 offset:3072
	ds_read_b128 v[146:149], v150
	ds_read_b128 v[156:159], v150 offset:1024
	ds_read_b128 v[170:173], v164
	ds_read_b128 v[174:177], v164 offset:1024
	ds_read_b128 v[178:181], v165
	ds_read_b128 v[182:185], v165 offset:1024
	ds_read_b128 v[186:189], v166
	ds_read_b128 v[190:193], v166 offset:1024
	global_load_lds_dwordx4 v[160:161], off
	v_lshl_add_u64 v[160:161], s[0:1], 0, v[0:1]
	v_readfirstlane_b32 s0, v167
	s_mov_b32 m0, s0
	s_nop 0
	global_load_lds_dwordx4 v[160:161], off
	s_waitcnt vmcnt(8)
	s_barrier
	s_waitcnt lgkmcnt(0)
	s_setprio 1
	s_waitcnt lgkmcnt(0)
	v_mfma_f32_16x16x32_bf16 v[126:129], v[146:149], v[130:133], v[126:129]
	v_mfma_f32_16x16x32_bf16 v[118:121], v[146:149], v[138:141], v[118:121]
	v_mfma_f32_16x16x32_bf16 v[110:113], v[170:173], v[130:133], v[110:113]
	v_mfma_f32_16x16x32_bf16 v[102:105], v[170:173], v[138:141], v[102:105]
	v_mfma_f32_16x16x32_bf16 v[98:101], v[178:181], v[130:133], v[98:101]
	v_mfma_f32_16x16x32_bf16 v[86:89], v[178:181], v[138:141], v[86:89]
	v_mfma_f32_16x16x32_bf16 v[78:81], v[186:189], v[130:133], v[78:81]
	v_mfma_f32_16x16x32_bf16 v[70:73], v[186:189], v[138:141], v[70:73]
	v_mfma_f32_16x16x32_bf16 v[126:129], v[156:159], v[134:137], v[126:129]
	v_mfma_f32_16x16x32_bf16 v[118:121], v[156:159], v[142:145], v[118:121]
	v_mfma_f32_16x16x32_bf16 v[110:113], v[174:177], v[134:137], v[110:113]
	v_mfma_f32_16x16x32_bf16 v[102:105], v[174:177], v[142:145], v[102:105]
	v_mfma_f32_16x16x32_bf16 v[98:101], v[182:185], v[134:137], v[98:101]
	v_mfma_f32_16x16x32_bf16 v[86:89], v[182:185], v[142:145], v[86:89]
	v_mfma_f32_16x16x32_bf16 v[78:81], v[190:193], v[134:137], v[78:81]
	v_mfma_f32_16x16x32_bf16 v[70:73], v[190:193], v[142:145], v[70:73]
	s_setprio 0
	s_barrier
; #define LDA(dst, b, h) for (int m = 0; m < 4; ++m) for (int k = 0; k < 2; ++k) \
;     dst[m][k] = *reinterpret_cast<const bf16x8*>((char*)SA(b, h) + lds_byte(wr * 64 + m * 16 + fr, k * 32 + fq * 8))
; #define LDB(dst, b, h) for (int n = 0; n < 2; ++n) for (int k = 0; k < 2; ++k) \
;     dst[n][k] = *reinterpret_cast<const bf16x8*>((char*)SB(b, h) + lds_byte(wc * 32 + n * 16 + fr, k * 32 + fq * 8))
; #define MMA(ai, bj, At_, Bt_) do { __builtin_amdgcn_s_setprio(1); \
;     for (int m = 0; m < 4; ++m) for (int n = 0; n < 2; ++n) for (int k = 0; k < 2; ++k) \
;       acc[ai][bj][m][n] = MFMA16(At_[m][k], Bt_[n][k], acc[ai][bj][m][n]); \
;     __builtin_amdgcn_s_setprio(0); } while (0)
; #define WAIT_V(n) asm volatile("s_waitcnt vmcnt(" #n ")" ::: "memory")
; #define WAIT_L(n) asm volatile("s_waitcnt lgkmcnt(" #n ")" ::: "memory")
; #define BAR __builtin_amdgcn_s_barrier()
; DI void gemm_core(WVP char* smem, const u16* __restrict__ A, int lda, int ar0, int ar1,
;                   const u16* __restrict__ B, int ldb, int bc0, int K, AccT& acc) {
;     ...
;     BAR; WAIT_L(0); MMA(0, 0, At, B0); BAR;
;     LDB(B1, 0, 1); BAR; WAIT_L(0); MMA(0, 1, At, B1); BAR;
;     LDA(At, 0, 1); WAIT_V(4); BAR; WAIT_L(0); MMA(1, 0, At, B0); MMA(1, 1, At, B1); BAR; }
;   { LDB(B0, 1, 0); LDA(At, 1, 0); WAIT_V(2); BAR; WAIT_L(0); MMA(0, 0, At, B0); BAR;
	ds_read_b128 v[194:197], v162
	ds_read_b128 v[198:201], v162 offset:1024
	ds_read_b128 v[206:209], v162 offset:2048
	ds_read_b128 v[160:163], v162 offset:3072
	s_barrier
	s_waitcnt lgkmcnt(0)
	s_setprio 1
	s_waitcnt lgkmcnt(0)
	v_mfma_f32_16x16x32_bf16 v[66:69], v[146:149], v[194:197], v[66:69]
	v_mfma_f32_16x16x32_bf16 v[54:57], v[146:149], v[206:209], v[54:57]
	v_mfma_f32_16x16x32_bf16 v[46:49], v[170:173], v[194:197], v[46:49]
	v_mfma_f32_16x16x32_bf16 v[38:41], v[170:173], v[206:209], v[38:41]
	v_mfma_f32_16x16x32_bf16 v[34:37], v[178:181], v[194:197], v[34:37]
	v_mfma_f32_16x16x32_bf16 v[22:25], v[178:181], v[206:209], v[22:25]
	v_mfma_f32_16x16x32_bf16 v[14:17], v[186:189], v[194:197], v[14:17]
	v_mfma_f32_16x16x32_bf16 v[6:9], v[186:189], v[206:209], v[6:9]
	v_mfma_f32_16x16x32_bf16 v[66:69], v[156:159], v[198:201], v[66:69]
	v_mfma_f32_16x16x32_bf16 v[54:57], v[156:159], v[160:163], v[54:57]
	v_mfma_f32_16x16x32_bf16 v[46:49], v[174:177], v[198:201], v[46:49]
	v_mfma_f32_16x16x32_bf16 v[38:41], v[174:177], v[160:163], v[38:41]
	v_mfma_f32_16x16x32_bf16 v[34:37], v[182:185], v[198:201], v[34:37]
	v_mfma_f32_16x16x32_bf16 v[22:25], v[182:185], v[160:163], v[22:25]
	v_mfma_f32_16x16x32_bf16 v[14:17], v[190:193], v[198:201], v[14:17]
	v_mfma_f32_16x16x32_bf16 v[6:9], v[190:193], v[160:163], v[6:9]
	s_setprio 0
	s_barrier
	ds_read_b128 v[146:149], v150 offset:16384
	ds_read_b128 v[156:159], v150 offset:17408
	ds_read_b128 v[168:171], v164 offset:16384
	ds_read_b128 v[172:175], v164 offset:17408
	ds_read_b128 v[176:179], v165 offset:16384
	ds_read_b128 v[180:183], v165 offset:17408
	ds_read_b128 v[184:187], v166 offset:16384
	ds_read_b128 v[188:191], v166 offset:17408
	s_waitcnt vmcnt(4)
	s_barrier
	s_waitcnt lgkmcnt(0)
	s_setprio 1
	s_waitcnt lgkmcnt(0)
	v_mfma_f32_16x16x32_bf16 v[122:125], v[146:149], v[130:133], v[122:125]
	v_mfma_f32_16x16x32_bf16 v[114:117], v[146:149], v[138:141], v[114:117]
	v_mfma_f32_16x16x32_bf16 v[106:109], v[168:171], v[130:133], v[106:109]
	v_mfma_f32_16x16x32_bf16 v[94:97], v[168:171], v[138:141], v[94:97]
	v_mfma_f32_16x16x32_bf16 v[90:93], v[176:179], v[130:133], v[90:93]
	v_mfma_f32_16x16x32_bf16 v[82:85], v[176:179], v[138:141], v[82:85]
	v_mfma_f32_16x16x32_bf16 v[74:77], v[184:187], v[130:133], v[74:77]
	v_mfma_f32_16x16x32_bf16 v[62:65], v[184:187], v[138:141], v[62:65]
	v_mfma_f32_16x16x32_bf16 v[122:125], v[156:159], v[134:137], v[122:125]
	v_mfma_f32_16x16x32_bf16 v[114:117], v[156:159], v[142:145], v[114:117]
	v_mfma_f32_16x16x32_bf16 v[106:109], v[172:175], v[134:137], v[106:109]
	v_mfma_f32_16x16x32_bf16 v[94:97], v[172:175], v[142:145], v[94:97]
	v_mfma_f32_16x16x32_bf16 v[90:93], v[180:183], v[134:137], v[90:93]
	v_mfma_f32_16x16x32_bf16 v[82:85], v[180:183], v[142:145], v[82:85]
	v_mfma_f32_16x16x32_bf16 v[74:77], v[188:191], v[134:137], v[74:77]
	v_mfma_f32_16x16x32_bf16 v[62:65], v[188:191], v[142:145], v[62:65]
	s_setprio 0
	s_setprio 1
	v_mfma_f32_16x16x32_bf16 v[58:61], v[146:149], v[194:197], v[58:61]
	v_mfma_f32_16x16x32_bf16 v[50:53], v[146:149], v[206:209], v[50:53]
	v_mfma_f32_16x16x32_bf16 v[42:45], v[168:171], v[194:197], v[42:45]
	v_mfma_f32_16x16x32_bf16 v[30:33], v[168:171], v[206:209], v[30:33]
	v_mfma_f32_16x16x32_bf16 v[26:29], v[176:179], v[194:197], v[26:29]
	v_mfma_f32_16x16x32_bf16 v[18:21], v[176:179], v[206:209], v[18:21]
	v_mfma_f32_16x16x32_bf16 v[10:13], v[184:187], v[194:197], v[10:13]
	v_mfma_f32_16x16x32_bf16 v[2:5], v[184:187], v[206:209], v[2:5]
	v_mfma_f32_16x16x32_bf16 v[58:61], v[156:159], v[198:201], v[58:61]
	v_mfma_f32_16x16x32_bf16 v[50:53], v[156:159], v[160:163], v[50:53]
	v_mfma_f32_16x16x32_bf16 v[42:45], v[172:175], v[198:201], v[42:45]
	v_mfma_f32_16x16x32_bf16 v[30:33], v[172:175], v[160:163], v[30:33]
	v_mfma_f32_16x16x32_bf16 v[26:29], v[180:183], v[198:201], v[26:29]
	v_mfma_f32_16x16x32_bf16 v[18:21], v[180:183], v[160:163], v[18:21]
	v_mfma_f32_16x16x32_bf16 v[10:13], v[188:191], v[198:201], v[10:13]
	v_mfma_f32_16x16x32_bf16 v[2:5], v[188:191], v[160:163], v[2:5]
	s_setprio 0
	s_barrier
	ds_read_b128 v[130:133], v154
	ds_read_b128 v[134:137], v154 offset:1024
	ds_read_b128 v[138:141], v154 offset:2048
	ds_read_b128 v[142:145], v154 offset:3072
	ds_read_b128 v[146:149], v150 offset:32768
	ds_read_b128 v[154:157], v150 offset:33792
	ds_read_b128 v[158:161], v164 offset:32768
	ds_read_b128 v[168:171], v164 offset:33792
	ds_read_b128 v[172:175], v165 offset:32768
	ds_read_b128 v[176:179], v165 offset:33792
	ds_read_b128 v[180:183], v166 offset:32768
	ds_read_b128 v[184:187], v166 offset:33792
	s_waitcnt vmcnt(2)
	s_barrier
; #define LDA(dst, b, h) for (int m = 0; m < 4; ++m) for (int k = 0; k < 2; ++k) \
;     dst[m][k] = *reinterpret_cast<const bf16x8*>((char*)SA(b, h) + lds_byte(wr * 64 + m * 16 + fr, k * 32 + fq * 8))
; #define LDB(dst, b, h) for (int n = 0; n < 2; ++n) for (int k = 0; k < 2; ++k) \
;     dst[n][k] = *reinterpret_cast<const bf16x8*>((char*)SB(b, h) + lds_byte(wc * 32 + n * 16 + fr, k * 32 + fq * 8))
; #define MMA(ai, bj, At_, Bt_) do { __builtin_amdgcn_s_setprio(1); \
;     for (int m = 0; m < 4; ++m) for (int n = 0; n < 2; ++n) for (int k = 0; k < 2; ++k) \
;       acc[ai][bj][m][n] = MFMA16(At_[m][k], Bt_[n][k], acc[ai][bj][m][n]); \
;     __builtin_amdgcn_s_setprio(0); } while (0)
; #define WAIT_V(n) asm volatile("s_waitcnt vmcnt(" #n ")" ::: "memory")
; #define WAIT_L(n) asm volatile("s_waitcnt lgkmcnt(" #n ")" ::: "memory")
; #define BAR __builtin_amdgcn_s_barrier()
; DI void gemm_core(WVP char* smem, const u16* __restrict__ A, int lda, int ar0, int ar1,
;                   const u16* __restrict__ B, int ldb, int bc0, int K, AccT& acc) {
;     ...
;   { LDB(B0, 1, 0); LDA(At, 1, 0); WAIT_V(2); BAR; WAIT_L(0); MMA(0, 0, At, B0); BAR;
;     LDB(B1, 1, 1); WAIT_V(0); BAR; WAIT_L(0); MMA(0, 1, At, B1); BAR;
;     LDA(At, 1, 1); BAR; WAIT_L(0); MMA(1, 0, At, B0); MMA(1, 1, At, B1); BAR; }
;   if (wr == 0) BAR;
; __global__ void __launch_bounds__(NTHR) mega(Params p) {
;     ...
;             if (b < 3) {
	s_waitcnt lgkmcnt(0)
	s_setprio 1
	s_waitcnt lgkmcnt(0)
	v_mfma_f32_16x16x32_bf16 v[126:129], v[146:149], v[130:133], v[126:129]
	v_mfma_f32_16x16x32_bf16 v[118:121], v[146:149], v[138:141], v[118:121]
	v_mfma_f32_16x16x32_bf16 v[110:113], v[158:161], v[130:133], v[110:113]
	v_mfma_f32_16x16x32_bf16 v[102:105], v[158:161], v[138:141], v[102:105]
	v_mfma_f32_16x16x32_bf16 v[98:101], v[172:175], v[130:133], v[98:101]
	v_mfma_f32_16x16x32_bf16 v[86:89], v[172:175], v[138:141], v[86:89]
	v_mfma_f32_16x16x32_bf16 v[78:81], v[180:183], v[130:133], v[78:81]
	v_mfma_f32_16x16x32_bf16 v[70:73], v[180:183], v[138:141], v[70:73]
	v_mfma_f32_16x16x32_bf16 v[126:129], v[154:157], v[134:137], v[126:129]
	v_mfma_f32_16x16x32_bf16 v[118:121], v[154:157], v[142:145], v[118:121]
	v_mfma_f32_16x16x32_bf16 v[110:113], v[168:171], v[134:137], v[110:113]
	v_mfma_f32_16x16x32_bf16 v[102:105], v[168:171], v[142:145], v[102:105]
	v_mfma_f32_16x16x32_bf16 v[98:101], v[176:179], v[134:137], v[98:101]
	v_mfma_f32_16x16x32_bf16 v[86:89], v[176:179], v[142:145], v[86:89]
	v_mfma_f32_16x16x32_bf16 v[78:81], v[184:187], v[134:137], v[78:81]
	v_mfma_f32_16x16x32_bf16 v[70:73], v[184:187], v[142:145], v[70:73]
	s_setprio 0
	s_barrier
	ds_read_b128 v[188:191], v153
	ds_read_b128 v[192:195], v153 offset:1024
	ds_read_b128 v[196:199], v153 offset:2048
	ds_read_b128 v[200:203], v153 offset:3072
	s_waitcnt vmcnt(0)
	s_barrier
	s_waitcnt lgkmcnt(0)
	s_setprio 1
	s_waitcnt lgkmcnt(0)
	v_mfma_f32_16x16x32_bf16 v[66:69], v[146:149], v[188:191], v[66:69]
	v_mfma_f32_16x16x32_bf16 v[54:57], v[146:149], v[196:199], v[54:57]
	v_mfma_f32_16x16x32_bf16 v[46:49], v[158:161], v[188:191], v[46:49]
	v_mfma_f32_16x16x32_bf16 v[38:41], v[158:161], v[196:199], v[38:41]
	v_mfma_f32_16x16x32_bf16 v[34:37], v[172:175], v[188:191], v[34:37]
	v_mfma_f32_16x16x32_bf16 v[22:25], v[172:175], v[196:199], v[22:25]
	v_mfma_f32_16x16x32_bf16 v[14:17], v[180:183], v[188:191], v[14:17]
	v_mfma_f32_16x16x32_bf16 v[6:9], v[180:183], v[196:199], v[6:9]
	v_mfma_f32_16x16x32_bf16 v[66:69], v[154:157], v[192:195], v[66:69]
	v_mfma_f32_16x16x32_bf16 v[54:57], v[154:157], v[200:203], v[54:57]
	v_mfma_f32_16x16x32_bf16 v[46:49], v[168:171], v[192:195], v[46:49]
	v_mfma_f32_16x16x32_bf16 v[38:41], v[168:171], v[200:203], v[38:41]
	v_mfma_f32_16x16x32_bf16 v[34:37], v[176:179], v[192:195], v[34:37]
	v_mfma_f32_16x16x32_bf16 v[22:25], v[176:179], v[200:203], v[22:25]
	v_mfma_f32_16x16x32_bf16 v[14:17], v[184:187], v[192:195], v[14:17]
	v_mfma_f32_16x16x32_bf16 v[6:9], v[184:187], v[200:203], v[6:9]
	s_setprio 0
	s_barrier
	ds_read_b128 v[146:149], v150 offset:49152
	ds_read_b128 v[150:153], v150 offset:50176
	ds_read_b128 v[154:157], v164 offset:49152
	ds_read_b128 v[158:161], v164 offset:50176
	ds_read_b128 v[168:171], v165 offset:49152
	ds_read_b128 v[162:165], v165 offset:50176
	ds_read_b128 v[172:175], v166 offset:49152
	ds_read_b128 v[176:179], v166 offset:50176
	s_barrier
	s_waitcnt lgkmcnt(0)
	s_setprio 1
	s_waitcnt lgkmcnt(0)
	v_mfma_f32_16x16x32_bf16 v[122:125], v[146:149], v[130:133], v[122:125]
	v_mfma_f32_16x16x32_bf16 v[114:117], v[146:149], v[138:141], v[114:117]
	v_mfma_f32_16x16x32_bf16 v[106:109], v[154:157], v[130:133], v[106:109]
	v_mfma_f32_16x16x32_bf16 v[94:97], v[154:157], v[138:141], v[94:97]
	v_mfma_f32_16x16x32_bf16 v[90:93], v[168:171], v[130:133], v[90:93]
	v_mfma_f32_16x16x32_bf16 v[82:85], v[168:171], v[138:141], v[82:85]
	v_mfma_f32_16x16x32_bf16 v[74:77], v[172:175], v[130:133], v[74:77]
	v_mfma_f32_16x16x32_bf16 v[62:65], v[172:175], v[138:141], v[62:65]
	v_mfma_f32_16x16x32_bf16 v[122:125], v[150:153], v[134:137], v[122:125]
	v_mfma_f32_16x16x32_bf16 v[114:117], v[150:153], v[142:145], v[114:117]
	v_mfma_f32_16x16x32_bf16 v[106:109], v[158:161], v[134:137], v[106:109]
	v_mfma_f32_16x16x32_bf16 v[94:97], v[158:161], v[142:145], v[94:97]
	v_mfma_f32_16x16x32_bf16 v[90:93], v[162:165], v[134:137], v[90:93]
	v_mfma_f32_16x16x32_bf16 v[82:85], v[162:165], v[142:145], v[82:85]
	v_mfma_f32_16x16x32_bf16 v[74:77], v[176:179], v[134:137], v[74:77]
	v_mfma_f32_16x16x32_bf16 v[62:65], v[176:179], v[142:145], v[62:65]
	s_setprio 0
	s_setprio 1
	v_mfma_f32_16x16x32_bf16 v[58:61], v[146:149], v[188:191], v[58:61]
	v_mfma_f32_16x16x32_bf16 v[50:53], v[146:149], v[196:199], v[50:53]
	v_mfma_f32_16x16x32_bf16 v[42:45], v[154:157], v[188:191], v[42:45]
	v_mfma_f32_16x16x32_bf16 v[30:33], v[154:157], v[196:199], v[30:33]
	v_mfma_f32_16x16x32_bf16 v[26:29], v[168:171], v[188:191], v[26:29]
	v_mfma_f32_16x16x32_bf16 v[18:21], v[168:171], v[196:199], v[18:21]
	v_mfma_f32_16x16x32_bf16 v[10:13], v[172:175], v[188:191], v[10:13]
	v_mfma_f32_16x16x32_bf16 v[2:5], v[172:175], v[196:199], v[2:5]
	v_mfma_f32_16x16x32_bf16 v[58:61], v[150:153], v[192:195], v[58:61]
	v_mfma_f32_16x16x32_bf16 v[50:53], v[150:153], v[200:203], v[50:53]
	v_mfma_f32_16x16x32_bf16 v[42:45], v[158:161], v[192:195], v[42:45]
	v_mfma_f32_16x16x32_bf16 v[30:33], v[158:161], v[200:203], v[30:33]
	v_mfma_f32_16x16x32_bf16 v[26:29], v[162:165], v[192:195], v[26:29]
	v_mfma_f32_16x16x32_bf16 v[18:21], v[162:165], v[200:203], v[18:21]
	v_mfma_f32_16x16x32_bf16 v[10:13], v[176:179], v[192:195], v[10:13]
	v_mfma_f32_16x16x32_bf16 v[2:5], v[176:179], v[200:203], v[2:5]
	s_setprio 0
	s_cmp_gt_u32 s35, 3
	s_barrier
	s_cbranch_scc0 .LBB0_240
	s_cmp_eq_u32 s34, 3
	s_cbranch_scc1 .LBB0_233
	s_branch .LBB0_241

; DI int get_tid(int wv) { int l; asm volatile("v_mbcnt_lo_u32_b32 %0, -1, 0\n\tv_mbcnt_hi_u32_b32 %0, -1, %0" : "=v"(l)); return wv * 64 + l; }
; DI int wave_of(int tid) { return __builtin_amdgcn_readfirstlane(tid >> 6); }
; #define STAGE_A(P, br, kt) do { const char* _g = (const char*)(A + (long)(br) * lda + (long)(kt) * BK); \
;     __builtin_amdgcn_global_load_lds((const unsigned*)(_g + (size_t)offA0), (unsigned*)((char*)(P) + sb0), 16, 0, 0); \
;     __builtin_amdgcn_global_load_lds((const unsigned*)(_g + (size_t)lda * 128 + (size_t)offA0), (unsigned*)((char*)(P) + sb1), 16, 0, 0); } while (0)
; #define STAGE_B(P, br, kt) do { const char* _g = (const char*)(B + (long)(br) * ldb + (long)(kt) * BK); \
;     __builtin_amdgcn_global_load_lds((const unsigned*)(_g + (size_t)offB0), (unsigned*)((char*)(P) + sb0), 16, 0, 0); \
;     __builtin_amdgcn_global_load_lds((const unsigned*)(_g + (size_t)ldb * 128 + (size_t)offB0), (unsigned*)((char*)(P) + sb1), 16, 0, 0); } while (0)
; #define WAIT_V(n) asm volatile("s_waitcnt vmcnt(" #n ")" ::: "memory")
; DI void gemm_core(WVP char* smem, const u16* __restrict__ A, int lda, int ar0, int ar1,
;                   const u16* __restrict__ B, int ldb, int bc0, int K, AccT& acc) {
;     ...
;   const int tid = get_tid(WV);
;   const int wid = wave_of(tid), lane = tid & 63, wr = wid >> 2, wc = wid & 3, fr = lane & 15, fq = lane >> 4;
;   const int sb0 = tid * 16, sb1 = sb0 + 8192;
;   int R0, C0; stage_rc(sb0, R0, C0);
;   const unsigned offA0 = (unsigned)(R0 * lda + C0) * 2u, offB0 = (unsigned)(R0 * ldb + C0) * 2u;
;   const int ac0 = ar0, ac1 = ar1, bb0 = bc0, bb1 = bc0 + HALF;
;   bf16x8 At[4][2], B0[2][2], B1[2][2];
;   const int nt = K / BK;
;   __syncthreads();
;   STAGE_B(SB(0, 0), bb0, 0); STAGE_A(SA(0, 0), ac0, 0);
;   STAGE_B(SB(0, 1), bb1, 0); STAGE_A(SA(0, 1), ac1, 0);
;   if (wr == 1) BAR;
;   WAIT_V(4); BAR;
;   STAGE_B(SB(1, 0), bb0, 1); STAGE_A(SA(1, 0), ac0, 1); STAGE_B(SB(1, 1), bb1, 1);
;   WAIT_V(6); BAR;
; __global__ void __launch_bounds__(NTHR) mega(Params p) {
;     ...
;         const int nR = 4, nC = TOK / 256, nwg = nR * nC;
;         for (int id = BID; id < nwg; id += G) {
;           int pr, pc; tile_map(id, nwg, nR, nC, pr, pc);
;           EpiGated<1> E{proj, INW, O2 + 512 + pr * 128};
;           gemm_tile_staged(WV, smem, WGLU, 512, pr * 128, 512 + pr * 128, proj + O3, INW, pc * 256, 512, E);
.LBB0_270:
	s_add_i32 s0, s1, s8
	s_ashr_i32 s1, s0, 31
	v_mbcnt_lo_u32_b32 v7, -1, 0
	v_mbcnt_hi_u32_b32 v7, -1, v7
	s_lshr_b32 s1, s1, 23
	v_add_u32_e32 v0, s3, v7
	v_ashrrev_i32_e32 v2, 31, v0
	s_add_i32 s1, s0, s1
	v_lshrrev_b32_e32 v2, 26, v2
	s_and_b32 s1, s1, 0xfffffe00
	v_readfirstlane_b32 s18, v0
	v_lshlrev_b32_e32 v11, 4, v0
	v_add_u32_e32 v2, v0, v2
	v_bfe_i32 v0, v0, 27, 1
	s_sub_i32 s0, s0, s1
	v_lshrrev_b32_e32 v0, 22, v0
	s_sext_i32_i16 s8, s0
	v_add_u32_e32 v0, v11, v0
	s_bfe_u32 s8, s8, 0x2001d
	v_and_b32_e32 v0, 0xfffffc00, v0
	s_add_i32 s8, s0, s8
	v_sub_u32_e32 v0, v11, v0
	s_sext_i32_i16 s9, s8
	s_and_b32 s8, s8, 0xfffc
	v_ashrrev_i32_e32 v6, 6, v2
	v_lshrrev_b32_e32 v2, 4, v0
	s_sub_i32 s0, s0, s8
	v_bitop3_b32 v0, v2, v0, 32 bitop3:0x6c
	s_sext_i32_i16 s0, s0
	v_ashrrev_i32_e32 v3, 31, v0
	s_ashr_i32 s17, s9, 2
	s_lshl_b32 s0, s0, 7
	v_lshrrev_b32_e32 v3, 26, v3
	s_add_i32 s8, s0, s1
	v_lshlrev_b32_e32 v2, 3, v6
	v_add_u32_e32 v3, v0, v3
	s_mul_i32 s10, s17, 0x260000
	s_add_i32 s14, s8, 0x200
	s_ashr_i32 s0, s18, 8
	v_and_b32_e32 v2, -16, v2
	v_ashrrev_i32_e32 v8, 6, v3
	v_and_b32_e32 v3, 0xc0, v3
	s_ashr_i32 s11, s10, 31
	v_add_u32_e32 v2, v8, v2
	v_sub_u32_e32 v0, v0, v3
	s_movk_i32 s1, 0x1300
	s_add_u32 s12, s4, s10
	v_lshlrev_b32_e32 v4, 5, v6
	v_ashrrev_i16_sdwa v0, v254, sext(v0) dst_sel:DWORD dst_unused:UNUSED_PAD src0_sel:DWORD src1_sel:BYTE_0
	v_lshlrev_b32_e32 v3, 10, v2
	v_mul_lo_u32 v2, v2, s1
	s_addc_u32 s13, s5, s11
	s_add_i32 s1, 0, 0x10000
	v_and_b32_e32 v10, 32, v4
	v_bfe_i32 v9, v0, 0, 16
	v_add_u32_e32 v138, s1, v11
	v_add_u32_e32 v0, v10, v9
	v_readfirstlane_b32 s9, v138
	v_add_u32_e32 v16, 0x2000, v11
	v_lshl_add_u32 v12, v0, 1, v3
	v_add_lshl_u32 v0, v0, v2, 1
	s_mov_b32 m0, s9
	s_barrier
	v_lshl_add_u64 v[2:3], s[12:13], 0, v[0:1]
	global_load_lds_dwordx4 v0, s[12:13]
	v_add_u32_e32 v0, s1, v16
	s_mov_b64 s[12:13], 0x98000
	v_readfirstlane_b32 s9, v0
	s_mov_b32 m0, s9
	s_ashr_i32 s9, s8, 31
	v_lshl_add_u64 v[4:5], v[2:3], 0, s[12:13]
	s_lshl_b64 s[12:13], s[8:9], 10
	v_readlane_b32 s19, v255, 43
	s_add_u32 s20, s19, s12
	v_readlane_b32 s24, v255, 44
	v_add_u32_e32 v140, 0, v11
	s_addc_u32 s21, s24, s13
	v_mov_b32_e32 v13, v1
	v_readfirstlane_b32 s15, v140
	v_add_u32_e32 v141, 0x2000, v140
	global_load_lds_dwordx4 v[4:5], off
	v_lshl_add_u64 v[4:5], s[20:21], 0, v[12:13]
	s_mov_b32 m0, s15
	s_mov_b64 s[22:23], 0x10000
	v_readfirstlane_b32 s15, v141
	v_add_u32_e32 v143, s60, v11
	global_load_lds_dwordx4 v12, s[20:21]
	v_lshl_add_u64 v[14:15], v[4:5], 0, s[22:23]
	s_mov_b32 m0, s15
	s_mov_b64 s[20:21], 0x130000
	v_readfirstlane_b32 s15, v143
	v_add_u32_e32 v0, s60, v16
	global_load_lds_dwordx4 v[14:15], off
	v_lshl_add_u64 v[14:15], v[2:3], 0, s[20:21]
	s_mov_b32 m0, s15
	v_readfirstlane_b32 s15, v0
	global_load_lds_dwordx4 v[14:15], off
	s_mov_b32 m0, s15
	s_ashr_i32 s15, s14, 31
	s_mov_b64 s[20:21], 0x1c8000
	s_lshl_b64 s[14:15], s[14:15], 10
	v_lshl_add_u64 v[14:15], v[2:3], 0, s[20:21]
	s_add_u32 s20, s19, s14
	v_add_u32_e32 v144, 0x4000, v140
	s_addc_u32 s21, s24, s15
	v_readfirstlane_b32 s19, v144
	v_add_u32_e32 v145, 0x6000, v140
	global_load_lds_dwordx4 v[14:15], off
	v_lshl_add_u64 v[130:131], s[20:21], 0, v[12:13]
	s_mov_b32 m0, s19
	v_readfirstlane_b32 s19, v145
	global_load_lds_dwordx4 v12, s[20:21]
	v_lshl_add_u64 v[12:13], v[130:131], 0, s[22:23]
	s_mov_b32 m0, s19
	s_cmp_lg_u32 s0, 1
	global_load_lds_dwordx4 v[12:13], off
	v_mov_b32_e32 v16, 0
	v_mov_b32_e32 v17, 0
	v_mov_b32_e32 v18, 0
	v_mov_b32_e32 v19, 0
	v_mov_b32_e32 v20, 0
	v_mov_b32_e32 v21, 0
	v_mov_b32_e32 v22, 0
	v_mov_b32_e32 v23, 0
	v_mov_b32_e32 v24, 0
	v_mov_b32_e32 v25, 0
	v_mov_b32_e32 v26, 0
	v_mov_b32_e32 v27, 0
	v_mov_b32_e32 v28, 0
	v_mov_b32_e32 v29, 0
	v_mov_b32_e32 v30, 0
	v_mov_b32_e32 v31, 0
	v_mov_b32_e32 v32, 0
	v_mov_b32_e32 v33, 0
	v_mov_b32_e32 v34, 0
	v_mov_b32_e32 v35, 0
	v_mov_b32_e32 v36, 0
	v_mov_b32_e32 v37, 0
	v_mov_b32_e32 v38, 0
	v_mov_b32_e32 v39, 0
	v_mov_b32_e32 v40, 0
	v_mov_b32_e32 v41, 0
	v_mov_b32_e32 v42, 0
	v_mov_b32_e32 v43, 0
	v_mov_b32_e32 v44, 0
	v_mov_b32_e32 v45, 0
	v_mov_b32_e32 v46, 0
	v_mov_b32_e32 v47, 0
	v_mov_b32_e32 v48, 0
	v_mov_b32_e32 v49, 0
	v_mov_b32_e32 v50, 0
	v_mov_b32_e32 v51, 0
	v_mov_b32_e32 v52, 0
	v_mov_b32_e32 v53, 0
	v_mov_b32_e32 v54, 0
	v_mov_b32_e32 v55, 0
	v_mov_b32_e32 v56, 0
	v_mov_b32_e32 v57, 0
	v_mov_b32_e32 v58, 0
	v_mov_b32_e32 v59, 0
	v_mov_b32_e32 v60, 0
	v_mov_b32_e32 v61, 0
	v_mov_b32_e32 v62, 0
	v_mov_b32_e32 v63, 0
	v_mov_b32_e32 v64, 0
	v_mov_b32_e32 v65, 0
	v_mov_b32_e32 v66, 0
	v_mov_b32_e32 v67, 0
	v_mov_b32_e32 v68, 0
	v_mov_b32_e32 v69, 0
	v_mov_b32_e32 v70, 0
	v_mov_b32_e32 v71, 0
	v_mov_b32_e32 v72, 0
	v_mov_b32_e32 v73, 0
	v_mov_b32_e32 v74, 0
	v_mov_b32_e32 v75, 0
	v_mov_b32_e32 v76, 0
	v_mov_b32_e32 v77, 0
	v_mov_b32_e32 v78, 0
	v_mov_b32_e32 v79, 0
	v_mov_b32_e32 v80, 0
	v_mov_b32_e32 v81, 0
	v_mov_b32_e32 v82, 0
	v_mov_b32_e32 v83, 0
	v_mov_b32_e32 v84, 0
	v_mov_b32_e32 v85, 0
	v_mov_b32_e32 v86, 0
	v_mov_b32_e32 v87, 0
	v_mov_b32_e32 v88, 0
	v_mov_b32_e32 v89, 0
	v_mov_b32_e32 v90, 0
	v_mov_b32_e32 v91, 0
	v_mov_b32_e32 v92, 0
	v_mov_b32_e32 v93, 0
	v_mov_b32_e32 v94, 0
	v_mov_b32_e32 v95, 0
	v_mov_b32_e32 v96, 0
	v_mov_b32_e32 v97, 0
	v_mov_b32_e32 v98, 0
	v_mov_b32_e32 v99, 0
	v_mov_b32_e32 v100, 0
	v_mov_b32_e32 v101, 0
	v_mov_b32_e32 v102, 0
	v_mov_b32_e32 v103, 0
	v_mov_b32_e32 v104, 0
	v_mov_b32_e32 v105, 0
	v_mov_b32_e32 v106, 0
	v_mov_b32_e32 v107, 0
	v_mov_b32_e32 v108, 0
	v_mov_b32_e32 v109, 0
	v_mov_b32_e32 v110, 0
	v_mov_b32_e32 v111, 0
	v_mov_b32_e32 v112, 0
	v_mov_b32_e32 v113, 0
	v_mov_b32_e32 v114, 0
	v_mov_b32_e32 v115, 0
	v_mov_b32_e32 v116, 0
	v_mov_b32_e32 v117, 0
	v_mov_b32_e32 v118, 0
	v_mov_b32_e32 v119, 0
	v_mov_b32_e32 v120, 0
	v_mov_b32_e32 v121, 0
	v_mov_b32_e32 v122, 0
	v_mov_b32_e32 v123, 0
	v_mov_b32_e32 v124, 0
	v_mov_b32_e32 v125, 0
	v_mov_b32_e32 v126, 0
	v_mov_b32_e32 v127, 0
	v_mov_b32_e32 v128, 0
	v_mov_b32_e32 v129, 0
	s_cbranch_scc1 .LBB0_272
	s_setprio 1
	s_barrier

; #define STAGE_A(P, br, kt) do { const char* _g = (const char*)(A + (long)(br) * lda + (long)(kt) * BK); \
;     __builtin_amdgcn_global_load_lds((const unsigned*)(_g + (size_t)offA0), (unsigned*)((char*)(P) + sb0), 16, 0, 0); \
;     __builtin_amdgcn_global_load_lds((const unsigned*)(_g + (size_t)lda * 128 + (size_t)offA0), (unsigned*)((char*)(P) + sb1), 16, 0, 0); } while (0)
; #define STAGE_B(P, br, kt) do { const char* _g = (const char*)(B + (long)(br) * ldb + (long)(kt) * BK); \
;     __builtin_amdgcn_global_load_lds((const unsigned*)(_g + (size_t)offB0), (unsigned*)((char*)(P) + sb0), 16, 0, 0); \
;     __builtin_amdgcn_global_load_lds((const unsigned*)(_g + (size_t)ldb * 128 + (size_t)offB0), (unsigned*)((char*)(P) + sb1), 16, 0, 0); } while (0)
; #define LDA(dst, b, h) for (int m = 0; m < 4; ++m) for (int k = 0; k < 2; ++k) \
;     dst[m][k] = *reinterpret_cast<const bf16x8*>((char*)SA(b, h) + lds_byte(wr * 64 + m * 16 + fr, k * 32 + fq * 8))
; #define LDB(dst, b, h) for (int n = 0; n < 2; ++n) for (int k = 0; k < 2; ++k) \
;     dst[n][k] = *reinterpret_cast<const bf16x8*>((char*)SB(b, h) + lds_byte(wc * 32 + n * 16 + fr, k * 32 + fq * 8))
; #define WAIT_V(n) asm volatile("s_waitcnt vmcnt(" #n ")" ::: "memory")
; #define WAIT_L(n) asm volatile("s_waitcnt lgkmcnt(" #n ")" ::: "memory")
; DI void gemm_core(WVP char* smem, const u16* __restrict__ A, int lda, int ar0, int ar1,
;                   const u16* __restrict__ B, int ldb, int bc0, int K, AccT& acc) {
;     ...
;   for (int t = 0; t < nt - 2; t += 2) {
;     LDB(B0, 0, 0); SCHED; LDA(At, 0, 0); STAGE_A(SA(1, 1), ac1, t + 1);
;     WAIT_L(8); BAR; WAIT_L(0); MMA(0, 0, At, B0); BAR; SCHED;
;     LDB(B1, 0, 1); STAGE_B(SB(0, 0), bb0, t + 2);
;     BAR; WAIT_L(0); MMA(0, 1, At, B1); BAR;
;     LDA(At, 0, 1); STAGE_A(SA(0, 0), ac0, t + 2);
;     BAR; WAIT_L(0); MMA(1, 0, At, B0); BAR; SCHED;
;     STAGE_B(SB(0, 1), bb1, t + 2);
;     WAIT_V(6); BAR; MMA(1, 1, At, B1); BAR;
;     LDB(B0, 1, 0); SCHED; LDA(At, 1, 0); STAGE_A(SA(0, 1), ac1, t + 2);
;     WAIT_L(8); BAR; WAIT_L(0); MMA(0, 0, At, B0); BAR; SCHED;
;     LDB(B1, 1, 1); STAGE_B(SB(1, 0), bb0, t + 3);
;     BAR; WAIT_L(0); MMA(0, 1, At, B1); BAR;
;     LDA(At, 1, 1); STAGE_A(SA(1, 0), ac0, t + 3);
;     BAR; WAIT_L(0); MMA(1, 0, At, B0); BAR; SCHED;
;     STAGE_B(SB(1, 1), bb1, t + 3);
;     WAIT_V(6); BAR; MMA(1, 1, At, B1); BAR;
;   }
.LBB0_273:
	v_add_u32_e32 v155, s0, v153
	v_add_u32_e32 v156, s1, v153
	v_add_u32_e32 v157, s19, v153
	ds_read_b128 v[160:163], v154
	ds_read_b128 v[164:167], v154 offset:1024
	ds_read_b128 v[168:171], v154 offset:2048
	ds_read_b128 v[172:175], v154 offset:3072
	ds_read_b128 v[176:179], v0
	ds_read_b128 v[180:183], v0 offset:1024
	ds_read_b128 v[184:187], v155
	ds_read_b128 v[188:191], v155 offset:1024
	ds_read_b128 v[192:195], v156
	ds_read_b128 v[196:199], v156 offset:1024
	ds_read_b128 v[200:203], v157
	ds_read_b128 v[206:209], v157 offset:1024
	ds_read_b128 v[210:213], v151
	ds_read_b128 v[214:217], v151 offset:1024
	ds_read_b128 v[218:221], v151 offset:2048
	ds_read_b128 v[222:225], v151 offset:3072
	v_add_u32_e32 v158, 0xc000, v140
	v_lshl_add_u64 v[228:229], s[10:11], 0, v[136:137]
	s_mov_b64 s[14:15], 0x1f900080
	v_lshl_add_u64 v[226:227], v[228:229], 0, s[14:15]
	v_readfirstlane_b32 s13, v158
	s_mov_b32 m0, s13
	s_nop 0
	global_load_lds_dwordx4 v[226:227], off
	v_add_u32_e32 v159, 0xe000, v140
	v_lshl_add_u64 v[228:229], s[10:11], 0, v[136:137]
	s_mov_b64 s[14:15], 0x1f910080
	v_lshl_add_u64 v[226:227], v[228:229], 0, s[14:15]
	v_readfirstlane_b32 s13, v159
	s_mov_b32 m0, s13
	s_nop 0
	global_load_lds_dwordx4 v[226:227], off
	s_waitcnt vmcnt(8)
	s_waitcnt lgkmcnt(0)
	s_barrier
	v_mfma_f32_16x16x32_bf16 v[126:129], v[176:179], v[160:163], v[126:129]
	v_mfma_f32_16x16x32_bf16 v[122:125], v[176:179], v[168:171], v[122:125]
	v_mfma_f32_16x16x32_bf16 v[118:121], v[184:187], v[160:163], v[118:121]
	v_mfma_f32_16x16x32_bf16 v[114:117], v[184:187], v[168:171], v[114:117]
	v_mfma_f32_16x16x32_bf16 v[110:113], v[192:195], v[160:163], v[110:113]
	v_mfma_f32_16x16x32_bf16 v[106:109], v[192:195], v[168:171], v[106:109]
	v_mfma_f32_16x16x32_bf16 v[102:105], v[200:203], v[160:163], v[102:105]
	v_mfma_f32_16x16x32_bf16 v[98:101], v[200:203], v[168:171], v[98:101]
	v_mfma_f32_16x16x32_bf16 v[126:129], v[180:183], v[164:167], v[126:129]
	v_mfma_f32_16x16x32_bf16 v[122:125], v[180:183], v[172:175], v[122:125]
	v_mfma_f32_16x16x32_bf16 v[118:121], v[188:191], v[164:167], v[118:121]
	v_mfma_f32_16x16x32_bf16 v[114:117], v[188:191], v[172:175], v[114:117]
	v_mfma_f32_16x16x32_bf16 v[110:113], v[196:199], v[164:167], v[110:113]
	v_mfma_f32_16x16x32_bf16 v[106:109], v[196:199], v[172:175], v[106:109]
	v_mfma_f32_16x16x32_bf16 v[102:105], v[206:209], v[164:167], v[102:105]
	v_mfma_f32_16x16x32_bf16 v[98:101], v[206:209], v[172:175], v[98:101]
	v_mfma_f32_16x16x32_bf16 v[94:97], v[176:179], v[210:213], v[94:97]
	v_mfma_f32_16x16x32_bf16 v[90:93], v[176:179], v[218:221], v[90:93]
	v_mfma_f32_16x16x32_bf16 v[86:89], v[184:187], v[210:213], v[86:89]
	v_mfma_f32_16x16x32_bf16 v[82:85], v[184:187], v[218:221], v[82:85]
	v_mfma_f32_16x16x32_bf16 v[78:81], v[192:195], v[210:213], v[78:81]
	v_mfma_f32_16x16x32_bf16 v[74:77], v[192:195], v[218:221], v[74:77]
	v_mfma_f32_16x16x32_bf16 v[70:73], v[200:203], v[210:213], v[70:73]
	v_mfma_f32_16x16x32_bf16 v[66:69], v[200:203], v[218:221], v[66:69]
	v_mfma_f32_16x16x32_bf16 v[94:97], v[180:183], v[214:217], v[94:97]
	v_mfma_f32_16x16x32_bf16 v[90:93], v[180:183], v[222:225], v[90:93]
	v_mfma_f32_16x16x32_bf16 v[86:89], v[188:191], v[214:217], v[86:89]
	v_mfma_f32_16x16x32_bf16 v[82:85], v[188:191], v[222:225], v[82:85]
	v_mfma_f32_16x16x32_bf16 v[78:81], v[196:199], v[214:217], v[78:81]
	v_mfma_f32_16x16x32_bf16 v[74:77], v[196:199], v[222:225], v[74:77]
	v_mfma_f32_16x16x32_bf16 v[70:73], v[206:209], v[214:217], v[70:73]
	v_mfma_f32_16x16x32_bf16 v[66:69], v[206:209], v[222:225], v[66:69]
	s_barrier
	ds_read_b128 v[176:179], v0 offset:16384
	ds_read_b128 v[180:183], v0 offset:17408
	ds_read_b128 v[184:187], v155 offset:16384
	ds_read_b128 v[188:191], v155 offset:17408
	ds_read_b128 v[192:195], v156 offset:16384
	ds_read_b128 v[196:199], v156 offset:17408
	ds_read_b128 v[200:203], v157 offset:16384
	ds_read_b128 v[206:209], v157 offset:17408
	v_lshl_add_u64 v[228:229], s[10:11], 0, v[132:133]
	s_mov_b64 s[14:15], 0x2300
	v_lshl_add_u64 v[226:227], v[228:229], 0, s[14:15]
	v_readfirstlane_b32 s13, v138
	s_mov_b32 m0, s13
	s_nop 0
	global_load_lds_dwordx4 v[226:227], off
	v_add_u32_e32 v205, 0x2000, v138
	v_lshl_add_u64 v[228:229], s[10:11], 0, v[132:133]
	s_mov_b64 s[14:15], 0x9a300
	v_lshl_add_u64 v[226:227], v[228:229], 0, s[14:15]
	v_readfirstlane_b32 s13, v205
	s_mov_b32 m0, s13
	s_nop 0
	global_load_lds_dwordx4 v[226:227], off
	v_lshl_add_u64 v[228:229], s[10:11], 0, v[134:135]
	v_lshl_add_u64 v[226:227], v[228:229], 0, s[20:21]
	v_readfirstlane_b32 s13, v140
	s_mov_b32 m0, s13
	s_nop 0
	global_load_lds_dwordx4 v[226:227], off
	v_lshl_add_u64 v[228:229], s[10:11], 0, v[134:135]
	v_lshl_add_u64 v[226:227], v[228:229], 0, s[22:23]
	v_readfirstlane_b32 s13, v141
	s_mov_b32 m0, s13
	s_nop 0
	global_load_lds_dwordx4 v[226:227], off
	v_lshl_add_u64 v[228:229], s[10:11], 0, v[132:133]
	s_mov_b64 s[14:15], 0x132300
	v_lshl_add_u64 v[226:227], v[228:229], 0, s[14:15]
	v_readfirstlane_b32 s13, v143
	s_mov_b32 m0, s13
	s_nop 0
	global_load_lds_dwordx4 v[226:227], off
	v_add_u32_e32 v230, 0x2000, v143
	v_lshl_add_u64 v[228:229], s[10:11], 0, v[132:133]
	s_mov_b64 s[14:15], 0x1ca300
	v_lshl_add_u64 v[226:227], v[228:229], 0, s[14:15]
	v_readfirstlane_b32 s13, v230
	s_mov_b32 m0, s13
	s_nop 0
	global_load_lds_dwordx4 v[226:227], off
	s_waitcnt vmcnt(8)
	s_waitcnt lgkmcnt(0)
	s_barrier
; #define STAGE_A(P, br, kt) do { const char* _g = (const char*)(A + (long)(br) * lda + (long)(kt) * BK); \
;     __builtin_amdgcn_global_load_lds((const unsigned*)(_g + (size_t)offA0), (unsigned*)((char*)(P) + sb0), 16, 0, 0); \
;     __builtin_amdgcn_global_load_lds((const unsigned*)(_g + (size_t)lda * 128 + (size_t)offA0), (unsigned*)((char*)(P) + sb1), 16, 0, 0); } while (0)
; #define STAGE_B(P, br, kt) do { const char* _g = (const char*)(B + (long)(br) * ldb + (long)(kt) * BK); \
;     __builtin_amdgcn_global_load_lds((const unsigned*)(_g + (size_t)offB0), (unsigned*)((char*)(P) + sb0), 16, 0, 0); \
;     __builtin_amdgcn_global_load_lds((const unsigned*)(_g + (size_t)ldb * 128 + (size_t)offB0), (unsigned*)((char*)(P) + sb1), 16, 0, 0); } while (0)
; #define LDA(dst, b, h) for (int m = 0; m < 4; ++m) for (int k = 0; k < 2; ++k) \
;     dst[m][k] = *reinterpret_cast<const bf16x8*>((char*)SA(b, h) + lds_byte(wr * 64 + m * 16 + fr, k * 32 + fq * 8))
; #define LDB(dst, b, h) for (int n = 0; n < 2; ++n) for (int k = 0; k < 2; ++k) \
;     dst[n][k] = *reinterpret_cast<const bf16x8*>((char*)SB(b, h) + lds_byte(wc * 32 + n * 16 + fr, k * 32 + fq * 8))
; #define WAIT_V(n) asm volatile("s_waitcnt vmcnt(" #n ")" ::: "memory")
; #define WAIT_L(n) asm volatile("s_waitcnt lgkmcnt(" #n ")" ::: "memory")
; DI void gemm_core(WVP char* smem, const u16* __restrict__ A, int lda, int ar0, int ar1,
;                   const u16* __restrict__ B, int ldb, int bc0, int K, AccT& acc) {
;     ...
;   for (int t = 0; t < nt - 2; t += 2) {
;     LDB(B0, 0, 0); SCHED; LDA(At, 0, 0); STAGE_A(SA(1, 1), ac1, t + 1);
;     WAIT_L(8); BAR; WAIT_L(0); MMA(0, 0, At, B0); BAR; SCHED;
;     LDB(B1, 0, 1); STAGE_B(SB(0, 0), bb0, t + 2);
;     BAR; WAIT_L(0); MMA(0, 1, At, B1); BAR;
;     LDA(At, 0, 1); STAGE_A(SA(0, 0), ac0, t + 2);
;     BAR; WAIT_L(0); MMA(1, 0, At, B0); BAR; SCHED;
;     STAGE_B(SB(0, 1), bb1, t + 2);
;     WAIT_V(6); BAR; MMA(1, 1, At, B1); BAR;
;     LDB(B0, 1, 0); SCHED; LDA(At, 1, 0); STAGE_A(SA(0, 1), ac1, t + 2);
;     WAIT_L(8); BAR; WAIT_L(0); MMA(0, 0, At, B0); BAR; SCHED;
;     LDB(B1, 1, 1); STAGE_B(SB(1, 0), bb0, t + 3);
;     BAR; WAIT_L(0); MMA(0, 1, At, B1); BAR;
;     LDA(At, 1, 1); STAGE_A(SA(1, 0), ac0, t + 3);
;     BAR; WAIT_L(0); MMA(1, 0, At, B0); BAR; SCHED;
;     STAGE_B(SB(1, 1), bb1, t + 3);
;     WAIT_V(6); BAR; MMA(1, 1, At, B1); BAR;
;   }
	v_mfma_f32_16x16x32_bf16 v[62:65], v[176:179], v[160:163], v[62:65]
	v_mfma_f32_16x16x32_bf16 v[58:61], v[176:179], v[168:171], v[58:61]
	v_mfma_f32_16x16x32_bf16 v[54:57], v[184:187], v[160:163], v[54:57]
	v_mfma_f32_16x16x32_bf16 v[50:53], v[184:187], v[168:171], v[50:53]
	v_mfma_f32_16x16x32_bf16 v[46:49], v[192:195], v[160:163], v[46:49]
	v_mfma_f32_16x16x32_bf16 v[42:45], v[192:195], v[168:171], v[42:45]
	v_mfma_f32_16x16x32_bf16 v[38:41], v[200:203], v[160:163], v[38:41]
	v_mfma_f32_16x16x32_bf16 v[34:37], v[200:203], v[168:171], v[34:37]
	v_mfma_f32_16x16x32_bf16 v[62:65], v[180:183], v[164:167], v[62:65]
	v_mfma_f32_16x16x32_bf16 v[58:61], v[180:183], v[172:175], v[58:61]
	v_mfma_f32_16x16x32_bf16 v[54:57], v[188:191], v[164:167], v[54:57]
	v_mfma_f32_16x16x32_bf16 v[50:53], v[188:191], v[172:175], v[50:53]
	v_mfma_f32_16x16x32_bf16 v[46:49], v[196:199], v[164:167], v[46:49]
	v_mfma_f32_16x16x32_bf16 v[42:45], v[196:199], v[172:175], v[42:45]
	v_mfma_f32_16x16x32_bf16 v[38:41], v[206:209], v[164:167], v[38:41]
	v_mfma_f32_16x16x32_bf16 v[34:37], v[206:209], v[172:175], v[34:37]
	v_mfma_f32_16x16x32_bf16 v[30:33], v[176:179], v[210:213], v[30:33]
	v_mfma_f32_16x16x32_bf16 v[26:29], v[176:179], v[218:221], v[26:29]
	v_mfma_f32_16x16x32_bf16 v[22:25], v[184:187], v[210:213], v[22:25]
	v_mfma_f32_16x16x32_bf16 v[18:21], v[184:187], v[218:221], v[18:21]
	v_mfma_f32_16x16x32_bf16 v[14:17], v[192:195], v[210:213], v[14:17]
	v_mfma_f32_16x16x32_bf16 v[10:13], v[192:195], v[218:221], v[10:13]
	v_mfma_f32_16x16x32_bf16 v[6:9], v[200:203], v[210:213], v[6:9]
	v_mfma_f32_16x16x32_bf16 v[2:5], v[200:203], v[218:221], v[2:5]
	v_mfma_f32_16x16x32_bf16 v[30:33], v[180:183], v[214:217], v[30:33]
	v_mfma_f32_16x16x32_bf16 v[26:29], v[180:183], v[222:225], v[26:29]
	v_mfma_f32_16x16x32_bf16 v[22:25], v[188:191], v[214:217], v[22:25]
	v_mfma_f32_16x16x32_bf16 v[18:21], v[188:191], v[222:225], v[18:21]
	v_mfma_f32_16x16x32_bf16 v[14:17], v[196:199], v[214:217], v[14:17]
	v_mfma_f32_16x16x32_bf16 v[10:13], v[196:199], v[222:225], v[10:13]
	v_mfma_f32_16x16x32_bf16 v[6:9], v[206:209], v[214:217], v[6:9]
	v_mfma_f32_16x16x32_bf16 v[2:5], v[206:209], v[222:225], v[2:5]
	s_barrier
	ds_read_b128 v[160:163], v142
	ds_read_b128 v[164:167], v142 offset:1024
	ds_read_b128 v[168:171], v142 offset:2048
	ds_read_b128 v[172:175], v142 offset:3072
	ds_read_b128 v[176:179], v0 offset:32768
	ds_read_b128 v[180:183], v0 offset:33792
	ds_read_b128 v[184:187], v155 offset:32768
	ds_read_b128 v[188:191], v155 offset:33792
	ds_read_b128 v[192:195], v156 offset:32768
	ds_read_b128 v[196:199], v156 offset:33792
	ds_read_b128 v[200:203], v157 offset:32768
	ds_read_b128 v[206:209], v157 offset:33792
	ds_read_b128 v[210:213], v139
	ds_read_b128 v[214:217], v139 offset:1024
	ds_read_b128 v[218:221], v139 offset:2048
	ds_read_b128 v[222:225], v139 offset:3072
	v_lshl_add_u64 v[228:229], s[10:11], 0, v[136:137]
	v_lshl_add_u64 v[226:227], v[228:229], 0, s[20:21]
	v_readfirstlane_b32 s13, v144
	s_mov_b32 m0, s13
	s_nop 0
	global_load_lds_dwordx4 v[226:227], off
	v_lshl_add_u64 v[228:229], s[10:11], 0, v[136:137]
	v_lshl_add_u64 v[226:227], v[228:229], 0, s[22:23]
	v_readfirstlane_b32 s13, v145
	s_mov_b32 m0, s13
	s_nop 0
	global_load_lds_dwordx4 v[226:227], off
	s_waitcnt vmcnt(8)
	s_waitcnt lgkmcnt(0)
	s_barrier
	v_mfma_f32_16x16x32_bf16 v[126:129], v[176:179], v[160:163], v[126:129]
	v_mfma_f32_16x16x32_bf16 v[122:125], v[176:179], v[168:171], v[122:125]
	v_mfma_f32_16x16x32_bf16 v[118:121], v[184:187], v[160:163], v[118:121]
	v_mfma_f32_16x16x32_bf16 v[114:117], v[184:187], v[168:171], v[114:117]
	v_mfma_f32_16x16x32_bf16 v[110:113], v[192:195], v[160:163], v[110:113]
	v_mfma_f32_16x16x32_bf16 v[106:109], v[192:195], v[168:171], v[106:109]
	v_mfma_f32_16x16x32_bf16 v[102:105], v[200:203], v[160:163], v[102:105]
	v_mfma_f32_16x16x32_bf16 v[98:101], v[200:203], v[168:171], v[98:101]
	v_mfma_f32_16x16x32_bf16 v[126:129], v[180:183], v[164:167], v[126:129]
	v_mfma_f32_16x16x32_bf16 v[122:125], v[180:183], v[172:175], v[122:125]
	v_mfma_f32_16x16x32_bf16 v[118:121], v[188:191], v[164:167], v[118:121]
	v_mfma_f32_16x16x32_bf16 v[114:117], v[188:191], v[172:175], v[114:117]
	v_mfma_f32_16x16x32_bf16 v[110:113], v[196:199], v[164:167], v[110:113]
	v_mfma_f32_16x16x32_bf16 v[106:109], v[196:199], v[172:175], v[106:109]
	v_mfma_f32_16x16x32_bf16 v[102:105], v[206:209], v[164:167], v[102:105]
	v_mfma_f32_16x16x32_bf16 v[98:101], v[206:209], v[172:175], v[98:101]
	v_mfma_f32_16x16x32_bf16 v[94:97], v[176:179], v[210:213], v[94:97]
	v_mfma_f32_16x16x32_bf16 v[90:93], v[176:179], v[218:221], v[90:93]
	v_mfma_f32_16x16x32_bf16 v[86:89], v[184:187], v[210:213], v[86:89]
	v_mfma_f32_16x16x32_bf16 v[82:85], v[184:187], v[218:221], v[82:85]
	v_mfma_f32_16x16x32_bf16 v[78:81], v[192:195], v[210:213], v[78:81]
	v_mfma_f32_16x16x32_bf16 v[74:77], v[192:195], v[218:221], v[74:77]
	v_mfma_f32_16x16x32_bf16 v[70:73], v[200:203], v[210:213], v[70:73]
	v_mfma_f32_16x16x32_bf16 v[66:69], v[200:203], v[218:221], v[66:69]
	v_mfma_f32_16x16x32_bf16 v[94:97], v[180:183], v[214:217], v[94:97]
	v_mfma_f32_16x16x32_bf16 v[90:93], v[180:183], v[222:225], v[90:93]
	v_mfma_f32_16x16x32_bf16 v[86:89], v[188:191], v[214:217], v[86:89]
	v_mfma_f32_16x16x32_bf16 v[82:85], v[188:191], v[222:225], v[82:85]
	v_mfma_f32_16x16x32_bf16 v[78:81], v[196:199], v[214:217], v[78:81]
	v_mfma_f32_16x16x32_bf16 v[74:77], v[196:199], v[222:225], v[74:77]
	v_mfma_f32_16x16x32_bf16 v[70:73], v[206:209], v[214:217], v[70:73]
	v_mfma_f32_16x16x32_bf16 v[66:69], v[206:209], v[222:225], v[66:69]
	s_barrier
; #define STAGE_A(P, br, kt) do { const char* _g = (const char*)(A + (long)(br) * lda + (long)(kt) * BK); \
;     __builtin_amdgcn_global_load_lds((const unsigned*)(_g + (size_t)offA0), (unsigned*)((char*)(P) + sb0), 16, 0, 0); \
;     __builtin_amdgcn_global_load_lds((const unsigned*)(_g + (size_t)lda * 128 + (size_t)offA0), (unsigned*)((char*)(P) + sb1), 16, 0, 0); } while (0)
; #define STAGE_B(P, br, kt) do { const char* _g = (const char*)(B + (long)(br) * ldb + (long)(kt) * BK); \
;     __builtin_amdgcn_global_load_lds((const unsigned*)(_g + (size_t)offB0), (unsigned*)((char*)(P) + sb0), 16, 0, 0); \
;     __builtin_amdgcn_global_load_lds((const unsigned*)(_g + (size_t)ldb * 128 + (size_t)offB0), (unsigned*)((char*)(P) + sb1), 16, 0, 0); } while (0)
; #define LDA(dst, b, h) for (int m = 0; m < 4; ++m) for (int k = 0; k < 2; ++k) \
;     dst[m][k] = *reinterpret_cast<const bf16x8*>((char*)SA(b, h) + lds_byte(wr * 64 + m * 16 + fr, k * 32 + fq * 8))
; #define LDB(dst, b, h) for (int n = 0; n < 2; ++n) for (int k = 0; k < 2; ++k) \
;     dst[n][k] = *reinterpret_cast<const bf16x8*>((char*)SB(b, h) + lds_byte(wc * 32 + n * 16 + fr, k * 32 + fq * 8))
; #define WAIT_V(n) asm volatile("s_waitcnt vmcnt(" #n ")" ::: "memory")
; DI void gemm_core(WVP char* smem, const u16* __restrict__ A, int lda, int ar0, int ar1,
;                   const u16* __restrict__ B, int ldb, int bc0, int K, AccT& acc) {
;     ...
;   for (int t = 0; t < nt - 2; t += 2) {
;     LDB(B0, 0, 0); SCHED; LDA(At, 0, 0); STAGE_A(SA(1, 1), ac1, t + 1);
;     WAIT_L(8); BAR; WAIT_L(0); MMA(0, 0, At, B0); BAR; SCHED;
;     LDB(B1, 0, 1); STAGE_B(SB(0, 0), bb0, t + 2);
;     BAR; WAIT_L(0); MMA(0, 1, At, B1); BAR;
;     LDA(At, 0, 1); STAGE_A(SA(0, 0), ac0, t + 2);
;     BAR; WAIT_L(0); MMA(1, 0, At, B0); BAR; SCHED;
;     STAGE_B(SB(0, 1), bb1, t + 2);
;     WAIT_V(6); BAR; MMA(1, 1, At, B1); BAR;
;     LDB(B0, 1, 0); SCHED; LDA(At, 1, 0); STAGE_A(SA(0, 1), ac1, t + 2);
;     WAIT_L(8); BAR; WAIT_L(0); MMA(0, 0, At, B0); BAR; SCHED;
;     LDB(B1, 1, 1); STAGE_B(SB(1, 0), bb0, t + 3);
;     BAR; WAIT_L(0); MMA(0, 1, At, B1); BAR;
;     LDA(At, 1, 1); STAGE_A(SA(1, 0), ac0, t + 3);
;     BAR; WAIT_L(0); MMA(1, 0, At, B0); BAR; SCHED;
;     STAGE_B(SB(1, 1), bb1, t + 3);
;     WAIT_V(6); BAR; MMA(1, 1, At, B1); BAR;
;   }
;   { LDB(B0, 0, 0); LDA(At, 0, 0); STAGE_A(SA(1, 1), ac1, nt - 1);
	ds_read_b128 v[176:179], v0 offset:49152
	ds_read_b128 v[180:183], v0 offset:50176
	ds_read_b128 v[184:187], v155 offset:49152
	ds_read_b128 v[188:191], v155 offset:50176
	ds_read_b128 v[192:195], v156 offset:49152
	ds_read_b128 v[196:199], v156 offset:50176
	ds_read_b128 v[200:203], v157 offset:49152
	ds_read_b128 v[206:209], v157 offset:50176
	v_lshl_add_u64 v[228:229], s[10:11], 0, v[132:133]
	s_mov_b64 s[14:15], 0x2380
	v_lshl_add_u64 v[226:227], v[228:229], 0, s[14:15]
	v_readfirstlane_b32 s13, v146
	s_mov_b32 m0, s13
	s_nop 0
	global_load_lds_dwordx4 v[226:227], off
	v_lshl_add_u64 v[228:229], s[10:11], 0, v[132:133]
	s_mov_b64 s[14:15], 0x9a380
	v_lshl_add_u64 v[226:227], v[228:229], 0, s[14:15]
	v_readfirstlane_b32 s13, v147
	s_mov_b32 m0, s13
	s_nop 0
	global_load_lds_dwordx4 v[226:227], off
	v_lshl_add_u64 v[228:229], s[10:11], 0, v[134:135]
	s_mov_b64 s[14:15], 0x1f900180
	v_lshl_add_u64 v[226:227], v[228:229], 0, s[14:15]
	v_readfirstlane_b32 s13, v148
	s_mov_b32 m0, s13
	s_nop 0
	global_load_lds_dwordx4 v[226:227], off
	v_lshl_add_u64 v[228:229], s[10:11], 0, v[134:135]
	s_mov_b64 s[14:15], 0x1f910180
	v_lshl_add_u64 v[226:227], v[228:229], 0, s[14:15]
	v_readfirstlane_b32 s13, v149
	s_mov_b32 m0, s13
	s_nop 0
	global_load_lds_dwordx4 v[226:227], off
	v_lshl_add_u64 v[228:229], s[10:11], 0, v[132:133]
	s_mov_b64 s[14:15], 0x132380
	v_lshl_add_u64 v[226:227], v[228:229], 0, s[14:15]
	v_readfirstlane_b32 s13, v150
	s_mov_b32 m0, s13
	s_nop 0
	global_load_lds_dwordx4 v[226:227], off
	v_lshl_add_u64 v[228:229], s[10:11], 0, v[132:133]
	s_mov_b64 s[14:15], 0x1ca380
	v_lshl_add_u64 v[226:227], v[228:229], 0, s[14:15]
	v_readfirstlane_b32 s13, v152
	s_mov_b32 m0, s13
	s_nop 0
	global_load_lds_dwordx4 v[226:227], off
	s_waitcnt vmcnt(8)
	s_waitcnt lgkmcnt(0)
	s_barrier
	v_mfma_f32_16x16x32_bf16 v[62:65], v[176:179], v[160:163], v[62:65]
	v_mfma_f32_16x16x32_bf16 v[58:61], v[176:179], v[168:171], v[58:61]
	v_mfma_f32_16x16x32_bf16 v[54:57], v[184:187], v[160:163], v[54:57]
	v_mfma_f32_16x16x32_bf16 v[50:53], v[184:187], v[168:171], v[50:53]
	v_mfma_f32_16x16x32_bf16 v[46:49], v[192:195], v[160:163], v[46:49]
	v_mfma_f32_16x16x32_bf16 v[42:45], v[192:195], v[168:171], v[42:45]
	v_mfma_f32_16x16x32_bf16 v[38:41], v[200:203], v[160:163], v[38:41]
	v_mfma_f32_16x16x32_bf16 v[34:37], v[200:203], v[168:171], v[34:37]
	v_mfma_f32_16x16x32_bf16 v[62:65], v[180:183], v[164:167], v[62:65]
	v_mfma_f32_16x16x32_bf16 v[58:61], v[180:183], v[172:175], v[58:61]
	v_mfma_f32_16x16x32_bf16 v[54:57], v[188:191], v[164:167], v[54:57]
	v_mfma_f32_16x16x32_bf16 v[50:53], v[188:191], v[172:175], v[50:53]
	v_mfma_f32_16x16x32_bf16 v[46:49], v[196:199], v[164:167], v[46:49]
	v_mfma_f32_16x16x32_bf16 v[42:45], v[196:199], v[172:175], v[42:45]
	v_mfma_f32_16x16x32_bf16 v[38:41], v[206:209], v[164:167], v[38:41]
	v_mfma_f32_16x16x32_bf16 v[34:37], v[206:209], v[172:175], v[34:37]
	v_mfma_f32_16x16x32_bf16 v[30:33], v[176:179], v[210:213], v[30:33]
	v_mfma_f32_16x16x32_bf16 v[26:29], v[176:179], v[218:221], v[26:29]
	v_mfma_f32_16x16x32_bf16 v[22:25], v[184:187], v[210:213], v[22:25]
	v_mfma_f32_16x16x32_bf16 v[18:21], v[184:187], v[218:221], v[18:21]
	v_mfma_f32_16x16x32_bf16 v[14:17], v[192:195], v[210:213], v[14:17]
	v_mfma_f32_16x16x32_bf16 v[10:13], v[192:195], v[218:221], v[10:13]
	v_mfma_f32_16x16x32_bf16 v[6:9], v[200:203], v[210:213], v[6:9]
	v_mfma_f32_16x16x32_bf16 v[2:5], v[200:203], v[218:221], v[2:5]
	v_mfma_f32_16x16x32_bf16 v[30:33], v[180:183], v[214:217], v[30:33]
	v_mfma_f32_16x16x32_bf16 v[26:29], v[180:183], v[222:225], v[26:29]
	v_mfma_f32_16x16x32_bf16 v[22:25], v[188:191], v[214:217], v[22:25]
	v_mfma_f32_16x16x32_bf16 v[18:21], v[188:191], v[222:225], v[18:21]
	v_mfma_f32_16x16x32_bf16 v[14:17], v[196:199], v[214:217], v[14:17]
	v_mfma_f32_16x16x32_bf16 v[10:13], v[196:199], v[222:225], v[10:13]
	v_mfma_f32_16x16x32_bf16 v[6:9], v[206:209], v[214:217], v[6:9]
	v_mfma_f32_16x16x32_bf16 v[2:5], v[206:209], v[222:225], v[2:5]
	s_add_i32 s12, s12, 2
	s_add_u32 s10, s10, 0x100
	s_addc_u32 s11, s11, 0
	s_cmp_lt_u32 s12, 4
	s_barrier
	s_cbranch_scc1 .LBB0_273
	s_mov_b64 s[0:1], 0x380
	v_lshl_add_u64 v[136:137], v[130:131], 0, s[0:1]
	v_readfirstlane_b32 s0, v158
	s_mov_b32 m0, s0
	s_mov_b64 s[0:1], 0x10380
	v_lshl_add_u64 v[130:131], v[130:131], 0, s[0:1]
	v_readfirstlane_b32 s0, v159
	ds_read_b128 v[132:135], v154
	ds_read_b128 v[144:147], v154 offset:1024
	ds_read_b128 v[160:163], v154 offset:2048
	ds_read_b128 v[164:167], v154 offset:3072
	ds_read_b128 v[168:171], v0
	ds_read_b128 v[172:175], v0 offset:1024
	ds_read_b128 v[176:179], v155
	ds_read_b128 v[180:183], v155 offset:1024
	ds_read_b128 v[184:187], v156
	ds_read_b128 v[188:191], v156 offset:1024
	ds_read_b128 v[192:195], v157
	ds_read_b128 v[196:199], v157 offset:1024
	global_load_lds_dwordx4 v[136:137], off
	s_mov_b32 m0, s0
	s_nop 0
	global_load_lds_dwordx4 v[130:131], off
	s_waitcnt vmcnt(8)
	s_barrier
	s_waitcnt lgkmcnt(0)
	s_setprio 1
	s_waitcnt lgkmcnt(0)
	v_mfma_f32_16x16x32_bf16 v[126:129], v[168:171], v[132:135], v[126:129]
	v_mfma_f32_16x16x32_bf16 v[122:125], v[168:171], v[160:163], v[122:125]
	v_mfma_f32_16x16x32_bf16 v[118:121], v[176:179], v[132:135], v[118:121]
	v_mfma_f32_16x16x32_bf16 v[110:113], v[184:187], v[132:135], v[110:113]
	v_mfma_f32_16x16x32_bf16 v[98:101], v[192:195], v[160:163], v[98:101]
	v_mfma_f32_16x16x32_bf16 v[126:129], v[172:175], v[144:147], v[126:129]
	v_mfma_f32_16x16x32_bf16 v[122:125], v[172:175], v[164:167], v[122:125]
	v_mfma_f32_16x16x32_bf16 v[118:121], v[180:183], v[144:147], v[118:121]
	v_mfma_f32_16x16x32_bf16 v[114:117], v[176:179], v[160:163], v[114:117]
	v_mfma_f32_16x16x32_bf16 v[110:113], v[188:191], v[144:147], v[110:113]
	v_mfma_f32_16x16x32_bf16 v[106:109], v[184:187], v[160:163], v[106:109]
	v_mfma_f32_16x16x32_bf16 v[102:105], v[192:195], v[132:135], v[102:105]
	v_mfma_f32_16x16x32_bf16 v[98:101], v[196:199], v[164:167], v[98:101]
	v_mfma_f32_16x16x32_bf16 v[200:203], v[180:183], v[164:167], v[114:117]
	v_mfma_f32_16x16x32_bf16 v[206:209], v[188:191], v[164:167], v[106:109]
	v_mfma_f32_16x16x32_bf16 v[210:213], v[196:199], v[144:147], v[102:105]
	s_setprio 0
	s_barrier
; #define LDA(dst, b, h) for (int m = 0; m < 4; ++m) for (int k = 0; k < 2; ++k) \
;     dst[m][k] = *reinterpret_cast<const bf16x8*>((char*)SA(b, h) + lds_byte(wr * 64 + m * 16 + fr, k * 32 + fq * 8))
; #define LDB(dst, b, h) for (int n = 0; n < 2; ++n) for (int k = 0; k < 2; ++k) \
;     dst[n][k] = *reinterpret_cast<const bf16x8*>((char*)SB(b, h) + lds_byte(wc * 32 + n * 16 + fr, k * 32 + fq * 8))
; #define MMA(ai, bj, At_, Bt_) do { __builtin_amdgcn_s_setprio(1); \
;     for (int m = 0; m < 4; ++m) for (int n = 0; n < 2; ++n) for (int k = 0; k < 2; ++k) \
;       acc[ai][bj][m][n] = MFMA16(At_[m][k], Bt_[n][k], acc[ai][bj][m][n]); \
;     __builtin_amdgcn_s_setprio(0); } while (0)
; #define WAIT_V(n) asm volatile("s_waitcnt vmcnt(" #n ")" ::: "memory")
; #define WAIT_L(n) asm volatile("s_waitcnt lgkmcnt(" #n ")" ::: "memory")
; #define BAR __builtin_amdgcn_s_barrier()
; DI void gemm_core(WVP char* smem, const u16* __restrict__ A, int lda, int ar0, int ar1,
;                   const u16* __restrict__ B, int ldb, int bc0, int K, AccT& acc) {
;     ...
;     BAR; WAIT_L(0); MMA(0, 0, At, B0); BAR;
;     LDB(B1, 0, 1); BAR; WAIT_L(0); MMA(0, 1, At, B1); BAR;
;     LDA(At, 0, 1); WAIT_V(4); BAR; WAIT_L(0); MMA(1, 0, At, B0); MMA(1, 1, At, B1); BAR; }
;   { LDB(B0, 1, 0); LDA(At, 1, 0); WAIT_V(2); BAR; WAIT_L(0); MMA(0, 0, At, B0); BAR;
	s_nop 1
	ds_read_b128 v[102:105], v151
	ds_read_b128 v[106:109], v151 offset:1024
	ds_read_b128 v[114:117], v151 offset:2048
	ds_read_b128 v[148:151], v151 offset:3072
	s_barrier
	s_waitcnt lgkmcnt(0)
	s_setprio 1
	s_waitcnt lgkmcnt(0)
	v_mfma_f32_16x16x32_bf16 v[90:93], v[168:171], v[114:117], v[90:93]
	v_mfma_f32_16x16x32_bf16 v[86:89], v[176:179], v[102:105], v[86:89]
	v_mfma_f32_16x16x32_bf16 v[78:81], v[184:187], v[102:105], v[78:81]
	v_mfma_f32_16x16x32_bf16 v[66:69], v[192:195], v[114:117], v[66:69]
	v_mfma_f32_16x16x32_bf16 v[94:97], v[168:171], v[102:105], v[94:97]
	v_mfma_f32_16x16x32_bf16 v[90:93], v[172:175], v[148:151], v[90:93]
	v_mfma_f32_16x16x32_bf16 v[86:89], v[180:183], v[106:109], v[86:89]
	v_mfma_f32_16x16x32_bf16 v[82:85], v[176:179], v[114:117], v[82:85]
	v_mfma_f32_16x16x32_bf16 v[78:81], v[188:191], v[106:109], v[78:81]
	v_mfma_f32_16x16x32_bf16 v[74:77], v[184:187], v[114:117], v[74:77]
	v_mfma_f32_16x16x32_bf16 v[70:73], v[192:195], v[102:105], v[70:73]
	v_mfma_f32_16x16x32_bf16 v[66:69], v[196:199], v[148:151], v[66:69]
	v_mfma_f32_16x16x32_bf16 v[214:217], v[172:175], v[106:109], v[94:97]
	v_mfma_f32_16x16x32_bf16 v[168:171], v[180:183], v[148:151], v[82:85]
	v_mfma_f32_16x16x32_bf16 v[172:175], v[188:191], v[148:151], v[74:77]
	v_mfma_f32_16x16x32_bf16 v[176:179], v[196:199], v[106:109], v[70:73]
	s_setprio 0
	s_barrier
	s_nop 0
	ds_read_b128 v[70:73], v0 offset:16384
	ds_read_b128 v[74:77], v0 offset:17408
	ds_read_b128 v[82:85], v155 offset:16384
	ds_read_b128 v[94:97], v155 offset:17408
	ds_read_b128 v[180:183], v156 offset:16384
	ds_read_b128 v[184:187], v156 offset:17408
	ds_read_b128 v[188:191], v157 offset:16384
	ds_read_b128 v[192:195], v157 offset:17408
	s_waitcnt vmcnt(4)
	s_barrier
	s_waitcnt lgkmcnt(0)
	s_setprio 1
	s_waitcnt lgkmcnt(0)
	v_mfma_f32_16x16x32_bf16 v[62:65], v[70:73], v[132:135], v[62:65]
	v_mfma_f32_16x16x32_bf16 v[50:53], v[82:85], v[160:163], v[50:53]
	v_mfma_f32_16x16x32_bf16 v[46:49], v[180:183], v[132:135], v[46:49]
	v_mfma_f32_16x16x32_bf16 v[34:37], v[188:191], v[160:163], v[34:37]
	v_mfma_f32_16x16x32_bf16 v[62:65], v[74:77], v[144:147], v[62:65]
	v_mfma_f32_16x16x32_bf16 v[58:61], v[70:73], v[160:163], v[58:61]
	v_mfma_f32_16x16x32_bf16 v[54:57], v[82:85], v[132:135], v[54:57]
	v_mfma_f32_16x16x32_bf16 v[50:53], v[94:97], v[164:167], v[50:53]
	v_mfma_f32_16x16x32_bf16 v[46:49], v[184:187], v[144:147], v[46:49]
	v_mfma_f32_16x16x32_bf16 v[42:45], v[180:183], v[160:163], v[42:45]
	v_mfma_f32_16x16x32_bf16 v[38:41], v[188:191], v[132:135], v[38:41]
	v_mfma_f32_16x16x32_bf16 v[34:37], v[192:195], v[164:167], v[34:37]
	v_mfma_f32_16x16x32_bf16 v[196:199], v[74:77], v[164:167], v[58:61]
	v_mfma_f32_16x16x32_bf16 v[218:221], v[94:97], v[144:147], v[54:57]
	v_mfma_f32_16x16x32_bf16 v[222:225], v[184:187], v[164:167], v[42:45]
	v_mfma_f32_16x16x32_bf16 v[130:133], v[192:195], v[144:147], v[38:41]
	s_setprio 0
	s_setprio 1
	v_mfma_f32_16x16x32_bf16 v[26:29], v[70:73], v[114:117], v[26:29]
	v_mfma_f32_16x16x32_bf16 v[18:21], v[82:85], v[114:117], v[18:21]
	v_mfma_f32_16x16x32_bf16 v[14:17], v[180:183], v[102:105], v[14:17]
	v_mfma_f32_16x16x32_bf16 v[30:33], v[70:73], v[102:105], v[30:33]
	v_mfma_f32_16x16x32_bf16 v[26:29], v[74:77], v[148:151], v[26:29]
	v_mfma_f32_16x16x32_bf16 v[22:25], v[82:85], v[102:105], v[22:25]
	v_mfma_f32_16x16x32_bf16 v[18:21], v[94:97], v[148:151], v[18:21]
	v_mfma_f32_16x16x32_bf16 v[14:17], v[184:187], v[106:109], v[14:17]
	v_mfma_f32_16x16x32_bf16 v[10:13], v[180:183], v[114:117], v[10:13]
	v_mfma_f32_16x16x32_bf16 v[6:9], v[188:191], v[102:105], v[6:9]
	v_mfma_f32_16x16x32_bf16 v[2:5], v[188:191], v[114:117], v[2:5]
	v_mfma_f32_16x16x32_bf16 v[134:137], v[74:77], v[106:109], v[30:33]
	v_mfma_f32_16x16x32_bf16 v[144:147], v[94:97], v[106:109], v[22:25]
	v_mfma_f32_16x16x32_bf16 v[158:161], v[184:187], v[148:151], v[10:13]
	v_mfma_f32_16x16x32_bf16 v[162:165], v[192:195], v[106:109], v[6:9]
	v_mfma_f32_16x16x32_bf16 v[148:151], v[192:195], v[148:151], v[2:5]
	s_setprio 0
	s_barrier
	ds_read_b128 v[180:183], v142
	ds_read_b128 v[184:187], v142 offset:1024
	ds_read_b128 v[188:191], v142 offset:2048
	ds_read_b128 v[140:143], v142 offset:3072
	ds_read_b128 v[2:5], v0 offset:32768
	ds_read_b128 v[6:9], v0 offset:33792
	ds_read_b128 v[10:13], v155 offset:32768
	ds_read_b128 v[22:25], v155 offset:33792
	ds_read_b128 v[192:195], v156 offset:32768
	ds_read_b128 v[226:229], v156 offset:33792
	ds_read_b128 v[230:233], v157 offset:32768
	ds_read_b128 v[234:237], v157 offset:33792
	s_waitcnt vmcnt(2)
	s_barrier
; #define LDA(dst, b, h) for (int m = 0; m < 4; ++m) for (int k = 0; k < 2; ++k) \
;     dst[m][k] = *reinterpret_cast<const bf16x8*>((char*)SA(b, h) + lds_byte(wr * 64 + m * 16 + fr, k * 32 + fq * 8))
; #define LDB(dst, b, h) for (int n = 0; n < 2; ++n) for (int k = 0; k < 2; ++k) \
;     dst[n][k] = *reinterpret_cast<const bf16x8*>((char*)SB(b, h) + lds_byte(wc * 32 + n * 16 + fr, k * 32 + fq * 8))
; #define MMA(ai, bj, At_, Bt_) do { __builtin_amdgcn_s_setprio(1); \
;     for (int m = 0; m < 4; ++m) for (int n = 0; n < 2; ++n) for (int k = 0; k < 2; ++k) \
;       acc[ai][bj][m][n] = MFMA16(At_[m][k], Bt_[n][k], acc[ai][bj][m][n]); \
;     __builtin_amdgcn_s_setprio(0); } while (0)
; #define WAIT_V(n) asm volatile("s_waitcnt vmcnt(" #n ")" ::: "memory")
; #define WAIT_L(n) asm volatile("s_waitcnt lgkmcnt(" #n ")" ::: "memory")
; #define BAR __builtin_amdgcn_s_barrier()
; DI void gemm_core(WVP char* smem, const u16* __restrict__ A, int lda, int ar0, int ar1,
;                   const u16* __restrict__ B, int ldb, int bc0, int K, AccT& acc) {
;     ...
;   { LDB(B0, 1, 0); LDA(At, 1, 0); WAIT_V(2); BAR; WAIT_L(0); MMA(0, 0, At, B0); BAR;
;     LDB(B1, 1, 1); WAIT_V(0); BAR; WAIT_L(0); MMA(0, 1, At, B1); BAR;
;     LDA(At, 1, 1); BAR; WAIT_L(0); MMA(1, 0, At, B0); MMA(1, 1, At, B1); BAR; }
;   if (wr == 0) BAR;
	s_waitcnt lgkmcnt(0)
	s_setprio 1
	s_waitcnt lgkmcnt(0)
	v_mfma_f32_16x16x32_bf16 v[30:33], v[2:5], v[180:183], v[126:129]
	v_mfma_f32_16x16x32_bf16 v[114:117], v[6:9], v[184:187], v[30:33]
	v_mfma_f32_16x16x32_bf16 v[30:33], v[2:5], v[188:191], v[122:125]
	v_mfma_f32_16x16x32_bf16 v[106:109], v[6:9], v[140:143], v[30:33]
	v_mfma_f32_16x16x32_bf16 v[30:33], v[10:13], v[180:183], v[118:121]
	v_mfma_f32_16x16x32_bf16 v[102:105], v[22:25], v[184:187], v[30:33]
	v_mfma_f32_16x16x32_bf16 v[30:33], v[10:13], v[188:191], v[200:203]
	v_mfma_f32_16x16x32_bf16 v[94:97], v[22:25], v[140:143], v[30:33]
	v_mfma_f32_16x16x32_bf16 v[30:33], v[192:195], v[180:183], v[110:113]
	v_mfma_f32_16x16x32_bf16 v[82:85], v[226:229], v[184:187], v[30:33]
	v_mfma_f32_16x16x32_bf16 v[30:33], v[192:195], v[188:191], v[206:209]
	v_mfma_f32_16x16x32_bf16 v[74:77], v[226:229], v[140:143], v[30:33]
	v_mfma_f32_16x16x32_bf16 v[30:33], v[230:233], v[180:183], v[210:213]
	v_mfma_f32_16x16x32_bf16 v[70:73], v[234:237], v[184:187], v[30:33]
	v_mfma_f32_16x16x32_bf16 v[30:33], v[230:233], v[188:191], v[98:101]
	v_mfma_f32_16x16x32_bf16 v[58:61], v[234:237], v[140:143], v[30:33]
	s_setprio 0
	s_barrier
	ds_read_b128 v[200:203], v139
	ds_read_b128 v[206:209], v139 offset:1024
	ds_read_b128 v[210:213], v139 offset:2048
	ds_read_b128 v[238:241], v139 offset:3072
	s_waitcnt vmcnt(0)
	s_barrier
	s_waitcnt lgkmcnt(0)
	s_setprio 1
	s_waitcnt lgkmcnt(0)
	v_mfma_f32_16x16x32_bf16 v[30:33], v[2:5], v[200:203], v[214:217]
	v_mfma_f32_16x16x32_bf16 v[2:5], v[2:5], v[210:213], v[90:93]
	v_mfma_f32_16x16x32_bf16 v[42:45], v[6:9], v[238:241], v[2:5]
	v_mfma_f32_16x16x32_bf16 v[2:5], v[10:13], v[200:203], v[86:89]
	v_mfma_f32_16x16x32_bf16 v[38:41], v[22:25], v[206:209], v[2:5]
	v_mfma_f32_16x16x32_bf16 v[2:5], v[10:13], v[210:213], v[168:171]
	v_mfma_f32_16x16x32_bf16 v[54:57], v[6:9], v[206:209], v[30:33]
	v_mfma_f32_16x16x32_bf16 v[30:33], v[22:25], v[238:241], v[2:5]
	v_mfma_f32_16x16x32_bf16 v[2:5], v[192:195], v[200:203], v[78:81]
	v_mfma_f32_16x16x32_bf16 v[22:25], v[226:229], v[206:209], v[2:5]
	v_mfma_f32_16x16x32_bf16 v[2:5], v[192:195], v[210:213], v[172:175]
	v_mfma_f32_16x16x32_bf16 v[10:13], v[226:229], v[238:241], v[2:5]
	v_mfma_f32_16x16x32_bf16 v[2:5], v[230:233], v[200:203], v[176:179]
	v_mfma_f32_16x16x32_bf16 v[6:9], v[234:237], v[206:209], v[2:5]
	v_mfma_f32_16x16x32_bf16 v[2:5], v[230:233], v[210:213], v[66:69]
	v_mfma_f32_16x16x32_bf16 v[2:5], v[234:237], v[238:241], v[2:5]
	s_setprio 0
	s_barrier
	ds_read_b128 v[166:169], v0 offset:49152
	ds_read_b128 v[170:173], v0 offset:50176
	ds_read_b128 v[174:177], v155 offset:49152
	ds_read_b128 v[152:155], v155 offset:50176
	ds_read_b128 v[192:195], v156 offset:49152
	ds_read_b128 v[214:217], v156 offset:50176
	ds_read_b128 v[226:229], v157 offset:49152
	ds_read_b128 v[230:233], v157 offset:50176
	s_barrier
	s_waitcnt lgkmcnt(0)
	s_setprio 1
	s_waitcnt lgkmcnt(0)
	v_mfma_f32_16x16x32_bf16 v[62:65], v[166:169], v[180:183], v[62:65]
	v_mfma_f32_16x16x32_bf16 v[46:49], v[192:195], v[180:183], v[46:49]
	v_mfma_f32_16x16x32_bf16 v[126:129], v[170:173], v[184:187], v[62:65]
	v_mfma_f32_16x16x32_bf16 v[62:65], v[166:169], v[188:191], v[196:199]
	v_mfma_f32_16x16x32_bf16 v[98:101], v[214:217], v[184:187], v[46:49]
	v_mfma_f32_16x16x32_bf16 v[46:49], v[192:195], v[188:191], v[222:225]
	v_mfma_f32_16x16x32_bf16 v[122:125], v[170:173], v[140:143], v[62:65]
	v_mfma_f32_16x16x32_bf16 v[62:65], v[174:177], v[180:183], v[218:221]
	v_mfma_f32_16x16x32_bf16 v[50:53], v[174:177], v[188:191], v[50:53]
	v_mfma_f32_16x16x32_bf16 v[90:93], v[214:217], v[140:143], v[46:49]
	v_mfma_f32_16x16x32_bf16 v[46:49], v[226:229], v[180:183], v[130:133]
	v_mfma_f32_16x16x32_bf16 v[34:37], v[226:229], v[188:191], v[34:37]
	v_mfma_f32_16x16x32_bf16 v[118:121], v[152:155], v[184:187], v[62:65]
	v_mfma_f32_16x16x32_bf16 v[110:113], v[152:155], v[140:143], v[50:53]
	v_mfma_f32_16x16x32_bf16 v[86:89], v[230:233], v[184:187], v[46:49]
	v_mfma_f32_16x16x32_bf16 v[78:81], v[230:233], v[140:143], v[34:37]
	s_setprio 0
	s_setprio 1
	v_mfma_f32_16x16x32_bf16 v[34:37], v[166:169], v[200:203], v[134:137]
	v_mfma_f32_16x16x32_bf16 v[26:29], v[166:169], v[210:213], v[26:29]
	v_mfma_f32_16x16x32_bf16 v[14:17], v[192:195], v[200:203], v[14:17]
	v_mfma_f32_16x16x32_bf16 v[66:69], v[170:173], v[206:209], v[34:37]
	v_mfma_f32_16x16x32_bf16 v[62:65], v[170:173], v[238:241], v[26:29]
	v_mfma_f32_16x16x32_bf16 v[26:29], v[174:177], v[200:203], v[144:147]
	v_mfma_f32_16x16x32_bf16 v[34:37], v[214:217], v[206:209], v[14:17]
	v_mfma_f32_16x16x32_bf16 v[14:17], v[192:195], v[210:213], v[158:161]
	v_mfma_f32_16x16x32_bf16 v[50:53], v[152:155], v[206:209], v[26:29]
	v_mfma_f32_16x16x32_bf16 v[18:21], v[174:177], v[210:213], v[18:21]
	v_mfma_f32_16x16x32_bf16 v[26:29], v[214:217], v[238:241], v[14:17]
	v_mfma_f32_16x16x32_bf16 v[14:17], v[226:229], v[200:203], v[162:165]
	v_mfma_f32_16x16x32_bf16 v[46:49], v[152:155], v[238:241], v[18:21]
	v_mfma_f32_16x16x32_bf16 v[18:21], v[230:233], v[206:209], v[14:17]
	v_mfma_f32_16x16x32_bf16 v[14:17], v[226:229], v[210:213], v[148:151]
	v_mfma_f32_16x16x32_bf16 v[14:17], v[230:233], v[238:241], v[14:17]
	s_setprio 0
	s_cmp_gt_u32 s18, 3
	s_barrier
	s_cbranch_scc1 .LBB0_265
	s_barrier
	s_branch .LBB0_265

; DI int get_tid(int wv) { int l; asm volatile("v_mbcnt_lo_u32_b32 %0, -1, 0\n\tv_mbcnt_hi_u32_b32 %0, -1, %0" : "=v"(l)); return wv * 64 + l; }
; DI int wave_of(int tid) { return __builtin_amdgcn_readfirstlane(tid >> 6); }
; #define STAGE_A(P, br, kt) do { const char* _g = (const char*)(A + (long)(br) * lda + (long)(kt) * BK); \
;     __builtin_amdgcn_global_load_lds((const unsigned*)(_g + (size_t)offA0), (unsigned*)((char*)(P) + sb0), 16, 0, 0); \
;     __builtin_amdgcn_global_load_lds((const unsigned*)(_g + (size_t)lda * 128 + (size_t)offA0), (unsigned*)((char*)(P) + sb1), 16, 0, 0); } while (0)
; #define STAGE_B(P, br, kt) do { const char* _g = (const char*)(B + (long)(br) * ldb + (long)(kt) * BK); \
;     __builtin_amdgcn_global_load_lds((const unsigned*)(_g + (size_t)offB0), (unsigned*)((char*)(P) + sb0), 16, 0, 0); \
;     __builtin_amdgcn_global_load_lds((const unsigned*)(_g + (size_t)ldb * 128 + (size_t)offB0), (unsigned*)((char*)(P) + sb1), 16, 0, 0); } while (0)
; #define BAR __builtin_amdgcn_s_barrier()
; DI void gemm_core(WVP char* smem, const u16* __restrict__ A, int lda, int ar0, int ar1,
;                   const u16* __restrict__ B, int ldb, int bc0, int K, AccT& acc) {
;     ...
;   const int tid = get_tid(WV);
;   const int wid = wave_of(tid), lane = tid & 63, wr = wid >> 2, wc = wid & 3, fr = lane & 15, fq = lane >> 4;
;   const int sb0 = tid * 16, sb1 = sb0 + 8192;
;   int R0, C0; stage_rc(sb0, R0, C0);
;   const unsigned offA0 = (unsigned)(R0 * lda + C0) * 2u, offB0 = (unsigned)(R0 * ldb + C0) * 2u;
;   const int ac0 = ar0, ac1 = ar1, bb0 = bc0, bb1 = bc0 + HALF;
;   bf16x8 At[4][2], B0[2][2], B1[2][2];
;   const int nt = K / BK;
;   __syncthreads();
;   STAGE_B(SB(0, 0), bb0, 0); STAGE_A(SA(0, 0), ac0, 0);
;   STAGE_B(SB(0, 1), bb1, 0); STAGE_A(SA(0, 1), ac1, 0);
;   if (wr == 1) BAR;
.LBB0_424:
	s_ashr_i32 s0, s4, 31
	s_lshr_b32 s0, s0, 29
	s_add_i32 s0, s4, s0
	s_ashr_i32 s1, s0, 3
	s_and_b32 s0, s0, -8
	s_sub_i32 s0, s4, s0
	s_mov_b32 s26, s4
	s_cmp_lt_i32 s0, 0
	s_movk_i32 s4, 0x131
	s_cselect_b32 s4, s4, 0x130
	s_mul_i32 s14, s0, s4
	s_add_i32 s14, s14, s1
	s_ashr_i32 s0, s14, 31
	s_lshr_b32 s0, s0, 23
	s_add_i32 s0, s14, s0
	s_ashr_i32 s15, s0, 9
	s_lshl_b32 s4, s15, 2
	s_sub_i32 s1, 19, s4
	s_min_u32 s5, s1, 4
	s_and_b32 s0, s0, 0xfffffe00
	s_sub_i32 s8, s14, s0
	v_cvt_f32_ubyte0_e32 v2, s5
	v_cvt_f32_i32_e32 v0, s8
	v_rcp_iflag_f32_e32 v3, v2
	s_ashr_i32 s0, s8, 30
	s_or_b32 s9, s0, 1
	v_mbcnt_lo_u32_b32 v9, -1, 0
	v_mbcnt_hi_u32_b32 v9, -1, v9
	v_mul_f32_e32 v3, v0, v3
	v_trunc_f32_e32 v3, v3
	v_fma_f32 v0, -v3, v2, v0
	v_cvt_i32_f32_e32 v3, v3
	v_cmp_ge_f32_e64 s[0:1], |v0|, v2
	s_and_b64 s[0:1], s[0:1], exec
	s_cselect_b32 s0, s9, 0
	v_readfirstlane_b32 s1, v3
	s_add_i32 s16, s1, s0
	s_sext_i32_i16 s0, s16
	s_mul_i32 s16, s16, s5
	v_add_u32_e32 v0, s3, v9
	s_sub_i32 s1, s8, s16
	v_ashrrev_i32_e32 v2, 31, v0
	s_sext_i32_i16 s1, s1
	v_lshrrev_b32_e32 v2, 26, v2
	s_add_i32 s4, s4, s1
	v_readfirstlane_b32 s1, v0
	v_lshlrev_b32_e32 v12, 4, v0
	v_add_u32_e32 v2, v0, v2
	v_bfe_i32 v0, v0, 27, 1
	v_lshrrev_b32_e32 v0, 22, v0
	v_add_u32_e32 v0, v12, v0
	v_and_b32_e32 v0, 0xfffffc00, v0
	v_sub_u32_e32 v0, v12, v0
	v_ashrrev_i32_e32 v8, 6, v2
	v_lshrrev_b32_e32 v2, 4, v0
	v_bitop3_b32 v0, v2, v0, 32 bitop3:0x6c
	v_ashrrev_i32_e32 v3, 31, v0
	s_lshl_b32 s10, s0, 8
	v_lshrrev_b32_e32 v3, 26, v3
	s_lshl_b32 s8, s4, 8
	v_add_u32_e32 v3, v0, v3
	s_ashr_i32 s11, s10, 31
	s_or_b32 s18, s8, 0x80
	s_ashr_i32 s0, s1, 8
	v_ashrrev_i32_e32 v10, 6, v3
	v_and_b32_e32 v3, 0xc0, v3
	s_or_b32 s20, s10, 0x80
	s_lshl_b64 s[12:13], s[10:11], 11
	v_readlane_b32 s28, v255, 29
	v_sub_u32_e32 v0, v0, v3
	v_readlane_b32 s29, v255, 30
	s_add_u32 s22, s28, s12
	v_lshlrev_b32_e32 v2, 3, v8
	v_lshlrev_b32_e32 v4, 5, v8
	v_ashrrev_i16_sdwa v0, v254, sext(v0) dst_sel:DWORD dst_unused:UNUSED_PAD src0_sel:DWORD src1_sel:BYTE_0
	s_addc_u32 s23, s29, s13
	s_add_i32 s5, 0, 0x10000
	v_and_b32_e32 v2, 0x1ffff0, v2
	v_and_b32_e32 v4, 32, v4
	v_bfe_i32 v11, v0, 0, 16
	v_add_u32_e32 v133, s5, v12
	v_add_u32_e32 v0, v4, v11
	v_add_lshl_u32 v2, v10, v2, 11
	v_readfirstlane_b32 s4, v133
	v_lshl_add_u32 v0, v0, 1, v2
	s_mov_b32 m0, s4
	s_ashr_i32 s9, s8, 31
	s_barrier
	v_lshl_add_u64 v[2:3], s[22:23], 0, v[0:1]
	global_load_lds_dwordx4 v0, s[22:23]
	s_lshl_b64 s[22:23], s[8:9], 11
	v_add_u32_e32 v13, 0x2000, v12
	s_add_u32 s22, s24, s22
	v_add_u32_e32 v6, s5, v13
	s_addc_u32 s23, s25, s23
	s_ashr_i32 s21, s20, 31
	v_readfirstlane_b32 s4, v6
	v_add_u32_e32 v135, 0, v12
	s_lshl_b64 s[20:21], s[20:21], 11
	v_lshl_add_u64 v[4:5], v[2:3], 0, s[76:77]
	s_mov_b32 m0, s4
	v_readfirstlane_b32 s4, v135
	v_add_u32_e32 v136, 0x2000, v135
	s_add_u32 s20, s28, s20
	global_load_lds_dwordx4 v[4:5], off
	v_lshl_add_u64 v[4:5], s[22:23], 0, v[0:1]
	s_mov_b32 m0, s4
	v_readfirstlane_b32 s4, v136
	s_addc_u32 s21, s29, s21
	v_add_u32_e32 v137, s60, v12
	s_ashr_i32 s19, s18, 31
	global_load_lds_dwordx4 v0, s[22:23]
	v_lshl_add_u64 v[6:7], v[4:5], 0, s[76:77]
	s_mov_b32 m0, s4
	v_readfirstlane_b32 s4, v137
	v_add_u32_e32 v13, s60, v13
	s_lshl_b64 s[18:19], s[18:19], 11
	global_load_lds_dwordx4 v[6:7], off
	v_lshl_add_u64 v[6:7], s[20:21], 0, v[0:1]
	s_mov_b32 m0, s4
	v_readfirstlane_b32 s4, v13
	s_add_u32 s18, s24, s18
	v_add_u32_e32 v139, 0x4000, v135
	global_load_lds_dwordx4 v0, s[20:21]
	v_lshl_add_u64 v[14:15], v[6:7], 0, s[76:77]
	s_mov_b32 m0, s4
	s_addc_u32 s19, s25, s19
	v_readfirstlane_b32 s4, v139
	v_add_u32_e32 v140, 0x6000, v135
	global_load_lds_dwordx4 v[14:15], off
	v_lshl_add_u64 v[130:131], s[18:19], 0, v[0:1]
	s_mov_b32 m0, s4
	v_readfirstlane_b32 s4, v140
	global_load_lds_dwordx4 v0, s[18:19]
	v_lshl_add_u64 v[14:15], v[130:131], 0, s[76:77]
	s_mov_b32 m0, s4
	s_cmp_lg_u32 s0, 1
	global_load_lds_dwordx4 v[14:15], off
	v_mov_b32_e32 v16, 0
	v_mov_b32_e32 v17, 0
	v_mov_b32_e32 v18, 0
	v_mov_b32_e32 v19, 0
	v_mov_b32_e32 v20, 0
	v_mov_b32_e32 v21, 0
	v_mov_b32_e32 v22, 0
	v_mov_b32_e32 v23, 0
	v_mov_b32_e32 v24, 0
	v_mov_b32_e32 v25, 0
	v_mov_b32_e32 v26, 0
	v_mov_b32_e32 v27, 0
	v_mov_b32_e32 v28, 0
	v_mov_b32_e32 v29, 0
	v_mov_b32_e32 v30, 0
	v_mov_b32_e32 v31, 0
	v_mov_b32_e32 v32, 0
	v_mov_b32_e32 v33, 0
	v_mov_b32_e32 v34, 0
	v_mov_b32_e32 v35, 0
	v_mov_b32_e32 v36, 0
	v_mov_b32_e32 v37, 0
	v_mov_b32_e32 v38, 0
	v_mov_b32_e32 v39, 0
	v_mov_b32_e32 v40, 0
	v_mov_b32_e32 v41, 0
	v_mov_b32_e32 v42, 0
	v_mov_b32_e32 v43, 0
	v_mov_b32_e32 v44, 0
	v_mov_b32_e32 v45, 0
	v_mov_b32_e32 v46, 0
	v_mov_b32_e32 v47, 0
	v_mov_b32_e32 v48, 0
	v_mov_b32_e32 v49, 0
	v_mov_b32_e32 v50, 0
	v_mov_b32_e32 v51, 0
	v_mov_b32_e32 v52, 0
	v_mov_b32_e32 v53, 0
	v_mov_b32_e32 v54, 0
	v_mov_b32_e32 v55, 0
	v_mov_b32_e32 v56, 0
	v_mov_b32_e32 v57, 0
	v_mov_b32_e32 v58, 0
	v_mov_b32_e32 v59, 0
	v_mov_b32_e32 v60, 0
	v_mov_b32_e32 v61, 0
	v_mov_b32_e32 v62, 0
	v_mov_b32_e32 v63, 0
	v_mov_b32_e32 v64, 0
	v_mov_b32_e32 v65, 0
	v_mov_b32_e32 v66, 0
	v_mov_b32_e32 v67, 0
	v_mov_b32_e32 v68, 0
	v_mov_b32_e32 v69, 0
	v_mov_b32_e32 v70, 0
	v_mov_b32_e32 v71, 0
	v_mov_b32_e32 v72, 0
	v_mov_b32_e32 v73, 0
	v_mov_b32_e32 v74, 0
	v_mov_b32_e32 v75, 0
	v_mov_b32_e32 v76, 0
	v_mov_b32_e32 v77, 0
	v_mov_b32_e32 v78, 0
	v_mov_b32_e32 v79, 0
	v_mov_b32_e32 v80, 0
	v_mov_b32_e32 v81, 0
	v_mov_b32_e32 v82, 0
	v_mov_b32_e32 v83, 0
	v_mov_b32_e32 v84, 0
	v_mov_b32_e32 v85, 0
	v_mov_b32_e32 v86, 0
	v_mov_b32_e32 v87, 0
	v_mov_b32_e32 v88, 0
	v_mov_b32_e32 v89, 0
	v_mov_b32_e32 v90, 0
	v_mov_b32_e32 v91, 0
	v_mov_b32_e32 v92, 0
	v_mov_b32_e32 v93, 0
	v_mov_b32_e32 v94, 0
	v_mov_b32_e32 v95, 0
	v_mov_b32_e32 v96, 0
	v_mov_b32_e32 v97, 0
	v_mov_b32_e32 v98, 0
	v_mov_b32_e32 v99, 0
	v_mov_b32_e32 v100, 0
	v_mov_b32_e32 v101, 0
	v_mov_b32_e32 v102, 0
	v_mov_b32_e32 v103, 0
	v_mov_b32_e32 v104, 0
	v_mov_b32_e32 v105, 0
	v_mov_b32_e32 v106, 0
	v_mov_b32_e32 v107, 0
	v_mov_b32_e32 v108, 0
	v_mov_b32_e32 v109, 0
	v_mov_b32_e32 v110, 0
	v_mov_b32_e32 v111, 0
	v_mov_b32_e32 v112, 0
	v_mov_b32_e32 v113, 0
	v_mov_b32_e32 v114, 0
	v_mov_b32_e32 v115, 0
	v_mov_b32_e32 v116, 0
	v_mov_b32_e32 v117, 0
	v_mov_b32_e32 v118, 0
	v_mov_b32_e32 v119, 0
	v_mov_b32_e32 v120, 0
	v_mov_b32_e32 v121, 0
	v_mov_b32_e32 v122, 0
	v_mov_b32_e32 v123, 0
	v_mov_b32_e32 v124, 0
	v_mov_b32_e32 v125, 0
	v_mov_b32_e32 v126, 0
	v_mov_b32_e32 v127, 0
	v_mov_b32_e32 v128, 0
	v_mov_b32_e32 v129, 0
	s_cbranch_scc1 .LBB0_426
	s_setprio 1
	s_barrier

; #define STAGE_A(P, br, kt) do { const char* _g = (const char*)(A + (long)(br) * lda + (long)(kt) * BK); \
;     __builtin_amdgcn_global_load_lds((const unsigned*)(_g + (size_t)offA0), (unsigned*)((char*)(P) + sb0), 16, 0, 0); \
;     __builtin_amdgcn_global_load_lds((const unsigned*)(_g + (size_t)lda * 128 + (size_t)offA0), (unsigned*)((char*)(P) + sb1), 16, 0, 0); } while (0)
; #define STAGE_B(P, br, kt) do { const char* _g = (const char*)(B + (long)(br) * ldb + (long)(kt) * BK); \
;     __builtin_amdgcn_global_load_lds((const unsigned*)(_g + (size_t)offB0), (unsigned*)((char*)(P) + sb0), 16, 0, 0); \
;     __builtin_amdgcn_global_load_lds((const unsigned*)(_g + (size_t)ldb * 128 + (size_t)offB0), (unsigned*)((char*)(P) + sb1), 16, 0, 0); } while (0)
; #define LDA(dst, b, h) for (int m = 0; m < 4; ++m) for (int k = 0; k < 2; ++k) \
;     dst[m][k] = *reinterpret_cast<const bf16x8*>((char*)SA(b, h) + lds_byte(wr * 64 + m * 16 + fr, k * 32 + fq * 8))
; #define LDB(dst, b, h) for (int n = 0; n < 2; ++n) for (int k = 0; k < 2; ++k) \
;     dst[n][k] = *reinterpret_cast<const bf16x8*>((char*)SB(b, h) + lds_byte(wc * 32 + n * 16 + fr, k * 32 + fq * 8))
; #define WAIT_V(n) asm volatile("s_waitcnt vmcnt(" #n ")" ::: "memory")
; #define WAIT_L(n) asm volatile("s_waitcnt lgkmcnt(" #n ")" ::: "memory")
; DI void gemm_core(WVP char* smem, const u16* __restrict__ A, int lda, int ar0, int ar1,
;                   const u16* __restrict__ B, int ldb, int bc0, int K, AccT& acc) {
;     ...
;   for (int t = 0; t < nt - 2; t += 2) {
;     LDB(B0, 0, 0); SCHED; LDA(At, 0, 0); STAGE_A(SA(1, 1), ac1, t + 1);
;     WAIT_L(8); BAR; WAIT_L(0); MMA(0, 0, At, B0); BAR; SCHED;
;     LDB(B1, 0, 1); STAGE_B(SB(0, 0), bb0, t + 2);
;     BAR; WAIT_L(0); MMA(0, 1, At, B1); BAR;
;     LDA(At, 0, 1); STAGE_A(SA(0, 0), ac0, t + 2);
;     BAR; WAIT_L(0); MMA(1, 0, At, B0); BAR; SCHED;
;     STAGE_B(SB(0, 1), bb1, t + 2);
;     WAIT_V(6); BAR; MMA(1, 1, At, B1); BAR;
;     LDB(B0, 1, 0); SCHED; LDA(At, 1, 0); STAGE_A(SA(0, 1), ac1, t + 2);
;     WAIT_L(8); BAR; WAIT_L(0); MMA(0, 0, At, B0); BAR; SCHED;
;     LDB(B1, 1, 1); STAGE_B(SB(1, 0), bb0, t + 3);
;     BAR; WAIT_L(0); MMA(0, 1, At, B1); BAR;
;     LDA(At, 1, 1); STAGE_A(SA(1, 0), ac0, t + 3);
;     BAR; WAIT_L(0); MMA(1, 0, At, B0); BAR; SCHED;
;     STAGE_B(SB(1, 1), bb1, t + 3);
;     WAIT_V(6); BAR; MMA(1, 1, At, B1); BAR;
;   }
.LBB0_427:
	v_add_u32_e32 v150, s0, v148
	v_add_u32_e32 v151, s1, v148
	v_add_u32_e32 v152, s5, v148
	ds_read_b128 v[156:159], v149
	ds_read_b128 v[160:163], v149 offset:1024
	ds_read_b128 v[164:167], v149 offset:2048
	ds_read_b128 v[168:171], v149 offset:3072
	ds_read_b128 v[172:175], v132
	ds_read_b128 v[176:179], v132 offset:1024
	ds_read_b128 v[180:183], v150
	ds_read_b128 v[184:187], v150 offset:1024
	ds_read_b128 v[188:191], v151
	ds_read_b128 v[206:209], v151 offset:1024
	ds_read_b128 v[210:213], v152
	ds_read_b128 v[214:217], v152 offset:1024
	ds_read_b128 v[218:221], v147
	ds_read_b128 v[222:225], v147 offset:1024
	ds_read_b128 v[226:229], v147 offset:2048
	ds_read_b128 v[230:233], v147 offset:3072
	v_add_u32_e32 v153, 0xc000, v135
	v_lshl_add_u64 v[194:195], s[14:15], 0, v[0:1]
	s_mov_b64 s[16:17], 0x1d1c0080
	v_lshl_add_u64 v[192:193], v[194:195], 0, s[16:17]
	v_readfirstlane_b32 s11, v153
	s_mov_b32 m0, s11
	s_nop 0
	global_load_lds_dwordx4 v[192:193], off
	v_add_u32_e32 v154, 0xe000, v135
	v_lshl_add_u64 v[194:195], s[14:15], 0, v[0:1]
	s_mov_b64 s[16:17], 0x1d1e0080
	v_lshl_add_u64 v[192:193], v[194:195], 0, s[16:17]
	v_readfirstlane_b32 s11, v154
	s_mov_b32 m0, s11
	s_nop 0
	global_load_lds_dwordx4 v[192:193], off
	s_waitcnt vmcnt(8)
	s_waitcnt lgkmcnt(0)
	s_barrier
	v_mfma_f32_16x16x32_bf16 v[126:129], v[172:175], v[156:159], v[126:129]
	v_mfma_f32_16x16x32_bf16 v[122:125], v[172:175], v[164:167], v[122:125]
	v_mfma_f32_16x16x32_bf16 v[118:121], v[180:183], v[156:159], v[118:121]
	v_mfma_f32_16x16x32_bf16 v[114:117], v[180:183], v[164:167], v[114:117]
	v_mfma_f32_16x16x32_bf16 v[110:113], v[188:191], v[156:159], v[110:113]
	v_mfma_f32_16x16x32_bf16 v[106:109], v[188:191], v[164:167], v[106:109]
	v_mfma_f32_16x16x32_bf16 v[102:105], v[210:213], v[156:159], v[102:105]
	v_mfma_f32_16x16x32_bf16 v[98:101], v[210:213], v[164:167], v[98:101]
	v_mfma_f32_16x16x32_bf16 v[126:129], v[176:179], v[160:163], v[126:129]
	v_mfma_f32_16x16x32_bf16 v[122:125], v[176:179], v[168:171], v[122:125]
	v_mfma_f32_16x16x32_bf16 v[118:121], v[184:187], v[160:163], v[118:121]
	v_mfma_f32_16x16x32_bf16 v[114:117], v[184:187], v[168:171], v[114:117]
	v_mfma_f32_16x16x32_bf16 v[110:113], v[206:209], v[160:163], v[110:113]
	v_mfma_f32_16x16x32_bf16 v[106:109], v[206:209], v[168:171], v[106:109]
	v_mfma_f32_16x16x32_bf16 v[102:105], v[214:217], v[160:163], v[102:105]
	v_mfma_f32_16x16x32_bf16 v[98:101], v[214:217], v[168:171], v[98:101]
	v_mfma_f32_16x16x32_bf16 v[94:97], v[172:175], v[218:221], v[94:97]
	v_mfma_f32_16x16x32_bf16 v[90:93], v[172:175], v[226:229], v[90:93]
	v_mfma_f32_16x16x32_bf16 v[86:89], v[180:183], v[218:221], v[86:89]
	v_mfma_f32_16x16x32_bf16 v[82:85], v[180:183], v[226:229], v[82:85]
	v_mfma_f32_16x16x32_bf16 v[78:81], v[188:191], v[218:221], v[78:81]
	v_mfma_f32_16x16x32_bf16 v[74:77], v[188:191], v[226:229], v[74:77]
	v_mfma_f32_16x16x32_bf16 v[70:73], v[210:213], v[218:221], v[70:73]
	v_mfma_f32_16x16x32_bf16 v[66:69], v[210:213], v[226:229], v[66:69]
	v_mfma_f32_16x16x32_bf16 v[94:97], v[176:179], v[222:225], v[94:97]
	v_mfma_f32_16x16x32_bf16 v[90:93], v[176:179], v[230:233], v[90:93]
	v_mfma_f32_16x16x32_bf16 v[86:89], v[184:187], v[222:225], v[86:89]
	v_mfma_f32_16x16x32_bf16 v[82:85], v[184:187], v[230:233], v[82:85]
	v_mfma_f32_16x16x32_bf16 v[78:81], v[206:209], v[222:225], v[78:81]
	v_mfma_f32_16x16x32_bf16 v[74:77], v[206:209], v[230:233], v[74:77]
	v_mfma_f32_16x16x32_bf16 v[70:73], v[214:217], v[222:225], v[70:73]
	v_mfma_f32_16x16x32_bf16 v[66:69], v[214:217], v[230:233], v[66:69]
	s_barrier
	ds_read_b128 v[172:175], v132 offset:16384
	ds_read_b128 v[176:179], v132 offset:17408
	ds_read_b128 v[180:183], v150 offset:16384
	ds_read_b128 v[184:187], v150 offset:17408
	ds_read_b128 v[188:191], v151 offset:16384
	ds_read_b128 v[206:209], v151 offset:17408
	ds_read_b128 v[210:213], v152 offset:16384
	ds_read_b128 v[214:217], v152 offset:17408
	v_lshl_add_u64 v[194:195], s[12:13], 0, v[0:1]
	v_lshl_add_u64 v[192:193], v[194:195], 0, s[80:81]
	v_readfirstlane_b32 s11, v133
	s_mov_b32 m0, s11
	s_nop 0
	global_load_lds_dwordx4 v[192:193], off
	v_add_u32_e32 v155, 0x2000, v133
	v_lshl_add_u64 v[194:195], s[12:13], 0, v[0:1]
	v_lshl_add_u64 v[192:193], v[194:195], 0, s[82:83]
	v_readfirstlane_b32 s11, v155
	s_mov_b32 m0, s11
	s_nop 0
	global_load_lds_dwordx4 v[192:193], off
	v_lshl_add_u64 v[194:195], s[14:15], 0, v[0:1]
	s_mov_b64 s[16:17], 0x1d180100
	v_lshl_add_u64 v[192:193], v[194:195], 0, s[16:17]
	v_readfirstlane_b32 s11, v135
	s_mov_b32 m0, s11
	s_nop 0
	global_load_lds_dwordx4 v[192:193], off
	v_lshl_add_u64 v[194:195], s[14:15], 0, v[0:1]
	s_mov_b64 s[16:17], 0x1d1a0100
	v_lshl_add_u64 v[192:193], v[194:195], 0, s[16:17]
	v_readfirstlane_b32 s11, v136
	s_mov_b32 m0, s11
	s_nop 0
	global_load_lds_dwordx4 v[192:193], off
	v_lshl_add_u64 v[194:195], s[12:13], 0, v[0:1]
	v_lshl_add_u64 v[192:193], v[194:195], 0, s[88:89]
	v_readfirstlane_b32 s11, v137
	s_mov_b32 m0, s11
	s_nop 0
	global_load_lds_dwordx4 v[192:193], off
	v_add_u32_e32 v155, 0x2000, v137
	v_lshl_add_u64 v[194:195], s[12:13], 0, v[0:1]
	v_lshl_add_u64 v[192:193], v[194:195], 0, s[90:91]
	v_readfirstlane_b32 s11, v155
	s_mov_b32 m0, s11
	s_nop 0
	global_load_lds_dwordx4 v[192:193], off
	s_waitcnt vmcnt(8)
	s_waitcnt lgkmcnt(0)
	s_barrier
; #define STAGE_A(P, br, kt) do { const char* _g = (const char*)(A + (long)(br) * lda + (long)(kt) * BK); \
;     __builtin_amdgcn_global_load_lds((const unsigned*)(_g + (size_t)offA0), (unsigned*)((char*)(P) + sb0), 16, 0, 0); \
;     __builtin_amdgcn_global_load_lds((const unsigned*)(_g + (size_t)lda * 128 + (size_t)offA0), (unsigned*)((char*)(P) + sb1), 16, 0, 0); } while (0)
; #define STAGE_B(P, br, kt) do { const char* _g = (const char*)(B + (long)(br) * ldb + (long)(kt) * BK); \
;     __builtin_amdgcn_global_load_lds((const unsigned*)(_g + (size_t)offB0), (unsigned*)((char*)(P) + sb0), 16, 0, 0); \
;     __builtin_amdgcn_global_load_lds((const unsigned*)(_g + (size_t)ldb * 128 + (size_t)offB0), (unsigned*)((char*)(P) + sb1), 16, 0, 0); } while (0)
; #define LDA(dst, b, h) for (int m = 0; m < 4; ++m) for (int k = 0; k < 2; ++k) \
;     dst[m][k] = *reinterpret_cast<const bf16x8*>((char*)SA(b, h) + lds_byte(wr * 64 + m * 16 + fr, k * 32 + fq * 8))
; #define LDB(dst, b, h) for (int n = 0; n < 2; ++n) for (int k = 0; k < 2; ++k) \
;     dst[n][k] = *reinterpret_cast<const bf16x8*>((char*)SB(b, h) + lds_byte(wc * 32 + n * 16 + fr, k * 32 + fq * 8))
; #define WAIT_V(n) asm volatile("s_waitcnt vmcnt(" #n ")" ::: "memory")
; #define WAIT_L(n) asm volatile("s_waitcnt lgkmcnt(" #n ")" ::: "memory")
; DI void gemm_core(WVP char* smem, const u16* __restrict__ A, int lda, int ar0, int ar1,
;                   const u16* __restrict__ B, int ldb, int bc0, int K, AccT& acc) {
;     ...
;   for (int t = 0; t < nt - 2; t += 2) {
;     LDB(B0, 0, 0); SCHED; LDA(At, 0, 0); STAGE_A(SA(1, 1), ac1, t + 1);
;     WAIT_L(8); BAR; WAIT_L(0); MMA(0, 0, At, B0); BAR; SCHED;
;     LDB(B1, 0, 1); STAGE_B(SB(0, 0), bb0, t + 2);
;     BAR; WAIT_L(0); MMA(0, 1, At, B1); BAR;
;     LDA(At, 0, 1); STAGE_A(SA(0, 0), ac0, t + 2);
;     BAR; WAIT_L(0); MMA(1, 0, At, B0); BAR; SCHED;
;     STAGE_B(SB(0, 1), bb1, t + 2);
;     WAIT_V(6); BAR; MMA(1, 1, At, B1); BAR;
;     LDB(B0, 1, 0); SCHED; LDA(At, 1, 0); STAGE_A(SA(0, 1), ac1, t + 2);
;     WAIT_L(8); BAR; WAIT_L(0); MMA(0, 0, At, B0); BAR; SCHED;
;     LDB(B1, 1, 1); STAGE_B(SB(1, 0), bb0, t + 3);
;     BAR; WAIT_L(0); MMA(0, 1, At, B1); BAR;
;     LDA(At, 1, 1); STAGE_A(SA(1, 0), ac0, t + 3);
;     BAR; WAIT_L(0); MMA(1, 0, At, B0); BAR; SCHED;
;     STAGE_B(SB(1, 1), bb1, t + 3);
;     WAIT_V(6); BAR; MMA(1, 1, At, B1); BAR;
;   }
	v_mfma_f32_16x16x32_bf16 v[62:65], v[172:175], v[156:159], v[62:65]
	v_mfma_f32_16x16x32_bf16 v[58:61], v[172:175], v[164:167], v[58:61]
	v_mfma_f32_16x16x32_bf16 v[54:57], v[180:183], v[156:159], v[54:57]
	v_mfma_f32_16x16x32_bf16 v[50:53], v[180:183], v[164:167], v[50:53]
	v_mfma_f32_16x16x32_bf16 v[46:49], v[188:191], v[156:159], v[46:49]
	v_mfma_f32_16x16x32_bf16 v[42:45], v[188:191], v[164:167], v[42:45]
	v_mfma_f32_16x16x32_bf16 v[38:41], v[210:213], v[156:159], v[38:41]
	v_mfma_f32_16x16x32_bf16 v[34:37], v[210:213], v[164:167], v[34:37]
	v_mfma_f32_16x16x32_bf16 v[62:65], v[176:179], v[160:163], v[62:65]
	v_mfma_f32_16x16x32_bf16 v[58:61], v[176:179], v[168:171], v[58:61]
	v_mfma_f32_16x16x32_bf16 v[54:57], v[184:187], v[160:163], v[54:57]
	v_mfma_f32_16x16x32_bf16 v[50:53], v[184:187], v[168:171], v[50:53]
	v_mfma_f32_16x16x32_bf16 v[46:49], v[206:209], v[160:163], v[46:49]
	v_mfma_f32_16x16x32_bf16 v[42:45], v[206:209], v[168:171], v[42:45]
	v_mfma_f32_16x16x32_bf16 v[38:41], v[214:217], v[160:163], v[38:41]
	v_mfma_f32_16x16x32_bf16 v[34:37], v[214:217], v[168:171], v[34:37]
	v_mfma_f32_16x16x32_bf16 v[30:33], v[172:175], v[218:221], v[30:33]
	v_mfma_f32_16x16x32_bf16 v[26:29], v[172:175], v[226:229], v[26:29]
	v_mfma_f32_16x16x32_bf16 v[22:25], v[180:183], v[218:221], v[22:25]
	v_mfma_f32_16x16x32_bf16 v[18:21], v[180:183], v[226:229], v[18:21]
	v_mfma_f32_16x16x32_bf16 v[14:17], v[188:191], v[218:221], v[14:17]
	v_mfma_f32_16x16x32_bf16 v[10:13], v[188:191], v[226:229], v[10:13]
	v_mfma_f32_16x16x32_bf16 v[6:9], v[210:213], v[218:221], v[6:9]
	v_mfma_f32_16x16x32_bf16 v[2:5], v[210:213], v[226:229], v[2:5]
	v_mfma_f32_16x16x32_bf16 v[30:33], v[176:179], v[222:225], v[30:33]
	v_mfma_f32_16x16x32_bf16 v[26:29], v[176:179], v[230:233], v[26:29]
	v_mfma_f32_16x16x32_bf16 v[22:25], v[184:187], v[222:225], v[22:25]
	v_mfma_f32_16x16x32_bf16 v[18:21], v[184:187], v[230:233], v[18:21]
	v_mfma_f32_16x16x32_bf16 v[14:17], v[206:209], v[222:225], v[14:17]
	v_mfma_f32_16x16x32_bf16 v[10:13], v[206:209], v[230:233], v[10:13]
	v_mfma_f32_16x16x32_bf16 v[6:9], v[214:217], v[222:225], v[6:9]
	v_mfma_f32_16x16x32_bf16 v[2:5], v[214:217], v[230:233], v[2:5]
	s_barrier
	ds_read_b128 v[156:159], v138
	ds_read_b128 v[160:163], v138 offset:1024
	ds_read_b128 v[164:167], v138 offset:2048
	ds_read_b128 v[168:171], v138 offset:3072
	ds_read_b128 v[172:175], v132 offset:32768
	ds_read_b128 v[176:179], v132 offset:33792
	ds_read_b128 v[180:183], v150 offset:32768
	ds_read_b128 v[184:187], v150 offset:33792
	ds_read_b128 v[188:191], v151 offset:32768
	ds_read_b128 v[206:209], v151 offset:33792
	ds_read_b128 v[210:213], v152 offset:32768
	ds_read_b128 v[214:217], v152 offset:33792
	ds_read_b128 v[218:221], v134
	ds_read_b128 v[222:225], v134 offset:1024
	ds_read_b128 v[226:229], v134 offset:2048
	ds_read_b128 v[230:233], v134 offset:3072
	v_lshl_add_u64 v[194:195], s[14:15], 0, v[0:1]
	s_mov_b64 s[16:17], 0x1d1c0100
	v_lshl_add_u64 v[192:193], v[194:195], 0, s[16:17]
	v_readfirstlane_b32 s11, v139
	s_mov_b32 m0, s11
	s_nop 0
	global_load_lds_dwordx4 v[192:193], off
	v_lshl_add_u64 v[194:195], s[14:15], 0, v[0:1]
	s_mov_b64 s[16:17], 0x1d1e0100
	v_lshl_add_u64 v[192:193], v[194:195], 0, s[16:17]
	v_readfirstlane_b32 s11, v140
	s_mov_b32 m0, s11
	s_nop 0
	global_load_lds_dwordx4 v[192:193], off
	s_waitcnt vmcnt(8)
	s_waitcnt lgkmcnt(0)
	s_barrier
	v_mfma_f32_16x16x32_bf16 v[126:129], v[172:175], v[156:159], v[126:129]
	v_mfma_f32_16x16x32_bf16 v[122:125], v[172:175], v[164:167], v[122:125]
	v_mfma_f32_16x16x32_bf16 v[118:121], v[180:183], v[156:159], v[118:121]
	v_mfma_f32_16x16x32_bf16 v[114:117], v[180:183], v[164:167], v[114:117]
	v_mfma_f32_16x16x32_bf16 v[110:113], v[188:191], v[156:159], v[110:113]
	v_mfma_f32_16x16x32_bf16 v[106:109], v[188:191], v[164:167], v[106:109]
	v_mfma_f32_16x16x32_bf16 v[102:105], v[210:213], v[156:159], v[102:105]
	v_mfma_f32_16x16x32_bf16 v[98:101], v[210:213], v[164:167], v[98:101]
	v_mfma_f32_16x16x32_bf16 v[126:129], v[176:179], v[160:163], v[126:129]
	v_mfma_f32_16x16x32_bf16 v[122:125], v[176:179], v[168:171], v[122:125]
	v_mfma_f32_16x16x32_bf16 v[118:121], v[184:187], v[160:163], v[118:121]
	v_mfma_f32_16x16x32_bf16 v[114:117], v[184:187], v[168:171], v[114:117]
	v_mfma_f32_16x16x32_bf16 v[110:113], v[206:209], v[160:163], v[110:113]
	v_mfma_f32_16x16x32_bf16 v[106:109], v[206:209], v[168:171], v[106:109]
	v_mfma_f32_16x16x32_bf16 v[102:105], v[214:217], v[160:163], v[102:105]
	v_mfma_f32_16x16x32_bf16 v[98:101], v[214:217], v[168:171], v[98:101]
	v_mfma_f32_16x16x32_bf16 v[94:97], v[172:175], v[218:221], v[94:97]
	v_mfma_f32_16x16x32_bf16 v[90:93], v[172:175], v[226:229], v[90:93]
	v_mfma_f32_16x16x32_bf16 v[86:89], v[180:183], v[218:221], v[86:89]
	v_mfma_f32_16x16x32_bf16 v[82:85], v[180:183], v[226:229], v[82:85]
	v_mfma_f32_16x16x32_bf16 v[78:81], v[188:191], v[218:221], v[78:81]
	v_mfma_f32_16x16x32_bf16 v[74:77], v[188:191], v[226:229], v[74:77]
	v_mfma_f32_16x16x32_bf16 v[70:73], v[210:213], v[218:221], v[70:73]
	v_mfma_f32_16x16x32_bf16 v[66:69], v[210:213], v[226:229], v[66:69]
	v_mfma_f32_16x16x32_bf16 v[94:97], v[176:179], v[222:225], v[94:97]
	v_mfma_f32_16x16x32_bf16 v[90:93], v[176:179], v[230:233], v[90:93]
	v_mfma_f32_16x16x32_bf16 v[86:89], v[184:187], v[222:225], v[86:89]
	v_mfma_f32_16x16x32_bf16 v[82:85], v[184:187], v[230:233], v[82:85]
	v_mfma_f32_16x16x32_bf16 v[78:81], v[206:209], v[222:225], v[78:81]
	v_mfma_f32_16x16x32_bf16 v[74:77], v[206:209], v[230:233], v[74:77]
	v_mfma_f32_16x16x32_bf16 v[70:73], v[214:217], v[222:225], v[70:73]
	v_mfma_f32_16x16x32_bf16 v[66:69], v[214:217], v[230:233], v[66:69]
	s_barrier
; #define STAGE_A(P, br, kt) do { const char* _g = (const char*)(A + (long)(br) * lda + (long)(kt) * BK); \
;     __builtin_amdgcn_global_load_lds((const unsigned*)(_g + (size_t)offA0), (unsigned*)((char*)(P) + sb0), 16, 0, 0); \
;     __builtin_amdgcn_global_load_lds((const unsigned*)(_g + (size_t)lda * 128 + (size_t)offA0), (unsigned*)((char*)(P) + sb1), 16, 0, 0); } while (0)
; #define STAGE_B(P, br, kt) do { const char* _g = (const char*)(B + (long)(br) * ldb + (long)(kt) * BK); \
;     __builtin_amdgcn_global_load_lds((const unsigned*)(_g + (size_t)offB0), (unsigned*)((char*)(P) + sb0), 16, 0, 0); \
;     __builtin_amdgcn_global_load_lds((const unsigned*)(_g + (size_t)ldb * 128 + (size_t)offB0), (unsigned*)((char*)(P) + sb1), 16, 0, 0); } while (0)
; #define LDA(dst, b, h) for (int m = 0; m < 4; ++m) for (int k = 0; k < 2; ++k) \
;     dst[m][k] = *reinterpret_cast<const bf16x8*>((char*)SA(b, h) + lds_byte(wr * 64 + m * 16 + fr, k * 32 + fq * 8))
; #define LDB(dst, b, h) for (int n = 0; n < 2; ++n) for (int k = 0; k < 2; ++k) \
;     dst[n][k] = *reinterpret_cast<const bf16x8*>((char*)SB(b, h) + lds_byte(wc * 32 + n * 16 + fr, k * 32 + fq * 8))
; #define WAIT_V(n) asm volatile("s_waitcnt vmcnt(" #n ")" ::: "memory")
; DI void gemm_core(WVP char* smem, const u16* __restrict__ A, int lda, int ar0, int ar1,
;                   const u16* __restrict__ B, int ldb, int bc0, int K, AccT& acc) {
;     ...
;   for (int t = 0; t < nt - 2; t += 2) {
;     LDB(B0, 0, 0); SCHED; LDA(At, 0, 0); STAGE_A(SA(1, 1), ac1, t + 1);
;     WAIT_L(8); BAR; WAIT_L(0); MMA(0, 0, At, B0); BAR; SCHED;
;     LDB(B1, 0, 1); STAGE_B(SB(0, 0), bb0, t + 2);
;     BAR; WAIT_L(0); MMA(0, 1, At, B1); BAR;
;     LDA(At, 0, 1); STAGE_A(SA(0, 0), ac0, t + 2);
;     BAR; WAIT_L(0); MMA(1, 0, At, B0); BAR; SCHED;
;     STAGE_B(SB(0, 1), bb1, t + 2);
;     WAIT_V(6); BAR; MMA(1, 1, At, B1); BAR;
;     LDB(B0, 1, 0); SCHED; LDA(At, 1, 0); STAGE_A(SA(0, 1), ac1, t + 2);
;     WAIT_L(8); BAR; WAIT_L(0); MMA(0, 0, At, B0); BAR; SCHED;
;     LDB(B1, 1, 1); STAGE_B(SB(1, 0), bb0, t + 3);
;     BAR; WAIT_L(0); MMA(0, 1, At, B1); BAR;
;     LDA(At, 1, 1); STAGE_A(SA(1, 0), ac0, t + 3);
;     BAR; WAIT_L(0); MMA(1, 0, At, B0); BAR; SCHED;
;     STAGE_B(SB(1, 1), bb1, t + 3);
;     WAIT_V(6); BAR; MMA(1, 1, At, B1); BAR;
;   }
;   { LDB(B0, 0, 0); LDA(At, 0, 0); STAGE_A(SA(1, 1), ac1, nt - 1);
	ds_read_b128 v[172:175], v132 offset:49152
	ds_read_b128 v[176:179], v132 offset:50176
	ds_read_b128 v[180:183], v150 offset:49152
	ds_read_b128 v[184:187], v150 offset:50176
	ds_read_b128 v[188:191], v151 offset:49152
	ds_read_b128 v[206:209], v151 offset:50176
	ds_read_b128 v[210:213], v152 offset:49152
	ds_read_b128 v[214:217], v152 offset:50176
	v_lshl_add_u64 v[194:195], s[12:13], 0, v[0:1]
	v_lshl_add_u64 v[192:193], v[194:195], 0, s[92:93]
	v_readfirstlane_b32 s11, v141
	s_mov_b32 m0, s11
	s_nop 0
	global_load_lds_dwordx4 v[192:193], off
	v_lshl_add_u64 v[194:195], s[12:13], 0, v[0:1]
	v_lshl_add_u64 v[192:193], v[194:195], 0, s[94:95]
	v_readfirstlane_b32 s11, v142
	s_mov_b32 m0, s11
	s_nop 0
	global_load_lds_dwordx4 v[192:193], off
	v_lshl_add_u64 v[194:195], s[14:15], 0, v[0:1]
	s_mov_b64 s[16:17], 0x1d180180
	v_lshl_add_u64 v[192:193], v[194:195], 0, s[16:17]
	v_readfirstlane_b32 s11, v143
	s_mov_b32 m0, s11
	s_nop 0
	global_load_lds_dwordx4 v[192:193], off
	v_lshl_add_u64 v[194:195], s[14:15], 0, v[0:1]
	s_mov_b64 s[16:17], 0x1d1a0180
	v_lshl_add_u64 v[192:193], v[194:195], 0, s[16:17]
	v_readfirstlane_b32 s11, v144
	s_mov_b32 m0, s11
	s_nop 0
	global_load_lds_dwordx4 v[192:193], off
	v_lshl_add_u64 v[194:195], s[12:13], 0, v[0:1]
	v_lshl_add_u64 v[192:193], v[194:195], 0, s[96:97]
	v_readfirstlane_b32 s11, v145
	s_mov_b32 m0, s11
	s_nop 0
	global_load_lds_dwordx4 v[192:193], off
	v_lshl_add_u64 v[194:195], s[12:13], 0, v[0:1]
	v_lshl_add_u64 v[192:193], v[194:195], 0, s[72:73]
	v_readfirstlane_b32 s11, v146
	s_mov_b32 m0, s11
	s_nop 0
	global_load_lds_dwordx4 v[192:193], off
	s_waitcnt vmcnt(8)
	s_waitcnt lgkmcnt(0)
	s_barrier
	v_mfma_f32_16x16x32_bf16 v[62:65], v[172:175], v[156:159], v[62:65]
	v_mfma_f32_16x16x32_bf16 v[58:61], v[172:175], v[164:167], v[58:61]
	v_mfma_f32_16x16x32_bf16 v[54:57], v[180:183], v[156:159], v[54:57]
	v_mfma_f32_16x16x32_bf16 v[50:53], v[180:183], v[164:167], v[50:53]
	v_mfma_f32_16x16x32_bf16 v[46:49], v[188:191], v[156:159], v[46:49]
	v_mfma_f32_16x16x32_bf16 v[42:45], v[188:191], v[164:167], v[42:45]
	v_mfma_f32_16x16x32_bf16 v[38:41], v[210:213], v[156:159], v[38:41]
	v_mfma_f32_16x16x32_bf16 v[34:37], v[210:213], v[164:167], v[34:37]
	v_mfma_f32_16x16x32_bf16 v[62:65], v[176:179], v[160:163], v[62:65]
	v_mfma_f32_16x16x32_bf16 v[58:61], v[176:179], v[168:171], v[58:61]
	v_mfma_f32_16x16x32_bf16 v[54:57], v[184:187], v[160:163], v[54:57]
	v_mfma_f32_16x16x32_bf16 v[50:53], v[184:187], v[168:171], v[50:53]
	v_mfma_f32_16x16x32_bf16 v[46:49], v[206:209], v[160:163], v[46:49]
	v_mfma_f32_16x16x32_bf16 v[42:45], v[206:209], v[168:171], v[42:45]
	v_mfma_f32_16x16x32_bf16 v[38:41], v[214:217], v[160:163], v[38:41]
	v_mfma_f32_16x16x32_bf16 v[34:37], v[214:217], v[168:171], v[34:37]
	v_mfma_f32_16x16x32_bf16 v[30:33], v[172:175], v[218:221], v[30:33]
	v_mfma_f32_16x16x32_bf16 v[26:29], v[172:175], v[226:229], v[26:29]
	v_mfma_f32_16x16x32_bf16 v[22:25], v[180:183], v[218:221], v[22:25]
	v_mfma_f32_16x16x32_bf16 v[18:21], v[180:183], v[226:229], v[18:21]
	v_mfma_f32_16x16x32_bf16 v[14:17], v[188:191], v[218:221], v[14:17]
	v_mfma_f32_16x16x32_bf16 v[10:13], v[188:191], v[226:229], v[10:13]
	v_mfma_f32_16x16x32_bf16 v[6:9], v[210:213], v[218:221], v[6:9]
	v_mfma_f32_16x16x32_bf16 v[2:5], v[210:213], v[226:229], v[2:5]
	v_mfma_f32_16x16x32_bf16 v[30:33], v[176:179], v[222:225], v[30:33]
	v_mfma_f32_16x16x32_bf16 v[26:29], v[176:179], v[230:233], v[26:29]
	v_mfma_f32_16x16x32_bf16 v[22:25], v[184:187], v[222:225], v[22:25]
	v_mfma_f32_16x16x32_bf16 v[18:21], v[184:187], v[230:233], v[18:21]
	v_mfma_f32_16x16x32_bf16 v[14:17], v[206:209], v[222:225], v[14:17]
	v_mfma_f32_16x16x32_bf16 v[10:13], v[206:209], v[230:233], v[10:13]
	v_mfma_f32_16x16x32_bf16 v[6:9], v[214:217], v[222:225], v[6:9]
	v_mfma_f32_16x16x32_bf16 v[2:5], v[214:217], v[230:233], v[2:5]
	s_add_i32 s9, s9, 2
	s_add_u32 s12, s12, 0x100
	s_addc_u32 s13, s13, 0
	s_add_u32 s14, s14, 0x100
	s_addc_u32 s15, s15, 0
	s_cmp_lt_u32 s9, 12
	s_barrier
	s_cbranch_scc1 .LBB0_427
	s_mov_b64 s[0:1], 0x780
	v_lshl_add_u64 v[136:137], v[130:131], 0, s[0:1]
	v_readfirstlane_b32 s0, v153
	s_mov_b32 m0, s0
	s_mov_b64 s[0:1], 0x20780
	v_lshl_add_u64 v[130:131], v[130:131], 0, s[0:1]
	v_readfirstlane_b32 s0, v154
	ds_read_b128 v[140:143], v149
	ds_read_b128 v[156:159], v149 offset:1024
	ds_read_b128 v[160:163], v149 offset:2048
	ds_read_b128 v[164:167], v149 offset:3072
	ds_read_b128 v[168:171], v132
	ds_read_b128 v[172:175], v132 offset:1024
	ds_read_b128 v[176:179], v150
	ds_read_b128 v[180:183], v150 offset:1024
	ds_read_b128 v[184:187], v151
	ds_read_b128 v[188:191], v151 offset:1024
	ds_read_b128 v[206:209], v152
	ds_read_b128 v[210:213], v152 offset:1024
	global_load_lds_dwordx4 v[136:137], off
	s_mov_b32 m0, s0
	s_nop 0
	global_load_lds_dwordx4 v[130:131], off
	s_waitcnt vmcnt(8)
	s_barrier
	s_waitcnt lgkmcnt(0)
	s_setprio 1
	s_waitcnt lgkmcnt(0)
	v_mfma_f32_16x16x32_bf16 v[126:129], v[168:171], v[140:143], v[126:129]
	v_mfma_f32_16x16x32_bf16 v[122:125], v[168:171], v[160:163], v[122:125]
	v_mfma_f32_16x16x32_bf16 v[118:121], v[176:179], v[140:143], v[118:121]
	v_mfma_f32_16x16x32_bf16 v[114:117], v[176:179], v[160:163], v[114:117]
	v_mfma_f32_16x16x32_bf16 v[110:113], v[184:187], v[140:143], v[110:113]
	v_mfma_f32_16x16x32_bf16 v[106:109], v[184:187], v[160:163], v[106:109]
	v_mfma_f32_16x16x32_bf16 v[102:105], v[206:209], v[140:143], v[102:105]
	v_mfma_f32_16x16x32_bf16 v[126:129], v[172:175], v[156:159], v[126:129]
	v_mfma_f32_16x16x32_bf16 v[122:125], v[172:175], v[164:167], v[122:125]
	v_mfma_f32_16x16x32_bf16 v[118:121], v[180:183], v[156:159], v[118:121]
	v_mfma_f32_16x16x32_bf16 v[114:117], v[180:183], v[164:167], v[114:117]
	v_mfma_f32_16x16x32_bf16 v[110:113], v[188:191], v[156:159], v[110:113]
	v_mfma_f32_16x16x32_bf16 v[106:109], v[188:191], v[164:167], v[106:109]
	v_mfma_f32_16x16x32_bf16 v[102:105], v[210:213], v[156:159], v[102:105]
	v_mfma_f32_16x16x32_bf16 v[98:101], v[206:209], v[160:163], v[98:101]
	v_mfma_f32_16x16x32_bf16 v[214:217], v[210:213], v[164:167], v[98:101]
	s_setprio 0
	s_barrier
; #define LDA(dst, b, h) for (int m = 0; m < 4; ++m) for (int k = 0; k < 2; ++k) \
;     dst[m][k] = *reinterpret_cast<const bf16x8*>((char*)SA(b, h) + lds_byte(wr * 64 + m * 16 + fr, k * 32 + fq * 8))
; #define LDB(dst, b, h) for (int n = 0; n < 2; ++n) for (int k = 0; k < 2; ++k) \
;     dst[n][k] = *reinterpret_cast<const bf16x8*>((char*)SB(b, h) + lds_byte(wc * 32 + n * 16 + fr, k * 32 + fq * 8))
; #define MMA(ai, bj, At_, Bt_) do { __builtin_amdgcn_s_setprio(1); \
;     for (int m = 0; m < 4; ++m) for (int n = 0; n < 2; ++n) for (int k = 0; k < 2; ++k) \
;       acc[ai][bj][m][n] = MFMA16(At_[m][k], Bt_[n][k], acc[ai][bj][m][n]); \
;     __builtin_amdgcn_s_setprio(0); } while (0)
; #define WAIT_V(n) asm volatile("s_waitcnt vmcnt(" #n ")" ::: "memory")
; #define WAIT_L(n) asm volatile("s_waitcnt lgkmcnt(" #n ")" ::: "memory")
; #define BAR __builtin_amdgcn_s_barrier()
; DI void gemm_core(WVP char* smem, const u16* __restrict__ A, int lda, int ar0, int ar1,
;                   const u16* __restrict__ B, int ldb, int bc0, int K, AccT& acc) {
;     ...
;     BAR; WAIT_L(0); MMA(0, 0, At, B0); BAR;
;     LDB(B1, 0, 1); BAR; WAIT_L(0); MMA(0, 1, At, B1); BAR;
;     LDA(At, 0, 1); WAIT_V(4); BAR; WAIT_L(0); MMA(1, 0, At, B0); MMA(1, 1, At, B1); BAR; }
;   { LDB(B0, 1, 0); LDA(At, 1, 0); WAIT_V(2); BAR; WAIT_L(0); MMA(0, 0, At, B0); BAR;
	s_nop 4
	ds_read_b128 v[98:101], v147
	ds_read_b128 v[218:221], v147 offset:1024
	ds_read_b128 v[222:225], v147 offset:2048
	ds_read_b128 v[144:147], v147 offset:3072
	s_barrier
	s_waitcnt lgkmcnt(0)
	s_setprio 1
	s_waitcnt lgkmcnt(0)
	v_mfma_f32_16x16x32_bf16 v[94:97], v[168:171], v[98:101], v[94:97]
	v_mfma_f32_16x16x32_bf16 v[86:89], v[176:179], v[98:101], v[86:89]
	v_mfma_f32_16x16x32_bf16 v[78:81], v[184:187], v[98:101], v[78:81]
	v_mfma_f32_16x16x32_bf16 v[70:73], v[206:209], v[98:101], v[70:73]
	v_mfma_f32_16x16x32_bf16 v[94:97], v[172:175], v[218:221], v[94:97]
	v_mfma_f32_16x16x32_bf16 v[90:93], v[168:171], v[222:225], v[90:93]
	v_mfma_f32_16x16x32_bf16 v[86:89], v[180:183], v[218:221], v[86:89]
	v_mfma_f32_16x16x32_bf16 v[82:85], v[176:179], v[222:225], v[82:85]
	v_mfma_f32_16x16x32_bf16 v[78:81], v[188:191], v[218:221], v[78:81]
	v_mfma_f32_16x16x32_bf16 v[74:77], v[184:187], v[222:225], v[74:77]
	v_mfma_f32_16x16x32_bf16 v[70:73], v[210:213], v[218:221], v[70:73]
	v_mfma_f32_16x16x32_bf16 v[66:69], v[206:209], v[222:225], v[66:69]
	v_mfma_f32_16x16x32_bf16 v[168:171], v[172:175], v[144:147], v[90:93]
	v_mfma_f32_16x16x32_bf16 v[172:175], v[180:183], v[144:147], v[82:85]
	v_mfma_f32_16x16x32_bf16 v[176:179], v[188:191], v[144:147], v[74:77]
	v_mfma_f32_16x16x32_bf16 v[180:183], v[210:213], v[144:147], v[66:69]
	s_setprio 0
	s_barrier
	s_nop 1
	ds_read_b128 v[66:69], v132 offset:16384
	ds_read_b128 v[74:77], v132 offset:17408
	ds_read_b128 v[82:85], v150 offset:16384
	ds_read_b128 v[90:93], v150 offset:17408
	ds_read_b128 v[184:187], v151 offset:16384
	ds_read_b128 v[188:191], v151 offset:17408
	ds_read_b128 v[206:209], v152 offset:16384
	ds_read_b128 v[210:213], v152 offset:17408
	s_waitcnt vmcnt(4)
	s_barrier
	s_waitcnt lgkmcnt(0)
	s_setprio 1
	s_waitcnt lgkmcnt(0)
	v_mfma_f32_16x16x32_bf16 v[62:65], v[66:69], v[140:143], v[62:65]
	v_mfma_f32_16x16x32_bf16 v[54:57], v[82:85], v[140:143], v[54:57]
	v_mfma_f32_16x16x32_bf16 v[42:45], v[184:187], v[160:163], v[42:45]
	v_mfma_f32_16x16x32_bf16 v[34:37], v[206:209], v[160:163], v[34:37]
	v_mfma_f32_16x16x32_bf16 v[62:65], v[74:77], v[156:159], v[62:65]
	v_mfma_f32_16x16x32_bf16 v[58:61], v[66:69], v[160:163], v[58:61]
	v_mfma_f32_16x16x32_bf16 v[54:57], v[90:93], v[156:159], v[54:57]
	v_mfma_f32_16x16x32_bf16 v[50:53], v[82:85], v[160:163], v[50:53]
	v_mfma_f32_16x16x32_bf16 v[46:49], v[184:187], v[140:143], v[46:49]
	v_mfma_f32_16x16x32_bf16 v[42:45], v[188:191], v[164:167], v[42:45]
	v_mfma_f32_16x16x32_bf16 v[38:41], v[206:209], v[140:143], v[38:41]
	v_mfma_f32_16x16x32_bf16 v[34:37], v[210:213], v[164:167], v[34:37]
	v_mfma_f32_16x16x32_bf16 v[226:229], v[74:77], v[164:167], v[58:61]
	v_mfma_f32_16x16x32_bf16 v[230:233], v[90:93], v[164:167], v[50:53]
	v_mfma_f32_16x16x32_bf16 v[234:237], v[188:191], v[156:159], v[46:49]
	v_mfma_f32_16x16x32_bf16 v[140:143], v[210:213], v[156:159], v[38:41]
	s_setprio 0
	s_setprio 1
	v_mfma_f32_16x16x32_bf16 v[26:29], v[66:69], v[222:225], v[26:29]
	v_mfma_f32_16x16x32_bf16 v[30:33], v[66:69], v[98:101], v[30:33]
	v_mfma_f32_16x16x32_bf16 v[26:29], v[74:77], v[144:147], v[26:29]
	v_mfma_f32_16x16x32_bf16 v[22:25], v[82:85], v[98:101], v[22:25]
	v_mfma_f32_16x16x32_bf16 v[18:21], v[82:85], v[222:225], v[18:21]
	v_mfma_f32_16x16x32_bf16 v[14:17], v[184:187], v[98:101], v[14:17]
	v_mfma_f32_16x16x32_bf16 v[10:13], v[184:187], v[222:225], v[10:13]
	v_mfma_f32_16x16x32_bf16 v[6:9], v[206:209], v[98:101], v[6:9]
	v_mfma_f32_16x16x32_bf16 v[2:5], v[206:209], v[222:225], v[2:5]
	v_mfma_f32_16x16x32_bf16 v[154:157], v[74:77], v[218:221], v[30:33]
	v_mfma_f32_16x16x32_bf16 v[158:161], v[90:93], v[218:221], v[22:25]
	v_mfma_f32_16x16x32_bf16 v[162:165], v[90:93], v[144:147], v[18:21]
	v_mfma_f32_16x16x32_bf16 v[238:241], v[188:191], v[218:221], v[14:17]
	v_mfma_f32_16x16x32_bf16 v[184:187], v[188:191], v[144:147], v[10:13]
	v_mfma_f32_16x16x32_bf16 v[188:191], v[210:213], v[218:221], v[6:9]
	v_mfma_f32_16x16x32_bf16 v[144:147], v[210:213], v[144:147], v[2:5]
	s_setprio 0
	s_barrier
	ds_read_b128 v[206:209], v138
	ds_read_b128 v[210:213], v138 offset:1024
	ds_read_b128 v[218:221], v138 offset:2048
	ds_read_b128 v[136:139], v138 offset:3072
	ds_read_b128 v[2:5], v132 offset:32768
	ds_read_b128 v[6:9], v132 offset:33792
	ds_read_b128 v[10:13], v150 offset:32768
	ds_read_b128 v[14:17], v150 offset:33792
	ds_read_b128 v[222:225], v151 offset:32768
	ds_read_b128 v[242:245], v151 offset:33792
	ds_read_b128 v[246:249], v152 offset:32768
	ds_read_b128 v[250:253], v152 offset:33792
	s_waitcnt vmcnt(2)
	s_barrier
; #define LDA(dst, b, h) for (int m = 0; m < 4; ++m) for (int k = 0; k < 2; ++k) \
;     dst[m][k] = *reinterpret_cast<const bf16x8*>((char*)SA(b, h) + lds_byte(wr * 64 + m * 16 + fr, k * 32 + fq * 8))
; #define LDB(dst, b, h) for (int n = 0; n < 2; ++n) for (int k = 0; k < 2; ++k) \
;     dst[n][k] = *reinterpret_cast<const bf16x8*>((char*)SB(b, h) + lds_byte(wc * 32 + n * 16 + fr, k * 32 + fq * 8))
; #define MMA(ai, bj, At_, Bt_) do { __builtin_amdgcn_s_setprio(1); \
;     for (int m = 0; m < 4; ++m) for (int n = 0; n < 2; ++n) for (int k = 0; k < 2; ++k) \
;       acc[ai][bj][m][n] = MFMA16(At_[m][k], Bt_[n][k], acc[ai][bj][m][n]); \
;     __builtin_amdgcn_s_setprio(0); } while (0)
; #define WAIT_V(n) asm volatile("s_waitcnt vmcnt(" #n ")" ::: "memory")
; #define WAIT_L(n) asm volatile("s_waitcnt lgkmcnt(" #n ")" ::: "memory")
; #define BAR __builtin_amdgcn_s_barrier()
; DI void gemm_core(WVP char* smem, const u16* __restrict__ A, int lda, int ar0, int ar1,
;                   const u16* __restrict__ B, int ldb, int bc0, int K, AccT& acc) {
;     ...
;   { LDB(B0, 1, 0); LDA(At, 1, 0); WAIT_V(2); BAR; WAIT_L(0); MMA(0, 0, At, B0); BAR;
;     LDB(B1, 1, 1); WAIT_V(0); BAR; WAIT_L(0); MMA(0, 1, At, B1); BAR;
;     LDA(At, 1, 1); BAR; WAIT_L(0); MMA(1, 0, At, B0); MMA(1, 1, At, B1); BAR; }
;   if (wr == 0) BAR;
	s_waitcnt lgkmcnt(0)
	s_setprio 1
	s_waitcnt lgkmcnt(0)
	v_mfma_f32_16x16x32_bf16 v[18:21], v[2:5], v[206:209], v[126:129]
	v_mfma_f32_16x16x32_bf16 v[98:101], v[6:9], v[210:213], v[18:21]
	v_mfma_f32_16x16x32_bf16 v[18:21], v[2:5], v[218:221], v[122:125]
	v_mfma_f32_16x16x32_bf16 v[90:93], v[6:9], v[136:139], v[18:21]
	v_mfma_f32_16x16x32_bf16 v[18:21], v[10:13], v[206:209], v[118:121]
	v_mfma_f32_16x16x32_bf16 v[82:85], v[14:17], v[210:213], v[18:21]
	v_mfma_f32_16x16x32_bf16 v[18:21], v[10:13], v[218:221], v[114:117]
	v_mfma_f32_16x16x32_bf16 v[74:77], v[14:17], v[136:139], v[18:21]
	v_mfma_f32_16x16x32_bf16 v[18:21], v[222:225], v[206:209], v[110:113]
	v_mfma_f32_16x16x32_bf16 v[66:69], v[242:245], v[210:213], v[18:21]
	v_mfma_f32_16x16x32_bf16 v[18:21], v[222:225], v[218:221], v[106:109]
	v_mfma_f32_16x16x32_bf16 v[58:61], v[242:245], v[136:139], v[18:21]
	v_mfma_f32_16x16x32_bf16 v[18:21], v[246:249], v[206:209], v[102:105]
	v_mfma_f32_16x16x32_bf16 v[50:53], v[250:253], v[210:213], v[18:21]
	v_mfma_f32_16x16x32_bf16 v[18:21], v[246:249], v[218:221], v[214:217]
	v_mfma_f32_16x16x32_bf16 v[38:41], v[250:253], v[136:139], v[18:21]
	s_setprio 0
	s_barrier
	ds_read_b128 v[214:217], v134
	ds_read_b128 v[196:199], v134 offset:1024
	ds_read_b128 v[192:195], v134 offset:2048
	ds_read_b128 v[200:203], v134 offset:3072
	s_waitcnt vmcnt(0)
	s_barrier
	s_waitcnt lgkmcnt(0)
	s_setprio 1
	s_waitcnt lgkmcnt(0)
	v_mfma_f32_16x16x32_bf16 v[18:21], v[2:5], v[214:217], v[94:97]
	v_mfma_f32_16x16x32_bf16 v[2:5], v[2:5], v[192:195], v[168:171]
	v_mfma_f32_16x16x32_bf16 v[30:33], v[6:9], v[200:203], v[2:5]
	v_mfma_f32_16x16x32_bf16 v[2:5], v[10:13], v[214:217], v[86:89]
	v_mfma_f32_16x16x32_bf16 v[22:25], v[14:17], v[196:199], v[2:5]
	v_mfma_f32_16x16x32_bf16 v[2:5], v[10:13], v[192:195], v[172:175]
	v_mfma_f32_16x16x32_bf16 v[46:49], v[6:9], v[196:199], v[18:21]
	v_mfma_f32_16x16x32_bf16 v[18:21], v[14:17], v[200:203], v[2:5]
	v_mfma_f32_16x16x32_bf16 v[2:5], v[222:225], v[214:217], v[78:81]
	v_mfma_f32_16x16x32_bf16 v[14:17], v[242:245], v[196:199], v[2:5]
	v_mfma_f32_16x16x32_bf16 v[2:5], v[222:225], v[192:195], v[176:179]
	v_mfma_f32_16x16x32_bf16 v[10:13], v[242:245], v[200:203], v[2:5]
	v_mfma_f32_16x16x32_bf16 v[2:5], v[246:249], v[214:217], v[70:73]
	v_mfma_f32_16x16x32_bf16 v[6:9], v[250:253], v[196:199], v[2:5]
	v_mfma_f32_16x16x32_bf16 v[2:5], v[246:249], v[192:195], v[180:183]
	v_mfma_f32_16x16x32_bf16 v[2:5], v[250:253], v[200:203], v[2:5]
	s_setprio 0
	s_barrier
	ds_read_b128 v[70:73], v132 offset:49152
	ds_read_b128 v[78:81], v132 offset:50176
	ds_read_b128 v[130:133], v150 offset:49152
	ds_read_b128 v[166:169], v150 offset:50176
	ds_read_b128 v[170:173], v151 offset:49152
	ds_read_b128 v[148:151], v151 offset:50176
	ds_read_b128 v[174:177], v152 offset:49152
	ds_read_b128 v[178:181], v152 offset:50176
	s_barrier
	s_waitcnt lgkmcnt(0)
	s_setprio 1
	s_waitcnt lgkmcnt(0)
	v_mfma_f32_16x16x32_bf16 v[54:57], v[130:133], v[206:209], v[54:57]
	v_mfma_f32_16x16x32_bf16 v[62:65], v[70:73], v[206:209], v[62:65]
	v_mfma_f32_16x16x32_bf16 v[118:121], v[166:169], v[210:213], v[54:57]
	v_mfma_f32_16x16x32_bf16 v[54:57], v[130:133], v[218:221], v[230:233]
	v_mfma_f32_16x16x32_bf16 v[42:45], v[170:173], v[218:221], v[42:45]
	v_mfma_f32_16x16x32_bf16 v[126:129], v[78:81], v[210:213], v[62:65]
	v_mfma_f32_16x16x32_bf16 v[62:65], v[70:73], v[218:221], v[226:229]
	v_mfma_f32_16x16x32_bf16 v[114:117], v[166:169], v[136:139], v[54:57]
	v_mfma_f32_16x16x32_bf16 v[54:57], v[170:173], v[206:209], v[234:237]
	v_mfma_f32_16x16x32_bf16 v[106:109], v[148:151], v[136:139], v[42:45]
	v_mfma_f32_16x16x32_bf16 v[42:45], v[174:177], v[206:209], v[140:143]
	v_mfma_f32_16x16x32_bf16 v[34:37], v[174:177], v[218:221], v[34:37]
	v_mfma_f32_16x16x32_bf16 v[122:125], v[78:81], v[136:139], v[62:65]
	v_mfma_f32_16x16x32_bf16 v[110:113], v[148:151], v[210:213], v[54:57]
	v_mfma_f32_16x16x32_bf16 v[102:105], v[178:181], v[210:213], v[42:45]
	v_mfma_f32_16x16x32_bf16 v[94:97], v[178:181], v[136:139], v[34:37]
	s_setprio 0
	s_setprio 1
	v_mfma_f32_16x16x32_bf16 v[34:37], v[70:73], v[214:217], v[154:157]
	v_mfma_f32_16x16x32_bf16 v[26:29], v[70:73], v[192:195], v[26:29]
	v_mfma_f32_16x16x32_bf16 v[86:89], v[78:81], v[196:199], v[34:37]
	v_mfma_f32_16x16x32_bf16 v[78:81], v[78:81], v[200:203], v[26:29]
	v_mfma_f32_16x16x32_bf16 v[26:29], v[130:133], v[214:217], v[158:161]
	v_mfma_f32_16x16x32_bf16 v[70:73], v[166:169], v[196:199], v[26:29]
	v_mfma_f32_16x16x32_bf16 v[26:29], v[130:133], v[192:195], v[162:165]
	v_mfma_f32_16x16x32_bf16 v[62:65], v[166:169], v[200:203], v[26:29]
	v_mfma_f32_16x16x32_bf16 v[26:29], v[170:173], v[214:217], v[238:241]
	v_mfma_f32_16x16x32_bf16 v[54:57], v[148:151], v[196:199], v[26:29]
	v_mfma_f32_16x16x32_bf16 v[26:29], v[170:173], v[192:195], v[184:187]
	v_mfma_f32_16x16x32_bf16 v[42:45], v[148:151], v[200:203], v[26:29]
	v_mfma_f32_16x16x32_bf16 v[26:29], v[174:177], v[214:217], v[188:191]
	v_mfma_f32_16x16x32_bf16 v[34:37], v[178:181], v[196:199], v[26:29]
	v_mfma_f32_16x16x32_bf16 v[26:29], v[174:177], v[192:195], v[144:147]
	v_mfma_f32_16x16x32_bf16 v[26:29], v[178:181], v[200:203], v[26:29]
	s_setprio 0
	s_cmp_gt_u32 s4, 3
	s_barrier
	s_cbranch_scc1 .LBB0_423
	s_barrier
	s_branch .LBB0_423
